# first trip of every GEMM K loop peeled with 0 as the MFMA addend, accumulator clear (127 v_mov per unit) removed; RoPE epilogue kept
# speedup vs baseline: 1.0283x; 1.0063x over previous
;     __device__ __forceinline__ bool next(int i, Unit& u) const { if (i != 0) return false; const int c0 = (G >= 8) ? G - 5 : G - 2; int k = -1; if (c == c0) k = 0; else if (c == G - 1) k = 1; if (k < 0 || k >= n) return false; u.pm = k; u.pn = 0; return true; }
; #define PG8_STAGE(bufoff, gbase, voff) do { _Pragma("unroll") for (int _i = 0; _i < 2; ++_i) \
;         __builtin_amdgcn_global_load_lds((const unsigned*)((const char*)(gbase) + (voff)[_i]), (PG8_LAS unsigned*)(lds + (bufoff) + ldsw + _i * 8192), 16, 0, 0); } while (0)
; #define PG8_LDA(dst, b, h) do { _Pragma("unroll") for (int m = 0; m < 4; ++m) _Pragma("unroll") for (int k = 0; k < 2; ++k) dst[m][k] = *(const PG8_LAS bf16x8*)(lds + PG8_SA(b, h) + aoff + m * 2048 + k * 1024); } while (0)
; #define PG8_LDB(dst, b, h) do { _Pragma("unroll") for (int n = 0; n < 2; ++n) _Pragma("unroll") for (int k = 0; k < 2; ++k) dst[n][k] = *(const PG8_LAS bf16x8*)(lds + PG8_SB(b, h) + boff + n * 2048 + k * 1024); } while (0)
; template <class Epi, class Sched, bool ALIGN_EPI = false, bool SP2 = false>
; __device__ __forceinline__ void gemm_phase(PG8_LAS unsigned char* lds, const Gemm g, const Sched& S, const Epi& E) {
;     ...
;         const bool has_next = S.next(ui + 1, nxt);
;         const char* nA = has_next ? (const char*)g.A + (size_t)nxt.pm * tstep : cA; const char* nB = has_next ? (const char*)g.Bt + (size_t)nxt.pn * tstep : cB;
;         for (int t = 0; t < nt; t += 2) {
;             const bool last = (t == nt - 2);
;             const char* a1 = cA + (size_t)(t + 1) * kstep;
;             const char* a2 = last ? nA : cA + (size_t)(t + 2) * kstep; const char* b2 = last ? nB : cB + (size_t)(t + 2) * kstep;
;             const char* a3 = a2 + kstep; const char* b3 = b2 + kstep;
;             if (last && has_next) S.a_ready(nxt);
;             if constexpr (SP2) {
;             PG8_LDB(B0, 0, 0); PG8_LDB(B1, 0, 1); PG8_SCHED; PG8_LDA(At, 0, 0); PG8_STAGE(PG8_SA(1, 1), a1 + hstep, voffA);
;             PG8_WAIT_V(8); PG8_WAIT_L(0); PG8_BAR; PG8_MMA(0, 0, At, B0); PG8_MMA(0, 1, At, B1); PG8_BAR; PG8_SCHED;
;             PG8_LDA(At, 0, 1); PG8_STAGE(PG8_SB(0, 0), b2, voffB); PG8_STAGE(PG8_SB(0, 1), b2 + hstep, voffB); PG8_STAGE(PG8_SA(0, 0), a2, voffA);
;             PG8_WAIT_V(8); PG8_WAIT_L(0); PG8_BAR; PG8_MMA(1, 0, At, B0); PG8_MMA(1, 1, At, B1); PG8_BAR; PG8_SCHED;
.LBB0_337:
	s_ashr_i32 s29, s28, 31
	s_lshl_b64 s[42:43], s[28:29], 19
	s_add_u32 s42, s97, s42
	s_addc_u32 s43, s3, s43
	s_and_b64 s[46:47], s[30:31], exec
	s_cselect_b32 s5, s43, s7
	s_cselect_b32 s29, s42, s6
	s_ashr_i32 s27, s26, 31
	s_lshl_b64 s[46:47], s[26:27], 19
	s_add_u32 s46, s90, s46
	s_addc_u32 s47, s91, s47
	s_and_b64 s[58:59], s[30:31], exec
	s_cselect_b32 s27, s47, s57
	s_cselect_b32 s60, s46, s56
	s_add_u32 s6, s6, 0x40080
	s_addc_u32 s7, s7, 0
	s_add_u32 s61, s56, 0x100
	v_mov_b32_e32 v0, 0
	s_addc_u32 s82, s57, 0
	s_mov_b32 s83, -2
	ds_read_b128 v[146:149], v163
	ds_read_b128 v[168:171], v163 offset:1024
	ds_read_b128 v[172:175], v163 offset:2048
	ds_read_b128 v[176:179], v163 offset:3072
	ds_read_b128 v[180:183], v164
	ds_read_b128 v[184:187], v164 offset:1024
	ds_read_b128 v[188:191], v164 offset:2048
	ds_read_b128 v[192:195], v164 offset:3072
	s_add_u32 s56, s6, 0xfffc0080
	s_addc_u32 s57, s7, -1
	s_cmp_eq_u32 s83, 12
	s_cselect_b32 s59, s5, s57
	s_cselect_b32 s58, s29, s56
	s_cselect_b32 s57, s27, s82
	s_cselect_b32 s56, s60, s61
	v_lshl_add_u64 v[150:151], s[6:7], 0, v[140:141]
	s_add_i32 m0, s41, 0xc000
	ds_read_b128 v[196:199], v165
	ds_read_b128 v[200:203], v165 offset:1024
	ds_read_b128 v[208:211], v165 offset:2048
	ds_read_b128 v[212:215], v165 offset:3072
	ds_read_b128 v[216:219], v165 offset:4096
	ds_read_b128 v[220:223], v165 offset:5120
	ds_read_b128 v[224:227], v165 offset:6144
	ds_read_b128 v[228:231], v165 offset:7168
	global_load_lds_dwordx4 v[150:151], off
	v_lshl_add_u64 v[150:151], s[6:7], 0, v[142:143]
	s_add_i32 m0, s41, 0xe000
	s_nop 0
	global_load_lds_dwordx4 v[150:151], off
	s_waitcnt vmcnt(8)
	s_waitcnt lgkmcnt(0)
	s_barrier
	s_setprio 1
	s_waitcnt lgkmcnt(0)
	v_mfma_f32_16x16x32_bf16 v[124:127], v[146:149], v[196:199], 0
	v_mfma_f32_16x16x32_bf16 v[120:123], v[172:175], v[196:199], 0
	v_mfma_f32_16x16x32_bf16 v[108:111], v[146:149], v[208:211], 0
	v_mfma_f32_16x16x32_bf16 v[104:107], v[172:175], v[208:211], 0
	v_mfma_f32_16x16x32_bf16 v[92:95], v[146:149], v[216:219], 0
	v_mfma_f32_16x16x32_bf16 v[88:91], v[172:175], v[216:219], 0
	v_mfma_f32_16x16x32_bf16 v[76:79], v[146:149], v[224:227], 0
	v_mfma_f32_16x16x32_bf16 v[72:75], v[172:175], v[224:227], 0
	v_mfma_f32_16x16x32_bf16 v[124:127], v[168:171], v[200:203], v[124:127]
	v_mfma_f32_16x16x32_bf16 v[120:123], v[176:179], v[200:203], v[120:123]
	v_mfma_f32_16x16x32_bf16 v[108:111], v[168:171], v[212:215], v[108:111]
	v_mfma_f32_16x16x32_bf16 v[104:107], v[176:179], v[212:215], v[104:107]
	v_mfma_f32_16x16x32_bf16 v[92:95], v[168:171], v[220:223], v[92:95]
	v_mfma_f32_16x16x32_bf16 v[88:91], v[176:179], v[220:223], v[88:91]
	v_mfma_f32_16x16x32_bf16 v[76:79], v[168:171], v[228:231], v[76:79]
	v_mfma_f32_16x16x32_bf16 v[72:75], v[176:179], v[228:231], v[72:75]
	s_setprio 0
	s_setprio 1
	v_mfma_f32_16x16x32_bf16 v[116:119], v[180:183], v[196:199], 0
	v_mfma_f32_16x16x32_bf16 v[112:115], v[188:191], v[196:199], 0
	v_mfma_f32_16x16x32_bf16 v[100:103], v[180:183], v[208:211], 0
	v_mfma_f32_16x16x32_bf16 v[96:99], v[188:191], v[208:211], 0
	v_mfma_f32_16x16x32_bf16 v[84:87], v[180:183], v[216:219], 0
	v_mfma_f32_16x16x32_bf16 v[80:83], v[188:191], v[216:219], 0
	v_mfma_f32_16x16x32_bf16 v[68:71], v[180:183], v[224:227], 0
	v_mfma_f32_16x16x32_bf16 v[64:67], v[188:191], v[224:227], 0
	v_mfma_f32_16x16x32_bf16 v[116:119], v[184:187], v[200:203], v[116:119]
	v_mfma_f32_16x16x32_bf16 v[112:115], v[192:195], v[200:203], v[112:115]
	v_mfma_f32_16x16x32_bf16 v[100:103], v[184:187], v[212:215], v[100:103]
	v_mfma_f32_16x16x32_bf16 v[96:99], v[192:195], v[212:215], v[96:99]
	v_mfma_f32_16x16x32_bf16 v[84:87], v[184:187], v[220:223], v[84:87]
	v_mfma_f32_16x16x32_bf16 v[80:83], v[192:195], v[220:223], v[80:83]
	v_mfma_f32_16x16x32_bf16 v[68:71], v[184:187], v[228:231], v[68:71]
	v_mfma_f32_16x16x32_bf16 v[64:67], v[192:195], v[228:231], v[64:67]
	s_setprio 0
	s_barrier
	s_add_i32 s92, s79, s25
	v_lshl_add_u64 v[150:151], s[56:57], 0, v[130:131]
	s_mov_b32 m0, s92
	ds_read_b128 v[196:199], v165 offset:16384
	ds_read_b128 v[200:203], v165 offset:17408
	ds_read_b128 v[208:211], v165 offset:18432
	ds_read_b128 v[212:215], v165 offset:19456
	ds_read_b128 v[216:219], v165 offset:20480
	ds_read_b128 v[220:223], v165 offset:21504
	ds_read_b128 v[224:227], v165 offset:22528
	ds_read_b128 v[228:231], v165 offset:23552
	global_load_lds_dwordx4 v[150:151], off
	s_add_i32 m0, s92, 0x2000
	s_add_u32 s92, s56, 0x40000
	v_lshl_add_u64 v[204:205], s[56:57], 0, v[134:135]
	s_addc_u32 s93, s57, 0
	s_add_i32 s94, s80, s25
	global_load_lds_dwordx4 v[204:205], off
	v_lshl_add_u64 v[232:233], s[92:93], 0, v[130:131]
	s_mov_b32 m0, s94
	v_lshl_add_u64 v[234:235], s[58:59], 0, v[132:133]
	global_load_lds_dwordx4 v[232:233], off
	v_lshl_add_u64 v[232:233], s[92:93], 0, v[134:135]
	s_add_i32 m0, s94, 0x2000
	s_nop 0
	global_load_lds_dwordx4 v[232:233], off
	v_lshl_add_u64 v[232:233], s[58:59], 0, v[128:129]
	s_mov_b32 m0, s41
	s_nop 0
	global_load_lds_dwordx4 v[232:233], off
	s_mov_b32 m0, s68
	s_nop 0
	global_load_lds_dwordx4 v[234:235], off
	s_waitcnt vmcnt(8)
	s_waitcnt lgkmcnt(0)
	s_barrier
; #define PG8_STAGE(bufoff, gbase, voff) do { _Pragma("unroll") for (int _i = 0; _i < 2; ++_i) \
;         __builtin_amdgcn_global_load_lds((const unsigned*)((const char*)(gbase) + (voff)[_i]), (PG8_LAS unsigned*)(lds + (bufoff) + ldsw + _i * 8192), 16, 0, 0); } while (0)
; #define PG8_LDA(dst, b, h) do { _Pragma("unroll") for (int m = 0; m < 4; ++m) _Pragma("unroll") for (int k = 0; k < 2; ++k) dst[m][k] = *(const PG8_LAS bf16x8*)(lds + PG8_SA(b, h) + aoff + m * 2048 + k * 1024); } while (0)
; #define PG8_LDB(dst, b, h) do { _Pragma("unroll") for (int n = 0; n < 2; ++n) _Pragma("unroll") for (int k = 0; k < 2; ++k) dst[n][k] = *(const PG8_LAS bf16x8*)(lds + PG8_SB(b, h) + boff + n * 2048 + k * 1024); } while (0)
; #define PG8_MMA(ai, bj, At, Bt) do { __builtin_amdgcn_s_setprio(1); _Pragma("unroll") for (int m = 0; m < 4; ++m) _Pragma("unroll") for (int n = 0; n < 2; ++n) _Pragma("unroll") for (int k = 0; k < 2; ++k) \
;         acc[ai][bj][m][n] = __builtin_amdgcn_mfma_f32_16x16x32_bf16(Bt[n][k], At[m][k], acc[ai][bj][m][n], 0, 0, 0); __builtin_amdgcn_s_setprio(0); } while (0)
; #define PG8_WAIT_V(n) asm volatile("s_waitcnt vmcnt(" #n ")" ::: "memory")
; #define PG8_WAIT_L(n) asm volatile("s_waitcnt lgkmcnt(" #n ")" ::: "memory")
; #define PG8_BAR __builtin_amdgcn_s_barrier()
; #define PG8_SCHED __builtin_amdgcn_sched_barrier(0)
; template <class Epi, class Sched, bool ALIGN_EPI = false, bool SP2 = false>
; __device__ __forceinline__ void gemm_phase(PG8_LAS unsigned char* lds, const Gemm g, const Sched& S, const Epi& E) {
;     ...
;             PG8_WAIT_V(8); PG8_WAIT_L(0); PG8_BAR; PG8_MMA(1, 0, At, B0); PG8_MMA(1, 1, At, B1); PG8_BAR; PG8_SCHED;
;             PG8_LDB(B0, 1, 0); PG8_LDB(B1, 1, 1); PG8_SCHED; PG8_LDA(At, 1, 0); PG8_STAGE(PG8_SA(0, 1), a2 + hstep, voffA);
;             PG8_WAIT_V(8); PG8_WAIT_L(0); PG8_BAR; PG8_MMA(0, 0, At, B0); PG8_MMA(0, 1, At, B1); PG8_BAR; PG8_SCHED;
	s_setprio 1
	s_waitcnt lgkmcnt(0)
	v_mfma_f32_16x16x32_bf16 v[60:63], v[146:149], v[196:199], 0
	v_mfma_f32_16x16x32_bf16 v[56:59], v[172:175], v[196:199], 0
	v_mfma_f32_16x16x32_bf16 v[44:47], v[146:149], v[208:211], 0
	v_mfma_f32_16x16x32_bf16 v[40:43], v[172:175], v[208:211], 0
	v_mfma_f32_16x16x32_bf16 v[28:31], v[146:149], v[216:219], 0
	v_mfma_f32_16x16x32_bf16 v[24:27], v[172:175], v[216:219], 0
	v_mfma_f32_16x16x32_bf16 v[12:15], v[146:149], v[224:227], 0
	v_mfma_f32_16x16x32_bf16 v[8:11], v[172:175], v[224:227], 0
	v_mfma_f32_16x16x32_bf16 v[60:63], v[168:171], v[200:203], v[60:63]
	v_mfma_f32_16x16x32_bf16 v[56:59], v[176:179], v[200:203], v[56:59]
	v_mfma_f32_16x16x32_bf16 v[44:47], v[168:171], v[212:215], v[44:47]
	v_mfma_f32_16x16x32_bf16 v[40:43], v[176:179], v[212:215], v[40:43]
	v_mfma_f32_16x16x32_bf16 v[28:31], v[168:171], v[220:223], v[28:31]
	v_mfma_f32_16x16x32_bf16 v[24:27], v[176:179], v[220:223], v[24:27]
	v_mfma_f32_16x16x32_bf16 v[12:15], v[168:171], v[228:231], v[12:15]
	v_mfma_f32_16x16x32_bf16 v[8:11], v[176:179], v[228:231], v[8:11]
	s_setprio 0
	s_setprio 1
	v_mfma_f32_16x16x32_bf16 v[52:55], v[180:183], v[196:199], 0
	v_mfma_f32_16x16x32_bf16 v[48:51], v[188:191], v[196:199], 0
	v_mfma_f32_16x16x32_bf16 v[36:39], v[180:183], v[208:211], 0
	v_mfma_f32_16x16x32_bf16 v[32:35], v[188:191], v[208:211], 0
	v_mfma_f32_16x16x32_bf16 v[20:23], v[180:183], v[216:219], 0
	v_mfma_f32_16x16x32_bf16 v[16:19], v[188:191], v[216:219], 0
	v_mfma_f32_16x16x32_bf16 v[4:7], v[180:183], v[224:227], 0
	v_mfma_f32_16x16x32_bf16 v[0:3], v[188:191], v[224:227], 0
	v_mfma_f32_16x16x32_bf16 v[52:55], v[184:187], v[200:203], v[52:55]
	v_mfma_f32_16x16x32_bf16 v[48:51], v[192:195], v[200:203], v[48:51]
	v_mfma_f32_16x16x32_bf16 v[36:39], v[184:187], v[212:215], v[36:39]
	v_mfma_f32_16x16x32_bf16 v[32:35], v[192:195], v[212:215], v[32:35]
	v_mfma_f32_16x16x32_bf16 v[20:23], v[184:187], v[220:223], v[20:23]
	v_mfma_f32_16x16x32_bf16 v[16:19], v[192:195], v[220:223], v[16:19]
	v_mfma_f32_16x16x32_bf16 v[4:7], v[184:187], v[228:231], v[4:7]
	v_mfma_f32_16x16x32_bf16 v[0:3], v[192:195], v[228:231], v[0:3]
	s_setprio 0
	s_barrier
	s_add_i32 s92, 0, 0x18000
	v_add_u32_e32 v167, s92, v161
	s_add_i32 s93, 0, 0x1c000
	ds_read_b128 v[146:149], v167
	ds_read_b128 v[168:171], v167 offset:1024
	ds_read_b128 v[172:175], v167 offset:2048
	ds_read_b128 v[176:179], v167 offset:3072
	v_add_u32_e32 v167, s93, v161
	ds_read_b128 v[180:183], v167
	ds_read_b128 v[184:187], v167 offset:1024
	ds_read_b128 v[188:191], v167 offset:2048
	ds_read_b128 v[192:195], v167 offset:3072
	s_add_u32 s58, s58, 0x40000
	s_addc_u32 s59, s59, 0
	s_mov_b32 m0, s69
	v_lshl_add_u64 v[236:237], s[58:59], 0, v[128:129]
	ds_read_b128 v[196:199], v165 offset:32768
	ds_read_b128 v[200:203], v165 offset:33792
	ds_read_b128 v[208:211], v165 offset:34816
	ds_read_b128 v[212:215], v165 offset:35840
	ds_read_b128 v[216:219], v165 offset:36864
	ds_read_b128 v[220:223], v165 offset:37888
	ds_read_b128 v[224:227], v165 offset:38912
	ds_read_b128 v[228:231], v165 offset:39936
	global_load_lds_dwordx4 v[236:237], off
	v_lshl_add_u64 v[236:237], s[58:59], 0, v[132:133]
	s_mov_b32 m0, s71
	s_nop 0
	global_load_lds_dwordx4 v[236:237], off
	s_waitcnt vmcnt(8)
	s_waitcnt lgkmcnt(0)
	s_barrier
	s_setprio 1
	s_waitcnt lgkmcnt(0)
	v_mfma_f32_16x16x32_bf16 v[124:127], v[146:149], v[196:199], v[124:127]
	v_mfma_f32_16x16x32_bf16 v[120:123], v[172:175], v[196:199], v[120:123]
	v_mfma_f32_16x16x32_bf16 v[108:111], v[146:149], v[208:211], v[108:111]
	v_mfma_f32_16x16x32_bf16 v[104:107], v[172:175], v[208:211], v[104:107]
	v_mfma_f32_16x16x32_bf16 v[92:95], v[146:149], v[216:219], v[92:95]
	v_mfma_f32_16x16x32_bf16 v[88:91], v[172:175], v[216:219], v[88:91]
	v_mfma_f32_16x16x32_bf16 v[76:79], v[146:149], v[224:227], v[76:79]
	v_mfma_f32_16x16x32_bf16 v[72:75], v[172:175], v[224:227], v[72:75]
	v_mfma_f32_16x16x32_bf16 v[124:127], v[168:171], v[200:203], v[124:127]
	v_mfma_f32_16x16x32_bf16 v[120:123], v[176:179], v[200:203], v[120:123]
	v_mfma_f32_16x16x32_bf16 v[108:111], v[168:171], v[212:215], v[108:111]
	v_mfma_f32_16x16x32_bf16 v[104:107], v[176:179], v[212:215], v[104:107]
	v_mfma_f32_16x16x32_bf16 v[92:95], v[168:171], v[220:223], v[92:95]
	v_mfma_f32_16x16x32_bf16 v[88:91], v[176:179], v[220:223], v[88:91]
	v_mfma_f32_16x16x32_bf16 v[76:79], v[168:171], v[228:231], v[76:79]
	v_mfma_f32_16x16x32_bf16 v[72:75], v[176:179], v[228:231], v[72:75]
	s_setprio 0
	s_setprio 1
	v_mfma_f32_16x16x32_bf16 v[116:119], v[180:183], v[196:199], v[116:119]
	v_mfma_f32_16x16x32_bf16 v[112:115], v[188:191], v[196:199], v[112:115]
	v_mfma_f32_16x16x32_bf16 v[100:103], v[180:183], v[208:211], v[100:103]
	v_mfma_f32_16x16x32_bf16 v[96:99], v[188:191], v[208:211], v[96:99]
	v_mfma_f32_16x16x32_bf16 v[84:87], v[180:183], v[216:219], v[84:87]
	v_mfma_f32_16x16x32_bf16 v[80:83], v[188:191], v[216:219], v[80:83]
	v_mfma_f32_16x16x32_bf16 v[68:71], v[180:183], v[224:227], v[68:71]
	v_mfma_f32_16x16x32_bf16 v[64:67], v[188:191], v[224:227], v[64:67]
	v_mfma_f32_16x16x32_bf16 v[116:119], v[184:187], v[200:203], v[116:119]
	v_mfma_f32_16x16x32_bf16 v[112:115], v[192:195], v[200:203], v[112:115]
	v_mfma_f32_16x16x32_bf16 v[100:103], v[184:187], v[212:215], v[100:103]
	v_mfma_f32_16x16x32_bf16 v[96:99], v[192:195], v[212:215], v[96:99]
	v_mfma_f32_16x16x32_bf16 v[84:87], v[184:187], v[220:223], v[84:87]
	v_mfma_f32_16x16x32_bf16 v[80:83], v[192:195], v[220:223], v[80:83]
	v_mfma_f32_16x16x32_bf16 v[68:71], v[184:187], v[228:231], v[68:71]
	v_mfma_f32_16x16x32_bf16 v[64:67], v[192:195], v[228:231], v[64:67]
	s_setprio 0
	s_barrier
; #define PG8_STAGE(bufoff, gbase, voff) do { _Pragma("unroll") for (int _i = 0; _i < 2; ++_i) \
;         __builtin_amdgcn_global_load_lds((const unsigned*)((const char*)(gbase) + (voff)[_i]), (PG8_LAS unsigned*)(lds + (bufoff) + ldsw + _i * 8192), 16, 0, 0); } while (0)
; #define PG8_LDA(dst, b, h) do { _Pragma("unroll") for (int m = 0; m < 4; ++m) _Pragma("unroll") for (int k = 0; k < 2; ++k) dst[m][k] = *(const PG8_LAS bf16x8*)(lds + PG8_SA(b, h) + aoff + m * 2048 + k * 1024); } while (0)
; #define PG8_MMA(ai, bj, At, Bt) do { __builtin_amdgcn_s_setprio(1); _Pragma("unroll") for (int m = 0; m < 4; ++m) _Pragma("unroll") for (int n = 0; n < 2; ++n) _Pragma("unroll") for (int k = 0; k < 2; ++k) \
;         acc[ai][bj][m][n] = __builtin_amdgcn_mfma_f32_16x16x32_bf16(Bt[n][k], At[m][k], acc[ai][bj][m][n], 0, 0, 0); __builtin_amdgcn_s_setprio(0); } while (0)
; #define PG8_WAIT_V(n) asm volatile("s_waitcnt vmcnt(" #n ")" ::: "memory")
; #define PG8_WAIT_L(n) asm volatile("s_waitcnt lgkmcnt(" #n ")" ::: "memory")
; #define PG8_BAR __builtin_amdgcn_s_barrier()
; #define PG8_SCHED __builtin_amdgcn_sched_barrier(0)
; template <class Epi, class Sched, bool ALIGN_EPI = false, bool SP2 = false>
; __device__ __forceinline__ void gemm_phase(PG8_LAS unsigned char* lds, const Gemm g, const Sched& S, const Epi& E) {
;     ...
;             PG8_LDA(At, 1, 1); PG8_STAGE(PG8_SB(1, 0), b3, voffB); PG8_STAGE(PG8_SB(1, 1), b3 + hstep, voffB); PG8_STAGE(PG8_SA(1, 0), a3, voffA);
;             PG8_WAIT_V(8); PG8_WAIT_L(0); PG8_BAR; PG8_MMA(1, 0, At, B0); PG8_MMA(1, 1, At, B1); PG8_BAR; PG8_SCHED;
	s_add_i32 s58, s92, s25
	v_lshl_add_u64 v[150:151], v[150:151], 0, s[20:21]
	s_mov_b32 m0, s58
	ds_read_b128 v[196:199], v165 offset:49152
	ds_read_b128 v[200:203], v165 offset:50176
	ds_read_b128 v[208:211], v165 offset:51200
	ds_read_b128 v[212:215], v165 offset:52224
	ds_read_b128 v[216:219], v165 offset:53248
	ds_read_b128 v[220:223], v165 offset:54272
	ds_read_b128 v[224:227], v165 offset:55296
	ds_read_b128 v[228:231], v165 offset:56320
	global_load_lds_dwordx4 v[150:151], off
	s_add_i32 m0, s58, 0x2000
	s_add_u32 s56, s56, 0x40080
	v_lshl_add_u64 v[150:151], v[204:205], 0, s[20:21]
	s_addc_u32 s57, s57, 0
	s_add_i32 s58, s93, s25
	global_load_lds_dwordx4 v[150:151], off
	v_lshl_add_u64 v[150:151], s[56:57], 0, v[130:131]
	s_mov_b32 m0, s58
	s_nop 0
	global_load_lds_dwordx4 v[150:151], off
	v_lshl_add_u64 v[150:151], s[56:57], 0, v[134:135]
	s_add_i32 m0, s58, 0x2000
	s_nop 0
	global_load_lds_dwordx4 v[150:151], off
	v_lshl_add_u64 v[150:151], v[232:233], 0, s[20:21]
	s_mov_b32 m0, s73
	s_nop 0
	global_load_lds_dwordx4 v[150:151], off
	v_lshl_add_u64 v[150:151], v[234:235], 0, s[20:21]
	s_mov_b32 m0, s74
	s_nop 0
	global_load_lds_dwordx4 v[150:151], off
	s_waitcnt vmcnt(8)
	s_waitcnt lgkmcnt(0)
	s_barrier
	s_setprio 1
	s_waitcnt lgkmcnt(0)
	v_mfma_f32_16x16x32_bf16 v[60:63], v[146:149], v[196:199], v[60:63]
	v_mfma_f32_16x16x32_bf16 v[56:59], v[172:175], v[196:199], v[56:59]
	v_mfma_f32_16x16x32_bf16 v[44:47], v[146:149], v[208:211], v[44:47]
	v_mfma_f32_16x16x32_bf16 v[40:43], v[172:175], v[208:211], v[40:43]
	v_mfma_f32_16x16x32_bf16 v[28:31], v[146:149], v[216:219], v[28:31]
	v_mfma_f32_16x16x32_bf16 v[24:27], v[172:175], v[216:219], v[24:27]
	v_mfma_f32_16x16x32_bf16 v[12:15], v[146:149], v[224:227], v[12:15]
	v_mfma_f32_16x16x32_bf16 v[8:11], v[172:175], v[224:227], v[8:11]
	v_mfma_f32_16x16x32_bf16 v[60:63], v[168:171], v[200:203], v[60:63]
	v_mfma_f32_16x16x32_bf16 v[56:59], v[176:179], v[200:203], v[56:59]
	v_mfma_f32_16x16x32_bf16 v[44:47], v[168:171], v[212:215], v[44:47]
	v_mfma_f32_16x16x32_bf16 v[40:43], v[176:179], v[212:215], v[40:43]
	v_mfma_f32_16x16x32_bf16 v[28:31], v[168:171], v[220:223], v[28:31]
	v_mfma_f32_16x16x32_bf16 v[24:27], v[176:179], v[220:223], v[24:27]
	v_mfma_f32_16x16x32_bf16 v[12:15], v[168:171], v[228:231], v[12:15]
	v_mfma_f32_16x16x32_bf16 v[8:11], v[176:179], v[228:231], v[8:11]
	s_setprio 0
	s_setprio 1
	v_mfma_f32_16x16x32_bf16 v[52:55], v[180:183], v[196:199], v[52:55]
	v_mfma_f32_16x16x32_bf16 v[48:51], v[188:191], v[196:199], v[48:51]
	v_mfma_f32_16x16x32_bf16 v[36:39], v[180:183], v[208:211], v[36:39]
	v_mfma_f32_16x16x32_bf16 v[32:35], v[188:191], v[208:211], v[32:35]
	v_mfma_f32_16x16x32_bf16 v[20:23], v[180:183], v[216:219], v[20:23]
	v_mfma_f32_16x16x32_bf16 v[16:19], v[188:191], v[216:219], v[16:19]
	v_mfma_f32_16x16x32_bf16 v[4:7], v[180:183], v[224:227], v[4:7]
	v_mfma_f32_16x16x32_bf16 v[0:3], v[188:191], v[224:227], v[0:3]
	v_mfma_f32_16x16x32_bf16 v[52:55], v[184:187], v[200:203], v[52:55]
	v_mfma_f32_16x16x32_bf16 v[48:51], v[192:195], v[200:203], v[48:51]
	v_mfma_f32_16x16x32_bf16 v[36:39], v[184:187], v[212:215], v[36:39]
	v_mfma_f32_16x16x32_bf16 v[32:35], v[192:195], v[212:215], v[32:35]
	v_mfma_f32_16x16x32_bf16 v[20:23], v[184:187], v[220:223], v[20:23]
	v_mfma_f32_16x16x32_bf16 v[16:19], v[192:195], v[220:223], v[16:19]
	v_mfma_f32_16x16x32_bf16 v[4:7], v[184:187], v[228:231], v[4:7]
	v_mfma_f32_16x16x32_bf16 v[0:3], v[192:195], v[228:231], v[0:3]
	s_setprio 0
	s_barrier
	s_add_i32 s83, s83, 2
	s_add_u32 s6, s6, 0x100
	s_addc_u32 s7, s7, 0
	s_add_u32 s61, s61, 0x100
	s_addc_u32 s82, s82, 0
	s_cmp_gt_u32 s83, 13
	s_cbranch_scc0 .LBB0_338
	s_branch .Lpeel_exit_1

; #define PG8_BAR __builtin_amdgcn_s_barrier()
; template <class Epi, class Sched, bool ALIGN_EPI = false, bool SP2 = false>
; __device__ __forceinline__ void gemm_phase(PG8_LAS unsigned char* lds, const Gemm g, const Sched& S, const Epi& E) {
;     ...
;         if constexpr (ALIGN_EPI) { if (wr == 0) PG8_BAR; }
;         if constexpr (!Epi::AFTER_DRAIN) { E(acc, cur, wr, wc, fr, fq); S.done(cur); }
.Lpeel_exit_1:
	s_and_b64 vcc, exec, s[22:23]
	s_cbranch_vccz .LBB0_341
	s_barrier

;     __device__ __forceinline__ bool next(int i, Unit& u) const { if (i != 0) return false; const int c0 = (G >= 8) ? G - 5 : G - 2; int k = -1; if (c == c0) k = 0; else if (c == G - 1) k = 1; if (k < 0 || k >= n) return false; u.pm = k; u.pn = 0; return true; }
; #define PG8_STAGE(bufoff, gbase, voff) do { _Pragma("unroll") for (int _i = 0; _i < 2; ++_i) \
;         __builtin_amdgcn_global_load_lds((const unsigned*)((const char*)(gbase) + (voff)[_i]), (PG8_LAS unsigned*)(lds + (bufoff) + ldsw + _i * 8192), 16, 0, 0); } while (0)
; #define PG8_WAIT_V(n) asm volatile("s_waitcnt vmcnt(" #n ")" ::: "memory")
; template <class Epi, class Sched, bool ALIGN_EPI = false, bool SP2 = false>
; __device__ __forceinline__ void gemm_phase(PG8_LAS unsigned char* lds, const Gemm g, const Sched& S, const Epi& E) {
;     ...
;         PG8_STAGE(PG8_SB(1, 0), cB + kstep, voffB); PG8_STAGE(PG8_SA(1, 0), cA + kstep, voffA); PG8_STAGE(PG8_SB(1, 1), cB + hstep + kstep, voffB);
;         PG8_WAIT_V(6); PG8_BAR;
;     } else {
;         PG8_STAGE(PG8_SB(0, 0), cB, voffB); PG8_STAGE(PG8_SA(0, 0), cA, voffA); PG8_STAGE(PG8_SB(0, 1), cB + hstep, voffB); PG8_STAGE(PG8_SA(0, 1), cA + hstep, voffA);
;         if (wr == 1) PG8_BAR;
;         PG8_WAIT_V(4); PG8_BAR;
;         PG8_STAGE(PG8_SB(1, 0), cB + kstep, voffB); PG8_STAGE(PG8_SA(1, 0), cA + kstep, voffA); PG8_STAGE(PG8_SB(1, 1), cB + hstep + kstep, voffB);
;         PG8_WAIT_V(6); PG8_BAR;
;     }
;     for (;;) {
;         const bool has_next = S.next(ui + 1, nxt);
;         const char* nA = has_next ? (const char*)g.A + (size_t)nxt.pm * tstep : cA; const char* nB = has_next ? (const char*)g.Bt + (size_t)nxt.pn * tstep : cB;
;         for (int t = 0; t < nt; t += 2) {
;             const bool last = (t == nt - 2);
;             const char* a1 = cA + (size_t)(t + 1) * kstep;
;             const char* a2 = last ? nA : cA + (size_t)(t + 2) * kstep; const char* b2 = last ? nB : cB + (size_t)(t + 2) * kstep;
;             const char* a3 = a2 + kstep; const char* b3 = b2 + kstep;
;             if (last && has_next) S.a_ready(nxt);
;             if constexpr (SP2) {
;             PG8_LDB(B0, 0, 0); PG8_LDB(B1, 0, 1); PG8_SCHED; PG8_LDA(At, 0, 0); PG8_STAGE(PG8_SA(1, 1), a1 + hstep, voffA);
;             PG8_WAIT_V(8); PG8_WAIT_L(0); PG8_BAR; PG8_MMA(0, 0, At, B0); PG8_MMA(0, 1, At, B1); PG8_BAR; PG8_SCHED;
.LBB0_396:
	s_lshl_b32 s14, s14, 5
	v_lshlrev_b32_e32 v4, 1, v152
	s_and_b32 s40, s14, 0x60
	v_lshl_or_b32 v140, s15, 6, v158
	v_lshl_or_b32 v5, v158, 6, v4
	s_lshl_b32 s15, s15, 13
	v_lshlrev_b32_e32 v6, 2, v158
	v_or_b32_e32 v4, v4, v157
	s_lshl_b32 s14, s40, 7
	v_and_b32_e32 v6, 32, v6
	v_bitop3_b32 v7, s14, v4, v159 bitop3:0xf6
	s_add_u32 s14, s50, 0x300080
	v_bitop3_b32 v6, v5, s15, v6 bitop3:0xde
	s_addc_u32 s15, s51, 0
	s_add_i32 m0, s5, 0x18000
	v_lshl_add_u64 v[4:5], s[14:15], 0, v[130:131]
	s_waitcnt vmcnt(2)
	s_barrier
	global_load_lds_dwordx4 v[4:5], off
	v_lshl_add_u64 v[4:5], s[14:15], 0, v[134:135]
	s_add_i32 m0, s5, 0x1a000
	s_mov_b64 s[14:15], 0x80
	s_add_i32 s41, s5, 0x8000
	s_add_i32 s42, s5, 0xa000
	global_load_lds_dwordx4 v[4:5], off
	v_lshl_add_u64 v[2:3], v[2:3], 0, s[14:15]
	s_mov_b32 m0, s41
	s_add_u32 s22, s50, 0x340080
	global_load_lds_dwordx4 v[2:3], off
	v_lshl_add_u64 v[0:1], v[0:1], 0, s[14:15]
	s_mov_b32 m0, s42
	s_addc_u32 s23, s51, 0
	global_load_lds_dwordx4 v[0:1], off
	s_add_i32 m0, s5, 0x1c000
	v_lshl_add_u64 v[0:1], s[22:23], 0, v[130:131]
	global_load_lds_dwordx4 v[0:1], off
	v_lshl_add_u64 v[0:1], s[22:23], 0, v[134:135]
	s_add_i32 m0, s5, 0x1e000
	v_lshlrev_b32_e32 v2, 11, v155
	global_load_lds_dwordx4 v[0:1], off
	v_lshlrev_b32_e32 v0, 8, v206
	v_and_b32_e32 v0, 0x38000, v0
	s_add_u32 s20, s50, s20
	v_or3_b32 v0, v153, v0, v2
	s_addc_u32 s21, s51, s21
	v_add_u32_e32 v0, v0, v154
	v_mov_b32_e32 v1, v131
	v_lshl_add_u64 v[0:1], s[20:21], 0, v[0:1]
	s_mov_b64 s[22:23], 0x7440080
	v_lshl_add_u64 v[136:137], v[0:1], 0, s[22:23]
	v_lshlrev_b32_e32 v0, 4, v156
	v_and_b32_e32 v0, 0x78000, v0
	v_or3_b32 v0, v153, v0, v2
	s_waitcnt vmcnt(6)
	v_add_u32_e32 v0, v0, v154
	v_mov_b32_e32 v1, v131
	s_add_i32 s56, 0, 0x10000
	s_add_i32 s58, 0, 0x14000
	s_add_i32 s60, 0, 0x18000
	s_add_i32 s68, 0, 0x1c000
	v_lshl_add_u64 v[0:1], s[20:21], 0, v[0:1]
	v_add_u32_e32 v141, s56, v7
	v_add_u32_e32 v142, s58, v7
	s_add_i32 s56, s56, s24
	s_add_i32 s58, s58, s24
	v_add_u32_e32 v144, s60, v7
	v_add_u32_e32 v145, s68, v7
	s_add_i32 s60, s60, s24
	s_add_i32 s68, s68, s24
	v_lshl_add_u64 v[138:139], v[0:1], 0, s[22:23]
	s_mov_b32 s43, -2
	s_mov_b64 s[22:23], 0
	v_add_u32_e32 v143, 0, v6
	s_add_i32 s46, s5, 0xc000
	s_add_i32 s47, s5, 0xe000
	s_add_i32 s57, s56, 0x2000
	s_add_i32 s59, s58, 0x2000
	s_add_i32 s61, s60, 0x2000
	s_add_i32 s69, s68, 0x2000
	s_barrier
	ds_read_b128 v[146:149], v141
	ds_read_b128 v[154:157], v141 offset:1024
	ds_read_b128 v[158:161], v141 offset:2048
	ds_read_b128 v[162:165], v141 offset:3072
	ds_read_b128 v[166:169], v142
	ds_read_b128 v[170:173], v142 offset:1024
	ds_read_b128 v[174:177], v142 offset:2048
	ds_read_b128 v[178:181], v142 offset:3072
	s_add_u32 s24, s20, s22
	s_addc_u32 s25, s21, s23
	s_add_u32 s24, s24, 0x7400100
	s_addc_u32 s25, s25, 0
	s_add_u32 s26, s50, s22
	s_addc_u32 s27, s51, s23
	s_add_u32 s71, s26, 0x300100
	s_addc_u32 s72, s27, 0
	s_cmpk_eq_i32 s22, 0x700
	s_cselect_b32 s27, s9, s25
	s_cselect_b32 s26, s8, s24
	s_cselect_b32 s25, s7, s72
	s_cselect_b32 s24, s6, s71
	s_mov_b32 m0, s46
	v_lshl_add_u64 v[150:151], v[136:137], 0, s[22:23]
	ds_read_b128 v[182:185], v143
	ds_read_b128 v[186:189], v143 offset:1024
	ds_read_b128 v[190:193], v143 offset:2048
	ds_read_b128 v[194:197], v143 offset:3072
	ds_read_b128 v[198:201], v143 offset:4096
	ds_read_b128 v[202:205], v143 offset:5120
	ds_read_b128 v[208:211], v143 offset:6144
	ds_read_b128 v[212:215], v143 offset:7168
	global_load_lds_dwordx4 v[150:151], off
	v_lshl_add_u64 v[150:151], v[138:139], 0, s[22:23]
	s_mov_b32 m0, s47
	s_nop 0
	global_load_lds_dwordx4 v[150:151], off
	s_waitcnt vmcnt(8)
	s_waitcnt lgkmcnt(0)
	s_barrier
	s_setprio 1
	s_waitcnt lgkmcnt(0)
	v_mfma_f32_16x16x32_bf16 v[124:127], v[146:149], v[182:185], 0
	v_mfma_f32_16x16x32_bf16 v[120:123], v[158:161], v[182:185], 0
	v_mfma_f32_16x16x32_bf16 v[116:119], v[146:149], v[190:193], 0
	v_mfma_f32_16x16x32_bf16 v[112:115], v[158:161], v[190:193], 0
	v_mfma_f32_16x16x32_bf16 v[100:103], v[146:149], v[198:201], 0
	v_mfma_f32_16x16x32_bf16 v[96:99], v[158:161], v[198:201], 0
	v_mfma_f32_16x16x32_bf16 v[84:87], v[146:149], v[208:211], 0
	v_mfma_f32_16x16x32_bf16 v[80:83], v[158:161], v[208:211], 0
	v_mfma_f32_16x16x32_bf16 v[124:127], v[154:157], v[186:189], v[124:127]
	v_mfma_f32_16x16x32_bf16 v[120:123], v[162:165], v[186:189], v[120:123]
	v_mfma_f32_16x16x32_bf16 v[116:119], v[154:157], v[194:197], v[116:119]
	v_mfma_f32_16x16x32_bf16 v[112:115], v[162:165], v[194:197], v[112:115]
	v_mfma_f32_16x16x32_bf16 v[100:103], v[154:157], v[202:205], v[100:103]
	v_mfma_f32_16x16x32_bf16 v[96:99], v[162:165], v[202:205], v[96:99]
	v_mfma_f32_16x16x32_bf16 v[84:87], v[154:157], v[212:215], v[84:87]
	v_mfma_f32_16x16x32_bf16 v[80:83], v[162:165], v[212:215], v[80:83]
	s_setprio 0
	s_setprio 1
	v_mfma_f32_16x16x32_bf16 v[108:111], v[166:169], v[182:185], 0
	v_mfma_f32_16x16x32_bf16 v[104:107], v[174:177], v[182:185], 0
	v_mfma_f32_16x16x32_bf16 v[92:95], v[166:169], v[190:193], 0
	v_mfma_f32_16x16x32_bf16 v[88:91], v[174:177], v[190:193], 0
	v_mfma_f32_16x16x32_bf16 v[76:79], v[166:169], v[198:201], 0
	v_mfma_f32_16x16x32_bf16 v[72:75], v[174:177], v[198:201], 0
	v_mfma_f32_16x16x32_bf16 v[68:71], v[166:169], v[208:211], 0
	v_mfma_f32_16x16x32_bf16 v[64:67], v[174:177], v[208:211], 0
	v_mfma_f32_16x16x32_bf16 v[108:111], v[170:173], v[186:189], v[108:111]
	v_mfma_f32_16x16x32_bf16 v[104:107], v[178:181], v[186:189], v[104:107]
	v_mfma_f32_16x16x32_bf16 v[92:95], v[170:173], v[194:197], v[92:95]
	v_mfma_f32_16x16x32_bf16 v[88:91], v[178:181], v[194:197], v[88:91]
	v_mfma_f32_16x16x32_bf16 v[76:79], v[170:173], v[202:205], v[76:79]
	v_mfma_f32_16x16x32_bf16 v[72:75], v[178:181], v[202:205], v[72:75]
	v_mfma_f32_16x16x32_bf16 v[68:71], v[170:173], v[212:215], v[68:71]
	v_mfma_f32_16x16x32_bf16 v[64:67], v[178:181], v[212:215], v[64:67]
	s_setprio 0
	s_barrier
; #define PG8_STAGE(bufoff, gbase, voff) do { _Pragma("unroll") for (int _i = 0; _i < 2; ++_i) \
;         __builtin_amdgcn_global_load_lds((const unsigned*)((const char*)(gbase) + (voff)[_i]), (PG8_LAS unsigned*)(lds + (bufoff) + ldsw + _i * 8192), 16, 0, 0); } while (0)
; #define PG8_LDA(dst, b, h) do { _Pragma("unroll") for (int m = 0; m < 4; ++m) _Pragma("unroll") for (int k = 0; k < 2; ++k) dst[m][k] = *(const PG8_LAS bf16x8*)(lds + PG8_SA(b, h) + aoff + m * 2048 + k * 1024); } while (0)
; #define PG8_LDB(dst, b, h) do { _Pragma("unroll") for (int n = 0; n < 2; ++n) _Pragma("unroll") for (int k = 0; k < 2; ++k) dst[n][k] = *(const PG8_LAS bf16x8*)(lds + PG8_SB(b, h) + boff + n * 2048 + k * 1024); } while (0)
; #define PG8_MMA(ai, bj, At, Bt) do { __builtin_amdgcn_s_setprio(1); _Pragma("unroll") for (int m = 0; m < 4; ++m) _Pragma("unroll") for (int n = 0; n < 2; ++n) _Pragma("unroll") for (int k = 0; k < 2; ++k) \
;         acc[ai][bj][m][n] = __builtin_amdgcn_mfma_f32_16x16x32_bf16(Bt[n][k], At[m][k], acc[ai][bj][m][n], 0, 0, 0); __builtin_amdgcn_s_setprio(0); } while (0)
; #define PG8_WAIT_V(n) asm volatile("s_waitcnt vmcnt(" #n ")" ::: "memory")
; #define PG8_WAIT_L(n) asm volatile("s_waitcnt lgkmcnt(" #n ")" ::: "memory")
; #define PG8_BAR __builtin_amdgcn_s_barrier()
; #define PG8_SCHED __builtin_amdgcn_sched_barrier(0)
; template <class Epi, class Sched, bool ALIGN_EPI = false, bool SP2 = false>
; __device__ __forceinline__ void gemm_phase(PG8_LAS unsigned char* lds, const Gemm g, const Sched& S, const Epi& E) {
;     ...
;             PG8_LDA(At, 0, 1); PG8_STAGE(PG8_SB(0, 0), b2, voffB); PG8_STAGE(PG8_SB(0, 1), b2 + hstep, voffB); PG8_STAGE(PG8_SA(0, 0), a2, voffA);
;             PG8_WAIT_V(8); PG8_WAIT_L(0); PG8_BAR; PG8_MMA(1, 0, At, B0); PG8_MMA(1, 1, At, B1); PG8_BAR; PG8_SCHED;
;             PG8_LDB(B0, 1, 0); PG8_LDB(B1, 1, 1); PG8_SCHED; PG8_LDA(At, 1, 0); PG8_STAGE(PG8_SA(0, 1), a2 + hstep, voffA);
	s_mov_b32 m0, s56
	v_lshl_add_u64 v[150:151], s[24:25], 0, v[130:131]
	s_add_u32 s72, s24, 0x40000
	ds_read_b128 v[182:185], v143 offset:16384
	ds_read_b128 v[186:189], v143 offset:17408
	ds_read_b128 v[190:193], v143 offset:18432
	ds_read_b128 v[194:197], v143 offset:19456
	ds_read_b128 v[198:201], v143 offset:20480
	ds_read_b128 v[202:205], v143 offset:21504
	ds_read_b128 v[208:211], v143 offset:22528
	ds_read_b128 v[212:215], v143 offset:23552
	global_load_lds_dwordx4 v[150:151], off
	v_lshl_add_u64 v[216:217], s[24:25], 0, v[134:135]
	s_mov_b32 m0, s57
	s_addc_u32 s73, s25, 0
	global_load_lds_dwordx4 v[216:217], off
	v_lshl_add_u64 v[218:219], s[72:73], 0, v[130:131]
	s_mov_b32 m0, s58
	v_lshl_add_u64 v[220:221], s[26:27], 0, v[132:133]
	global_load_lds_dwordx4 v[218:219], off
	v_lshl_add_u64 v[218:219], s[72:73], 0, v[134:135]
	s_mov_b32 m0, s59
	s_nop 0
	global_load_lds_dwordx4 v[218:219], off
	v_lshl_add_u64 v[218:219], s[26:27], 0, v[128:129]
	s_mov_b32 m0, s5
	s_nop 0
	global_load_lds_dwordx4 v[218:219], off
	s_mov_b32 m0, s29
	s_nop 0
	global_load_lds_dwordx4 v[220:221], off
	s_waitcnt vmcnt(8)
	s_waitcnt lgkmcnt(0)
	s_barrier
	s_setprio 1
	s_waitcnt lgkmcnt(0)
	v_mfma_f32_16x16x32_bf16 v[60:63], v[146:149], v[182:185], 0
	v_mfma_f32_16x16x32_bf16 v[56:59], v[158:161], v[182:185], 0
	v_mfma_f32_16x16x32_bf16 v[52:55], v[146:149], v[190:193], 0
	v_mfma_f32_16x16x32_bf16 v[48:51], v[158:161], v[190:193], 0
	v_mfma_f32_16x16x32_bf16 v[36:39], v[146:149], v[198:201], 0
	v_mfma_f32_16x16x32_bf16 v[32:35], v[158:161], v[198:201], 0
	v_mfma_f32_16x16x32_bf16 v[20:23], v[146:149], v[208:211], 0
	v_mfma_f32_16x16x32_bf16 v[16:19], v[158:161], v[208:211], 0
	v_mfma_f32_16x16x32_bf16 v[60:63], v[154:157], v[186:189], v[60:63]
	v_mfma_f32_16x16x32_bf16 v[56:59], v[162:165], v[186:189], v[56:59]
	v_mfma_f32_16x16x32_bf16 v[52:55], v[154:157], v[194:197], v[52:55]
	v_mfma_f32_16x16x32_bf16 v[48:51], v[162:165], v[194:197], v[48:51]
	v_mfma_f32_16x16x32_bf16 v[36:39], v[154:157], v[202:205], v[36:39]
	v_mfma_f32_16x16x32_bf16 v[32:35], v[162:165], v[202:205], v[32:35]
	v_mfma_f32_16x16x32_bf16 v[20:23], v[154:157], v[212:215], v[20:23]
	v_mfma_f32_16x16x32_bf16 v[16:19], v[162:165], v[212:215], v[16:19]
	s_setprio 0
	s_setprio 1
	v_mfma_f32_16x16x32_bf16 v[44:47], v[166:169], v[182:185], 0
	v_mfma_f32_16x16x32_bf16 v[40:43], v[174:177], v[182:185], 0
	v_mfma_f32_16x16x32_bf16 v[28:31], v[166:169], v[190:193], 0
	v_mfma_f32_16x16x32_bf16 v[24:27], v[174:177], v[190:193], 0
	v_mfma_f32_16x16x32_bf16 v[12:15], v[166:169], v[198:201], 0
	v_mfma_f32_16x16x32_bf16 v[8:11], v[174:177], v[198:201], 0
	v_mfma_f32_16x16x32_bf16 v[4:7], v[166:169], v[208:211], 0
	v_mfma_f32_16x16x32_bf16 v[0:3], v[174:177], v[208:211], 0
	v_mfma_f32_16x16x32_bf16 v[44:47], v[170:173], v[186:189], v[44:47]
	v_mfma_f32_16x16x32_bf16 v[40:43], v[178:181], v[186:189], v[40:43]
	v_mfma_f32_16x16x32_bf16 v[28:31], v[170:173], v[194:197], v[28:31]
	v_mfma_f32_16x16x32_bf16 v[24:27], v[178:181], v[194:197], v[24:27]
	v_mfma_f32_16x16x32_bf16 v[12:15], v[170:173], v[202:205], v[12:15]
	v_mfma_f32_16x16x32_bf16 v[8:11], v[178:181], v[202:205], v[8:11]
	v_mfma_f32_16x16x32_bf16 v[4:7], v[170:173], v[212:215], v[4:7]
	v_mfma_f32_16x16x32_bf16 v[0:3], v[178:181], v[212:215], v[0:3]
	s_setprio 0
	s_barrier
	ds_read_b128 v[146:149], v144
	ds_read_b128 v[154:157], v144 offset:1024
	ds_read_b128 v[158:161], v144 offset:2048
	ds_read_b128 v[162:165], v144 offset:3072
	ds_read_b128 v[166:169], v145
	ds_read_b128 v[170:173], v145 offset:1024
	ds_read_b128 v[174:177], v145 offset:2048
	ds_read_b128 v[178:181], v145 offset:3072
	s_add_u32 s26, s26, 0x40000
	s_addc_u32 s27, s27, 0
	s_mov_b32 m0, s30
	v_lshl_add_u64 v[222:223], s[26:27], 0, v[128:129]
	ds_read_b128 v[182:185], v143 offset:32768
	ds_read_b128 v[186:189], v143 offset:33792
	ds_read_b128 v[190:193], v143 offset:34816
	ds_read_b128 v[194:197], v143 offset:35840
	ds_read_b128 v[198:201], v143 offset:36864
	ds_read_b128 v[202:205], v143 offset:37888
	ds_read_b128 v[208:211], v143 offset:38912
	ds_read_b128 v[212:215], v143 offset:39936
	global_load_lds_dwordx4 v[222:223], off
	v_lshl_add_u64 v[222:223], s[26:27], 0, v[132:133]
	s_mov_b32 m0, s31
	s_nop 0
	global_load_lds_dwordx4 v[222:223], off
	s_waitcnt vmcnt(8)
	s_waitcnt lgkmcnt(0)
	s_barrier
; #define PG8_STAGE(bufoff, gbase, voff) do { _Pragma("unroll") for (int _i = 0; _i < 2; ++_i) \
;         __builtin_amdgcn_global_load_lds((const unsigned*)((const char*)(gbase) + (voff)[_i]), (PG8_LAS unsigned*)(lds + (bufoff) + ldsw + _i * 8192), 16, 0, 0); } while (0)
; #define PG8_LDA(dst, b, h) do { _Pragma("unroll") for (int m = 0; m < 4; ++m) _Pragma("unroll") for (int k = 0; k < 2; ++k) dst[m][k] = *(const PG8_LAS bf16x8*)(lds + PG8_SA(b, h) + aoff + m * 2048 + k * 1024); } while (0)
; #define PG8_LDB(dst, b, h) do { _Pragma("unroll") for (int n = 0; n < 2; ++n) _Pragma("unroll") for (int k = 0; k < 2; ++k) dst[n][k] = *(const PG8_LAS bf16x8*)(lds + PG8_SB(b, h) + boff + n * 2048 + k * 1024); } while (0)
; template <class Epi, class Sched, bool ALIGN_EPI = false, bool SP2 = false>
; __device__ __forceinline__ void gemm_phase(PG8_LAS unsigned char* lds, const Gemm g, const Sched& S, const Epi& E) {
;     ...
;         for (int t = 0; t < nt; t += 2) {
;             const bool last = (t == nt - 2);
;             const char* a1 = cA + (size_t)(t + 1) * kstep;
;             const char* a2 = last ? nA : cA + (size_t)(t + 2) * kstep; const char* b2 = last ? nB : cB + (size_t)(t + 2) * kstep;
;             const char* a3 = a2 + kstep; const char* b3 = b2 + kstep;
;             if (last && has_next) S.a_ready(nxt);
;             if constexpr (SP2) {
;             PG8_LDB(B0, 0, 0); PG8_LDB(B1, 0, 1); PG8_SCHED; PG8_LDA(At, 0, 0); PG8_STAGE(PG8_SA(1, 1), a1 + hstep, voffA);
;             PG8_WAIT_V(8); PG8_WAIT_L(0); PG8_BAR; PG8_MMA(0, 0, At, B0); PG8_MMA(0, 1, At, B1); PG8_BAR; PG8_SCHED;
;             PG8_LDA(At, 0, 1); PG8_STAGE(PG8_SB(0, 0), b2, voffB); PG8_STAGE(PG8_SB(0, 1), b2 + hstep, voffB); PG8_STAGE(PG8_SA(0, 0), a2, voffA);
;             PG8_WAIT_V(8); PG8_WAIT_L(0); PG8_BAR; PG8_MMA(1, 0, At, B0); PG8_MMA(1, 1, At, B1); PG8_BAR; PG8_SCHED;
;             PG8_LDB(B0, 1, 0); PG8_LDB(B1, 1, 1); PG8_SCHED; PG8_LDA(At, 1, 0); PG8_STAGE(PG8_SA(0, 1), a2 + hstep, voffA);
;             PG8_WAIT_V(8); PG8_WAIT_L(0); PG8_BAR; PG8_MMA(0, 0, At, B0); PG8_MMA(0, 1, At, B1); PG8_BAR; PG8_SCHED;
;             PG8_LDA(At, 1, 1); PG8_STAGE(PG8_SB(1, 0), b3, voffB); PG8_STAGE(PG8_SB(1, 1), b3 + hstep, voffB); PG8_STAGE(PG8_SA(1, 0), a3, voffA);
;             PG8_WAIT_V(8); PG8_WAIT_L(0); PG8_BAR; PG8_MMA(1, 0, At, B0); PG8_MMA(1, 1, At, B1); PG8_BAR; PG8_SCHED;
	s_setprio 1
	s_waitcnt lgkmcnt(0)
	v_mfma_f32_16x16x32_bf16 v[124:127], v[146:149], v[182:185], v[124:127]
	v_mfma_f32_16x16x32_bf16 v[120:123], v[158:161], v[182:185], v[120:123]
	v_mfma_f32_16x16x32_bf16 v[116:119], v[146:149], v[190:193], v[116:119]
	v_mfma_f32_16x16x32_bf16 v[112:115], v[158:161], v[190:193], v[112:115]
	v_mfma_f32_16x16x32_bf16 v[100:103], v[146:149], v[198:201], v[100:103]
	v_mfma_f32_16x16x32_bf16 v[96:99], v[158:161], v[198:201], v[96:99]
	v_mfma_f32_16x16x32_bf16 v[84:87], v[146:149], v[208:211], v[84:87]
	v_mfma_f32_16x16x32_bf16 v[80:83], v[158:161], v[208:211], v[80:83]
	v_mfma_f32_16x16x32_bf16 v[124:127], v[154:157], v[186:189], v[124:127]
	v_mfma_f32_16x16x32_bf16 v[120:123], v[162:165], v[186:189], v[120:123]
	v_mfma_f32_16x16x32_bf16 v[116:119], v[154:157], v[194:197], v[116:119]
	v_mfma_f32_16x16x32_bf16 v[112:115], v[162:165], v[194:197], v[112:115]
	v_mfma_f32_16x16x32_bf16 v[100:103], v[154:157], v[202:205], v[100:103]
	v_mfma_f32_16x16x32_bf16 v[96:99], v[162:165], v[202:205], v[96:99]
	v_mfma_f32_16x16x32_bf16 v[84:87], v[154:157], v[212:215], v[84:87]
	v_mfma_f32_16x16x32_bf16 v[80:83], v[162:165], v[212:215], v[80:83]
	s_setprio 0
	s_setprio 1
	v_mfma_f32_16x16x32_bf16 v[108:111], v[166:169], v[182:185], v[108:111]
	v_mfma_f32_16x16x32_bf16 v[104:107], v[174:177], v[182:185], v[104:107]
	v_mfma_f32_16x16x32_bf16 v[92:95], v[166:169], v[190:193], v[92:95]
	v_mfma_f32_16x16x32_bf16 v[88:91], v[174:177], v[190:193], v[88:91]
	v_mfma_f32_16x16x32_bf16 v[76:79], v[166:169], v[198:201], v[76:79]
	v_mfma_f32_16x16x32_bf16 v[72:75], v[174:177], v[198:201], v[72:75]
	v_mfma_f32_16x16x32_bf16 v[68:71], v[166:169], v[208:211], v[68:71]
	v_mfma_f32_16x16x32_bf16 v[64:67], v[174:177], v[208:211], v[64:67]
	v_mfma_f32_16x16x32_bf16 v[108:111], v[170:173], v[186:189], v[108:111]
	v_mfma_f32_16x16x32_bf16 v[104:107], v[178:181], v[186:189], v[104:107]
	v_mfma_f32_16x16x32_bf16 v[92:95], v[170:173], v[194:197], v[92:95]
	v_mfma_f32_16x16x32_bf16 v[88:91], v[178:181], v[194:197], v[88:91]
	v_mfma_f32_16x16x32_bf16 v[76:79], v[170:173], v[202:205], v[76:79]
	v_mfma_f32_16x16x32_bf16 v[72:75], v[178:181], v[202:205], v[72:75]
	v_mfma_f32_16x16x32_bf16 v[68:71], v[170:173], v[212:215], v[68:71]
	v_mfma_f32_16x16x32_bf16 v[64:67], v[178:181], v[212:215], v[64:67]
	s_setprio 0
	s_barrier
	s_mov_b32 m0, s60
	v_lshl_add_u64 v[150:151], v[150:151], 0, s[14:15]
	s_add_u32 s24, s24, 0x40080
	ds_read_b128 v[182:185], v143 offset:49152
	ds_read_b128 v[186:189], v143 offset:50176
	ds_read_b128 v[190:193], v143 offset:51200
	ds_read_b128 v[194:197], v143 offset:52224
	ds_read_b128 v[198:201], v143 offset:53248
	ds_read_b128 v[202:205], v143 offset:54272
	ds_read_b128 v[208:211], v143 offset:55296
	ds_read_b128 v[212:215], v143 offset:56320
	global_load_lds_dwordx4 v[150:151], off
	v_lshl_add_u64 v[150:151], v[216:217], 0, s[14:15]
	s_mov_b32 m0, s61
	s_addc_u32 s25, s25, 0
	global_load_lds_dwordx4 v[150:151], off
	v_lshl_add_u64 v[150:151], s[24:25], 0, v[130:131]
	s_mov_b32 m0, s68
	s_nop 0
	global_load_lds_dwordx4 v[150:151], off
	v_lshl_add_u64 v[150:151], s[24:25], 0, v[134:135]
	s_mov_b32 m0, s69
	s_nop 0
	global_load_lds_dwordx4 v[150:151], off
	v_lshl_add_u64 v[150:151], v[218:219], 0, s[14:15]
	s_mov_b32 m0, s41
	s_nop 0
	global_load_lds_dwordx4 v[150:151], off
	v_lshl_add_u64 v[150:151], v[220:221], 0, s[14:15]
	s_mov_b32 m0, s42
	s_nop 0
	global_load_lds_dwordx4 v[150:151], off
	s_waitcnt vmcnt(8)
	s_waitcnt lgkmcnt(0)
	s_barrier
	s_setprio 1
	s_waitcnt lgkmcnt(0)
	v_mfma_f32_16x16x32_bf16 v[60:63], v[146:149], v[182:185], v[60:63]
	v_mfma_f32_16x16x32_bf16 v[56:59], v[158:161], v[182:185], v[56:59]
	v_mfma_f32_16x16x32_bf16 v[52:55], v[146:149], v[190:193], v[52:55]
	v_mfma_f32_16x16x32_bf16 v[48:51], v[158:161], v[190:193], v[48:51]
	v_mfma_f32_16x16x32_bf16 v[36:39], v[146:149], v[198:201], v[36:39]
	v_mfma_f32_16x16x32_bf16 v[32:35], v[158:161], v[198:201], v[32:35]
	v_mfma_f32_16x16x32_bf16 v[20:23], v[146:149], v[208:211], v[20:23]
	v_mfma_f32_16x16x32_bf16 v[16:19], v[158:161], v[208:211], v[16:19]
	v_mfma_f32_16x16x32_bf16 v[60:63], v[154:157], v[186:189], v[60:63]
	v_mfma_f32_16x16x32_bf16 v[56:59], v[162:165], v[186:189], v[56:59]
	v_mfma_f32_16x16x32_bf16 v[52:55], v[154:157], v[194:197], v[52:55]
	v_mfma_f32_16x16x32_bf16 v[48:51], v[162:165], v[194:197], v[48:51]
	v_mfma_f32_16x16x32_bf16 v[36:39], v[154:157], v[202:205], v[36:39]
	v_mfma_f32_16x16x32_bf16 v[32:35], v[162:165], v[202:205], v[32:35]
	v_mfma_f32_16x16x32_bf16 v[20:23], v[154:157], v[212:215], v[20:23]
	v_mfma_f32_16x16x32_bf16 v[16:19], v[162:165], v[212:215], v[16:19]
	s_setprio 0
	s_setprio 1
	v_mfma_f32_16x16x32_bf16 v[44:47], v[166:169], v[182:185], v[44:47]
	v_mfma_f32_16x16x32_bf16 v[40:43], v[174:177], v[182:185], v[40:43]
	v_mfma_f32_16x16x32_bf16 v[28:31], v[166:169], v[190:193], v[28:31]
	v_mfma_f32_16x16x32_bf16 v[24:27], v[174:177], v[190:193], v[24:27]
	v_mfma_f32_16x16x32_bf16 v[12:15], v[166:169], v[198:201], v[12:15]
	v_mfma_f32_16x16x32_bf16 v[8:11], v[174:177], v[198:201], v[8:11]
	v_mfma_f32_16x16x32_bf16 v[4:7], v[166:169], v[208:211], v[4:7]
	v_mfma_f32_16x16x32_bf16 v[0:3], v[174:177], v[208:211], v[0:3]
	v_mfma_f32_16x16x32_bf16 v[44:47], v[170:173], v[186:189], v[44:47]
	v_mfma_f32_16x16x32_bf16 v[40:43], v[178:181], v[186:189], v[40:43]
	v_mfma_f32_16x16x32_bf16 v[28:31], v[170:173], v[194:197], v[28:31]
	v_mfma_f32_16x16x32_bf16 v[24:27], v[178:181], v[194:197], v[24:27]
	v_mfma_f32_16x16x32_bf16 v[12:15], v[170:173], v[202:205], v[12:15]
	v_mfma_f32_16x16x32_bf16 v[8:11], v[178:181], v[202:205], v[8:11]
	v_mfma_f32_16x16x32_bf16 v[4:7], v[170:173], v[212:215], v[4:7]
	v_mfma_f32_16x16x32_bf16 v[0:3], v[178:181], v[212:215], v[0:3]
	s_setprio 0
	s_barrier
	s_add_i32 s43, s43, 2
	s_add_u32 s22, s22, 0x100
	s_addc_u32 s23, s23, 0
	s_cmp_gt_u32 s43, 13
	s_cbranch_scc0 .LBB0_397
	s_branch .Lpeel_exit_2

; #define PG8_BAR __builtin_amdgcn_s_barrier()
; template <class Epi, class Sched, bool ALIGN_EPI = false, bool SP2 = false>
; __device__ __forceinline__ void gemm_phase(PG8_LAS unsigned char* lds, const Gemm g, const Sched& S, const Epi& E) {
;     ...
;         if constexpr (ALIGN_EPI) { if (wr == 0) PG8_BAR; }
.Lpeel_exit_2:
	s_cmpk_lt_u32 s28, 0x100
	s_cbranch_scc0 .LBB0_400
	s_barrier

;     __device__ __forceinline__ bool next(int i, Unit& u) const { if (i != 0) return false; const int c0 = (G >= 8) ? G - 5 : G - 2; int k = -1; if (c == c0) k = 0; else if (c == G - 1) k = 1; if (k < 0 || k >= n) return false; u.pm = k; u.pn = 0; return true; }
; #define PG8_STAGE(bufoff, gbase, voff) do { _Pragma("unroll") for (int _i = 0; _i < 2; ++_i) \
;         __builtin_amdgcn_global_load_lds((const unsigned*)((const char*)(gbase) + (voff)[_i]), (PG8_LAS unsigned*)(lds + (bufoff) + ldsw + _i * 8192), 16, 0, 0); } while (0)
; #define PG8_LDA(dst, b, h) do { _Pragma("unroll") for (int m = 0; m < 4; ++m) _Pragma("unroll") for (int k = 0; k < 2; ++k) dst[m][k] = *(const PG8_LAS bf16x8*)(lds + PG8_SA(b, h) + aoff + m * 2048 + k * 1024); } while (0)
; #define PG8_LDB(dst, b, h) do { _Pragma("unroll") for (int n = 0; n < 2; ++n) _Pragma("unroll") for (int k = 0; k < 2; ++k) dst[n][k] = *(const PG8_LAS bf16x8*)(lds + PG8_SB(b, h) + boff + n * 2048 + k * 1024); } while (0)
; template <class Epi, class Sched, bool ALIGN_EPI = false, bool SP2 = false>
; __device__ __forceinline__ void gemm_phase(PG8_LAS unsigned char* lds, const Gemm g, const Sched& S, const Epi& E) {
;     ...
;         const bool has_next = S.next(ui + 1, nxt);
;         const char* nA = has_next ? (const char*)g.A + (size_t)nxt.pm * tstep : cA; const char* nB = has_next ? (const char*)g.Bt + (size_t)nxt.pn * tstep : cB;
;         for (int t = 0; t < nt; t += 2) {
;             const bool last = (t == nt - 2);
;             const char* a1 = cA + (size_t)(t + 1) * kstep;
;             const char* a2 = last ? nA : cA + (size_t)(t + 2) * kstep; const char* b2 = last ? nB : cB + (size_t)(t + 2) * kstep;
;             const char* a3 = a2 + kstep; const char* b3 = b2 + kstep;
;             if (last && has_next) S.a_ready(nxt);
;             if constexpr (SP2) {
;             PG8_LDB(B0, 0, 0); PG8_LDB(B1, 0, 1); PG8_SCHED; PG8_LDA(At, 0, 0); PG8_STAGE(PG8_SA(1, 1), a1 + hstep, voffA);
;             PG8_WAIT_V(8); PG8_WAIT_L(0); PG8_BAR; PG8_MMA(0, 0, At, B0); PG8_MMA(0, 1, At, B1); PG8_BAR; PG8_SCHED;
;             PG8_LDA(At, 0, 1); PG8_STAGE(PG8_SB(0, 0), b2, voffB); PG8_STAGE(PG8_SB(0, 1), b2 + hstep, voffB); PG8_STAGE(PG8_SA(0, 0), a2, voffA);
;             PG8_WAIT_V(8); PG8_WAIT_L(0); PG8_BAR; PG8_MMA(1, 0, At, B0); PG8_MMA(1, 1, At, B1); PG8_BAR; PG8_SCHED;
.LBB0_658:
	s_ashr_i32 s39, s38, 31
	s_lshl_b64 s[42:43], s[38:39], 19
	s_add_u32 s42, s14, s42
	s_addc_u32 s43, s15, s43
	s_and_b64 s[46:47], s[40:41], exec
	s_cselect_b32 s39, s43, s57
	s_cselect_b32 s82, s42, s56
	s_ashr_i32 s31, s30, 31
	s_lshl_b64 s[46:47], s[30:31], 19
	s_add_u32 s46, s34, s46
	s_addc_u32 s47, s35, s47
	s_and_b64 s[60:61], s[40:41], exec
	s_cselect_b32 s31, s47, s59
	s_cselect_b32 s83, s46, s58
	s_add_u32 s56, s56, 0x40080
	s_addc_u32 s57, s57, 0
	s_add_u32 s90, s58, 0x100
	v_mov_b32_e32 v0, 0
	s_addc_u32 s91, s59, 0
	s_mov_b32 s92, -2
	ds_read_b128 v[148:151], v145
	ds_read_b128 v[152:155], v145 offset:1024
	ds_read_b128 v[156:159], v145 offset:2048
	ds_read_b128 v[160:163], v145 offset:3072
	ds_read_b128 v[164:167], v146
	ds_read_b128 v[168:171], v146 offset:1024
	ds_read_b128 v[172:175], v146 offset:2048
	ds_read_b128 v[176:179], v146 offset:3072
	s_add_u32 s58, s56, 0xfffc0080
	s_addc_u32 s59, s57, -1
	s_cmp_eq_u32 s92, 12
	s_cselect_b32 s61, s39, s59
	s_cselect_b32 s60, s82, s58
	s_cselect_b32 s59, s31, s91
	s_cselect_b32 s58, s83, s90
	v_lshl_add_u64 v[204:205], s[56:57], 0, v[136:137]
	s_add_i32 m0, s66, 0xc000
	ds_read_b128 v[180:183], v147
	ds_read_b128 v[184:187], v147 offset:1024
	ds_read_b128 v[188:191], v147 offset:2048
	ds_read_b128 v[192:195], v147 offset:3072
	ds_read_b128 v[196:199], v147 offset:4096
	ds_read_b128 v[200:203], v147 offset:5120
	ds_read_b128 v[208:211], v147 offset:6144
	ds_read_b128 v[212:215], v147 offset:7168
	global_load_lds_dwordx4 v[204:205], off
	v_lshl_add_u64 v[204:205], s[56:57], 0, v[138:139]
	s_add_i32 m0, s66, 0xe000
	s_nop 0
	global_load_lds_dwordx4 v[204:205], off
	s_waitcnt vmcnt(8)
	s_waitcnt lgkmcnt(0)
	s_barrier
	s_setprio 1
	s_waitcnt lgkmcnt(0)
	v_mfma_f32_16x16x32_bf16 v[124:127], v[148:151], v[180:183], 0
	v_mfma_f32_16x16x32_bf16 v[120:123], v[156:159], v[180:183], 0
	v_mfma_f32_16x16x32_bf16 v[116:119], v[148:151], v[188:191], 0
	v_mfma_f32_16x16x32_bf16 v[112:115], v[156:159], v[188:191], 0
	v_mfma_f32_16x16x32_bf16 v[100:103], v[148:151], v[196:199], 0
	v_mfma_f32_16x16x32_bf16 v[96:99], v[156:159], v[196:199], 0
	v_mfma_f32_16x16x32_bf16 v[84:87], v[148:151], v[208:211], 0
	v_mfma_f32_16x16x32_bf16 v[80:83], v[156:159], v[208:211], 0
	v_mfma_f32_16x16x32_bf16 v[124:127], v[152:155], v[184:187], v[124:127]
	v_mfma_f32_16x16x32_bf16 v[120:123], v[160:163], v[184:187], v[120:123]
	v_mfma_f32_16x16x32_bf16 v[116:119], v[152:155], v[192:195], v[116:119]
	v_mfma_f32_16x16x32_bf16 v[112:115], v[160:163], v[192:195], v[112:115]
	v_mfma_f32_16x16x32_bf16 v[100:103], v[152:155], v[200:203], v[100:103]
	v_mfma_f32_16x16x32_bf16 v[96:99], v[160:163], v[200:203], v[96:99]
	v_mfma_f32_16x16x32_bf16 v[84:87], v[152:155], v[212:215], v[84:87]
	v_mfma_f32_16x16x32_bf16 v[80:83], v[160:163], v[212:215], v[80:83]
	s_setprio 0
	s_setprio 1
	v_mfma_f32_16x16x32_bf16 v[108:111], v[164:167], v[180:183], 0
	v_mfma_f32_16x16x32_bf16 v[104:107], v[172:175], v[180:183], 0
	v_mfma_f32_16x16x32_bf16 v[92:95], v[164:167], v[188:191], 0
	v_mfma_f32_16x16x32_bf16 v[88:91], v[172:175], v[188:191], 0
	v_mfma_f32_16x16x32_bf16 v[76:79], v[164:167], v[196:199], 0
	v_mfma_f32_16x16x32_bf16 v[72:75], v[172:175], v[196:199], 0
	v_mfma_f32_16x16x32_bf16 v[68:71], v[164:167], v[208:211], 0
	v_mfma_f32_16x16x32_bf16 v[64:67], v[172:175], v[208:211], 0
	v_mfma_f32_16x16x32_bf16 v[108:111], v[168:171], v[184:187], v[108:111]
	v_mfma_f32_16x16x32_bf16 v[104:107], v[176:179], v[184:187], v[104:107]
	v_mfma_f32_16x16x32_bf16 v[92:95], v[168:171], v[192:195], v[92:95]
	v_mfma_f32_16x16x32_bf16 v[88:91], v[176:179], v[192:195], v[88:91]
	v_mfma_f32_16x16x32_bf16 v[76:79], v[168:171], v[200:203], v[76:79]
	v_mfma_f32_16x16x32_bf16 v[72:75], v[176:179], v[200:203], v[72:75]
	v_mfma_f32_16x16x32_bf16 v[68:71], v[168:171], v[212:215], v[68:71]
	v_mfma_f32_16x16x32_bf16 v[64:67], v[176:179], v[212:215], v[64:67]
	s_setprio 0
	s_barrier
	s_add_i32 s93, s76, s65
	v_lshl_add_u64 v[204:205], s[58:59], 0, v[130:131]
	s_mov_b32 m0, s93
	ds_read_b128 v[180:183], v147 offset:16384
	ds_read_b128 v[184:187], v147 offset:17408
	ds_read_b128 v[188:191], v147 offset:18432
	ds_read_b128 v[192:195], v147 offset:19456
	ds_read_b128 v[196:199], v147 offset:20480
	ds_read_b128 v[200:203], v147 offset:21504
	ds_read_b128 v[208:211], v147 offset:22528
	ds_read_b128 v[212:215], v147 offset:23552
	global_load_lds_dwordx4 v[204:205], off
	s_add_i32 m0, s93, 0x2000
	s_add_u32 s94, s58, 0x40000
	v_lshl_add_u64 v[216:217], s[58:59], 0, v[134:135]
	s_addc_u32 s95, s59, 0
	s_add_i32 s93, s77, s65
	global_load_lds_dwordx4 v[216:217], off
	v_lshl_add_u64 v[218:219], s[94:95], 0, v[130:131]
	s_mov_b32 m0, s93
	v_lshl_add_u64 v[220:221], s[60:61], 0, v[132:133]
	global_load_lds_dwordx4 v[218:219], off
	v_lshl_add_u64 v[218:219], s[94:95], 0, v[134:135]
	s_add_i32 m0, s93, 0x2000
	s_nop 0
	global_load_lds_dwordx4 v[218:219], off
	v_lshl_add_u64 v[218:219], s[60:61], 0, v[128:129]
	s_mov_b32 m0, s66
	s_nop 0
	global_load_lds_dwordx4 v[218:219], off
	s_mov_b32 m0, s67
	s_nop 0
	global_load_lds_dwordx4 v[220:221], off
	s_waitcnt vmcnt(8)
	s_waitcnt lgkmcnt(0)
	s_barrier
; #define PG8_STAGE(bufoff, gbase, voff) do { _Pragma("unroll") for (int _i = 0; _i < 2; ++_i) \
;         __builtin_amdgcn_global_load_lds((const unsigned*)((const char*)(gbase) + (voff)[_i]), (PG8_LAS unsigned*)(lds + (bufoff) + ldsw + _i * 8192), 16, 0, 0); } while (0)
; #define PG8_LDA(dst, b, h) do { _Pragma("unroll") for (int m = 0; m < 4; ++m) _Pragma("unroll") for (int k = 0; k < 2; ++k) dst[m][k] = *(const PG8_LAS bf16x8*)(lds + PG8_SA(b, h) + aoff + m * 2048 + k * 1024); } while (0)
; #define PG8_LDB(dst, b, h) do { _Pragma("unroll") for (int n = 0; n < 2; ++n) _Pragma("unroll") for (int k = 0; k < 2; ++k) dst[n][k] = *(const PG8_LAS bf16x8*)(lds + PG8_SB(b, h) + boff + n * 2048 + k * 1024); } while (0)
; #define PG8_MMA(ai, bj, At, Bt) do { __builtin_amdgcn_s_setprio(1); _Pragma("unroll") for (int m = 0; m < 4; ++m) _Pragma("unroll") for (int n = 0; n < 2; ++n) _Pragma("unroll") for (int k = 0; k < 2; ++k) \
;         acc[ai][bj][m][n] = __builtin_amdgcn_mfma_f32_16x16x32_bf16(Bt[n][k], At[m][k], acc[ai][bj][m][n], 0, 0, 0); __builtin_amdgcn_s_setprio(0); } while (0)
; #define PG8_WAIT_V(n) asm volatile("s_waitcnt vmcnt(" #n ")" ::: "memory")
; #define PG8_WAIT_L(n) asm volatile("s_waitcnt lgkmcnt(" #n ")" ::: "memory")
; #define PG8_BAR __builtin_amdgcn_s_barrier()
; #define PG8_SCHED __builtin_amdgcn_sched_barrier(0)
; template <class Epi, class Sched, bool ALIGN_EPI = false, bool SP2 = false>
; __device__ __forceinline__ void gemm_phase(PG8_LAS unsigned char* lds, const Gemm g, const Sched& S, const Epi& E) {
;     ...
;             PG8_WAIT_V(8); PG8_WAIT_L(0); PG8_BAR; PG8_MMA(1, 0, At, B0); PG8_MMA(1, 1, At, B1); PG8_BAR; PG8_SCHED;
;             PG8_LDB(B0, 1, 0); PG8_LDB(B1, 1, 1); PG8_SCHED; PG8_LDA(At, 1, 0); PG8_STAGE(PG8_SA(0, 1), a2 + hstep, voffA);
;             PG8_WAIT_V(8); PG8_WAIT_L(0); PG8_BAR; PG8_MMA(0, 0, At, B0); PG8_MMA(0, 1, At, B1); PG8_BAR; PG8_SCHED;
	s_setprio 1
	s_waitcnt lgkmcnt(0)
	v_mfma_f32_16x16x32_bf16 v[60:63], v[148:151], v[180:183], 0
	v_mfma_f32_16x16x32_bf16 v[56:59], v[156:159], v[180:183], 0
	v_mfma_f32_16x16x32_bf16 v[52:55], v[148:151], v[188:191], 0
	v_mfma_f32_16x16x32_bf16 v[48:51], v[156:159], v[188:191], 0
	v_mfma_f32_16x16x32_bf16 v[36:39], v[148:151], v[196:199], 0
	v_mfma_f32_16x16x32_bf16 v[32:35], v[156:159], v[196:199], 0
	v_mfma_f32_16x16x32_bf16 v[20:23], v[148:151], v[208:211], 0
	v_mfma_f32_16x16x32_bf16 v[16:19], v[156:159], v[208:211], 0
	v_mfma_f32_16x16x32_bf16 v[60:63], v[152:155], v[184:187], v[60:63]
	v_mfma_f32_16x16x32_bf16 v[56:59], v[160:163], v[184:187], v[56:59]
	v_mfma_f32_16x16x32_bf16 v[52:55], v[152:155], v[192:195], v[52:55]
	v_mfma_f32_16x16x32_bf16 v[48:51], v[160:163], v[192:195], v[48:51]
	v_mfma_f32_16x16x32_bf16 v[36:39], v[152:155], v[200:203], v[36:39]
	v_mfma_f32_16x16x32_bf16 v[32:35], v[160:163], v[200:203], v[32:35]
	v_mfma_f32_16x16x32_bf16 v[20:23], v[152:155], v[212:215], v[20:23]
	v_mfma_f32_16x16x32_bf16 v[16:19], v[160:163], v[212:215], v[16:19]
	s_setprio 0
	s_setprio 1
	v_mfma_f32_16x16x32_bf16 v[44:47], v[164:167], v[180:183], 0
	v_mfma_f32_16x16x32_bf16 v[40:43], v[172:175], v[180:183], 0
	v_mfma_f32_16x16x32_bf16 v[28:31], v[164:167], v[188:191], 0
	v_mfma_f32_16x16x32_bf16 v[24:27], v[172:175], v[188:191], 0
	v_mfma_f32_16x16x32_bf16 v[12:15], v[164:167], v[196:199], 0
	v_mfma_f32_16x16x32_bf16 v[8:11], v[172:175], v[196:199], 0
	v_mfma_f32_16x16x32_bf16 v[4:7], v[164:167], v[208:211], 0
	v_mfma_f32_16x16x32_bf16 v[0:3], v[172:175], v[208:211], 0
	v_mfma_f32_16x16x32_bf16 v[44:47], v[168:171], v[184:187], v[44:47]
	v_mfma_f32_16x16x32_bf16 v[40:43], v[176:179], v[184:187], v[40:43]
	v_mfma_f32_16x16x32_bf16 v[28:31], v[168:171], v[192:195], v[28:31]
	v_mfma_f32_16x16x32_bf16 v[24:27], v[176:179], v[192:195], v[24:27]
	v_mfma_f32_16x16x32_bf16 v[12:15], v[168:171], v[200:203], v[12:15]
	v_mfma_f32_16x16x32_bf16 v[8:11], v[176:179], v[200:203], v[8:11]
	v_mfma_f32_16x16x32_bf16 v[4:7], v[168:171], v[212:215], v[4:7]
	v_mfma_f32_16x16x32_bf16 v[0:3], v[176:179], v[212:215], v[0:3]
	s_setprio 0
	s_barrier
	s_add_i32 s93, 0, 0x18000
	s_add_i32 s94, 0, 0x1c000
	v_add_u32_e32 v160, s93, v143
	v_add_u32_e32 v176, s94, v143
	ds_read_b128 v[148:151], v160
	ds_read_b128 v[152:155], v160 offset:1024
	ds_read_b128 v[156:159], v160 offset:2048
	ds_read_b128 v[160:163], v160 offset:3072
	ds_read_b128 v[164:167], v176
	ds_read_b128 v[168:171], v176 offset:1024
	ds_read_b128 v[172:175], v176 offset:2048
	ds_read_b128 v[176:179], v176 offset:3072
	s_add_u32 s60, s60, 0x40000
	s_addc_u32 s61, s61, 0
	s_mov_b32 m0, s68
	v_lshl_add_u64 v[222:223], s[60:61], 0, v[128:129]
	ds_read_b128 v[180:183], v147 offset:32768
	ds_read_b128 v[184:187], v147 offset:33792
	ds_read_b128 v[188:191], v147 offset:34816
	ds_read_b128 v[192:195], v147 offset:35840
	ds_read_b128 v[196:199], v147 offset:36864
	ds_read_b128 v[200:203], v147 offset:37888
	ds_read_b128 v[208:211], v147 offset:38912
	ds_read_b128 v[212:215], v147 offset:39936
	global_load_lds_dwordx4 v[222:223], off
	v_lshl_add_u64 v[222:223], s[60:61], 0, v[132:133]
	s_mov_b32 m0, s69
	s_nop 0
	global_load_lds_dwordx4 v[222:223], off
	s_waitcnt vmcnt(8)
	s_waitcnt lgkmcnt(0)
	s_barrier
	s_setprio 1
	s_waitcnt lgkmcnt(0)
	v_mfma_f32_16x16x32_bf16 v[124:127], v[148:151], v[180:183], v[124:127]
	v_mfma_f32_16x16x32_bf16 v[120:123], v[156:159], v[180:183], v[120:123]
	v_mfma_f32_16x16x32_bf16 v[116:119], v[148:151], v[188:191], v[116:119]
	v_mfma_f32_16x16x32_bf16 v[112:115], v[156:159], v[188:191], v[112:115]
	v_mfma_f32_16x16x32_bf16 v[100:103], v[148:151], v[196:199], v[100:103]
	v_mfma_f32_16x16x32_bf16 v[96:99], v[156:159], v[196:199], v[96:99]
	v_mfma_f32_16x16x32_bf16 v[84:87], v[148:151], v[208:211], v[84:87]
	v_mfma_f32_16x16x32_bf16 v[80:83], v[156:159], v[208:211], v[80:83]
	v_mfma_f32_16x16x32_bf16 v[124:127], v[152:155], v[184:187], v[124:127]
	v_mfma_f32_16x16x32_bf16 v[120:123], v[160:163], v[184:187], v[120:123]
	v_mfma_f32_16x16x32_bf16 v[116:119], v[152:155], v[192:195], v[116:119]
	v_mfma_f32_16x16x32_bf16 v[112:115], v[160:163], v[192:195], v[112:115]
	v_mfma_f32_16x16x32_bf16 v[100:103], v[152:155], v[200:203], v[100:103]
	v_mfma_f32_16x16x32_bf16 v[96:99], v[160:163], v[200:203], v[96:99]
	v_mfma_f32_16x16x32_bf16 v[84:87], v[152:155], v[212:215], v[84:87]
	v_mfma_f32_16x16x32_bf16 v[80:83], v[160:163], v[212:215], v[80:83]
	s_setprio 0
	s_setprio 1
	v_mfma_f32_16x16x32_bf16 v[108:111], v[164:167], v[180:183], v[108:111]
	v_mfma_f32_16x16x32_bf16 v[104:107], v[172:175], v[180:183], v[104:107]
	v_mfma_f32_16x16x32_bf16 v[92:95], v[164:167], v[188:191], v[92:95]
	v_mfma_f32_16x16x32_bf16 v[88:91], v[172:175], v[188:191], v[88:91]
	v_mfma_f32_16x16x32_bf16 v[76:79], v[164:167], v[196:199], v[76:79]
	v_mfma_f32_16x16x32_bf16 v[72:75], v[172:175], v[196:199], v[72:75]
	v_mfma_f32_16x16x32_bf16 v[68:71], v[164:167], v[208:211], v[68:71]
	v_mfma_f32_16x16x32_bf16 v[64:67], v[172:175], v[208:211], v[64:67]
	v_mfma_f32_16x16x32_bf16 v[108:111], v[168:171], v[184:187], v[108:111]
	v_mfma_f32_16x16x32_bf16 v[104:107], v[176:179], v[184:187], v[104:107]
	v_mfma_f32_16x16x32_bf16 v[92:95], v[168:171], v[192:195], v[92:95]
	v_mfma_f32_16x16x32_bf16 v[88:91], v[176:179], v[192:195], v[88:91]
	v_mfma_f32_16x16x32_bf16 v[76:79], v[168:171], v[200:203], v[76:79]
	v_mfma_f32_16x16x32_bf16 v[72:75], v[176:179], v[200:203], v[72:75]
	v_mfma_f32_16x16x32_bf16 v[68:71], v[168:171], v[212:215], v[68:71]
	v_mfma_f32_16x16x32_bf16 v[64:67], v[176:179], v[212:215], v[64:67]
	s_setprio 0
	s_barrier
; #define PG8_STAGE(bufoff, gbase, voff) do { _Pragma("unroll") for (int _i = 0; _i < 2; ++_i) \
;         __builtin_amdgcn_global_load_lds((const unsigned*)((const char*)(gbase) + (voff)[_i]), (PG8_LAS unsigned*)(lds + (bufoff) + ldsw + _i * 8192), 16, 0, 0); } while (0)
; #define PG8_LDA(dst, b, h) do { _Pragma("unroll") for (int m = 0; m < 4; ++m) _Pragma("unroll") for (int k = 0; k < 2; ++k) dst[m][k] = *(const PG8_LAS bf16x8*)(lds + PG8_SA(b, h) + aoff + m * 2048 + k * 1024); } while (0)
; #define PG8_LDB(dst, b, h) do { _Pragma("unroll") for (int n = 0; n < 2; ++n) _Pragma("unroll") for (int k = 0; k < 2; ++k) dst[n][k] = *(const PG8_LAS bf16x8*)(lds + PG8_SB(b, h) + boff + n * 2048 + k * 1024); } while (0)
; template <class Epi, class Sched, bool ALIGN_EPI = false, bool SP2 = false>
; __device__ __forceinline__ void gemm_phase(PG8_LAS unsigned char* lds, const Gemm g, const Sched& S, const Epi& E) {
;     ...
;         for (int t = 0; t < nt; t += 2) {
;             const bool last = (t == nt - 2);
;             const char* a1 = cA + (size_t)(t + 1) * kstep;
;             const char* a2 = last ? nA : cA + (size_t)(t + 2) * kstep; const char* b2 = last ? nB : cB + (size_t)(t + 2) * kstep;
;             const char* a3 = a2 + kstep; const char* b3 = b2 + kstep;
;             if (last && has_next) S.a_ready(nxt);
;             if constexpr (SP2) {
;             PG8_LDB(B0, 0, 0); PG8_LDB(B1, 0, 1); PG8_SCHED; PG8_LDA(At, 0, 0); PG8_STAGE(PG8_SA(1, 1), a1 + hstep, voffA);
;             PG8_WAIT_V(8); PG8_WAIT_L(0); PG8_BAR; PG8_MMA(0, 0, At, B0); PG8_MMA(0, 1, At, B1); PG8_BAR; PG8_SCHED;
;             PG8_LDA(At, 0, 1); PG8_STAGE(PG8_SB(0, 0), b2, voffB); PG8_STAGE(PG8_SB(0, 1), b2 + hstep, voffB); PG8_STAGE(PG8_SA(0, 0), a2, voffA);
;             PG8_WAIT_V(8); PG8_WAIT_L(0); PG8_BAR; PG8_MMA(1, 0, At, B0); PG8_MMA(1, 1, At, B1); PG8_BAR; PG8_SCHED;
;             PG8_LDB(B0, 1, 0); PG8_LDB(B1, 1, 1); PG8_SCHED; PG8_LDA(At, 1, 0); PG8_STAGE(PG8_SA(0, 1), a2 + hstep, voffA);
;             PG8_WAIT_V(8); PG8_WAIT_L(0); PG8_BAR; PG8_MMA(0, 0, At, B0); PG8_MMA(0, 1, At, B1); PG8_BAR; PG8_SCHED;
;             PG8_LDA(At, 1, 1); PG8_STAGE(PG8_SB(1, 0), b3, voffB); PG8_STAGE(PG8_SB(1, 1), b3 + hstep, voffB); PG8_STAGE(PG8_SA(1, 0), a3, voffA);
;             PG8_WAIT_V(8); PG8_WAIT_L(0); PG8_BAR; PG8_MMA(1, 0, At, B0); PG8_MMA(1, 1, At, B1); PG8_BAR; PG8_SCHED;
	s_add_i32 s60, s93, s65
	v_lshl_add_u64 v[204:205], v[204:205], 0, s[18:19]
	s_mov_b32 m0, s60
	ds_read_b128 v[180:183], v147 offset:49152
	ds_read_b128 v[184:187], v147 offset:50176
	ds_read_b128 v[188:191], v147 offset:51200
	ds_read_b128 v[192:195], v147 offset:52224
	ds_read_b128 v[196:199], v147 offset:53248
	ds_read_b128 v[200:203], v147 offset:54272
	ds_read_b128 v[208:211], v147 offset:55296
	ds_read_b128 v[212:215], v147 offset:56320
	global_load_lds_dwordx4 v[204:205], off
	s_add_i32 m0, s60, 0x2000
	s_add_u32 s58, s58, 0x40080
	v_lshl_add_u64 v[204:205], v[216:217], 0, s[18:19]
	s_addc_u32 s59, s59, 0
	s_add_i32 s60, s94, s65
	global_load_lds_dwordx4 v[204:205], off
	v_lshl_add_u64 v[204:205], s[58:59], 0, v[130:131]
	s_mov_b32 m0, s60
	s_nop 0
	global_load_lds_dwordx4 v[204:205], off
	v_lshl_add_u64 v[204:205], s[58:59], 0, v[134:135]
	s_add_i32 m0, s60, 0x2000
	s_nop 0
	global_load_lds_dwordx4 v[204:205], off
	v_lshl_add_u64 v[204:205], v[218:219], 0, s[18:19]
	s_mov_b32 m0, s73
	s_nop 0
	global_load_lds_dwordx4 v[204:205], off
	v_lshl_add_u64 v[204:205], v[220:221], 0, s[18:19]
	s_mov_b32 m0, s74
	s_nop 0
	global_load_lds_dwordx4 v[204:205], off
	s_waitcnt vmcnt(8)
	s_waitcnt lgkmcnt(0)
	s_barrier
	s_setprio 1
	s_waitcnt lgkmcnt(0)
	v_mfma_f32_16x16x32_bf16 v[60:63], v[148:151], v[180:183], v[60:63]
	v_mfma_f32_16x16x32_bf16 v[56:59], v[156:159], v[180:183], v[56:59]
	v_mfma_f32_16x16x32_bf16 v[52:55], v[148:151], v[188:191], v[52:55]
	v_mfma_f32_16x16x32_bf16 v[48:51], v[156:159], v[188:191], v[48:51]
	v_mfma_f32_16x16x32_bf16 v[36:39], v[148:151], v[196:199], v[36:39]
	v_mfma_f32_16x16x32_bf16 v[32:35], v[156:159], v[196:199], v[32:35]
	v_mfma_f32_16x16x32_bf16 v[20:23], v[148:151], v[208:211], v[20:23]
	v_mfma_f32_16x16x32_bf16 v[16:19], v[156:159], v[208:211], v[16:19]
	v_mfma_f32_16x16x32_bf16 v[60:63], v[152:155], v[184:187], v[60:63]
	v_mfma_f32_16x16x32_bf16 v[56:59], v[160:163], v[184:187], v[56:59]
	v_mfma_f32_16x16x32_bf16 v[52:55], v[152:155], v[192:195], v[52:55]
	v_mfma_f32_16x16x32_bf16 v[48:51], v[160:163], v[192:195], v[48:51]
	v_mfma_f32_16x16x32_bf16 v[36:39], v[152:155], v[200:203], v[36:39]
	v_mfma_f32_16x16x32_bf16 v[32:35], v[160:163], v[200:203], v[32:35]
	v_mfma_f32_16x16x32_bf16 v[20:23], v[152:155], v[212:215], v[20:23]
	v_mfma_f32_16x16x32_bf16 v[16:19], v[160:163], v[212:215], v[16:19]
	s_setprio 0
	s_setprio 1
	v_mfma_f32_16x16x32_bf16 v[44:47], v[164:167], v[180:183], v[44:47]
	v_mfma_f32_16x16x32_bf16 v[40:43], v[172:175], v[180:183], v[40:43]
	v_mfma_f32_16x16x32_bf16 v[28:31], v[164:167], v[188:191], v[28:31]
	v_mfma_f32_16x16x32_bf16 v[24:27], v[172:175], v[188:191], v[24:27]
	v_mfma_f32_16x16x32_bf16 v[12:15], v[164:167], v[196:199], v[12:15]
	v_mfma_f32_16x16x32_bf16 v[8:11], v[172:175], v[196:199], v[8:11]
	v_mfma_f32_16x16x32_bf16 v[4:7], v[164:167], v[208:211], v[4:7]
	v_mfma_f32_16x16x32_bf16 v[0:3], v[172:175], v[208:211], v[0:3]
	v_mfma_f32_16x16x32_bf16 v[44:47], v[168:171], v[184:187], v[44:47]
	v_mfma_f32_16x16x32_bf16 v[40:43], v[176:179], v[184:187], v[40:43]
	v_mfma_f32_16x16x32_bf16 v[28:31], v[168:171], v[192:195], v[28:31]
	v_mfma_f32_16x16x32_bf16 v[24:27], v[176:179], v[192:195], v[24:27]
	v_mfma_f32_16x16x32_bf16 v[12:15], v[168:171], v[200:203], v[12:15]
	v_mfma_f32_16x16x32_bf16 v[8:11], v[176:179], v[200:203], v[8:11]
	v_mfma_f32_16x16x32_bf16 v[4:7], v[168:171], v[212:215], v[4:7]
	v_mfma_f32_16x16x32_bf16 v[0:3], v[176:179], v[212:215], v[0:3]
	s_setprio 0
	s_barrier
	s_add_i32 s92, s92, 2
	s_add_u32 s56, s56, 0x100
	s_addc_u32 s57, s57, 0
	s_add_u32 s90, s90, 0x100
	s_addc_u32 s91, s91, 0
	s_cmp_gt_u32 s92, 13
	s_cbranch_scc0 .LBB0_659
	s_branch .Lpeel_exit_3

; #define PG8_BAR __builtin_amdgcn_s_barrier()
; template <class Epi, class Sched, bool ALIGN_EPI = false, bool SP2 = false>
; __device__ __forceinline__ void gemm_phase(PG8_LAS unsigned char* lds, const Gemm g, const Sched& S, const Epi& E) {
;     ...
;         if constexpr (ALIGN_EPI) { if (wr == 0) PG8_BAR; }
.Lpeel_exit_3:
	s_and_b64 vcc, exec, s[20:21]
	s_cbranch_vccz .LBB0_662
	s_barrier

;     __device__ __forceinline__ bool next(int i, Unit& u) const { if (i != 0) return false; const int c0 = (G >= 8) ? G - 5 : G - 2; int k = -1; if (c == c0) k = 0; else if (c == G - 1) k = 1; if (k < 0 || k >= n) return false; u.pm = k; u.pn = 0; return true; }
; #define PG8_STAGE(bufoff, gbase, voff) do { _Pragma("unroll") for (int _i = 0; _i < 2; ++_i) \
;         __builtin_amdgcn_global_load_lds((const unsigned*)((const char*)(gbase) + (voff)[_i]), (PG8_LAS unsigned*)(lds + (bufoff) + ldsw + _i * 8192), 16, 0, 0); } while (0)
; #define PG8_LDA(dst, b, h) do { _Pragma("unroll") for (int m = 0; m < 4; ++m) _Pragma("unroll") for (int k = 0; k < 2; ++k) dst[m][k] = *(const PG8_LAS bf16x8*)(lds + PG8_SA(b, h) + aoff + m * 2048 + k * 1024); } while (0)
; #define PG8_LDB(dst, b, h) do { _Pragma("unroll") for (int n = 0; n < 2; ++n) _Pragma("unroll") for (int k = 0; k < 2; ++k) dst[n][k] = *(const PG8_LAS bf16x8*)(lds + PG8_SB(b, h) + boff + n * 2048 + k * 1024); } while (0)
; template <class Epi, class Sched, bool ALIGN_EPI = false, bool SP2 = false>
; __device__ __forceinline__ void gemm_phase(PG8_LAS unsigned char* lds, const Gemm g, const Sched& S, const Epi& E) {
;     ...
;         const bool has_next = S.next(ui + 1, nxt);
;         const char* nA = has_next ? (const char*)g.A + (size_t)nxt.pm * tstep : cA; const char* nB = has_next ? (const char*)g.Bt + (size_t)nxt.pn * tstep : cB;
;         for (int t = 0; t < nt; t += 2) {
;             const bool last = (t == nt - 2);
;             const char* a1 = cA + (size_t)(t + 1) * kstep;
;             const char* a2 = last ? nA : cA + (size_t)(t + 2) * kstep; const char* b2 = last ? nB : cB + (size_t)(t + 2) * kstep;
;             const char* a3 = a2 + kstep; const char* b3 = b2 + kstep;
;             if (last && has_next) S.a_ready(nxt);
;             if constexpr (SP2) {
;             PG8_LDB(B0, 0, 0); PG8_LDB(B1, 0, 1); PG8_SCHED; PG8_LDA(At, 0, 0); PG8_STAGE(PG8_SA(1, 1), a1 + hstep, voffA);
;             PG8_WAIT_V(8); PG8_WAIT_L(0); PG8_BAR; PG8_MMA(0, 0, At, B0); PG8_MMA(0, 1, At, B1); PG8_BAR; PG8_SCHED;
;             PG8_LDA(At, 0, 1); PG8_STAGE(PG8_SB(0, 0), b2, voffB); PG8_STAGE(PG8_SB(0, 1), b2 + hstep, voffB); PG8_STAGE(PG8_SA(0, 0), a2, voffA);
;             PG8_WAIT_V(8); PG8_WAIT_L(0); PG8_BAR; PG8_MMA(1, 0, At, B0); PG8_MMA(1, 1, At, B1); PG8_BAR; PG8_SCHED;
.LBB0_855:
	s_ashr_i32 s23, s22, 31
	s_lshl_b64 s[26:27], s[22:23], 19
	s_add_u32 s26, s97, s26
	s_addc_u32 s27, s3, s27
	s_and_b64 s[28:29], s[24:25], exec
	s_cselect_b32 s23, s27, s39
	s_cselect_b32 s74, s26, s38
	s_ashr_i32 s21, s20, 31
	s_lshl_b64 s[28:29], s[20:21], 19
	s_add_u32 s28, s46, s28
	s_addc_u32 s29, s47, s29
	s_and_b64 s[42:43], s[24:25], exec
	s_cselect_b32 s21, s29, s41
	s_cselect_b32 s75, s28, s40
	s_add_u32 s38, s38, 0x40080
	s_addc_u32 s39, s39, 0
	s_add_u32 s76, s40, 0x100
	v_mov_b32_e32 v0, 0
	s_addc_u32 s77, s41, 0
	s_mov_b32 s78, -2
	ds_read_b128 v[164:167], v160
	ds_read_b128 v[168:171], v160 offset:1024
	ds_read_b128 v[172:175], v160 offset:2048
	ds_read_b128 v[176:179], v160 offset:3072
	ds_read_b128 v[180:183], v161
	ds_read_b128 v[184:187], v161 offset:1024
	ds_read_b128 v[188:191], v161 offset:2048
	ds_read_b128 v[192:195], v161 offset:3072
	s_add_u32 s40, s38, 0xfffc0080
	s_addc_u32 s41, s39, -1
	s_cmp_eq_u32 s78, 12
	s_cselect_b32 s43, s23, s41
	s_cselect_b32 s42, s74, s40
	s_cselect_b32 s41, s21, s77
	s_cselect_b32 s40, s75, s76
	v_lshl_add_u64 v[142:143], s[38:39], 0, v[136:137]
	s_add_i32 m0, s31, 0xc000
	ds_read_b128 v[196:199], v162
	ds_read_b128 v[200:203], v162 offset:1024
	ds_read_b128 v[208:211], v162 offset:2048
	ds_read_b128 v[212:215], v162 offset:3072
	ds_read_b128 v[216:219], v162 offset:4096
	ds_read_b128 v[220:223], v162 offset:5120
	ds_read_b128 v[224:227], v162 offset:6144
	ds_read_b128 v[228:231], v162 offset:7168
	global_load_lds_dwordx4 v[142:143], off
	v_lshl_add_u64 v[142:143], s[38:39], 0, v[138:139]
	s_add_i32 m0, s31, 0xe000
	s_nop 0
	global_load_lds_dwordx4 v[142:143], off
	s_waitcnt vmcnt(8)
	s_waitcnt lgkmcnt(0)
	s_barrier
	s_setprio 1
	s_waitcnt lgkmcnt(0)
	v_mfma_f32_16x16x32_bf16 v[124:127], v[164:167], v[196:199], 0
	v_mfma_f32_16x16x32_bf16 v[120:123], v[172:175], v[196:199], 0
	v_mfma_f32_16x16x32_bf16 v[108:111], v[164:167], v[208:211], 0
	v_mfma_f32_16x16x32_bf16 v[104:107], v[172:175], v[208:211], 0
	v_mfma_f32_16x16x32_bf16 v[92:95], v[164:167], v[216:219], 0
	v_mfma_f32_16x16x32_bf16 v[88:91], v[172:175], v[216:219], 0
	v_mfma_f32_16x16x32_bf16 v[76:79], v[164:167], v[224:227], 0
	v_mfma_f32_16x16x32_bf16 v[72:75], v[172:175], v[224:227], 0
	v_mfma_f32_16x16x32_bf16 v[124:127], v[168:171], v[200:203], v[124:127]
	v_mfma_f32_16x16x32_bf16 v[120:123], v[176:179], v[200:203], v[120:123]
	v_mfma_f32_16x16x32_bf16 v[108:111], v[168:171], v[212:215], v[108:111]
	v_mfma_f32_16x16x32_bf16 v[104:107], v[176:179], v[212:215], v[104:107]
	v_mfma_f32_16x16x32_bf16 v[92:95], v[168:171], v[220:223], v[92:95]
	v_mfma_f32_16x16x32_bf16 v[88:91], v[176:179], v[220:223], v[88:91]
	v_mfma_f32_16x16x32_bf16 v[76:79], v[168:171], v[228:231], v[76:79]
	v_mfma_f32_16x16x32_bf16 v[72:75], v[176:179], v[228:231], v[72:75]
	s_setprio 0
	s_setprio 1
	v_mfma_f32_16x16x32_bf16 v[116:119], v[180:183], v[196:199], 0
	v_mfma_f32_16x16x32_bf16 v[112:115], v[188:191], v[196:199], 0
	v_mfma_f32_16x16x32_bf16 v[100:103], v[180:183], v[208:211], 0
	v_mfma_f32_16x16x32_bf16 v[96:99], v[188:191], v[208:211], 0
	v_mfma_f32_16x16x32_bf16 v[84:87], v[180:183], v[216:219], 0
	v_mfma_f32_16x16x32_bf16 v[80:83], v[188:191], v[216:219], 0
	v_mfma_f32_16x16x32_bf16 v[68:71], v[180:183], v[224:227], 0
	v_mfma_f32_16x16x32_bf16 v[64:67], v[188:191], v[224:227], 0
	v_mfma_f32_16x16x32_bf16 v[116:119], v[184:187], v[200:203], v[116:119]
	v_mfma_f32_16x16x32_bf16 v[112:115], v[192:195], v[200:203], v[112:115]
	v_mfma_f32_16x16x32_bf16 v[100:103], v[184:187], v[212:215], v[100:103]
	v_mfma_f32_16x16x32_bf16 v[96:99], v[192:195], v[212:215], v[96:99]
	v_mfma_f32_16x16x32_bf16 v[84:87], v[184:187], v[220:223], v[84:87]
	v_mfma_f32_16x16x32_bf16 v[80:83], v[192:195], v[220:223], v[80:83]
	v_mfma_f32_16x16x32_bf16 v[68:71], v[184:187], v[228:231], v[68:71]
	v_mfma_f32_16x16x32_bf16 v[64:67], v[192:195], v[228:231], v[64:67]
	s_setprio 0
	s_barrier
	s_add_i32 s79, s69, s56
	v_lshl_add_u64 v[142:143], s[40:41], 0, v[130:131]
	s_mov_b32 m0, s79
	ds_read_b128 v[196:199], v162 offset:16384
	ds_read_b128 v[200:203], v162 offset:17408
	ds_read_b128 v[208:211], v162 offset:18432
	ds_read_b128 v[212:215], v162 offset:19456
	ds_read_b128 v[216:219], v162 offset:20480
	ds_read_b128 v[220:223], v162 offset:21504
	ds_read_b128 v[224:227], v162 offset:22528
	ds_read_b128 v[228:231], v162 offset:23552
	global_load_lds_dwordx4 v[142:143], off
	s_add_i32 m0, s79, 0x2000
	s_add_u32 s80, s40, 0x40000
	v_lshl_add_u64 v[204:205], s[40:41], 0, v[134:135]
	s_addc_u32 s81, s41, 0
	s_add_i32 s79, s71, s56
	global_load_lds_dwordx4 v[204:205], off
	v_lshl_add_u64 v[232:233], s[80:81], 0, v[130:131]
	s_mov_b32 m0, s79
	v_lshl_add_u64 v[234:235], s[42:43], 0, v[132:133]
	global_load_lds_dwordx4 v[232:233], off
	v_lshl_add_u64 v[232:233], s[80:81], 0, v[134:135]
	s_add_i32 m0, s79, 0x2000
	s_nop 0
	global_load_lds_dwordx4 v[232:233], off
	v_lshl_add_u64 v[232:233], s[42:43], 0, v[128:129]
	s_mov_b32 m0, s31
	s_nop 0
	global_load_lds_dwordx4 v[232:233], off
	s_mov_b32 m0, s59
	s_nop 0
	global_load_lds_dwordx4 v[234:235], off
	s_waitcnt vmcnt(8)
	s_waitcnt lgkmcnt(0)
	s_barrier
; #define PG8_STAGE(bufoff, gbase, voff) do { _Pragma("unroll") for (int _i = 0; _i < 2; ++_i) \
;         __builtin_amdgcn_global_load_lds((const unsigned*)((const char*)(gbase) + (voff)[_i]), (PG8_LAS unsigned*)(lds + (bufoff) + ldsw + _i * 8192), 16, 0, 0); } while (0)
; #define PG8_LDA(dst, b, h) do { _Pragma("unroll") for (int m = 0; m < 4; ++m) _Pragma("unroll") for (int k = 0; k < 2; ++k) dst[m][k] = *(const PG8_LAS bf16x8*)(lds + PG8_SA(b, h) + aoff + m * 2048 + k * 1024); } while (0)
; #define PG8_LDB(dst, b, h) do { _Pragma("unroll") for (int n = 0; n < 2; ++n) _Pragma("unroll") for (int k = 0; k < 2; ++k) dst[n][k] = *(const PG8_LAS bf16x8*)(lds + PG8_SB(b, h) + boff + n * 2048 + k * 1024); } while (0)
; #define PG8_MMA(ai, bj, At, Bt) do { __builtin_amdgcn_s_setprio(1); _Pragma("unroll") for (int m = 0; m < 4; ++m) _Pragma("unroll") for (int n = 0; n < 2; ++n) _Pragma("unroll") for (int k = 0; k < 2; ++k) \
;         acc[ai][bj][m][n] = __builtin_amdgcn_mfma_f32_16x16x32_bf16(Bt[n][k], At[m][k], acc[ai][bj][m][n], 0, 0, 0); __builtin_amdgcn_s_setprio(0); } while (0)
; #define PG8_WAIT_V(n) asm volatile("s_waitcnt vmcnt(" #n ")" ::: "memory")
; #define PG8_WAIT_L(n) asm volatile("s_waitcnt lgkmcnt(" #n ")" ::: "memory")
; #define PG8_BAR __builtin_amdgcn_s_barrier()
; #define PG8_SCHED __builtin_amdgcn_sched_barrier(0)
; template <class Epi, class Sched, bool ALIGN_EPI = false, bool SP2 = false>
; __device__ __forceinline__ void gemm_phase(PG8_LAS unsigned char* lds, const Gemm g, const Sched& S, const Epi& E) {
;     ...
;             PG8_WAIT_V(8); PG8_WAIT_L(0); PG8_BAR; PG8_MMA(1, 0, At, B0); PG8_MMA(1, 1, At, B1); PG8_BAR; PG8_SCHED;
;             PG8_LDB(B0, 1, 0); PG8_LDB(B1, 1, 1); PG8_SCHED; PG8_LDA(At, 1, 0); PG8_STAGE(PG8_SA(0, 1), a2 + hstep, voffA);
;             PG8_WAIT_V(8); PG8_WAIT_L(0); PG8_BAR; PG8_MMA(0, 0, At, B0); PG8_MMA(0, 1, At, B1); PG8_BAR; PG8_SCHED;
	s_setprio 1
	s_waitcnt lgkmcnt(0)
	v_mfma_f32_16x16x32_bf16 v[60:63], v[164:167], v[196:199], 0
	v_mfma_f32_16x16x32_bf16 v[56:59], v[172:175], v[196:199], 0
	v_mfma_f32_16x16x32_bf16 v[44:47], v[164:167], v[208:211], 0
	v_mfma_f32_16x16x32_bf16 v[40:43], v[172:175], v[208:211], 0
	v_mfma_f32_16x16x32_bf16 v[28:31], v[164:167], v[216:219], 0
	v_mfma_f32_16x16x32_bf16 v[24:27], v[172:175], v[216:219], 0
	v_mfma_f32_16x16x32_bf16 v[12:15], v[164:167], v[224:227], 0
	v_mfma_f32_16x16x32_bf16 v[8:11], v[172:175], v[224:227], 0
	v_mfma_f32_16x16x32_bf16 v[60:63], v[168:171], v[200:203], v[60:63]
	v_mfma_f32_16x16x32_bf16 v[56:59], v[176:179], v[200:203], v[56:59]
	v_mfma_f32_16x16x32_bf16 v[44:47], v[168:171], v[212:215], v[44:47]
	v_mfma_f32_16x16x32_bf16 v[40:43], v[176:179], v[212:215], v[40:43]
	v_mfma_f32_16x16x32_bf16 v[28:31], v[168:171], v[220:223], v[28:31]
	v_mfma_f32_16x16x32_bf16 v[24:27], v[176:179], v[220:223], v[24:27]
	v_mfma_f32_16x16x32_bf16 v[12:15], v[168:171], v[228:231], v[12:15]
	v_mfma_f32_16x16x32_bf16 v[8:11], v[176:179], v[228:231], v[8:11]
	s_setprio 0
	s_setprio 1
	v_mfma_f32_16x16x32_bf16 v[52:55], v[180:183], v[196:199], 0
	v_mfma_f32_16x16x32_bf16 v[48:51], v[188:191], v[196:199], 0
	v_mfma_f32_16x16x32_bf16 v[36:39], v[180:183], v[208:211], 0
	v_mfma_f32_16x16x32_bf16 v[32:35], v[188:191], v[208:211], 0
	v_mfma_f32_16x16x32_bf16 v[20:23], v[180:183], v[216:219], 0
	v_mfma_f32_16x16x32_bf16 v[16:19], v[188:191], v[216:219], 0
	v_mfma_f32_16x16x32_bf16 v[4:7], v[180:183], v[224:227], 0
	v_mfma_f32_16x16x32_bf16 v[0:3], v[188:191], v[224:227], 0
	v_mfma_f32_16x16x32_bf16 v[52:55], v[184:187], v[200:203], v[52:55]
	v_mfma_f32_16x16x32_bf16 v[48:51], v[192:195], v[200:203], v[48:51]
	v_mfma_f32_16x16x32_bf16 v[36:39], v[184:187], v[212:215], v[36:39]
	v_mfma_f32_16x16x32_bf16 v[32:35], v[192:195], v[212:215], v[32:35]
	v_mfma_f32_16x16x32_bf16 v[20:23], v[184:187], v[220:223], v[20:23]
	v_mfma_f32_16x16x32_bf16 v[16:19], v[192:195], v[220:223], v[16:19]
	v_mfma_f32_16x16x32_bf16 v[4:7], v[184:187], v[228:231], v[4:7]
	v_mfma_f32_16x16x32_bf16 v[0:3], v[192:195], v[228:231], v[0:3]
	s_setprio 0
	s_barrier
	s_add_i32 s79, 0, 0x18000
	v_add_u32_e32 v163, s79, v158
	s_add_i32 s80, 0, 0x1c000
	ds_read_b128 v[164:167], v163
	ds_read_b128 v[168:171], v163 offset:1024
	ds_read_b128 v[172:175], v163 offset:2048
	ds_read_b128 v[176:179], v163 offset:3072
	v_add_u32_e32 v163, s80, v158
	ds_read_b128 v[180:183], v163
	ds_read_b128 v[184:187], v163 offset:1024
	ds_read_b128 v[188:191], v163 offset:2048
	ds_read_b128 v[192:195], v163 offset:3072
	s_add_u32 s42, s42, 0x40000
	s_addc_u32 s43, s43, 0
	s_mov_b32 m0, s60
	v_lshl_add_u64 v[236:237], s[42:43], 0, v[128:129]
	ds_read_b128 v[196:199], v162 offset:32768
	ds_read_b128 v[200:203], v162 offset:33792
	ds_read_b128 v[208:211], v162 offset:34816
	ds_read_b128 v[212:215], v162 offset:35840
	ds_read_b128 v[216:219], v162 offset:36864
	ds_read_b128 v[220:223], v162 offset:37888
	ds_read_b128 v[224:227], v162 offset:38912
	ds_read_b128 v[228:231], v162 offset:39936
	global_load_lds_dwordx4 v[236:237], off
	v_lshl_add_u64 v[236:237], s[42:43], 0, v[132:133]
	s_mov_b32 m0, s61
	s_nop 0
	global_load_lds_dwordx4 v[236:237], off
	s_waitcnt vmcnt(8)
	s_waitcnt lgkmcnt(0)
	s_barrier
	s_setprio 1
	s_waitcnt lgkmcnt(0)
	v_mfma_f32_16x16x32_bf16 v[124:127], v[164:167], v[196:199], v[124:127]
	v_mfma_f32_16x16x32_bf16 v[120:123], v[172:175], v[196:199], v[120:123]
	v_mfma_f32_16x16x32_bf16 v[108:111], v[164:167], v[208:211], v[108:111]
	v_mfma_f32_16x16x32_bf16 v[104:107], v[172:175], v[208:211], v[104:107]
	v_mfma_f32_16x16x32_bf16 v[92:95], v[164:167], v[216:219], v[92:95]
	v_mfma_f32_16x16x32_bf16 v[88:91], v[172:175], v[216:219], v[88:91]
	v_mfma_f32_16x16x32_bf16 v[76:79], v[164:167], v[224:227], v[76:79]
	v_mfma_f32_16x16x32_bf16 v[72:75], v[172:175], v[224:227], v[72:75]
	v_mfma_f32_16x16x32_bf16 v[124:127], v[168:171], v[200:203], v[124:127]
	v_mfma_f32_16x16x32_bf16 v[120:123], v[176:179], v[200:203], v[120:123]
	v_mfma_f32_16x16x32_bf16 v[108:111], v[168:171], v[212:215], v[108:111]
	v_mfma_f32_16x16x32_bf16 v[104:107], v[176:179], v[212:215], v[104:107]
	v_mfma_f32_16x16x32_bf16 v[92:95], v[168:171], v[220:223], v[92:95]
	v_mfma_f32_16x16x32_bf16 v[88:91], v[176:179], v[220:223], v[88:91]
	v_mfma_f32_16x16x32_bf16 v[76:79], v[168:171], v[228:231], v[76:79]
	v_mfma_f32_16x16x32_bf16 v[72:75], v[176:179], v[228:231], v[72:75]
	s_setprio 0
	s_setprio 1
	v_mfma_f32_16x16x32_bf16 v[116:119], v[180:183], v[196:199], v[116:119]
	v_mfma_f32_16x16x32_bf16 v[112:115], v[188:191], v[196:199], v[112:115]
	v_mfma_f32_16x16x32_bf16 v[100:103], v[180:183], v[208:211], v[100:103]
	v_mfma_f32_16x16x32_bf16 v[96:99], v[188:191], v[208:211], v[96:99]
	v_mfma_f32_16x16x32_bf16 v[84:87], v[180:183], v[216:219], v[84:87]
	v_mfma_f32_16x16x32_bf16 v[80:83], v[188:191], v[216:219], v[80:83]
	v_mfma_f32_16x16x32_bf16 v[68:71], v[180:183], v[224:227], v[68:71]
	v_mfma_f32_16x16x32_bf16 v[64:67], v[188:191], v[224:227], v[64:67]
	v_mfma_f32_16x16x32_bf16 v[116:119], v[184:187], v[200:203], v[116:119]
	v_mfma_f32_16x16x32_bf16 v[112:115], v[192:195], v[200:203], v[112:115]
	v_mfma_f32_16x16x32_bf16 v[100:103], v[184:187], v[212:215], v[100:103]
	v_mfma_f32_16x16x32_bf16 v[96:99], v[192:195], v[212:215], v[96:99]
	v_mfma_f32_16x16x32_bf16 v[84:87], v[184:187], v[220:223], v[84:87]
	v_mfma_f32_16x16x32_bf16 v[80:83], v[192:195], v[220:223], v[80:83]
	v_mfma_f32_16x16x32_bf16 v[68:71], v[184:187], v[228:231], v[68:71]
	v_mfma_f32_16x16x32_bf16 v[64:67], v[192:195], v[228:231], v[64:67]
	s_setprio 0
	s_barrier
; #define PG8_STAGE(bufoff, gbase, voff) do { _Pragma("unroll") for (int _i = 0; _i < 2; ++_i) \
;         __builtin_amdgcn_global_load_lds((const unsigned*)((const char*)(gbase) + (voff)[_i]), (PG8_LAS unsigned*)(lds + (bufoff) + ldsw + _i * 8192), 16, 0, 0); } while (0)
; #define PG8_LDA(dst, b, h) do { _Pragma("unroll") for (int m = 0; m < 4; ++m) _Pragma("unroll") for (int k = 0; k < 2; ++k) dst[m][k] = *(const PG8_LAS bf16x8*)(lds + PG8_SA(b, h) + aoff + m * 2048 + k * 1024); } while (0)
; #define PG8_LDB(dst, b, h) do { _Pragma("unroll") for (int n = 0; n < 2; ++n) _Pragma("unroll") for (int k = 0; k < 2; ++k) dst[n][k] = *(const PG8_LAS bf16x8*)(lds + PG8_SB(b, h) + boff + n * 2048 + k * 1024); } while (0)
; template <class Epi, class Sched, bool ALIGN_EPI = false, bool SP2 = false>
; __device__ __forceinline__ void gemm_phase(PG8_LAS unsigned char* lds, const Gemm g, const Sched& S, const Epi& E) {
;     ...
;         for (int t = 0; t < nt; t += 2) {
;             const bool last = (t == nt - 2);
;             const char* a1 = cA + (size_t)(t + 1) * kstep;
;             const char* a2 = last ? nA : cA + (size_t)(t + 2) * kstep; const char* b2 = last ? nB : cB + (size_t)(t + 2) * kstep;
;             const char* a3 = a2 + kstep; const char* b3 = b2 + kstep;
;             if (last && has_next) S.a_ready(nxt);
;             if constexpr (SP2) {
;             PG8_LDB(B0, 0, 0); PG8_LDB(B1, 0, 1); PG8_SCHED; PG8_LDA(At, 0, 0); PG8_STAGE(PG8_SA(1, 1), a1 + hstep, voffA);
;             PG8_WAIT_V(8); PG8_WAIT_L(0); PG8_BAR; PG8_MMA(0, 0, At, B0); PG8_MMA(0, 1, At, B1); PG8_BAR; PG8_SCHED;
;             PG8_LDA(At, 0, 1); PG8_STAGE(PG8_SB(0, 0), b2, voffB); PG8_STAGE(PG8_SB(0, 1), b2 + hstep, voffB); PG8_STAGE(PG8_SA(0, 0), a2, voffA);
;             PG8_WAIT_V(8); PG8_WAIT_L(0); PG8_BAR; PG8_MMA(1, 0, At, B0); PG8_MMA(1, 1, At, B1); PG8_BAR; PG8_SCHED;
;             PG8_LDB(B0, 1, 0); PG8_LDB(B1, 1, 1); PG8_SCHED; PG8_LDA(At, 1, 0); PG8_STAGE(PG8_SA(0, 1), a2 + hstep, voffA);
;             PG8_WAIT_V(8); PG8_WAIT_L(0); PG8_BAR; PG8_MMA(0, 0, At, B0); PG8_MMA(0, 1, At, B1); PG8_BAR; PG8_SCHED;
;             PG8_LDA(At, 1, 1); PG8_STAGE(PG8_SB(1, 0), b3, voffB); PG8_STAGE(PG8_SB(1, 1), b3 + hstep, voffB); PG8_STAGE(PG8_SA(1, 0), a3, voffA);
;             PG8_WAIT_V(8); PG8_WAIT_L(0); PG8_BAR; PG8_MMA(1, 0, At, B0); PG8_MMA(1, 1, At, B1); PG8_BAR; PG8_SCHED;
	s_add_i32 s42, s79, s56
	v_lshl_add_u64 v[142:143], v[142:143], 0, s[8:9]
	s_mov_b32 m0, s42
	ds_read_b128 v[196:199], v162 offset:49152
	ds_read_b128 v[200:203], v162 offset:50176
	ds_read_b128 v[208:211], v162 offset:51200
	ds_read_b128 v[212:215], v162 offset:52224
	ds_read_b128 v[216:219], v162 offset:53248
	ds_read_b128 v[220:223], v162 offset:54272
	ds_read_b128 v[224:227], v162 offset:55296
	ds_read_b128 v[228:231], v162 offset:56320
	global_load_lds_dwordx4 v[142:143], off
	s_add_i32 m0, s42, 0x2000
	s_add_u32 s40, s40, 0x40080
	v_lshl_add_u64 v[142:143], v[204:205], 0, s[8:9]
	s_addc_u32 s41, s41, 0
	s_add_i32 s42, s80, s56
	global_load_lds_dwordx4 v[142:143], off
	v_lshl_add_u64 v[142:143], s[40:41], 0, v[130:131]
	s_mov_b32 m0, s42
	s_nop 0
	global_load_lds_dwordx4 v[142:143], off
	v_lshl_add_u64 v[142:143], s[40:41], 0, v[134:135]
	s_add_i32 m0, s42, 0x2000
	s_nop 0
	global_load_lds_dwordx4 v[142:143], off
	v_lshl_add_u64 v[142:143], v[232:233], 0, s[8:9]
	s_mov_b32 m0, s66
	s_nop 0
	global_load_lds_dwordx4 v[142:143], off
	v_lshl_add_u64 v[142:143], v[234:235], 0, s[8:9]
	s_mov_b32 m0, s67
	s_nop 0
	global_load_lds_dwordx4 v[142:143], off
	s_waitcnt vmcnt(8)
	s_waitcnt lgkmcnt(0)
	s_barrier
	s_setprio 1
	s_waitcnt lgkmcnt(0)
	v_mfma_f32_16x16x32_bf16 v[60:63], v[164:167], v[196:199], v[60:63]
	v_mfma_f32_16x16x32_bf16 v[56:59], v[172:175], v[196:199], v[56:59]
	v_mfma_f32_16x16x32_bf16 v[44:47], v[164:167], v[208:211], v[44:47]
	v_mfma_f32_16x16x32_bf16 v[40:43], v[172:175], v[208:211], v[40:43]
	v_mfma_f32_16x16x32_bf16 v[28:31], v[164:167], v[216:219], v[28:31]
	v_mfma_f32_16x16x32_bf16 v[24:27], v[172:175], v[216:219], v[24:27]
	v_mfma_f32_16x16x32_bf16 v[12:15], v[164:167], v[224:227], v[12:15]
	v_mfma_f32_16x16x32_bf16 v[8:11], v[172:175], v[224:227], v[8:11]
	v_mfma_f32_16x16x32_bf16 v[60:63], v[168:171], v[200:203], v[60:63]
	v_mfma_f32_16x16x32_bf16 v[56:59], v[176:179], v[200:203], v[56:59]
	v_mfma_f32_16x16x32_bf16 v[44:47], v[168:171], v[212:215], v[44:47]
	v_mfma_f32_16x16x32_bf16 v[40:43], v[176:179], v[212:215], v[40:43]
	v_mfma_f32_16x16x32_bf16 v[28:31], v[168:171], v[220:223], v[28:31]
	v_mfma_f32_16x16x32_bf16 v[24:27], v[176:179], v[220:223], v[24:27]
	v_mfma_f32_16x16x32_bf16 v[12:15], v[168:171], v[228:231], v[12:15]
	v_mfma_f32_16x16x32_bf16 v[8:11], v[176:179], v[228:231], v[8:11]
	s_setprio 0
	s_setprio 1
	v_mfma_f32_16x16x32_bf16 v[52:55], v[180:183], v[196:199], v[52:55]
	v_mfma_f32_16x16x32_bf16 v[48:51], v[188:191], v[196:199], v[48:51]
	v_mfma_f32_16x16x32_bf16 v[36:39], v[180:183], v[208:211], v[36:39]
	v_mfma_f32_16x16x32_bf16 v[32:35], v[188:191], v[208:211], v[32:35]
	v_mfma_f32_16x16x32_bf16 v[20:23], v[180:183], v[216:219], v[20:23]
	v_mfma_f32_16x16x32_bf16 v[16:19], v[188:191], v[216:219], v[16:19]
	v_mfma_f32_16x16x32_bf16 v[4:7], v[180:183], v[224:227], v[4:7]
	v_mfma_f32_16x16x32_bf16 v[0:3], v[188:191], v[224:227], v[0:3]
	v_mfma_f32_16x16x32_bf16 v[52:55], v[184:187], v[200:203], v[52:55]
	v_mfma_f32_16x16x32_bf16 v[48:51], v[192:195], v[200:203], v[48:51]
	v_mfma_f32_16x16x32_bf16 v[36:39], v[184:187], v[212:215], v[36:39]
	v_mfma_f32_16x16x32_bf16 v[32:35], v[192:195], v[212:215], v[32:35]
	v_mfma_f32_16x16x32_bf16 v[20:23], v[184:187], v[220:223], v[20:23]
	v_mfma_f32_16x16x32_bf16 v[16:19], v[192:195], v[220:223], v[16:19]
	v_mfma_f32_16x16x32_bf16 v[4:7], v[184:187], v[228:231], v[4:7]
	v_mfma_f32_16x16x32_bf16 v[0:3], v[192:195], v[228:231], v[0:3]
	s_setprio 0
	s_barrier
	s_add_i32 s78, s78, 2
	s_add_u32 s38, s38, 0x100
	s_addc_u32 s39, s39, 0
	s_add_u32 s76, s76, 0x100
	s_addc_u32 s77, s77, 0
	s_cmp_gt_u32 s78, 13
	s_cbranch_scc0 .LBB0_856
	s_branch .Lpeel_exit_4

; #define PG8_BAR __builtin_amdgcn_s_barrier()
; template <class Epi, class Sched, bool ALIGN_EPI = false, bool SP2 = false>
; __device__ __forceinline__ void gemm_phase(PG8_LAS unsigned char* lds, const Gemm g, const Sched& S, const Epi& E) {
;     ...
;         if constexpr (ALIGN_EPI) { if (wr == 0) PG8_BAR; }
.Lpeel_exit_4:
	s_and_b64 vcc, exec, s[18:19]
	s_cbranch_vccz .LBB0_859
	s_barrier

;     __device__ __forceinline__ bool next(int i, Unit& u) const { if (i != 0) return false; const int c0 = (G >= 8) ? G - 5 : G - 2; int k = -1; if (c == c0) k = 0; else if (c == G - 1) k = 1; if (k < 0 || k >= n) return false; u.pm = k; u.pn = 0; return true; }
; #define PG8_STAGE(bufoff, gbase, voff) do { _Pragma("unroll") for (int _i = 0; _i < 2; ++_i) \
;         __builtin_amdgcn_global_load_lds((const unsigned*)((const char*)(gbase) + (voff)[_i]), (PG8_LAS unsigned*)(lds + (bufoff) + ldsw + _i * 8192), 16, 0, 0); } while (0)
; #define PG8_LDA(dst, b, h) do { _Pragma("unroll") for (int m = 0; m < 4; ++m) _Pragma("unroll") for (int k = 0; k < 2; ++k) dst[m][k] = *(const PG8_LAS bf16x8*)(lds + PG8_SA(b, h) + aoff + m * 2048 + k * 1024); } while (0)
; #define PG8_LDB(dst, b, h) do { _Pragma("unroll") for (int n = 0; n < 2; ++n) _Pragma("unroll") for (int k = 0; k < 2; ++k) dst[n][k] = *(const PG8_LAS bf16x8*)(lds + PG8_SB(b, h) + boff + n * 2048 + k * 1024); } while (0)
; template <class Epi, class Sched, bool ALIGN_EPI = false, bool SP2 = false>
; __device__ __forceinline__ void gemm_phase(PG8_LAS unsigned char* lds, const Gemm g, const Sched& S, const Epi& E) {
;     ...
;         const bool has_next = S.next(ui + 1, nxt);
;         const char* nA = has_next ? (const char*)g.A + (size_t)nxt.pm * tstep : cA; const char* nB = has_next ? (const char*)g.Bt + (size_t)nxt.pn * tstep : cB;
;         for (int t = 0; t < nt; t += 2) {
;             const bool last = (t == nt - 2);
;             const char* a1 = cA + (size_t)(t + 1) * kstep;
;             const char* a2 = last ? nA : cA + (size_t)(t + 2) * kstep; const char* b2 = last ? nB : cB + (size_t)(t + 2) * kstep;
;             const char* a3 = a2 + kstep; const char* b3 = b2 + kstep;
;             if (last && has_next) S.a_ready(nxt);
;             if constexpr (SP2) {
;             PG8_LDB(B0, 0, 0); PG8_LDB(B1, 0, 1); PG8_SCHED; PG8_LDA(At, 0, 0); PG8_STAGE(PG8_SA(1, 1), a1 + hstep, voffA);
;             PG8_WAIT_V(8); PG8_WAIT_L(0); PG8_BAR; PG8_MMA(0, 0, At, B0); PG8_MMA(0, 1, At, B1); PG8_BAR; PG8_SCHED;
;             PG8_LDA(At, 0, 1); PG8_STAGE(PG8_SB(0, 0), b2, voffB); PG8_STAGE(PG8_SB(0, 1), b2 + hstep, voffB); PG8_STAGE(PG8_SA(0, 0), a2, voffA);
;             PG8_WAIT_V(8); PG8_WAIT_L(0); PG8_BAR; PG8_MMA(1, 0, At, B0); PG8_MMA(1, 1, At, B1); PG8_BAR; PG8_SCHED;
.LBB0_876:
	s_ashr_i32 s21, s20, 31
	s_lshl_b64 s[26:27], s[20:21], 19
	s_add_u32 s26, s97, s26
	s_addc_u32 s27, s3, s27
	s_and_b64 s[28:29], s[24:25], exec
	s_cselect_b32 s21, s27, s39
	s_cselect_b32 s72, s26, s38
	s_ashr_i32 s23, s22, 31
	s_lshl_b64 s[28:29], s[22:23], 19
	s_add_u32 s28, s46, s28
	s_addc_u32 s29, s47, s29
	s_and_b64 s[42:43], s[24:25], exec
	s_cselect_b32 s23, s29, s41
	s_cselect_b32 s73, s28, s40
	s_add_u32 s38, s38, 0x40080
	s_addc_u32 s39, s39, 0
	s_add_u32 s74, s40, 0x100
	v_mov_b32_e32 v0, 0
	s_addc_u32 s75, s41, 0
	s_mov_b32 s76, -2
	ds_read_b128 v[164:167], v160
	ds_read_b128 v[168:171], v160 offset:1024
	ds_read_b128 v[172:175], v160 offset:2048
	ds_read_b128 v[176:179], v160 offset:3072
	ds_read_b128 v[180:183], v161
	ds_read_b128 v[184:187], v161 offset:1024
	ds_read_b128 v[188:191], v161 offset:2048
	ds_read_b128 v[192:195], v161 offset:3072
	s_add_u32 s40, s38, 0xfffc0080
	s_addc_u32 s41, s39, -1
	s_cmp_eq_u32 s76, 12
	s_cselect_b32 s43, s21, s41
	s_cselect_b32 s42, s72, s40
	s_cselect_b32 s41, s23, s75
	s_cselect_b32 s40, s73, s74
	v_lshl_add_u64 v[142:143], s[38:39], 0, v[136:137]
	s_add_i32 m0, s31, 0xc000
	ds_read_b128 v[196:199], v162
	ds_read_b128 v[200:203], v162 offset:1024
	ds_read_b128 v[208:211], v162 offset:2048
	ds_read_b128 v[212:215], v162 offset:3072
	ds_read_b128 v[216:219], v162 offset:4096
	ds_read_b128 v[220:223], v162 offset:5120
	ds_read_b128 v[224:227], v162 offset:6144
	ds_read_b128 v[228:231], v162 offset:7168
	global_load_lds_dwordx4 v[142:143], off
	v_lshl_add_u64 v[142:143], s[38:39], 0, v[138:139]
	s_add_i32 m0, s31, 0xe000
	s_nop 0
	global_load_lds_dwordx4 v[142:143], off
	s_waitcnt vmcnt(8)
	s_waitcnt lgkmcnt(0)
	s_barrier
	s_setprio 1
	s_waitcnt lgkmcnt(0)
	v_mfma_f32_16x16x32_bf16 v[124:127], v[164:167], v[196:199], 0
	v_mfma_f32_16x16x32_bf16 v[120:123], v[172:175], v[196:199], 0
	v_mfma_f32_16x16x32_bf16 v[108:111], v[164:167], v[208:211], 0
	v_mfma_f32_16x16x32_bf16 v[104:107], v[172:175], v[208:211], 0
	v_mfma_f32_16x16x32_bf16 v[92:95], v[164:167], v[216:219], 0
	v_mfma_f32_16x16x32_bf16 v[88:91], v[172:175], v[216:219], 0
	v_mfma_f32_16x16x32_bf16 v[76:79], v[164:167], v[224:227], 0
	v_mfma_f32_16x16x32_bf16 v[72:75], v[172:175], v[224:227], 0
	v_mfma_f32_16x16x32_bf16 v[124:127], v[168:171], v[200:203], v[124:127]
	v_mfma_f32_16x16x32_bf16 v[120:123], v[176:179], v[200:203], v[120:123]
	v_mfma_f32_16x16x32_bf16 v[108:111], v[168:171], v[212:215], v[108:111]
	v_mfma_f32_16x16x32_bf16 v[104:107], v[176:179], v[212:215], v[104:107]
	v_mfma_f32_16x16x32_bf16 v[92:95], v[168:171], v[220:223], v[92:95]
	v_mfma_f32_16x16x32_bf16 v[88:91], v[176:179], v[220:223], v[88:91]
	v_mfma_f32_16x16x32_bf16 v[76:79], v[168:171], v[228:231], v[76:79]
	v_mfma_f32_16x16x32_bf16 v[72:75], v[176:179], v[228:231], v[72:75]
	s_setprio 0
	s_setprio 1
	v_mfma_f32_16x16x32_bf16 v[116:119], v[180:183], v[196:199], 0
	v_mfma_f32_16x16x32_bf16 v[112:115], v[188:191], v[196:199], 0
	v_mfma_f32_16x16x32_bf16 v[100:103], v[180:183], v[208:211], 0
	v_mfma_f32_16x16x32_bf16 v[96:99], v[188:191], v[208:211], 0
	v_mfma_f32_16x16x32_bf16 v[84:87], v[180:183], v[216:219], 0
	v_mfma_f32_16x16x32_bf16 v[80:83], v[188:191], v[216:219], 0
	v_mfma_f32_16x16x32_bf16 v[68:71], v[180:183], v[224:227], 0
	v_mfma_f32_16x16x32_bf16 v[64:67], v[188:191], v[224:227], 0
	v_mfma_f32_16x16x32_bf16 v[116:119], v[184:187], v[200:203], v[116:119]
	v_mfma_f32_16x16x32_bf16 v[112:115], v[192:195], v[200:203], v[112:115]
	v_mfma_f32_16x16x32_bf16 v[100:103], v[184:187], v[212:215], v[100:103]
	v_mfma_f32_16x16x32_bf16 v[96:99], v[192:195], v[212:215], v[96:99]
	v_mfma_f32_16x16x32_bf16 v[84:87], v[184:187], v[220:223], v[84:87]
	v_mfma_f32_16x16x32_bf16 v[80:83], v[192:195], v[220:223], v[80:83]
	v_mfma_f32_16x16x32_bf16 v[68:71], v[184:187], v[228:231], v[68:71]
	v_mfma_f32_16x16x32_bf16 v[64:67], v[192:195], v[228:231], v[64:67]
	s_setprio 0
	s_barrier
	s_add_i32 s77, s67, s57
	v_lshl_add_u64 v[142:143], s[40:41], 0, v[130:131]
	s_mov_b32 m0, s77
	ds_read_b128 v[196:199], v162 offset:16384
	ds_read_b128 v[200:203], v162 offset:17408
	ds_read_b128 v[208:211], v162 offset:18432
	ds_read_b128 v[212:215], v162 offset:19456
	ds_read_b128 v[216:219], v162 offset:20480
	ds_read_b128 v[220:223], v162 offset:21504
	ds_read_b128 v[224:227], v162 offset:22528
	ds_read_b128 v[228:231], v162 offset:23552
	global_load_lds_dwordx4 v[142:143], off
	s_add_i32 m0, s77, 0x2000
	s_add_u32 s78, s40, 0x40000
	v_lshl_add_u64 v[204:205], s[40:41], 0, v[134:135]
	s_addc_u32 s79, s41, 0
	s_add_i32 s77, s68, s57
	global_load_lds_dwordx4 v[204:205], off
	v_lshl_add_u64 v[232:233], s[78:79], 0, v[130:131]
	s_mov_b32 m0, s77
	v_lshl_add_u64 v[234:235], s[42:43], 0, v[132:133]
	global_load_lds_dwordx4 v[232:233], off
	v_lshl_add_u64 v[232:233], s[78:79], 0, v[134:135]
	s_add_i32 m0, s77, 0x2000
	s_nop 0
	global_load_lds_dwordx4 v[232:233], off
	v_lshl_add_u64 v[232:233], s[42:43], 0, v[128:129]
	s_mov_b32 m0, s31
	s_nop 0
	global_load_lds_dwordx4 v[232:233], off
	s_mov_b32 m0, s59
	s_nop 0
	global_load_lds_dwordx4 v[234:235], off
	s_waitcnt vmcnt(8)
	s_waitcnt lgkmcnt(0)
	s_barrier
; #define PG8_STAGE(bufoff, gbase, voff) do { _Pragma("unroll") for (int _i = 0; _i < 2; ++_i) \
;         __builtin_amdgcn_global_load_lds((const unsigned*)((const char*)(gbase) + (voff)[_i]), (PG8_LAS unsigned*)(lds + (bufoff) + ldsw + _i * 8192), 16, 0, 0); } while (0)
; #define PG8_LDA(dst, b, h) do { _Pragma("unroll") for (int m = 0; m < 4; ++m) _Pragma("unroll") for (int k = 0; k < 2; ++k) dst[m][k] = *(const PG8_LAS bf16x8*)(lds + PG8_SA(b, h) + aoff + m * 2048 + k * 1024); } while (0)
; #define PG8_LDB(dst, b, h) do { _Pragma("unroll") for (int n = 0; n < 2; ++n) _Pragma("unroll") for (int k = 0; k < 2; ++k) dst[n][k] = *(const PG8_LAS bf16x8*)(lds + PG8_SB(b, h) + boff + n * 2048 + k * 1024); } while (0)
; #define PG8_MMA(ai, bj, At, Bt) do { __builtin_amdgcn_s_setprio(1); _Pragma("unroll") for (int m = 0; m < 4; ++m) _Pragma("unroll") for (int n = 0; n < 2; ++n) _Pragma("unroll") for (int k = 0; k < 2; ++k) \
;         acc[ai][bj][m][n] = __builtin_amdgcn_mfma_f32_16x16x32_bf16(Bt[n][k], At[m][k], acc[ai][bj][m][n], 0, 0, 0); __builtin_amdgcn_s_setprio(0); } while (0)
; #define PG8_WAIT_V(n) asm volatile("s_waitcnt vmcnt(" #n ")" ::: "memory")
; #define PG8_WAIT_L(n) asm volatile("s_waitcnt lgkmcnt(" #n ")" ::: "memory")
; #define PG8_BAR __builtin_amdgcn_s_barrier()
; #define PG8_SCHED __builtin_amdgcn_sched_barrier(0)
; template <class Epi, class Sched, bool ALIGN_EPI = false, bool SP2 = false>
; __device__ __forceinline__ void gemm_phase(PG8_LAS unsigned char* lds, const Gemm g, const Sched& S, const Epi& E) {
;     ...
;             PG8_WAIT_V(8); PG8_WAIT_L(0); PG8_BAR; PG8_MMA(1, 0, At, B0); PG8_MMA(1, 1, At, B1); PG8_BAR; PG8_SCHED;
;             PG8_LDB(B0, 1, 0); PG8_LDB(B1, 1, 1); PG8_SCHED; PG8_LDA(At, 1, 0); PG8_STAGE(PG8_SA(0, 1), a2 + hstep, voffA);
;             PG8_WAIT_V(8); PG8_WAIT_L(0); PG8_BAR; PG8_MMA(0, 0, At, B0); PG8_MMA(0, 1, At, B1); PG8_BAR; PG8_SCHED;
	s_setprio 1
	s_waitcnt lgkmcnt(0)
	v_mfma_f32_16x16x32_bf16 v[60:63], v[164:167], v[196:199], 0
	v_mfma_f32_16x16x32_bf16 v[56:59], v[172:175], v[196:199], 0
	v_mfma_f32_16x16x32_bf16 v[44:47], v[164:167], v[208:211], 0
	v_mfma_f32_16x16x32_bf16 v[40:43], v[172:175], v[208:211], 0
	v_mfma_f32_16x16x32_bf16 v[28:31], v[164:167], v[216:219], 0
	v_mfma_f32_16x16x32_bf16 v[24:27], v[172:175], v[216:219], 0
	v_mfma_f32_16x16x32_bf16 v[12:15], v[164:167], v[224:227], 0
	v_mfma_f32_16x16x32_bf16 v[8:11], v[172:175], v[224:227], 0
	v_mfma_f32_16x16x32_bf16 v[60:63], v[168:171], v[200:203], v[60:63]
	v_mfma_f32_16x16x32_bf16 v[56:59], v[176:179], v[200:203], v[56:59]
	v_mfma_f32_16x16x32_bf16 v[44:47], v[168:171], v[212:215], v[44:47]
	v_mfma_f32_16x16x32_bf16 v[40:43], v[176:179], v[212:215], v[40:43]
	v_mfma_f32_16x16x32_bf16 v[28:31], v[168:171], v[220:223], v[28:31]
	v_mfma_f32_16x16x32_bf16 v[24:27], v[176:179], v[220:223], v[24:27]
	v_mfma_f32_16x16x32_bf16 v[12:15], v[168:171], v[228:231], v[12:15]
	v_mfma_f32_16x16x32_bf16 v[8:11], v[176:179], v[228:231], v[8:11]
	s_setprio 0
	s_setprio 1
	v_mfma_f32_16x16x32_bf16 v[52:55], v[180:183], v[196:199], 0
	v_mfma_f32_16x16x32_bf16 v[48:51], v[188:191], v[196:199], 0
	v_mfma_f32_16x16x32_bf16 v[36:39], v[180:183], v[208:211], 0
	v_mfma_f32_16x16x32_bf16 v[32:35], v[188:191], v[208:211], 0
	v_mfma_f32_16x16x32_bf16 v[20:23], v[180:183], v[216:219], 0
	v_mfma_f32_16x16x32_bf16 v[16:19], v[188:191], v[216:219], 0
	v_mfma_f32_16x16x32_bf16 v[4:7], v[180:183], v[224:227], 0
	v_mfma_f32_16x16x32_bf16 v[0:3], v[188:191], v[224:227], 0
	v_mfma_f32_16x16x32_bf16 v[52:55], v[184:187], v[200:203], v[52:55]
	v_mfma_f32_16x16x32_bf16 v[48:51], v[192:195], v[200:203], v[48:51]
	v_mfma_f32_16x16x32_bf16 v[36:39], v[184:187], v[212:215], v[36:39]
	v_mfma_f32_16x16x32_bf16 v[32:35], v[192:195], v[212:215], v[32:35]
	v_mfma_f32_16x16x32_bf16 v[20:23], v[184:187], v[220:223], v[20:23]
	v_mfma_f32_16x16x32_bf16 v[16:19], v[192:195], v[220:223], v[16:19]
	v_mfma_f32_16x16x32_bf16 v[4:7], v[184:187], v[228:231], v[4:7]
	v_mfma_f32_16x16x32_bf16 v[0:3], v[192:195], v[228:231], v[0:3]
	s_setprio 0
	s_barrier
	s_add_i32 s77, 0, 0x18000
	v_add_u32_e32 v163, s77, v158
	s_add_i32 s78, 0, 0x1c000
	ds_read_b128 v[164:167], v163
	ds_read_b128 v[168:171], v163 offset:1024
	ds_read_b128 v[172:175], v163 offset:2048
	ds_read_b128 v[176:179], v163 offset:3072
	v_add_u32_e32 v163, s78, v158
	ds_read_b128 v[180:183], v163
	ds_read_b128 v[184:187], v163 offset:1024
	ds_read_b128 v[188:191], v163 offset:2048
	ds_read_b128 v[192:195], v163 offset:3072
	s_add_u32 s42, s42, 0x40000
	s_addc_u32 s43, s43, 0
	s_mov_b32 m0, s60
	v_lshl_add_u64 v[236:237], s[42:43], 0, v[128:129]
	ds_read_b128 v[196:199], v162 offset:32768
	ds_read_b128 v[200:203], v162 offset:33792
	ds_read_b128 v[208:211], v162 offset:34816
	ds_read_b128 v[212:215], v162 offset:35840
	ds_read_b128 v[216:219], v162 offset:36864
	ds_read_b128 v[220:223], v162 offset:37888
	ds_read_b128 v[224:227], v162 offset:38912
	ds_read_b128 v[228:231], v162 offset:39936
	global_load_lds_dwordx4 v[236:237], off
	v_lshl_add_u64 v[236:237], s[42:43], 0, v[132:133]
	s_mov_b32 m0, s61
	s_nop 0
	global_load_lds_dwordx4 v[236:237], off
	s_waitcnt vmcnt(8)
	s_waitcnt lgkmcnt(0)
	s_barrier
	s_setprio 1
	s_waitcnt lgkmcnt(0)
	v_mfma_f32_16x16x32_bf16 v[124:127], v[164:167], v[196:199], v[124:127]
	v_mfma_f32_16x16x32_bf16 v[120:123], v[172:175], v[196:199], v[120:123]
	v_mfma_f32_16x16x32_bf16 v[108:111], v[164:167], v[208:211], v[108:111]
	v_mfma_f32_16x16x32_bf16 v[104:107], v[172:175], v[208:211], v[104:107]
	v_mfma_f32_16x16x32_bf16 v[92:95], v[164:167], v[216:219], v[92:95]
	v_mfma_f32_16x16x32_bf16 v[88:91], v[172:175], v[216:219], v[88:91]
	v_mfma_f32_16x16x32_bf16 v[76:79], v[164:167], v[224:227], v[76:79]
	v_mfma_f32_16x16x32_bf16 v[72:75], v[172:175], v[224:227], v[72:75]
	v_mfma_f32_16x16x32_bf16 v[124:127], v[168:171], v[200:203], v[124:127]
	v_mfma_f32_16x16x32_bf16 v[120:123], v[176:179], v[200:203], v[120:123]
	v_mfma_f32_16x16x32_bf16 v[108:111], v[168:171], v[212:215], v[108:111]
	v_mfma_f32_16x16x32_bf16 v[104:107], v[176:179], v[212:215], v[104:107]
	v_mfma_f32_16x16x32_bf16 v[92:95], v[168:171], v[220:223], v[92:95]
	v_mfma_f32_16x16x32_bf16 v[88:91], v[176:179], v[220:223], v[88:91]
	v_mfma_f32_16x16x32_bf16 v[76:79], v[168:171], v[228:231], v[76:79]
	v_mfma_f32_16x16x32_bf16 v[72:75], v[176:179], v[228:231], v[72:75]
	s_setprio 0
	s_setprio 1
	v_mfma_f32_16x16x32_bf16 v[116:119], v[180:183], v[196:199], v[116:119]
	v_mfma_f32_16x16x32_bf16 v[112:115], v[188:191], v[196:199], v[112:115]
	v_mfma_f32_16x16x32_bf16 v[100:103], v[180:183], v[208:211], v[100:103]
	v_mfma_f32_16x16x32_bf16 v[96:99], v[188:191], v[208:211], v[96:99]
	v_mfma_f32_16x16x32_bf16 v[84:87], v[180:183], v[216:219], v[84:87]
	v_mfma_f32_16x16x32_bf16 v[80:83], v[188:191], v[216:219], v[80:83]
	v_mfma_f32_16x16x32_bf16 v[68:71], v[180:183], v[224:227], v[68:71]
	v_mfma_f32_16x16x32_bf16 v[64:67], v[188:191], v[224:227], v[64:67]
	v_mfma_f32_16x16x32_bf16 v[116:119], v[184:187], v[200:203], v[116:119]
	v_mfma_f32_16x16x32_bf16 v[112:115], v[192:195], v[200:203], v[112:115]
	v_mfma_f32_16x16x32_bf16 v[100:103], v[184:187], v[212:215], v[100:103]
	v_mfma_f32_16x16x32_bf16 v[96:99], v[192:195], v[212:215], v[96:99]
	v_mfma_f32_16x16x32_bf16 v[84:87], v[184:187], v[220:223], v[84:87]
	v_mfma_f32_16x16x32_bf16 v[80:83], v[192:195], v[220:223], v[80:83]
	v_mfma_f32_16x16x32_bf16 v[68:71], v[184:187], v[228:231], v[68:71]
	v_mfma_f32_16x16x32_bf16 v[64:67], v[192:195], v[228:231], v[64:67]
	s_setprio 0
	s_barrier
; #define PG8_STAGE(bufoff, gbase, voff) do { _Pragma("unroll") for (int _i = 0; _i < 2; ++_i) \
;         __builtin_amdgcn_global_load_lds((const unsigned*)((const char*)(gbase) + (voff)[_i]), (PG8_LAS unsigned*)(lds + (bufoff) + ldsw + _i * 8192), 16, 0, 0); } while (0)
; #define PG8_LDA(dst, b, h) do { _Pragma("unroll") for (int m = 0; m < 4; ++m) _Pragma("unroll") for (int k = 0; k < 2; ++k) dst[m][k] = *(const PG8_LAS bf16x8*)(lds + PG8_SA(b, h) + aoff + m * 2048 + k * 1024); } while (0)
; #define PG8_LDB(dst, b, h) do { _Pragma("unroll") for (int n = 0; n < 2; ++n) _Pragma("unroll") for (int k = 0; k < 2; ++k) dst[n][k] = *(const PG8_LAS bf16x8*)(lds + PG8_SB(b, h) + boff + n * 2048 + k * 1024); } while (0)
; template <class Epi, class Sched, bool ALIGN_EPI = false, bool SP2 = false>
; __device__ __forceinline__ void gemm_phase(PG8_LAS unsigned char* lds, const Gemm g, const Sched& S, const Epi& E) {
;     ...
;         for (int t = 0; t < nt; t += 2) {
;             const bool last = (t == nt - 2);
;             const char* a1 = cA + (size_t)(t + 1) * kstep;
;             const char* a2 = last ? nA : cA + (size_t)(t + 2) * kstep; const char* b2 = last ? nB : cB + (size_t)(t + 2) * kstep;
;             const char* a3 = a2 + kstep; const char* b3 = b2 + kstep;
;             if (last && has_next) S.a_ready(nxt);
;             if constexpr (SP2) {
;             PG8_LDB(B0, 0, 0); PG8_LDB(B1, 0, 1); PG8_SCHED; PG8_LDA(At, 0, 0); PG8_STAGE(PG8_SA(1, 1), a1 + hstep, voffA);
;             PG8_WAIT_V(8); PG8_WAIT_L(0); PG8_BAR; PG8_MMA(0, 0, At, B0); PG8_MMA(0, 1, At, B1); PG8_BAR; PG8_SCHED;
;             PG8_LDA(At, 0, 1); PG8_STAGE(PG8_SB(0, 0), b2, voffB); PG8_STAGE(PG8_SB(0, 1), b2 + hstep, voffB); PG8_STAGE(PG8_SA(0, 0), a2, voffA);
;             PG8_WAIT_V(8); PG8_WAIT_L(0); PG8_BAR; PG8_MMA(1, 0, At, B0); PG8_MMA(1, 1, At, B1); PG8_BAR; PG8_SCHED;
;             PG8_LDB(B0, 1, 0); PG8_LDB(B1, 1, 1); PG8_SCHED; PG8_LDA(At, 1, 0); PG8_STAGE(PG8_SA(0, 1), a2 + hstep, voffA);
;             PG8_WAIT_V(8); PG8_WAIT_L(0); PG8_BAR; PG8_MMA(0, 0, At, B0); PG8_MMA(0, 1, At, B1); PG8_BAR; PG8_SCHED;
;             PG8_LDA(At, 1, 1); PG8_STAGE(PG8_SB(1, 0), b3, voffB); PG8_STAGE(PG8_SB(1, 1), b3 + hstep, voffB); PG8_STAGE(PG8_SA(1, 0), a3, voffA);
;             PG8_WAIT_V(8); PG8_WAIT_L(0); PG8_BAR; PG8_MMA(1, 0, At, B0); PG8_MMA(1, 1, At, B1); PG8_BAR; PG8_SCHED;
	s_add_i32 s42, s77, s57
	v_lshl_add_u64 v[142:143], v[142:143], 0, s[8:9]
	s_mov_b32 m0, s42
	ds_read_b128 v[196:199], v162 offset:49152
	ds_read_b128 v[200:203], v162 offset:50176
	ds_read_b128 v[208:211], v162 offset:51200
	ds_read_b128 v[212:215], v162 offset:52224
	ds_read_b128 v[216:219], v162 offset:53248
	ds_read_b128 v[220:223], v162 offset:54272
	ds_read_b128 v[224:227], v162 offset:55296
	ds_read_b128 v[228:231], v162 offset:56320
	global_load_lds_dwordx4 v[142:143], off
	s_add_i32 m0, s42, 0x2000
	s_add_u32 s40, s40, 0x40080
	v_lshl_add_u64 v[142:143], v[204:205], 0, s[8:9]
	s_addc_u32 s41, s41, 0
	s_add_i32 s42, s78, s57
	global_load_lds_dwordx4 v[142:143], off
	v_lshl_add_u64 v[142:143], s[40:41], 0, v[130:131]
	s_mov_b32 m0, s42
	s_nop 0
	global_load_lds_dwordx4 v[142:143], off
	v_lshl_add_u64 v[142:143], s[40:41], 0, v[134:135]
	s_add_i32 m0, s42, 0x2000
	s_nop 0
	global_load_lds_dwordx4 v[142:143], off
	v_lshl_add_u64 v[142:143], v[232:233], 0, s[8:9]
	s_mov_b32 m0, s65
	s_nop 0
	global_load_lds_dwordx4 v[142:143], off
	v_lshl_add_u64 v[142:143], v[234:235], 0, s[8:9]
	s_mov_b32 m0, s66
	s_nop 0
	global_load_lds_dwordx4 v[142:143], off
	s_waitcnt vmcnt(8)
	s_waitcnt lgkmcnt(0)
	s_barrier
	s_setprio 1
	s_waitcnt lgkmcnt(0)
	v_mfma_f32_16x16x32_bf16 v[60:63], v[164:167], v[196:199], v[60:63]
	v_mfma_f32_16x16x32_bf16 v[56:59], v[172:175], v[196:199], v[56:59]
	v_mfma_f32_16x16x32_bf16 v[44:47], v[164:167], v[208:211], v[44:47]
	v_mfma_f32_16x16x32_bf16 v[40:43], v[172:175], v[208:211], v[40:43]
	v_mfma_f32_16x16x32_bf16 v[28:31], v[164:167], v[216:219], v[28:31]
	v_mfma_f32_16x16x32_bf16 v[24:27], v[172:175], v[216:219], v[24:27]
	v_mfma_f32_16x16x32_bf16 v[12:15], v[164:167], v[224:227], v[12:15]
	v_mfma_f32_16x16x32_bf16 v[8:11], v[172:175], v[224:227], v[8:11]
	v_mfma_f32_16x16x32_bf16 v[60:63], v[168:171], v[200:203], v[60:63]
	v_mfma_f32_16x16x32_bf16 v[56:59], v[176:179], v[200:203], v[56:59]
	v_mfma_f32_16x16x32_bf16 v[44:47], v[168:171], v[212:215], v[44:47]
	v_mfma_f32_16x16x32_bf16 v[40:43], v[176:179], v[212:215], v[40:43]
	v_mfma_f32_16x16x32_bf16 v[28:31], v[168:171], v[220:223], v[28:31]
	v_mfma_f32_16x16x32_bf16 v[24:27], v[176:179], v[220:223], v[24:27]
	v_mfma_f32_16x16x32_bf16 v[12:15], v[168:171], v[228:231], v[12:15]
	v_mfma_f32_16x16x32_bf16 v[8:11], v[176:179], v[228:231], v[8:11]
	s_setprio 0
	s_setprio 1
	v_mfma_f32_16x16x32_bf16 v[52:55], v[180:183], v[196:199], v[52:55]
	v_mfma_f32_16x16x32_bf16 v[48:51], v[188:191], v[196:199], v[48:51]
	v_mfma_f32_16x16x32_bf16 v[36:39], v[180:183], v[208:211], v[36:39]
	v_mfma_f32_16x16x32_bf16 v[32:35], v[188:191], v[208:211], v[32:35]
	v_mfma_f32_16x16x32_bf16 v[20:23], v[180:183], v[216:219], v[20:23]
	v_mfma_f32_16x16x32_bf16 v[16:19], v[188:191], v[216:219], v[16:19]
	v_mfma_f32_16x16x32_bf16 v[4:7], v[180:183], v[224:227], v[4:7]
	v_mfma_f32_16x16x32_bf16 v[0:3], v[188:191], v[224:227], v[0:3]
	v_mfma_f32_16x16x32_bf16 v[52:55], v[184:187], v[200:203], v[52:55]
	v_mfma_f32_16x16x32_bf16 v[48:51], v[192:195], v[200:203], v[48:51]
	v_mfma_f32_16x16x32_bf16 v[36:39], v[184:187], v[212:215], v[36:39]
	v_mfma_f32_16x16x32_bf16 v[32:35], v[192:195], v[212:215], v[32:35]
	v_mfma_f32_16x16x32_bf16 v[20:23], v[184:187], v[220:223], v[20:23]
	v_mfma_f32_16x16x32_bf16 v[16:19], v[192:195], v[220:223], v[16:19]
	v_mfma_f32_16x16x32_bf16 v[4:7], v[184:187], v[228:231], v[4:7]
	v_mfma_f32_16x16x32_bf16 v[0:3], v[192:195], v[228:231], v[0:3]
	s_setprio 0
	s_barrier
	s_add_i32 s76, s76, 2
	s_add_u32 s38, s38, 0x100
	s_addc_u32 s39, s39, 0
	s_add_u32 s74, s74, 0x100
	s_addc_u32 s75, s75, 0
	s_cmp_gt_u32 s76, 13
	s_cbranch_scc0 .LBB0_877
	s_branch .Lpeel_exit_5

;     __device__ __forceinline__ bool next(int i, Unit& u) const { if (i != 0) return false; const int c0 = (G >= 8) ? G - 5 : G - 2; int k = -1; if (c == c0) k = 0; else if (c == G - 1) k = 1; if (k < 0 || k >= n) return false; u.pm = k; u.pn = 0; return true; }
; #define PG8_STAGE(bufoff, gbase, voff) do { _Pragma("unroll") for (int _i = 0; _i < 2; ++_i) \
;         __builtin_amdgcn_global_load_lds((const unsigned*)((const char*)(gbase) + (voff)[_i]), (PG8_LAS unsigned*)(lds + (bufoff) + ldsw + _i * 8192), 16, 0, 0); } while (0)
; #define PG8_WAIT_V(n) asm volatile("s_waitcnt vmcnt(" #n ")" ::: "memory")
; template <class Epi, class Sched, bool ALIGN_EPI = false, bool SP2 = false>
; __device__ __forceinline__ void gemm_phase(PG8_LAS unsigned char* lds, const Gemm g, const Sched& S, const Epi& E) {
;     ...
;         PG8_STAGE(PG8_SB(1, 0), cB + kstep, voffB); PG8_STAGE(PG8_SA(1, 0), cA + kstep, voffA); PG8_STAGE(PG8_SB(1, 1), cB + hstep + kstep, voffB);
;         PG8_WAIT_V(6); PG8_BAR;
;     } else {
;         PG8_STAGE(PG8_SB(0, 0), cB, voffB); PG8_STAGE(PG8_SA(0, 0), cA, voffA); PG8_STAGE(PG8_SB(0, 1), cB + hstep, voffB); PG8_STAGE(PG8_SA(0, 1), cA + hstep, voffA);
;         if (wr == 1) PG8_BAR;
;         PG8_WAIT_V(4); PG8_BAR;
;         PG8_STAGE(PG8_SB(1, 0), cB + kstep, voffB); PG8_STAGE(PG8_SA(1, 0), cA + kstep, voffA); PG8_STAGE(PG8_SB(1, 1), cB + hstep + kstep, voffB);
;         PG8_WAIT_V(6); PG8_BAR;
;     }
;     for (;;) {
;         const bool has_next = S.next(ui + 1, nxt);
;         const char* nA = has_next ? (const char*)g.A + (size_t)nxt.pm * tstep : cA; const char* nB = has_next ? (const char*)g.Bt + (size_t)nxt.pn * tstep : cB;
;         for (int t = 0; t < nt; t += 2) {
;             const bool last = (t == nt - 2);
;             const char* a1 = cA + (size_t)(t + 1) * kstep;
;             const char* a2 = last ? nA : cA + (size_t)(t + 2) * kstep; const char* b2 = last ? nB : cB + (size_t)(t + 2) * kstep;
;             const char* a3 = a2 + kstep; const char* b3 = b2 + kstep;
;             if (last && has_next) S.a_ready(nxt);
;             if constexpr (SP2) {
;             PG8_LDB(B0, 0, 0); PG8_LDB(B1, 0, 1); PG8_SCHED; PG8_LDA(At, 0, 0); PG8_STAGE(PG8_SA(1, 1), a1 + hstep, voffA);
;             PG8_WAIT_V(8); PG8_WAIT_L(0); PG8_BAR; PG8_MMA(0, 0, At, B0); PG8_MMA(0, 1, At, B1); PG8_BAR; PG8_SCHED;
.LBB0_965:
	v_lshlrev_b32_e32 v11, 2, v153
	v_lshl_or_b32 v129, s19, 6, v153
	v_lshl_or_b32 v10, v153, 6, v154
	s_lshl_b32 s19, s19, 13
	v_and_b32_e32 v11, 32, v11
	s_lshl_b32 s18, s18, 5
	v_bitop3_b32 v10, v10, s19, v11 bitop3:0xde
	s_and_b32 s39, s18, 0x60
	s_mov_b64 s[18:19], 0x80
	s_add_i32 m0, s29, 0x18000
	v_lshl_add_u64 v[6:7], v[6:7], 0, s[18:19]
	s_waitcnt vmcnt(2)
	s_barrier
	global_load_lds_dwordx4 v[6:7], off
	v_lshl_add_u64 v[4:5], v[4:5], 0, s[18:19]
	s_add_i32 m0, s29, 0x1a000
	s_add_i32 s40, s29, 0x8000
	s_add_i32 s41, s29, 0xa000
	global_load_lds_dwordx4 v[4:5], off
	v_lshl_add_u64 v[2:3], v[2:3], 0, s[18:19]
	s_mov_b32 m0, s40
	s_add_u32 s24, s6, 0xb0080
	global_load_lds_dwordx4 v[2:3], off
	v_lshl_add_u64 v[0:1], v[0:1], 0, s[18:19]
	s_mov_b32 m0, s41
	s_addc_u32 s25, s7, 0
	global_load_lds_dwordx4 v[0:1], off
	s_add_i32 m0, s29, 0x1c000
	v_lshl_add_u64 v[0:1], s[24:25], 0, v[138:139]
	global_load_lds_dwordx4 v[0:1], off
	v_lshl_add_u64 v[0:1], s[24:25], 0, v[142:143]
	s_add_i32 m0, s29, 0x1e000
	s_add_u32 s24, s50, s21
	global_load_lds_dwordx4 v[0:1], off
	v_add_u16_e32 v0, v148, v149
	v_lshrrev_b16_e32 v2, 1, v0
	v_lshl_or_b32 v11, s39, 7, v155
	s_waitcnt vmcnt(6)
	v_add_lshl_u32 v0, v9, v2, 1
	v_mov_b32_e32 v1, v139
	s_addc_u32 s25, s51, s20
	s_add_i32 s58, 0, 0x10000
	s_add_i32 s60, 0, 0x14000
	s_add_i32 s64, 0, 0x18000
	s_add_i32 s66, 0, 0x1c000
	v_lshl_add_u64 v[144:145], s[24:25], 0, v[0:1]
	v_add_lshl_u32 v0, v8, v2, 1
	v_add_u32_e32 v131, s58, v11
	v_add_u32_e32 v133, s60, v11
	s_add_i32 s58, s58, s22
	s_add_i32 s60, s60, s22
	v_add_u32_e32 v156, s64, v11
	v_add_u32_e32 v157, s66, v11
	s_add_i32 s64, s64, s22
	s_add_i32 s66, s66, s22
	v_lshl_add_u64 v[146:147], s[24:25], 0, v[0:1]
	s_mov_b32 s42, -2
	s_mov_b64 s[20:21], 0x78b0080
	v_add_u32_e32 v135, 0, v10
	s_add_i32 s43, s29, 0xc000
	s_add_i32 s57, s29, 0xe000
	s_add_i32 s59, s58, 0x2000
	s_add_i32 s61, s60, 0x2000
	s_add_i32 s65, s64, 0x2000
	s_add_i32 s67, s66, 0x2000
	s_barrier
	ds_read_b128 v[158:161], v131
	ds_read_b128 v[162:165], v131 offset:1024
	ds_read_b128 v[166:169], v131 offset:2048
	ds_read_b128 v[170:173], v131 offset:3072
	ds_read_b128 v[174:177], v133
	ds_read_b128 v[178:181], v133 offset:1024
	ds_read_b128 v[182:185], v133 offset:2048
	ds_read_b128 v[186:189], v133 offset:3072
	s_add_u32 s22, s20, 0xf8750080
	s_addc_u32 s23, s21, -1
	s_cmp_lg_u32 s42, 40
	s_cselect_b32 s22, s22, 0
	s_cselect_b32 s23, s23, 0
	s_add_u32 s24, s8, s22
	s_addc_u32 s25, s9, s23
	s_add_u32 s22, s6, s22
	s_addc_u32 s23, s7, s23
	s_mov_b32 m0, s43
	v_lshl_add_u64 v[224:225], v[144:145], 0, s[20:21]
	ds_read_b128 v[190:193], v135
	ds_read_b128 v[194:197], v135 offset:1024
	ds_read_b128 v[198:201], v135 offset:2048
	ds_read_b128 v[202:205], v135 offset:3072
	ds_read_b128 v[208:211], v135 offset:4096
	ds_read_b128 v[212:215], v135 offset:5120
	ds_read_b128 v[216:219], v135 offset:6144
	ds_read_b128 v[220:223], v135 offset:7168
	global_load_lds_dwordx4 v[224:225], off
	v_lshl_add_u64 v[224:225], v[146:147], 0, s[20:21]
	s_mov_b32 m0, s57
	s_nop 0
	global_load_lds_dwordx4 v[224:225], off
	s_waitcnt vmcnt(8)
	s_waitcnt lgkmcnt(0)
	s_barrier
	s_setprio 1
	s_waitcnt lgkmcnt(0)
	v_mfma_f32_16x16x32_bf16 v[124:127], v[158:161], v[190:193], 0
	v_mfma_f32_16x16x32_bf16 v[120:123], v[166:169], v[190:193], 0
	v_mfma_f32_16x16x32_bf16 v[116:119], v[158:161], v[198:201], 0
	v_mfma_f32_16x16x32_bf16 v[112:115], v[166:169], v[198:201], 0
	v_mfma_f32_16x16x32_bf16 v[100:103], v[158:161], v[208:211], 0
	v_mfma_f32_16x16x32_bf16 v[96:99], v[166:169], v[208:211], 0
	v_mfma_f32_16x16x32_bf16 v[84:87], v[158:161], v[216:219], 0
	v_mfma_f32_16x16x32_bf16 v[80:83], v[166:169], v[216:219], 0
	v_mfma_f32_16x16x32_bf16 v[124:127], v[162:165], v[194:197], v[124:127]
	v_mfma_f32_16x16x32_bf16 v[120:123], v[170:173], v[194:197], v[120:123]
	v_mfma_f32_16x16x32_bf16 v[116:119], v[162:165], v[202:205], v[116:119]
	v_mfma_f32_16x16x32_bf16 v[112:115], v[170:173], v[202:205], v[112:115]
	v_mfma_f32_16x16x32_bf16 v[100:103], v[162:165], v[212:215], v[100:103]
	v_mfma_f32_16x16x32_bf16 v[96:99], v[170:173], v[212:215], v[96:99]
	v_mfma_f32_16x16x32_bf16 v[84:87], v[162:165], v[220:223], v[84:87]
	v_mfma_f32_16x16x32_bf16 v[80:83], v[170:173], v[220:223], v[80:83]
	s_setprio 0
	s_setprio 1
	v_mfma_f32_16x16x32_bf16 v[108:111], v[174:177], v[190:193], 0
	v_mfma_f32_16x16x32_bf16 v[104:107], v[182:185], v[190:193], 0
	v_mfma_f32_16x16x32_bf16 v[92:95], v[174:177], v[198:201], 0
	v_mfma_f32_16x16x32_bf16 v[88:91], v[182:185], v[198:201], 0
	v_mfma_f32_16x16x32_bf16 v[76:79], v[174:177], v[208:211], 0
	v_mfma_f32_16x16x32_bf16 v[72:75], v[182:185], v[208:211], 0
	v_mfma_f32_16x16x32_bf16 v[68:71], v[174:177], v[216:219], 0
	v_mfma_f32_16x16x32_bf16 v[64:67], v[182:185], v[216:219], 0
	v_mfma_f32_16x16x32_bf16 v[108:111], v[178:181], v[194:197], v[108:111]
	v_mfma_f32_16x16x32_bf16 v[104:107], v[186:189], v[194:197], v[104:107]
	v_mfma_f32_16x16x32_bf16 v[92:95], v[178:181], v[202:205], v[92:95]
	v_mfma_f32_16x16x32_bf16 v[88:91], v[186:189], v[202:205], v[88:91]
	v_mfma_f32_16x16x32_bf16 v[76:79], v[178:181], v[212:215], v[76:79]
	v_mfma_f32_16x16x32_bf16 v[72:75], v[186:189], v[212:215], v[72:75]
	v_mfma_f32_16x16x32_bf16 v[68:71], v[178:181], v[220:223], v[68:71]
	v_mfma_f32_16x16x32_bf16 v[64:67], v[186:189], v[220:223], v[64:67]
	s_setprio 0
	s_barrier
; #define PG8_STAGE(bufoff, gbase, voff) do { _Pragma("unroll") for (int _i = 0; _i < 2; ++_i) \
;         __builtin_amdgcn_global_load_lds((const unsigned*)((const char*)(gbase) + (voff)[_i]), (PG8_LAS unsigned*)(lds + (bufoff) + ldsw + _i * 8192), 16, 0, 0); } while (0)
; #define PG8_LDA(dst, b, h) do { _Pragma("unroll") for (int m = 0; m < 4; ++m) _Pragma("unroll") for (int k = 0; k < 2; ++k) dst[m][k] = *(const PG8_LAS bf16x8*)(lds + PG8_SA(b, h) + aoff + m * 2048 + k * 1024); } while (0)
; #define PG8_LDB(dst, b, h) do { _Pragma("unroll") for (int n = 0; n < 2; ++n) _Pragma("unroll") for (int k = 0; k < 2; ++k) dst[n][k] = *(const PG8_LAS bf16x8*)(lds + PG8_SB(b, h) + boff + n * 2048 + k * 1024); } while (0)
; #define PG8_MMA(ai, bj, At, Bt) do { __builtin_amdgcn_s_setprio(1); _Pragma("unroll") for (int m = 0; m < 4; ++m) _Pragma("unroll") for (int n = 0; n < 2; ++n) _Pragma("unroll") for (int k = 0; k < 2; ++k) \
;         acc[ai][bj][m][n] = __builtin_amdgcn_mfma_f32_16x16x32_bf16(Bt[n][k], At[m][k], acc[ai][bj][m][n], 0, 0, 0); __builtin_amdgcn_s_setprio(0); } while (0)
; #define PG8_WAIT_V(n) asm volatile("s_waitcnt vmcnt(" #n ")" ::: "memory")
; #define PG8_WAIT_L(n) asm volatile("s_waitcnt lgkmcnt(" #n ")" ::: "memory")
; #define PG8_BAR __builtin_amdgcn_s_barrier()
; #define PG8_SCHED __builtin_amdgcn_sched_barrier(0)
; template <class Epi, class Sched, bool ALIGN_EPI = false, bool SP2 = false>
; __device__ __forceinline__ void gemm_phase(PG8_LAS unsigned char* lds, const Gemm g, const Sched& S, const Epi& E) {
;     ...
;             PG8_LDA(At, 0, 1); PG8_STAGE(PG8_SB(0, 0), b2, voffB); PG8_STAGE(PG8_SB(0, 1), b2 + hstep, voffB); PG8_STAGE(PG8_SA(0, 0), a2, voffA);
;             PG8_WAIT_V(8); PG8_WAIT_L(0); PG8_BAR; PG8_MMA(1, 0, At, B0); PG8_MMA(1, 1, At, B1); PG8_BAR; PG8_SCHED;
;             PG8_LDB(B0, 1, 0); PG8_LDB(B1, 1, 1); PG8_SCHED; PG8_LDA(At, 1, 0); PG8_STAGE(PG8_SA(0, 1), a2 + hstep, voffA);
	s_mov_b32 m0, s58
	v_lshl_add_u64 v[224:225], s[22:23], 0, v[138:139]
	s_add_u32 s68, s22, 0xb0000
	ds_read_b128 v[190:193], v135 offset:16384
	ds_read_b128 v[194:197], v135 offset:17408
	ds_read_b128 v[198:201], v135 offset:18432
	ds_read_b128 v[202:205], v135 offset:19456
	ds_read_b128 v[208:211], v135 offset:20480
	ds_read_b128 v[212:215], v135 offset:21504
	ds_read_b128 v[216:219], v135 offset:22528
	ds_read_b128 v[220:223], v135 offset:23552
	global_load_lds_dwordx4 v[224:225], off
	v_lshl_add_u64 v[226:227], s[22:23], 0, v[142:143]
	s_mov_b32 m0, s59
	s_addc_u32 s69, s23, 0
	global_load_lds_dwordx4 v[226:227], off
	v_lshl_add_u64 v[228:229], s[68:69], 0, v[138:139]
	s_mov_b32 m0, s60
	v_lshl_add_u64 v[230:231], s[24:25], 0, v[140:141]
	global_load_lds_dwordx4 v[228:229], off
	v_lshl_add_u64 v[228:229], s[68:69], 0, v[142:143]
	s_mov_b32 m0, s61
	s_nop 0
	global_load_lds_dwordx4 v[228:229], off
	v_lshl_add_u64 v[228:229], s[24:25], 0, v[136:137]
	s_mov_b32 m0, s29
	s_nop 0
	global_load_lds_dwordx4 v[228:229], off
	s_mov_b32 m0, s30
	s_nop 0
	global_load_lds_dwordx4 v[230:231], off
	s_waitcnt vmcnt(8)
	s_waitcnt lgkmcnt(0)
	s_barrier
	s_setprio 1
	s_waitcnt lgkmcnt(0)
	v_mfma_f32_16x16x32_bf16 v[60:63], v[158:161], v[190:193], 0
	v_mfma_f32_16x16x32_bf16 v[56:59], v[166:169], v[190:193], 0
	v_mfma_f32_16x16x32_bf16 v[52:55], v[158:161], v[198:201], 0
	v_mfma_f32_16x16x32_bf16 v[48:51], v[166:169], v[198:201], 0
	v_mfma_f32_16x16x32_bf16 v[36:39], v[158:161], v[208:211], 0
	v_mfma_f32_16x16x32_bf16 v[32:35], v[166:169], v[208:211], 0
	v_mfma_f32_16x16x32_bf16 v[20:23], v[158:161], v[216:219], 0
	v_mfma_f32_16x16x32_bf16 v[16:19], v[166:169], v[216:219], 0
	v_mfma_f32_16x16x32_bf16 v[60:63], v[162:165], v[194:197], v[60:63]
	v_mfma_f32_16x16x32_bf16 v[56:59], v[170:173], v[194:197], v[56:59]
	v_mfma_f32_16x16x32_bf16 v[52:55], v[162:165], v[202:205], v[52:55]
	v_mfma_f32_16x16x32_bf16 v[48:51], v[170:173], v[202:205], v[48:51]
	v_mfma_f32_16x16x32_bf16 v[36:39], v[162:165], v[212:215], v[36:39]
	v_mfma_f32_16x16x32_bf16 v[32:35], v[170:173], v[212:215], v[32:35]
	v_mfma_f32_16x16x32_bf16 v[20:23], v[162:165], v[220:223], v[20:23]
	v_mfma_f32_16x16x32_bf16 v[16:19], v[170:173], v[220:223], v[16:19]
	s_setprio 0
	s_setprio 1
	v_mfma_f32_16x16x32_bf16 v[44:47], v[174:177], v[190:193], 0
	v_mfma_f32_16x16x32_bf16 v[40:43], v[182:185], v[190:193], 0
	v_mfma_f32_16x16x32_bf16 v[28:31], v[174:177], v[198:201], 0
	v_mfma_f32_16x16x32_bf16 v[24:27], v[182:185], v[198:201], 0
	v_mfma_f32_16x16x32_bf16 v[12:15], v[174:177], v[208:211], 0
	v_mfma_f32_16x16x32_bf16 v[8:11], v[182:185], v[208:211], 0
	v_mfma_f32_16x16x32_bf16 v[4:7], v[174:177], v[216:219], 0
	v_mfma_f32_16x16x32_bf16 v[0:3], v[182:185], v[216:219], 0
	v_mfma_f32_16x16x32_bf16 v[44:47], v[178:181], v[194:197], v[44:47]
	v_mfma_f32_16x16x32_bf16 v[40:43], v[186:189], v[194:197], v[40:43]
	v_mfma_f32_16x16x32_bf16 v[28:31], v[178:181], v[202:205], v[28:31]
	v_mfma_f32_16x16x32_bf16 v[24:27], v[186:189], v[202:205], v[24:27]
	v_mfma_f32_16x16x32_bf16 v[12:15], v[178:181], v[212:215], v[12:15]
	v_mfma_f32_16x16x32_bf16 v[8:11], v[186:189], v[212:215], v[8:11]
	v_mfma_f32_16x16x32_bf16 v[4:7], v[178:181], v[220:223], v[4:7]
	v_mfma_f32_16x16x32_bf16 v[0:3], v[186:189], v[220:223], v[0:3]
	s_setprio 0
	s_barrier
	ds_read_b128 v[158:161], v156
	ds_read_b128 v[162:165], v156 offset:1024
	ds_read_b128 v[166:169], v156 offset:2048
	ds_read_b128 v[170:173], v156 offset:3072
	ds_read_b128 v[174:177], v157
	ds_read_b128 v[178:181], v157 offset:1024
	ds_read_b128 v[182:185], v157 offset:2048
	ds_read_b128 v[186:189], v157 offset:3072
	s_add_u32 s24, s24, 0xb0000
	s_addc_u32 s25, s25, 0
	s_mov_b32 m0, s31
	v_lshl_add_u64 v[232:233], s[24:25], 0, v[136:137]
	ds_read_b128 v[190:193], v135 offset:32768
	ds_read_b128 v[194:197], v135 offset:33792
	ds_read_b128 v[198:201], v135 offset:34816
	ds_read_b128 v[202:205], v135 offset:35840
	ds_read_b128 v[208:211], v135 offset:36864
	ds_read_b128 v[212:215], v135 offset:37888
	ds_read_b128 v[216:219], v135 offset:38912
	ds_read_b128 v[220:223], v135 offset:39936
	global_load_lds_dwordx4 v[232:233], off
	v_lshl_add_u64 v[232:233], s[24:25], 0, v[140:141]
	s_mov_b32 m0, s38
	s_nop 0
	global_load_lds_dwordx4 v[232:233], off
	s_waitcnt vmcnt(8)
	s_waitcnt lgkmcnt(0)
	s_barrier
; #define PG8_STAGE(bufoff, gbase, voff) do { _Pragma("unroll") for (int _i = 0; _i < 2; ++_i) \
;         __builtin_amdgcn_global_load_lds((const unsigned*)((const char*)(gbase) + (voff)[_i]), (PG8_LAS unsigned*)(lds + (bufoff) + ldsw + _i * 8192), 16, 0, 0); } while (0)
; #define PG8_LDA(dst, b, h) do { _Pragma("unroll") for (int m = 0; m < 4; ++m) _Pragma("unroll") for (int k = 0; k < 2; ++k) dst[m][k] = *(const PG8_LAS bf16x8*)(lds + PG8_SA(b, h) + aoff + m * 2048 + k * 1024); } while (0)
; #define PG8_LDB(dst, b, h) do { _Pragma("unroll") for (int n = 0; n < 2; ++n) _Pragma("unroll") for (int k = 0; k < 2; ++k) dst[n][k] = *(const PG8_LAS bf16x8*)(lds + PG8_SB(b, h) + boff + n * 2048 + k * 1024); } while (0)
; template <class Epi, class Sched, bool ALIGN_EPI = false, bool SP2 = false>
; __device__ __forceinline__ void gemm_phase(PG8_LAS unsigned char* lds, const Gemm g, const Sched& S, const Epi& E) {
;     ...
;         for (int t = 0; t < nt; t += 2) {
;             const bool last = (t == nt - 2);
;             const char* a1 = cA + (size_t)(t + 1) * kstep;
;             const char* a2 = last ? nA : cA + (size_t)(t + 2) * kstep; const char* b2 = last ? nB : cB + (size_t)(t + 2) * kstep;
;             const char* a3 = a2 + kstep; const char* b3 = b2 + kstep;
;             if (last && has_next) S.a_ready(nxt);
;             if constexpr (SP2) {
;             PG8_LDB(B0, 0, 0); PG8_LDB(B1, 0, 1); PG8_SCHED; PG8_LDA(At, 0, 0); PG8_STAGE(PG8_SA(1, 1), a1 + hstep, voffA);
;             PG8_WAIT_V(8); PG8_WAIT_L(0); PG8_BAR; PG8_MMA(0, 0, At, B0); PG8_MMA(0, 1, At, B1); PG8_BAR; PG8_SCHED;
;             PG8_LDA(At, 0, 1); PG8_STAGE(PG8_SB(0, 0), b2, voffB); PG8_STAGE(PG8_SB(0, 1), b2 + hstep, voffB); PG8_STAGE(PG8_SA(0, 0), a2, voffA);
;             PG8_WAIT_V(8); PG8_WAIT_L(0); PG8_BAR; PG8_MMA(1, 0, At, B0); PG8_MMA(1, 1, At, B1); PG8_BAR; PG8_SCHED;
;             PG8_LDB(B0, 1, 0); PG8_LDB(B1, 1, 1); PG8_SCHED; PG8_LDA(At, 1, 0); PG8_STAGE(PG8_SA(0, 1), a2 + hstep, voffA);
;             PG8_WAIT_V(8); PG8_WAIT_L(0); PG8_BAR; PG8_MMA(0, 0, At, B0); PG8_MMA(0, 1, At, B1); PG8_BAR; PG8_SCHED;
;             PG8_LDA(At, 1, 1); PG8_STAGE(PG8_SB(1, 0), b3, voffB); PG8_STAGE(PG8_SB(1, 1), b3 + hstep, voffB); PG8_STAGE(PG8_SA(1, 0), a3, voffA);
;             PG8_WAIT_V(8); PG8_WAIT_L(0); PG8_BAR; PG8_MMA(1, 0, At, B0); PG8_MMA(1, 1, At, B1); PG8_BAR; PG8_SCHED;
	s_setprio 1
	s_waitcnt lgkmcnt(0)
	v_mfma_f32_16x16x32_bf16 v[124:127], v[158:161], v[190:193], v[124:127]
	v_mfma_f32_16x16x32_bf16 v[120:123], v[166:169], v[190:193], v[120:123]
	v_mfma_f32_16x16x32_bf16 v[116:119], v[158:161], v[198:201], v[116:119]
	v_mfma_f32_16x16x32_bf16 v[112:115], v[166:169], v[198:201], v[112:115]
	v_mfma_f32_16x16x32_bf16 v[100:103], v[158:161], v[208:211], v[100:103]
	v_mfma_f32_16x16x32_bf16 v[96:99], v[166:169], v[208:211], v[96:99]
	v_mfma_f32_16x16x32_bf16 v[84:87], v[158:161], v[216:219], v[84:87]
	v_mfma_f32_16x16x32_bf16 v[80:83], v[166:169], v[216:219], v[80:83]
	v_mfma_f32_16x16x32_bf16 v[124:127], v[162:165], v[194:197], v[124:127]
	v_mfma_f32_16x16x32_bf16 v[120:123], v[170:173], v[194:197], v[120:123]
	v_mfma_f32_16x16x32_bf16 v[116:119], v[162:165], v[202:205], v[116:119]
	v_mfma_f32_16x16x32_bf16 v[112:115], v[170:173], v[202:205], v[112:115]
	v_mfma_f32_16x16x32_bf16 v[100:103], v[162:165], v[212:215], v[100:103]
	v_mfma_f32_16x16x32_bf16 v[96:99], v[170:173], v[212:215], v[96:99]
	v_mfma_f32_16x16x32_bf16 v[84:87], v[162:165], v[220:223], v[84:87]
	v_mfma_f32_16x16x32_bf16 v[80:83], v[170:173], v[220:223], v[80:83]
	s_setprio 0
	s_setprio 1
	v_mfma_f32_16x16x32_bf16 v[108:111], v[174:177], v[190:193], v[108:111]
	v_mfma_f32_16x16x32_bf16 v[104:107], v[182:185], v[190:193], v[104:107]
	v_mfma_f32_16x16x32_bf16 v[92:95], v[174:177], v[198:201], v[92:95]
	v_mfma_f32_16x16x32_bf16 v[88:91], v[182:185], v[198:201], v[88:91]
	v_mfma_f32_16x16x32_bf16 v[76:79], v[174:177], v[208:211], v[76:79]
	v_mfma_f32_16x16x32_bf16 v[72:75], v[182:185], v[208:211], v[72:75]
	v_mfma_f32_16x16x32_bf16 v[68:71], v[174:177], v[216:219], v[68:71]
	v_mfma_f32_16x16x32_bf16 v[64:67], v[182:185], v[216:219], v[64:67]
	v_mfma_f32_16x16x32_bf16 v[108:111], v[178:181], v[194:197], v[108:111]
	v_mfma_f32_16x16x32_bf16 v[104:107], v[186:189], v[194:197], v[104:107]
	v_mfma_f32_16x16x32_bf16 v[92:95], v[178:181], v[202:205], v[92:95]
	v_mfma_f32_16x16x32_bf16 v[88:91], v[186:189], v[202:205], v[88:91]
	v_mfma_f32_16x16x32_bf16 v[76:79], v[178:181], v[212:215], v[76:79]
	v_mfma_f32_16x16x32_bf16 v[72:75], v[186:189], v[212:215], v[72:75]
	v_mfma_f32_16x16x32_bf16 v[68:71], v[178:181], v[220:223], v[68:71]
	v_mfma_f32_16x16x32_bf16 v[64:67], v[186:189], v[220:223], v[64:67]
	s_setprio 0
	s_barrier
	s_mov_b32 m0, s64
	v_lshl_add_u64 v[224:225], v[224:225], 0, s[18:19]
	s_add_u32 s22, s22, 0xb0080
	ds_read_b128 v[190:193], v135 offset:49152
	ds_read_b128 v[194:197], v135 offset:50176
	ds_read_b128 v[198:201], v135 offset:51200
	ds_read_b128 v[202:205], v135 offset:52224
	ds_read_b128 v[208:211], v135 offset:53248
	ds_read_b128 v[212:215], v135 offset:54272
	ds_read_b128 v[216:219], v135 offset:55296
	ds_read_b128 v[220:223], v135 offset:56320
	global_load_lds_dwordx4 v[224:225], off
	v_lshl_add_u64 v[224:225], v[226:227], 0, s[18:19]
	s_mov_b32 m0, s65
	s_addc_u32 s23, s23, 0
	global_load_lds_dwordx4 v[224:225], off
	v_lshl_add_u64 v[224:225], s[22:23], 0, v[138:139]
	s_mov_b32 m0, s66
	s_nop 0
	global_load_lds_dwordx4 v[224:225], off
	v_lshl_add_u64 v[224:225], s[22:23], 0, v[142:143]
	s_mov_b32 m0, s67
	s_nop 0
	global_load_lds_dwordx4 v[224:225], off
	v_lshl_add_u64 v[224:225], v[228:229], 0, s[18:19]
	s_mov_b32 m0, s40
	s_nop 0
	global_load_lds_dwordx4 v[224:225], off
	v_lshl_add_u64 v[224:225], v[230:231], 0, s[18:19]
	s_mov_b32 m0, s41
	s_nop 0
	global_load_lds_dwordx4 v[224:225], off
	s_waitcnt vmcnt(8)
	s_waitcnt lgkmcnt(0)
	s_barrier
	s_setprio 1
	s_waitcnt lgkmcnt(0)
	v_mfma_f32_16x16x32_bf16 v[60:63], v[158:161], v[190:193], v[60:63]
	v_mfma_f32_16x16x32_bf16 v[56:59], v[166:169], v[190:193], v[56:59]
	v_mfma_f32_16x16x32_bf16 v[52:55], v[158:161], v[198:201], v[52:55]
	v_mfma_f32_16x16x32_bf16 v[48:51], v[166:169], v[198:201], v[48:51]
	v_mfma_f32_16x16x32_bf16 v[36:39], v[158:161], v[208:211], v[36:39]
	v_mfma_f32_16x16x32_bf16 v[32:35], v[166:169], v[208:211], v[32:35]
	v_mfma_f32_16x16x32_bf16 v[20:23], v[158:161], v[216:219], v[20:23]
	v_mfma_f32_16x16x32_bf16 v[16:19], v[166:169], v[216:219], v[16:19]
	v_mfma_f32_16x16x32_bf16 v[60:63], v[162:165], v[194:197], v[60:63]
	v_mfma_f32_16x16x32_bf16 v[56:59], v[170:173], v[194:197], v[56:59]
	v_mfma_f32_16x16x32_bf16 v[52:55], v[162:165], v[202:205], v[52:55]
	v_mfma_f32_16x16x32_bf16 v[48:51], v[170:173], v[202:205], v[48:51]
	v_mfma_f32_16x16x32_bf16 v[36:39], v[162:165], v[212:215], v[36:39]
	v_mfma_f32_16x16x32_bf16 v[32:35], v[170:173], v[212:215], v[32:35]
	v_mfma_f32_16x16x32_bf16 v[20:23], v[162:165], v[220:223], v[20:23]
	v_mfma_f32_16x16x32_bf16 v[16:19], v[170:173], v[220:223], v[16:19]
	s_setprio 0
	s_setprio 1
	v_mfma_f32_16x16x32_bf16 v[44:47], v[174:177], v[190:193], v[44:47]
	v_mfma_f32_16x16x32_bf16 v[40:43], v[182:185], v[190:193], v[40:43]
	v_mfma_f32_16x16x32_bf16 v[28:31], v[174:177], v[198:201], v[28:31]
	v_mfma_f32_16x16x32_bf16 v[24:27], v[182:185], v[198:201], v[24:27]
	v_mfma_f32_16x16x32_bf16 v[12:15], v[174:177], v[208:211], v[12:15]
	v_mfma_f32_16x16x32_bf16 v[8:11], v[182:185], v[208:211], v[8:11]
	v_mfma_f32_16x16x32_bf16 v[4:7], v[174:177], v[216:219], v[4:7]
	v_mfma_f32_16x16x32_bf16 v[0:3], v[182:185], v[216:219], v[0:3]
	v_mfma_f32_16x16x32_bf16 v[44:47], v[178:181], v[194:197], v[44:47]
	v_mfma_f32_16x16x32_bf16 v[40:43], v[186:189], v[194:197], v[40:43]
	v_mfma_f32_16x16x32_bf16 v[28:31], v[178:181], v[202:205], v[28:31]
	v_mfma_f32_16x16x32_bf16 v[24:27], v[186:189], v[202:205], v[24:27]
	v_mfma_f32_16x16x32_bf16 v[12:15], v[178:181], v[212:215], v[12:15]
	v_mfma_f32_16x16x32_bf16 v[8:11], v[186:189], v[212:215], v[8:11]
	v_mfma_f32_16x16x32_bf16 v[4:7], v[178:181], v[220:223], v[4:7]
	v_mfma_f32_16x16x32_bf16 v[0:3], v[186:189], v[220:223], v[0:3]
	s_setprio 0
	s_barrier
	s_add_i32 s42, s42, 2
	s_add_u32 s20, s20, 0x100
	s_addc_u32 s21, s21, 0
	s_cmp_gt_u32 s42, 41
	s_cbranch_scc0 .LBB0_966
	s_branch .Lpeel_exit_6

; #define PG8_BAR __builtin_amdgcn_s_barrier()
; template <class Epi, class Sched, bool ALIGN_EPI = false, bool SP2 = false>
; __device__ __forceinline__ void gemm_phase(PG8_LAS unsigned char* lds, const Gemm g, const Sched& S, const Epi& E) {
;     ...
;         if constexpr (ALIGN_EPI) { if (wr == 0) PG8_BAR; }
.Lpeel_exit_6:
	s_cmpk_lt_u32 s26, 0x100
	s_cbranch_scc0 .LBB0_969
	s_barrier

;     __device__ __forceinline__ bool next(int i, Unit& u) const { if (i != 0) return false; const int c0 = (G >= 8) ? G - 5 : G - 2; int k = -1; if (c == c0) k = 0; else if (c == G - 1) k = 1; if (k < 0 || k >= n) return false; u.pm = k; u.pn = 0; return true; }
; #define PG8_STAGE(bufoff, gbase, voff) do { _Pragma("unroll") for (int _i = 0; _i < 2; ++_i) \
;         __builtin_amdgcn_global_load_lds((const unsigned*)((const char*)(gbase) + (voff)[_i]), (PG8_LAS unsigned*)(lds + (bufoff) + ldsw + _i * 8192), 16, 0, 0); } while (0)
; #define PG8_LDA(dst, b, h) do { _Pragma("unroll") for (int m = 0; m < 4; ++m) _Pragma("unroll") for (int k = 0; k < 2; ++k) dst[m][k] = *(const PG8_LAS bf16x8*)(lds + PG8_SA(b, h) + aoff + m * 2048 + k * 1024); } while (0)
; #define PG8_LDB(dst, b, h) do { _Pragma("unroll") for (int n = 0; n < 2; ++n) _Pragma("unroll") for (int k = 0; k < 2; ++k) dst[n][k] = *(const PG8_LAS bf16x8*)(lds + PG8_SB(b, h) + boff + n * 2048 + k * 1024); } while (0)
; template <class Epi, class Sched, bool ALIGN_EPI = false, bool SP2 = false>
; __device__ __forceinline__ void gemm_phase(PG8_LAS unsigned char* lds, const Gemm g, const Sched& S, const Epi& E) {
;     ...
;         const bool has_next = S.next(ui + 1, nxt);
;         const char* nA = has_next ? (const char*)g.A + (size_t)nxt.pm * tstep : cA; const char* nB = has_next ? (const char*)g.Bt + (size_t)nxt.pn * tstep : cB;
;         for (int t = 0; t < nt; t += 2) {
;             const bool last = (t == nt - 2);
;             const char* a1 = cA + (size_t)(t + 1) * kstep;
;             const char* a2 = last ? nA : cA + (size_t)(t + 2) * kstep; const char* b2 = last ? nB : cB + (size_t)(t + 2) * kstep;
;             const char* a3 = a2 + kstep; const char* b3 = b2 + kstep;
;             if (last && has_next) S.a_ready(nxt);
;             if constexpr (SP2) {
;             PG8_LDB(B0, 0, 0); PG8_LDB(B1, 0, 1); PG8_SCHED; PG8_LDA(At, 0, 0); PG8_STAGE(PG8_SA(1, 1), a1 + hstep, voffA);
;             PG8_WAIT_V(8); PG8_WAIT_L(0); PG8_BAR; PG8_MMA(0, 0, At, B0); PG8_MMA(0, 1, At, B1); PG8_BAR; PG8_SCHED;
;             PG8_LDA(At, 0, 1); PG8_STAGE(PG8_SB(0, 0), b2, voffB); PG8_STAGE(PG8_SB(0, 1), b2 + hstep, voffB); PG8_STAGE(PG8_SA(0, 0), a2, voffA);
;             PG8_WAIT_V(8); PG8_WAIT_L(0); PG8_BAR; PG8_MMA(1, 0, At, B0); PG8_MMA(1, 1, At, B1); PG8_BAR; PG8_SCHED;
.LBB0_1051:
	s_ashr_i32 s21, s20, 31
	s_lshl_b64 s[26:27], s[20:21], 19
	s_add_u32 s26, s97, s26
	s_addc_u32 s27, s3, s27
	s_and_b64 s[28:29], s[24:25], exec
	s_cselect_b32 s21, s27, s39
	s_cselect_b32 s72, s26, s38
	s_ashr_i32 s23, s22, 31
	s_lshl_b64 s[28:29], s[22:23], 19
	s_add_u32 s28, s46, s28
	s_addc_u32 s29, s47, s29
	s_and_b64 s[42:43], s[24:25], exec
	s_cselect_b32 s23, s29, s41
	s_cselect_b32 s73, s28, s40
	s_add_u32 s38, s38, 0x40080
	s_addc_u32 s39, s39, 0
	s_add_u32 s74, s40, 0x100
	v_mov_b32_e32 v0, 0
	s_addc_u32 s75, s41, 0
	s_mov_b32 s76, -2
	ds_read_b128 v[150:153], v147
	ds_read_b128 v[154:157], v147 offset:1024
	ds_read_b128 v[158:161], v147 offset:2048
	ds_read_b128 v[162:165], v147 offset:3072
	ds_read_b128 v[166:169], v148
	ds_read_b128 v[170:173], v148 offset:1024
	ds_read_b128 v[174:177], v148 offset:2048
	ds_read_b128 v[178:181], v148 offset:3072
	s_add_u32 s40, s38, 0xfffc0080
	s_addc_u32 s41, s39, -1
	s_cmp_eq_u32 s76, 12
	s_cselect_b32 s43, s21, s41
	s_cselect_b32 s42, s72, s40
	s_cselect_b32 s41, s23, s75
	s_cselect_b32 s40, s73, s74
	v_lshl_add_u64 v[142:143], s[38:39], 0, v[136:137]
	s_add_i32 m0, s31, 0xc000
	ds_read_b128 v[182:185], v149
	ds_read_b128 v[186:189], v149 offset:1024
	ds_read_b128 v[190:193], v149 offset:2048
	ds_read_b128 v[194:197], v149 offset:3072
	ds_read_b128 v[198:201], v149 offset:4096
	ds_read_b128 v[202:205], v149 offset:5120
	ds_read_b128 v[208:211], v149 offset:6144
	ds_read_b128 v[212:215], v149 offset:7168
	global_load_lds_dwordx4 v[142:143], off
	v_lshl_add_u64 v[142:143], s[38:39], 0, v[138:139]
	s_add_i32 m0, s31, 0xe000
	s_nop 0
	global_load_lds_dwordx4 v[142:143], off
	s_waitcnt vmcnt(8)
	s_waitcnt lgkmcnt(0)
	s_barrier
	s_setprio 1
	s_waitcnt lgkmcnt(0)
	v_mfma_f32_16x16x32_bf16 v[124:127], v[150:153], v[182:185], 0
	v_mfma_f32_16x16x32_bf16 v[120:123], v[158:161], v[182:185], 0
	v_mfma_f32_16x16x32_bf16 v[108:111], v[150:153], v[190:193], 0
	v_mfma_f32_16x16x32_bf16 v[104:107], v[158:161], v[190:193], 0
	v_mfma_f32_16x16x32_bf16 v[92:95], v[150:153], v[198:201], 0
	v_mfma_f32_16x16x32_bf16 v[88:91], v[158:161], v[198:201], 0
	v_mfma_f32_16x16x32_bf16 v[76:79], v[150:153], v[208:211], 0
	v_mfma_f32_16x16x32_bf16 v[72:75], v[158:161], v[208:211], 0
	v_mfma_f32_16x16x32_bf16 v[124:127], v[154:157], v[186:189], v[124:127]
	v_mfma_f32_16x16x32_bf16 v[120:123], v[162:165], v[186:189], v[120:123]
	v_mfma_f32_16x16x32_bf16 v[108:111], v[154:157], v[194:197], v[108:111]
	v_mfma_f32_16x16x32_bf16 v[104:107], v[162:165], v[194:197], v[104:107]
	v_mfma_f32_16x16x32_bf16 v[92:95], v[154:157], v[202:205], v[92:95]
	v_mfma_f32_16x16x32_bf16 v[88:91], v[162:165], v[202:205], v[88:91]
	v_mfma_f32_16x16x32_bf16 v[76:79], v[154:157], v[212:215], v[76:79]
	v_mfma_f32_16x16x32_bf16 v[72:75], v[162:165], v[212:215], v[72:75]
	s_setprio 0
	s_setprio 1
	v_mfma_f32_16x16x32_bf16 v[116:119], v[166:169], v[182:185], 0
	v_mfma_f32_16x16x32_bf16 v[112:115], v[174:177], v[182:185], 0
	v_mfma_f32_16x16x32_bf16 v[100:103], v[166:169], v[190:193], 0
	v_mfma_f32_16x16x32_bf16 v[96:99], v[174:177], v[190:193], 0
	v_mfma_f32_16x16x32_bf16 v[84:87], v[166:169], v[198:201], 0
	v_mfma_f32_16x16x32_bf16 v[80:83], v[174:177], v[198:201], 0
	v_mfma_f32_16x16x32_bf16 v[68:71], v[166:169], v[208:211], 0
	v_mfma_f32_16x16x32_bf16 v[64:67], v[174:177], v[208:211], 0
	v_mfma_f32_16x16x32_bf16 v[116:119], v[170:173], v[186:189], v[116:119]
	v_mfma_f32_16x16x32_bf16 v[112:115], v[178:181], v[186:189], v[112:115]
	v_mfma_f32_16x16x32_bf16 v[100:103], v[170:173], v[194:197], v[100:103]
	v_mfma_f32_16x16x32_bf16 v[96:99], v[178:181], v[194:197], v[96:99]
	v_mfma_f32_16x16x32_bf16 v[84:87], v[170:173], v[202:205], v[84:87]
	v_mfma_f32_16x16x32_bf16 v[80:83], v[178:181], v[202:205], v[80:83]
	v_mfma_f32_16x16x32_bf16 v[68:71], v[170:173], v[212:215], v[68:71]
	v_mfma_f32_16x16x32_bf16 v[64:67], v[178:181], v[212:215], v[64:67]
	s_setprio 0
	s_barrier
	s_add_i32 s77, s67, s57
	v_lshl_add_u64 v[142:143], s[40:41], 0, v[130:131]
	s_mov_b32 m0, s77
	ds_read_b128 v[182:185], v149 offset:16384
	ds_read_b128 v[186:189], v149 offset:17408
	ds_read_b128 v[190:193], v149 offset:18432
	ds_read_b128 v[194:197], v149 offset:19456
	ds_read_b128 v[198:201], v149 offset:20480
	ds_read_b128 v[202:205], v149 offset:21504
	ds_read_b128 v[208:211], v149 offset:22528
	ds_read_b128 v[212:215], v149 offset:23552
	global_load_lds_dwordx4 v[142:143], off
	s_add_i32 m0, s77, 0x2000
	s_add_u32 s78, s40, 0x40000
	v_lshl_add_u64 v[216:217], s[40:41], 0, v[134:135]
	s_addc_u32 s79, s41, 0
	s_add_i32 s77, s68, s57
	global_load_lds_dwordx4 v[216:217], off
	v_lshl_add_u64 v[218:219], s[78:79], 0, v[130:131]
	s_mov_b32 m0, s77
	v_lshl_add_u64 v[220:221], s[42:43], 0, v[132:133]
	global_load_lds_dwordx4 v[218:219], off
	v_lshl_add_u64 v[218:219], s[78:79], 0, v[134:135]
	s_add_i32 m0, s77, 0x2000
	s_nop 0
	global_load_lds_dwordx4 v[218:219], off
	v_lshl_add_u64 v[218:219], s[42:43], 0, v[128:129]
	s_mov_b32 m0, s31
	s_nop 0
	global_load_lds_dwordx4 v[218:219], off
	s_mov_b32 m0, s59
	s_nop 0
	global_load_lds_dwordx4 v[220:221], off
	s_waitcnt vmcnt(8)
	s_waitcnt lgkmcnt(0)
	s_barrier
; #define PG8_STAGE(bufoff, gbase, voff) do { _Pragma("unroll") for (int _i = 0; _i < 2; ++_i) \
;         __builtin_amdgcn_global_load_lds((const unsigned*)((const char*)(gbase) + (voff)[_i]), (PG8_LAS unsigned*)(lds + (bufoff) + ldsw + _i * 8192), 16, 0, 0); } while (0)
; #define PG8_LDA(dst, b, h) do { _Pragma("unroll") for (int m = 0; m < 4; ++m) _Pragma("unroll") for (int k = 0; k < 2; ++k) dst[m][k] = *(const PG8_LAS bf16x8*)(lds + PG8_SA(b, h) + aoff + m * 2048 + k * 1024); } while (0)
; #define PG8_LDB(dst, b, h) do { _Pragma("unroll") for (int n = 0; n < 2; ++n) _Pragma("unroll") for (int k = 0; k < 2; ++k) dst[n][k] = *(const PG8_LAS bf16x8*)(lds + PG8_SB(b, h) + boff + n * 2048 + k * 1024); } while (0)
; #define PG8_MMA(ai, bj, At, Bt) do { __builtin_amdgcn_s_setprio(1); _Pragma("unroll") for (int m = 0; m < 4; ++m) _Pragma("unroll") for (int n = 0; n < 2; ++n) _Pragma("unroll") for (int k = 0; k < 2; ++k) \
;         acc[ai][bj][m][n] = __builtin_amdgcn_mfma_f32_16x16x32_bf16(Bt[n][k], At[m][k], acc[ai][bj][m][n], 0, 0, 0); __builtin_amdgcn_s_setprio(0); } while (0)
; #define PG8_WAIT_V(n) asm volatile("s_waitcnt vmcnt(" #n ")" ::: "memory")
; #define PG8_WAIT_L(n) asm volatile("s_waitcnt lgkmcnt(" #n ")" ::: "memory")
; #define PG8_BAR __builtin_amdgcn_s_barrier()
; #define PG8_SCHED __builtin_amdgcn_sched_barrier(0)
; template <class Epi, class Sched, bool ALIGN_EPI = false, bool SP2 = false>
; __device__ __forceinline__ void gemm_phase(PG8_LAS unsigned char* lds, const Gemm g, const Sched& S, const Epi& E) {
;     ...
;             PG8_WAIT_V(8); PG8_WAIT_L(0); PG8_BAR; PG8_MMA(1, 0, At, B0); PG8_MMA(1, 1, At, B1); PG8_BAR; PG8_SCHED;
;             PG8_LDB(B0, 1, 0); PG8_LDB(B1, 1, 1); PG8_SCHED; PG8_LDA(At, 1, 0); PG8_STAGE(PG8_SA(0, 1), a2 + hstep, voffA);
;             PG8_WAIT_V(8); PG8_WAIT_L(0); PG8_BAR; PG8_MMA(0, 0, At, B0); PG8_MMA(0, 1, At, B1); PG8_BAR; PG8_SCHED;
	s_setprio 1
	s_waitcnt lgkmcnt(0)
	v_mfma_f32_16x16x32_bf16 v[60:63], v[150:153], v[182:185], 0
	v_mfma_f32_16x16x32_bf16 v[56:59], v[158:161], v[182:185], 0
	v_mfma_f32_16x16x32_bf16 v[44:47], v[150:153], v[190:193], 0
	v_mfma_f32_16x16x32_bf16 v[40:43], v[158:161], v[190:193], 0
	v_mfma_f32_16x16x32_bf16 v[28:31], v[150:153], v[198:201], 0
	v_mfma_f32_16x16x32_bf16 v[24:27], v[158:161], v[198:201], 0
	v_mfma_f32_16x16x32_bf16 v[12:15], v[150:153], v[208:211], 0
	v_mfma_f32_16x16x32_bf16 v[8:11], v[158:161], v[208:211], 0
	v_mfma_f32_16x16x32_bf16 v[60:63], v[154:157], v[186:189], v[60:63]
	v_mfma_f32_16x16x32_bf16 v[56:59], v[162:165], v[186:189], v[56:59]
	v_mfma_f32_16x16x32_bf16 v[44:47], v[154:157], v[194:197], v[44:47]
	v_mfma_f32_16x16x32_bf16 v[40:43], v[162:165], v[194:197], v[40:43]
	v_mfma_f32_16x16x32_bf16 v[28:31], v[154:157], v[202:205], v[28:31]
	v_mfma_f32_16x16x32_bf16 v[24:27], v[162:165], v[202:205], v[24:27]
	v_mfma_f32_16x16x32_bf16 v[12:15], v[154:157], v[212:215], v[12:15]
	v_mfma_f32_16x16x32_bf16 v[8:11], v[162:165], v[212:215], v[8:11]
	s_setprio 0
	s_setprio 1
	v_mfma_f32_16x16x32_bf16 v[52:55], v[166:169], v[182:185], 0
	v_mfma_f32_16x16x32_bf16 v[48:51], v[174:177], v[182:185], 0
	v_mfma_f32_16x16x32_bf16 v[36:39], v[166:169], v[190:193], 0
	v_mfma_f32_16x16x32_bf16 v[32:35], v[174:177], v[190:193], 0
	v_mfma_f32_16x16x32_bf16 v[20:23], v[166:169], v[198:201], 0
	v_mfma_f32_16x16x32_bf16 v[16:19], v[174:177], v[198:201], 0
	v_mfma_f32_16x16x32_bf16 v[4:7], v[166:169], v[208:211], 0
	v_mfma_f32_16x16x32_bf16 v[0:3], v[174:177], v[208:211], 0
	v_mfma_f32_16x16x32_bf16 v[52:55], v[170:173], v[186:189], v[52:55]
	v_mfma_f32_16x16x32_bf16 v[48:51], v[178:181], v[186:189], v[48:51]
	v_mfma_f32_16x16x32_bf16 v[36:39], v[170:173], v[194:197], v[36:39]
	v_mfma_f32_16x16x32_bf16 v[32:35], v[178:181], v[194:197], v[32:35]
	v_mfma_f32_16x16x32_bf16 v[20:23], v[170:173], v[202:205], v[20:23]
	v_mfma_f32_16x16x32_bf16 v[16:19], v[178:181], v[202:205], v[16:19]
	v_mfma_f32_16x16x32_bf16 v[4:7], v[170:173], v[212:215], v[4:7]
	v_mfma_f32_16x16x32_bf16 v[0:3], v[178:181], v[212:215], v[0:3]
	s_setprio 0
	s_barrier
	s_add_i32 s77, 0, 0x18000
	s_add_i32 s78, 0, 0x1c000
	v_add_u32_e32 v162, s77, v145
	v_add_u32_e32 v178, s78, v145
	ds_read_b128 v[150:153], v162
	ds_read_b128 v[154:157], v162 offset:1024
	ds_read_b128 v[158:161], v162 offset:2048
	ds_read_b128 v[162:165], v162 offset:3072
	ds_read_b128 v[166:169], v178
	ds_read_b128 v[170:173], v178 offset:1024
	ds_read_b128 v[174:177], v178 offset:2048
	ds_read_b128 v[178:181], v178 offset:3072
	s_add_u32 s42, s42, 0x40000
	s_addc_u32 s43, s43, 0
	s_mov_b32 m0, s60
	v_lshl_add_u64 v[222:223], s[42:43], 0, v[128:129]
	ds_read_b128 v[182:185], v149 offset:32768
	ds_read_b128 v[186:189], v149 offset:33792
	ds_read_b128 v[190:193], v149 offset:34816
	ds_read_b128 v[194:197], v149 offset:35840
	ds_read_b128 v[198:201], v149 offset:36864
	ds_read_b128 v[202:205], v149 offset:37888
	ds_read_b128 v[208:211], v149 offset:38912
	ds_read_b128 v[212:215], v149 offset:39936
	global_load_lds_dwordx4 v[222:223], off
	v_lshl_add_u64 v[222:223], s[42:43], 0, v[132:133]
	s_mov_b32 m0, s61
	s_nop 0
	global_load_lds_dwordx4 v[222:223], off
	s_waitcnt vmcnt(8)
	s_waitcnt lgkmcnt(0)
	s_barrier
	s_setprio 1
	s_waitcnt lgkmcnt(0)
	v_mfma_f32_16x16x32_bf16 v[124:127], v[150:153], v[182:185], v[124:127]
	v_mfma_f32_16x16x32_bf16 v[120:123], v[158:161], v[182:185], v[120:123]
	v_mfma_f32_16x16x32_bf16 v[108:111], v[150:153], v[190:193], v[108:111]
	v_mfma_f32_16x16x32_bf16 v[104:107], v[158:161], v[190:193], v[104:107]
	v_mfma_f32_16x16x32_bf16 v[92:95], v[150:153], v[198:201], v[92:95]
	v_mfma_f32_16x16x32_bf16 v[88:91], v[158:161], v[198:201], v[88:91]
	v_mfma_f32_16x16x32_bf16 v[76:79], v[150:153], v[208:211], v[76:79]
	v_mfma_f32_16x16x32_bf16 v[72:75], v[158:161], v[208:211], v[72:75]
	v_mfma_f32_16x16x32_bf16 v[124:127], v[154:157], v[186:189], v[124:127]
	v_mfma_f32_16x16x32_bf16 v[120:123], v[162:165], v[186:189], v[120:123]
	v_mfma_f32_16x16x32_bf16 v[108:111], v[154:157], v[194:197], v[108:111]
	v_mfma_f32_16x16x32_bf16 v[104:107], v[162:165], v[194:197], v[104:107]
	v_mfma_f32_16x16x32_bf16 v[92:95], v[154:157], v[202:205], v[92:95]
	v_mfma_f32_16x16x32_bf16 v[88:91], v[162:165], v[202:205], v[88:91]
	v_mfma_f32_16x16x32_bf16 v[76:79], v[154:157], v[212:215], v[76:79]
	v_mfma_f32_16x16x32_bf16 v[72:75], v[162:165], v[212:215], v[72:75]
	s_setprio 0
	s_setprio 1
	v_mfma_f32_16x16x32_bf16 v[116:119], v[166:169], v[182:185], v[116:119]
	v_mfma_f32_16x16x32_bf16 v[112:115], v[174:177], v[182:185], v[112:115]
	v_mfma_f32_16x16x32_bf16 v[100:103], v[166:169], v[190:193], v[100:103]
	v_mfma_f32_16x16x32_bf16 v[96:99], v[174:177], v[190:193], v[96:99]
	v_mfma_f32_16x16x32_bf16 v[84:87], v[166:169], v[198:201], v[84:87]
	v_mfma_f32_16x16x32_bf16 v[80:83], v[174:177], v[198:201], v[80:83]
	v_mfma_f32_16x16x32_bf16 v[68:71], v[166:169], v[208:211], v[68:71]
	v_mfma_f32_16x16x32_bf16 v[64:67], v[174:177], v[208:211], v[64:67]
	v_mfma_f32_16x16x32_bf16 v[116:119], v[170:173], v[186:189], v[116:119]
	v_mfma_f32_16x16x32_bf16 v[112:115], v[178:181], v[186:189], v[112:115]
	v_mfma_f32_16x16x32_bf16 v[100:103], v[170:173], v[194:197], v[100:103]
	v_mfma_f32_16x16x32_bf16 v[96:99], v[178:181], v[194:197], v[96:99]
	v_mfma_f32_16x16x32_bf16 v[84:87], v[170:173], v[202:205], v[84:87]
	v_mfma_f32_16x16x32_bf16 v[80:83], v[178:181], v[202:205], v[80:83]
	v_mfma_f32_16x16x32_bf16 v[68:71], v[170:173], v[212:215], v[68:71]
	v_mfma_f32_16x16x32_bf16 v[64:67], v[178:181], v[212:215], v[64:67]
	s_setprio 0
	s_barrier
; #define PG8_STAGE(bufoff, gbase, voff) do { _Pragma("unroll") for (int _i = 0; _i < 2; ++_i) \
;         __builtin_amdgcn_global_load_lds((const unsigned*)((const char*)(gbase) + (voff)[_i]), (PG8_LAS unsigned*)(lds + (bufoff) + ldsw + _i * 8192), 16, 0, 0); } while (0)
; #define PG8_LDA(dst, b, h) do { _Pragma("unroll") for (int m = 0; m < 4; ++m) _Pragma("unroll") for (int k = 0; k < 2; ++k) dst[m][k] = *(const PG8_LAS bf16x8*)(lds + PG8_SA(b, h) + aoff + m * 2048 + k * 1024); } while (0)
; #define PG8_LDB(dst, b, h) do { _Pragma("unroll") for (int n = 0; n < 2; ++n) _Pragma("unroll") for (int k = 0; k < 2; ++k) dst[n][k] = *(const PG8_LAS bf16x8*)(lds + PG8_SB(b, h) + boff + n * 2048 + k * 1024); } while (0)
; template <class Epi, class Sched, bool ALIGN_EPI = false, bool SP2 = false>
; __device__ __forceinline__ void gemm_phase(PG8_LAS unsigned char* lds, const Gemm g, const Sched& S, const Epi& E) {
;     ...
;         for (int t = 0; t < nt; t += 2) {
;             const bool last = (t == nt - 2);
;             const char* a1 = cA + (size_t)(t + 1) * kstep;
;             const char* a2 = last ? nA : cA + (size_t)(t + 2) * kstep; const char* b2 = last ? nB : cB + (size_t)(t + 2) * kstep;
;             const char* a3 = a2 + kstep; const char* b3 = b2 + kstep;
;             if (last && has_next) S.a_ready(nxt);
;             if constexpr (SP2) {
;             PG8_LDB(B0, 0, 0); PG8_LDB(B1, 0, 1); PG8_SCHED; PG8_LDA(At, 0, 0); PG8_STAGE(PG8_SA(1, 1), a1 + hstep, voffA);
;             PG8_WAIT_V(8); PG8_WAIT_L(0); PG8_BAR; PG8_MMA(0, 0, At, B0); PG8_MMA(0, 1, At, B1); PG8_BAR; PG8_SCHED;
;             PG8_LDA(At, 0, 1); PG8_STAGE(PG8_SB(0, 0), b2, voffB); PG8_STAGE(PG8_SB(0, 1), b2 + hstep, voffB); PG8_STAGE(PG8_SA(0, 0), a2, voffA);
;             PG8_WAIT_V(8); PG8_WAIT_L(0); PG8_BAR; PG8_MMA(1, 0, At, B0); PG8_MMA(1, 1, At, B1); PG8_BAR; PG8_SCHED;
;             PG8_LDB(B0, 1, 0); PG8_LDB(B1, 1, 1); PG8_SCHED; PG8_LDA(At, 1, 0); PG8_STAGE(PG8_SA(0, 1), a2 + hstep, voffA);
;             PG8_WAIT_V(8); PG8_WAIT_L(0); PG8_BAR; PG8_MMA(0, 0, At, B0); PG8_MMA(0, 1, At, B1); PG8_BAR; PG8_SCHED;
;             PG8_LDA(At, 1, 1); PG8_STAGE(PG8_SB(1, 0), b3, voffB); PG8_STAGE(PG8_SB(1, 1), b3 + hstep, voffB); PG8_STAGE(PG8_SA(1, 0), a3, voffA);
;             PG8_WAIT_V(8); PG8_WAIT_L(0); PG8_BAR; PG8_MMA(1, 0, At, B0); PG8_MMA(1, 1, At, B1); PG8_BAR; PG8_SCHED;
	s_add_i32 s42, s77, s57
	v_lshl_add_u64 v[142:143], v[142:143], 0, s[8:9]
	s_mov_b32 m0, s42
	ds_read_b128 v[182:185], v149 offset:49152
	ds_read_b128 v[186:189], v149 offset:50176
	ds_read_b128 v[190:193], v149 offset:51200
	ds_read_b128 v[194:197], v149 offset:52224
	ds_read_b128 v[198:201], v149 offset:53248
	ds_read_b128 v[202:205], v149 offset:54272
	ds_read_b128 v[208:211], v149 offset:55296
	ds_read_b128 v[212:215], v149 offset:56320
	global_load_lds_dwordx4 v[142:143], off
	s_add_i32 m0, s42, 0x2000
	s_add_u32 s40, s40, 0x40080
	v_lshl_add_u64 v[142:143], v[216:217], 0, s[8:9]
	s_addc_u32 s41, s41, 0
	s_add_i32 s42, s78, s57
	global_load_lds_dwordx4 v[142:143], off
	v_lshl_add_u64 v[142:143], s[40:41], 0, v[130:131]
	s_mov_b32 m0, s42
	s_nop 0
	global_load_lds_dwordx4 v[142:143], off
	v_lshl_add_u64 v[142:143], s[40:41], 0, v[134:135]
	s_add_i32 m0, s42, 0x2000
	s_nop 0
	global_load_lds_dwordx4 v[142:143], off
	v_lshl_add_u64 v[142:143], v[218:219], 0, s[8:9]
	s_mov_b32 m0, s65
	s_nop 0
	global_load_lds_dwordx4 v[142:143], off
	v_lshl_add_u64 v[142:143], v[220:221], 0, s[8:9]
	s_mov_b32 m0, s66
	s_nop 0
	global_load_lds_dwordx4 v[142:143], off
	s_waitcnt vmcnt(8)
	s_waitcnt lgkmcnt(0)
	s_barrier
	s_setprio 1
	s_waitcnt lgkmcnt(0)
	v_mfma_f32_16x16x32_bf16 v[60:63], v[150:153], v[182:185], v[60:63]
	v_mfma_f32_16x16x32_bf16 v[56:59], v[158:161], v[182:185], v[56:59]
	v_mfma_f32_16x16x32_bf16 v[44:47], v[150:153], v[190:193], v[44:47]
	v_mfma_f32_16x16x32_bf16 v[40:43], v[158:161], v[190:193], v[40:43]
	v_mfma_f32_16x16x32_bf16 v[28:31], v[150:153], v[198:201], v[28:31]
	v_mfma_f32_16x16x32_bf16 v[24:27], v[158:161], v[198:201], v[24:27]
	v_mfma_f32_16x16x32_bf16 v[12:15], v[150:153], v[208:211], v[12:15]
	v_mfma_f32_16x16x32_bf16 v[8:11], v[158:161], v[208:211], v[8:11]
	v_mfma_f32_16x16x32_bf16 v[60:63], v[154:157], v[186:189], v[60:63]
	v_mfma_f32_16x16x32_bf16 v[56:59], v[162:165], v[186:189], v[56:59]
	v_mfma_f32_16x16x32_bf16 v[44:47], v[154:157], v[194:197], v[44:47]
	v_mfma_f32_16x16x32_bf16 v[40:43], v[162:165], v[194:197], v[40:43]
	v_mfma_f32_16x16x32_bf16 v[28:31], v[154:157], v[202:205], v[28:31]
	v_mfma_f32_16x16x32_bf16 v[24:27], v[162:165], v[202:205], v[24:27]
	v_mfma_f32_16x16x32_bf16 v[12:15], v[154:157], v[212:215], v[12:15]
	v_mfma_f32_16x16x32_bf16 v[8:11], v[162:165], v[212:215], v[8:11]
	s_setprio 0
	s_setprio 1
	v_mfma_f32_16x16x32_bf16 v[52:55], v[166:169], v[182:185], v[52:55]
	v_mfma_f32_16x16x32_bf16 v[48:51], v[174:177], v[182:185], v[48:51]
	v_mfma_f32_16x16x32_bf16 v[36:39], v[166:169], v[190:193], v[36:39]
	v_mfma_f32_16x16x32_bf16 v[32:35], v[174:177], v[190:193], v[32:35]
	v_mfma_f32_16x16x32_bf16 v[20:23], v[166:169], v[198:201], v[20:23]
	v_mfma_f32_16x16x32_bf16 v[16:19], v[174:177], v[198:201], v[16:19]
	v_mfma_f32_16x16x32_bf16 v[4:7], v[166:169], v[208:211], v[4:7]
	v_mfma_f32_16x16x32_bf16 v[0:3], v[174:177], v[208:211], v[0:3]
	v_mfma_f32_16x16x32_bf16 v[52:55], v[170:173], v[186:189], v[52:55]
	v_mfma_f32_16x16x32_bf16 v[48:51], v[178:181], v[186:189], v[48:51]
	v_mfma_f32_16x16x32_bf16 v[36:39], v[170:173], v[194:197], v[36:39]
	v_mfma_f32_16x16x32_bf16 v[32:35], v[178:181], v[194:197], v[32:35]
	v_mfma_f32_16x16x32_bf16 v[20:23], v[170:173], v[202:205], v[20:23]
	v_mfma_f32_16x16x32_bf16 v[16:19], v[178:181], v[202:205], v[16:19]
	v_mfma_f32_16x16x32_bf16 v[4:7], v[170:173], v[212:215], v[4:7]
	v_mfma_f32_16x16x32_bf16 v[0:3], v[178:181], v[212:215], v[0:3]
	s_setprio 0
	s_barrier
	s_add_i32 s76, s76, 2
	s_add_u32 s38, s38, 0x100
	s_addc_u32 s39, s39, 0
	s_add_u32 s74, s74, 0x100
	s_addc_u32 s75, s75, 0
	s_cmp_gt_u32 s76, 13
	s_cbranch_scc0 .LBB0_1052
	s_branch .Lpeel_exit_7

;     __device__ __forceinline__ bool next(int i, Unit& u) const { if (i != 0) return false; const int c0 = (G >= 8) ? G - 5 : G - 2; int k = -1; if (c == c0) k = 0; else if (c == G - 1) k = 1; if (k < 0 || k >= n) return false; u.pm = k; u.pn = 0; return true; }
; #define PG8_STAGE(bufoff, gbase, voff) do { _Pragma("unroll") for (int _i = 0; _i < 2; ++_i) \
;         __builtin_amdgcn_global_load_lds((const unsigned*)((const char*)(gbase) + (voff)[_i]), (PG8_LAS unsigned*)(lds + (bufoff) + ldsw + _i * 8192), 16, 0, 0); } while (0)
; #define PG8_LDA(dst, b, h) do { _Pragma("unroll") for (int m = 0; m < 4; ++m) _Pragma("unroll") for (int k = 0; k < 2; ++k) dst[m][k] = *(const PG8_LAS bf16x8*)(lds + PG8_SA(b, h) + aoff + m * 2048 + k * 1024); } while (0)
; #define PG8_LDB(dst, b, h) do { _Pragma("unroll") for (int n = 0; n < 2; ++n) _Pragma("unroll") for (int k = 0; k < 2; ++k) dst[n][k] = *(const PG8_LAS bf16x8*)(lds + PG8_SB(b, h) + boff + n * 2048 + k * 1024); } while (0)
; template <class Epi, class Sched, bool ALIGN_EPI = false, bool SP2 = false>
; __device__ __forceinline__ void gemm_phase(PG8_LAS unsigned char* lds, const Gemm g, const Sched& S, const Epi& E) {
;     ...
;         const bool has_next = S.next(ui + 1, nxt);
;         const char* nA = has_next ? (const char*)g.A + (size_t)nxt.pm * tstep : cA; const char* nB = has_next ? (const char*)g.Bt + (size_t)nxt.pn * tstep : cB;
;         for (int t = 0; t < nt; t += 2) {
;             const bool last = (t == nt - 2);
;             const char* a1 = cA + (size_t)(t + 1) * kstep;
;             const char* a2 = last ? nA : cA + (size_t)(t + 2) * kstep; const char* b2 = last ? nB : cB + (size_t)(t + 2) * kstep;
;             const char* a3 = a2 + kstep; const char* b3 = b2 + kstep;
;             if (last && has_next) S.a_ready(nxt);
;             if constexpr (SP2) {
;             PG8_LDB(B0, 0, 0); PG8_LDB(B1, 0, 1); PG8_SCHED; PG8_LDA(At, 0, 0); PG8_STAGE(PG8_SA(1, 1), a1 + hstep, voffA);
;             PG8_WAIT_V(8); PG8_WAIT_L(0); PG8_BAR; PG8_MMA(0, 0, At, B0); PG8_MMA(0, 1, At, B1); PG8_BAR; PG8_SCHED;
;             PG8_LDA(At, 0, 1); PG8_STAGE(PG8_SB(0, 0), b2, voffB); PG8_STAGE(PG8_SB(0, 1), b2 + hstep, voffB); PG8_STAGE(PG8_SA(0, 0), a2, voffA);
;             PG8_WAIT_V(8); PG8_WAIT_L(0); PG8_BAR; PG8_MMA(1, 0, At, B0); PG8_MMA(1, 1, At, B1); PG8_BAR; PG8_SCHED;
.LBB0_1162:
	s_add_u32 s46, s46, 0xb0080
	s_addc_u32 s47, s47, 0
	s_add_u32 s91, s56, 0x100
	v_mov_b32_e32 v0, 0
	s_addc_u32 s92, s57, 0
	s_mov_b32 s93, -2
	ds_read_b128 v[148:151], v145
	ds_read_b128 v[152:155], v145 offset:1024
	ds_read_b128 v[156:159], v145 offset:2048
	ds_read_b128 v[160:163], v145 offset:3072
	ds_read_b128 v[164:167], v146
	ds_read_b128 v[168:171], v146 offset:1024
	ds_read_b128 v[172:175], v146 offset:2048
	ds_read_b128 v[176:179], v146 offset:3072
	s_add_u32 s56, s46, 0xfff50080
	s_addc_u32 s57, s47, -1
	s_cmp_eq_u32 s93, 40
	s_cselect_b32 s59, s41, s57
	s_cselect_b32 s58, s40, s56
	s_cselect_b32 s57, s43, s92
	s_cselect_b32 s56, s42, s91
	v_lshl_add_u64 v[204:205], s[46:47], 0, v[136:137]
	s_add_i32 m0, s69, 0xc000
	ds_read_b128 v[180:183], v147
	ds_read_b128 v[184:187], v147 offset:1024
	ds_read_b128 v[188:191], v147 offset:2048
	ds_read_b128 v[192:195], v147 offset:3072
	ds_read_b128 v[196:199], v147 offset:4096
	ds_read_b128 v[200:203], v147 offset:5120
	ds_read_b128 v[208:211], v147 offset:6144
	ds_read_b128 v[212:215], v147 offset:7168
	global_load_lds_dwordx4 v[204:205], off
	v_lshl_add_u64 v[204:205], s[46:47], 0, v[138:139]
	s_add_i32 m0, s69, 0xe000
	s_nop 0
	global_load_lds_dwordx4 v[204:205], off
	s_waitcnt vmcnt(8)
	s_waitcnt lgkmcnt(0)
	s_barrier
	s_setprio 1
	s_waitcnt lgkmcnt(0)
	v_mfma_f32_16x16x32_bf16 v[124:127], v[148:151], v[180:183], 0
	v_mfma_f32_16x16x32_bf16 v[120:123], v[156:159], v[180:183], 0
	v_mfma_f32_16x16x32_bf16 v[116:119], v[148:151], v[188:191], 0
	v_mfma_f32_16x16x32_bf16 v[112:115], v[156:159], v[188:191], 0
	v_mfma_f32_16x16x32_bf16 v[100:103], v[148:151], v[196:199], 0
	v_mfma_f32_16x16x32_bf16 v[96:99], v[156:159], v[196:199], 0
	v_mfma_f32_16x16x32_bf16 v[84:87], v[148:151], v[208:211], 0
	v_mfma_f32_16x16x32_bf16 v[80:83], v[156:159], v[208:211], 0
	v_mfma_f32_16x16x32_bf16 v[124:127], v[152:155], v[184:187], v[124:127]
	v_mfma_f32_16x16x32_bf16 v[120:123], v[160:163], v[184:187], v[120:123]
	v_mfma_f32_16x16x32_bf16 v[116:119], v[152:155], v[192:195], v[116:119]
	v_mfma_f32_16x16x32_bf16 v[112:115], v[160:163], v[192:195], v[112:115]
	v_mfma_f32_16x16x32_bf16 v[100:103], v[152:155], v[200:203], v[100:103]
	v_mfma_f32_16x16x32_bf16 v[96:99], v[160:163], v[200:203], v[96:99]
	v_mfma_f32_16x16x32_bf16 v[84:87], v[152:155], v[212:215], v[84:87]
	v_mfma_f32_16x16x32_bf16 v[80:83], v[160:163], v[212:215], v[80:83]
	s_setprio 0
	s_setprio 1
	v_mfma_f32_16x16x32_bf16 v[108:111], v[164:167], v[180:183], 0
	v_mfma_f32_16x16x32_bf16 v[104:107], v[172:175], v[180:183], 0
	v_mfma_f32_16x16x32_bf16 v[92:95], v[164:167], v[188:191], 0
	v_mfma_f32_16x16x32_bf16 v[88:91], v[172:175], v[188:191], 0
	v_mfma_f32_16x16x32_bf16 v[76:79], v[164:167], v[196:199], 0
	v_mfma_f32_16x16x32_bf16 v[72:75], v[172:175], v[196:199], 0
	v_mfma_f32_16x16x32_bf16 v[68:71], v[164:167], v[208:211], 0
	v_mfma_f32_16x16x32_bf16 v[64:67], v[172:175], v[208:211], 0
	v_mfma_f32_16x16x32_bf16 v[108:111], v[168:171], v[184:187], v[108:111]
	v_mfma_f32_16x16x32_bf16 v[104:107], v[176:179], v[184:187], v[104:107]
	v_mfma_f32_16x16x32_bf16 v[92:95], v[168:171], v[192:195], v[92:95]
	v_mfma_f32_16x16x32_bf16 v[88:91], v[176:179], v[192:195], v[88:91]
	v_mfma_f32_16x16x32_bf16 v[76:79], v[168:171], v[200:203], v[76:79]
	v_mfma_f32_16x16x32_bf16 v[72:75], v[176:179], v[200:203], v[72:75]
	v_mfma_f32_16x16x32_bf16 v[68:71], v[168:171], v[212:215], v[68:71]
	v_mfma_f32_16x16x32_bf16 v[64:67], v[176:179], v[212:215], v[64:67]
	s_setprio 0
	s_barrier
	s_add_i32 s94, s77, s66
	v_lshl_add_u64 v[204:205], s[56:57], 0, v[130:131]
	s_mov_b32 m0, s94
	ds_read_b128 v[180:183], v147 offset:16384
	ds_read_b128 v[184:187], v147 offset:17408
	ds_read_b128 v[188:191], v147 offset:18432
	ds_read_b128 v[192:195], v147 offset:19456
	ds_read_b128 v[196:199], v147 offset:20480
	ds_read_b128 v[200:203], v147 offset:21504
	ds_read_b128 v[208:211], v147 offset:22528
	ds_read_b128 v[212:215], v147 offset:23552
	global_load_lds_dwordx4 v[204:205], off
	s_add_i32 m0, s94, 0x2000
	s_add_u32 s94, s56, 0xb0000
	v_lshl_add_u64 v[216:217], s[56:57], 0, v[134:135]
	s_addc_u32 s95, s57, 0
	s_add_i32 s96, s78, s66
	global_load_lds_dwordx4 v[216:217], off
	v_lshl_add_u64 v[218:219], s[94:95], 0, v[130:131]
	s_mov_b32 m0, s96
	v_lshl_add_u64 v[220:221], s[58:59], 0, v[132:133]
	global_load_lds_dwordx4 v[218:219], off
	v_lshl_add_u64 v[218:219], s[94:95], 0, v[134:135]
	s_add_i32 m0, s96, 0x2000
	s_nop 0
	global_load_lds_dwordx4 v[218:219], off
	v_lshl_add_u64 v[218:219], s[58:59], 0, v[128:129]
	s_mov_b32 m0, s69
	s_nop 0
	global_load_lds_dwordx4 v[218:219], off
	s_mov_b32 m0, s71
	s_nop 0
	global_load_lds_dwordx4 v[220:221], off
	s_waitcnt vmcnt(8)
	s_waitcnt lgkmcnt(0)
	s_barrier
; #define PG8_STAGE(bufoff, gbase, voff) do { _Pragma("unroll") for (int _i = 0; _i < 2; ++_i) \
;         __builtin_amdgcn_global_load_lds((const unsigned*)((const char*)(gbase) + (voff)[_i]), (PG8_LAS unsigned*)(lds + (bufoff) + ldsw + _i * 8192), 16, 0, 0); } while (0)
; #define PG8_LDA(dst, b, h) do { _Pragma("unroll") for (int m = 0; m < 4; ++m) _Pragma("unroll") for (int k = 0; k < 2; ++k) dst[m][k] = *(const PG8_LAS bf16x8*)(lds + PG8_SA(b, h) + aoff + m * 2048 + k * 1024); } while (0)
; #define PG8_LDB(dst, b, h) do { _Pragma("unroll") for (int n = 0; n < 2; ++n) _Pragma("unroll") for (int k = 0; k < 2; ++k) dst[n][k] = *(const PG8_LAS bf16x8*)(lds + PG8_SB(b, h) + boff + n * 2048 + k * 1024); } while (0)
; #define PG8_MMA(ai, bj, At, Bt) do { __builtin_amdgcn_s_setprio(1); _Pragma("unroll") for (int m = 0; m < 4; ++m) _Pragma("unroll") for (int n = 0; n < 2; ++n) _Pragma("unroll") for (int k = 0; k < 2; ++k) \
;         acc[ai][bj][m][n] = __builtin_amdgcn_mfma_f32_16x16x32_bf16(Bt[n][k], At[m][k], acc[ai][bj][m][n], 0, 0, 0); __builtin_amdgcn_s_setprio(0); } while (0)
; #define PG8_WAIT_V(n) asm volatile("s_waitcnt vmcnt(" #n ")" ::: "memory")
; #define PG8_WAIT_L(n) asm volatile("s_waitcnt lgkmcnt(" #n ")" ::: "memory")
; #define PG8_BAR __builtin_amdgcn_s_barrier()
; #define PG8_SCHED __builtin_amdgcn_sched_barrier(0)
; template <class Epi, class Sched, bool ALIGN_EPI = false, bool SP2 = false>
; __device__ __forceinline__ void gemm_phase(PG8_LAS unsigned char* lds, const Gemm g, const Sched& S, const Epi& E) {
;     ...
;             PG8_WAIT_V(8); PG8_WAIT_L(0); PG8_BAR; PG8_MMA(1, 0, At, B0); PG8_MMA(1, 1, At, B1); PG8_BAR; PG8_SCHED;
;             PG8_LDB(B0, 1, 0); PG8_LDB(B1, 1, 1); PG8_SCHED; PG8_LDA(At, 1, 0); PG8_STAGE(PG8_SA(0, 1), a2 + hstep, voffA);
;             PG8_WAIT_V(8); PG8_WAIT_L(0); PG8_BAR; PG8_MMA(0, 0, At, B0); PG8_MMA(0, 1, At, B1); PG8_BAR; PG8_SCHED;
	s_setprio 1
	s_waitcnt lgkmcnt(0)
	v_mfma_f32_16x16x32_bf16 v[60:63], v[148:151], v[180:183], 0
	v_mfma_f32_16x16x32_bf16 v[56:59], v[156:159], v[180:183], 0
	v_mfma_f32_16x16x32_bf16 v[52:55], v[148:151], v[188:191], 0
	v_mfma_f32_16x16x32_bf16 v[48:51], v[156:159], v[188:191], 0
	v_mfma_f32_16x16x32_bf16 v[36:39], v[148:151], v[196:199], 0
	v_mfma_f32_16x16x32_bf16 v[32:35], v[156:159], v[196:199], 0
	v_mfma_f32_16x16x32_bf16 v[20:23], v[148:151], v[208:211], 0
	v_mfma_f32_16x16x32_bf16 v[16:19], v[156:159], v[208:211], 0
	v_mfma_f32_16x16x32_bf16 v[60:63], v[152:155], v[184:187], v[60:63]
	v_mfma_f32_16x16x32_bf16 v[56:59], v[160:163], v[184:187], v[56:59]
	v_mfma_f32_16x16x32_bf16 v[52:55], v[152:155], v[192:195], v[52:55]
	v_mfma_f32_16x16x32_bf16 v[48:51], v[160:163], v[192:195], v[48:51]
	v_mfma_f32_16x16x32_bf16 v[36:39], v[152:155], v[200:203], v[36:39]
	v_mfma_f32_16x16x32_bf16 v[32:35], v[160:163], v[200:203], v[32:35]
	v_mfma_f32_16x16x32_bf16 v[20:23], v[152:155], v[212:215], v[20:23]
	v_mfma_f32_16x16x32_bf16 v[16:19], v[160:163], v[212:215], v[16:19]
	s_setprio 0
	s_setprio 1
	v_mfma_f32_16x16x32_bf16 v[44:47], v[164:167], v[180:183], 0
	v_mfma_f32_16x16x32_bf16 v[40:43], v[172:175], v[180:183], 0
	v_mfma_f32_16x16x32_bf16 v[28:31], v[164:167], v[188:191], 0
	v_mfma_f32_16x16x32_bf16 v[24:27], v[172:175], v[188:191], 0
	v_mfma_f32_16x16x32_bf16 v[12:15], v[164:167], v[196:199], 0
	v_mfma_f32_16x16x32_bf16 v[8:11], v[172:175], v[196:199], 0
	v_mfma_f32_16x16x32_bf16 v[4:7], v[164:167], v[208:211], 0
	v_mfma_f32_16x16x32_bf16 v[0:3], v[172:175], v[208:211], 0
	v_mfma_f32_16x16x32_bf16 v[44:47], v[168:171], v[184:187], v[44:47]
	v_mfma_f32_16x16x32_bf16 v[40:43], v[176:179], v[184:187], v[40:43]
	v_mfma_f32_16x16x32_bf16 v[28:31], v[168:171], v[192:195], v[28:31]
	v_mfma_f32_16x16x32_bf16 v[24:27], v[176:179], v[192:195], v[24:27]
	v_mfma_f32_16x16x32_bf16 v[12:15], v[168:171], v[200:203], v[12:15]
	v_mfma_f32_16x16x32_bf16 v[8:11], v[176:179], v[200:203], v[8:11]
	v_mfma_f32_16x16x32_bf16 v[4:7], v[168:171], v[212:215], v[4:7]
	v_mfma_f32_16x16x32_bf16 v[0:3], v[176:179], v[212:215], v[0:3]
	s_setprio 0
	s_barrier
	s_add_i32 s94, 0, 0x18000
	s_add_i32 s95, 0, 0x1c000
	v_add_u32_e32 v160, s94, v143
	v_add_u32_e32 v176, s95, v143
	ds_read_b128 v[148:151], v160
	ds_read_b128 v[152:155], v160 offset:1024
	ds_read_b128 v[156:159], v160 offset:2048
	ds_read_b128 v[160:163], v160 offset:3072
	ds_read_b128 v[164:167], v176
	ds_read_b128 v[168:171], v176 offset:1024
	ds_read_b128 v[172:175], v176 offset:2048
	ds_read_b128 v[176:179], v176 offset:3072
	s_add_u32 s58, s58, 0xb0000
	s_addc_u32 s59, s59, 0
	s_mov_b32 m0, s72
	v_lshl_add_u64 v[222:223], s[58:59], 0, v[128:129]
	ds_read_b128 v[180:183], v147 offset:32768
	ds_read_b128 v[184:187], v147 offset:33792
	ds_read_b128 v[188:191], v147 offset:34816
	ds_read_b128 v[192:195], v147 offset:35840
	ds_read_b128 v[196:199], v147 offset:36864
	ds_read_b128 v[200:203], v147 offset:37888
	ds_read_b128 v[208:211], v147 offset:38912
	ds_read_b128 v[212:215], v147 offset:39936
	global_load_lds_dwordx4 v[222:223], off
	v_lshl_add_u64 v[222:223], s[58:59], 0, v[132:133]
	s_mov_b32 m0, s73
	s_nop 0
	global_load_lds_dwordx4 v[222:223], off
	s_waitcnt vmcnt(8)
	s_waitcnt lgkmcnt(0)
	s_barrier
	s_setprio 1
	s_waitcnt lgkmcnt(0)
	v_mfma_f32_16x16x32_bf16 v[124:127], v[148:151], v[180:183], v[124:127]
	v_mfma_f32_16x16x32_bf16 v[120:123], v[156:159], v[180:183], v[120:123]
	v_mfma_f32_16x16x32_bf16 v[116:119], v[148:151], v[188:191], v[116:119]
	v_mfma_f32_16x16x32_bf16 v[112:115], v[156:159], v[188:191], v[112:115]
	v_mfma_f32_16x16x32_bf16 v[100:103], v[148:151], v[196:199], v[100:103]
	v_mfma_f32_16x16x32_bf16 v[96:99], v[156:159], v[196:199], v[96:99]
	v_mfma_f32_16x16x32_bf16 v[84:87], v[148:151], v[208:211], v[84:87]
	v_mfma_f32_16x16x32_bf16 v[80:83], v[156:159], v[208:211], v[80:83]
	v_mfma_f32_16x16x32_bf16 v[124:127], v[152:155], v[184:187], v[124:127]
	v_mfma_f32_16x16x32_bf16 v[120:123], v[160:163], v[184:187], v[120:123]
	v_mfma_f32_16x16x32_bf16 v[116:119], v[152:155], v[192:195], v[116:119]
	v_mfma_f32_16x16x32_bf16 v[112:115], v[160:163], v[192:195], v[112:115]
	v_mfma_f32_16x16x32_bf16 v[100:103], v[152:155], v[200:203], v[100:103]
	v_mfma_f32_16x16x32_bf16 v[96:99], v[160:163], v[200:203], v[96:99]
	v_mfma_f32_16x16x32_bf16 v[84:87], v[152:155], v[212:215], v[84:87]
	v_mfma_f32_16x16x32_bf16 v[80:83], v[160:163], v[212:215], v[80:83]
	s_setprio 0
	s_setprio 1
	v_mfma_f32_16x16x32_bf16 v[108:111], v[164:167], v[180:183], v[108:111]
	v_mfma_f32_16x16x32_bf16 v[104:107], v[172:175], v[180:183], v[104:107]
	v_mfma_f32_16x16x32_bf16 v[92:95], v[164:167], v[188:191], v[92:95]
	v_mfma_f32_16x16x32_bf16 v[88:91], v[172:175], v[188:191], v[88:91]
	v_mfma_f32_16x16x32_bf16 v[76:79], v[164:167], v[196:199], v[76:79]
	v_mfma_f32_16x16x32_bf16 v[72:75], v[172:175], v[196:199], v[72:75]
	v_mfma_f32_16x16x32_bf16 v[68:71], v[164:167], v[208:211], v[68:71]
	v_mfma_f32_16x16x32_bf16 v[64:67], v[172:175], v[208:211], v[64:67]
	v_mfma_f32_16x16x32_bf16 v[108:111], v[168:171], v[184:187], v[108:111]
	v_mfma_f32_16x16x32_bf16 v[104:107], v[176:179], v[184:187], v[104:107]
	v_mfma_f32_16x16x32_bf16 v[92:95], v[168:171], v[192:195], v[92:95]
	v_mfma_f32_16x16x32_bf16 v[88:91], v[176:179], v[192:195], v[88:91]
	v_mfma_f32_16x16x32_bf16 v[76:79], v[168:171], v[200:203], v[76:79]
	v_mfma_f32_16x16x32_bf16 v[72:75], v[176:179], v[200:203], v[72:75]
	v_mfma_f32_16x16x32_bf16 v[68:71], v[168:171], v[212:215], v[68:71]
	v_mfma_f32_16x16x32_bf16 v[64:67], v[176:179], v[212:215], v[64:67]
	s_setprio 0
	s_barrier
; #define PG8_STAGE(bufoff, gbase, voff) do { _Pragma("unroll") for (int _i = 0; _i < 2; ++_i) \
;         __builtin_amdgcn_global_load_lds((const unsigned*)((const char*)(gbase) + (voff)[_i]), (PG8_LAS unsigned*)(lds + (bufoff) + ldsw + _i * 8192), 16, 0, 0); } while (0)
; #define PG8_LDA(dst, b, h) do { _Pragma("unroll") for (int m = 0; m < 4; ++m) _Pragma("unroll") for (int k = 0; k < 2; ++k) dst[m][k] = *(const PG8_LAS bf16x8*)(lds + PG8_SA(b, h) + aoff + m * 2048 + k * 1024); } while (0)
; #define PG8_LDB(dst, b, h) do { _Pragma("unroll") for (int n = 0; n < 2; ++n) _Pragma("unroll") for (int k = 0; k < 2; ++k) dst[n][k] = *(const PG8_LAS bf16x8*)(lds + PG8_SB(b, h) + boff + n * 2048 + k * 1024); } while (0)
; template <class Epi, class Sched, bool ALIGN_EPI = false, bool SP2 = false>
; __device__ __forceinline__ void gemm_phase(PG8_LAS unsigned char* lds, const Gemm g, const Sched& S, const Epi& E) {
;     ...
;         for (int t = 0; t < nt; t += 2) {
;             const bool last = (t == nt - 2);
;             const char* a1 = cA + (size_t)(t + 1) * kstep;
;             const char* a2 = last ? nA : cA + (size_t)(t + 2) * kstep; const char* b2 = last ? nB : cB + (size_t)(t + 2) * kstep;
;             const char* a3 = a2 + kstep; const char* b3 = b2 + kstep;
;             if (last && has_next) S.a_ready(nxt);
;             if constexpr (SP2) {
;             PG8_LDB(B0, 0, 0); PG8_LDB(B1, 0, 1); PG8_SCHED; PG8_LDA(At, 0, 0); PG8_STAGE(PG8_SA(1, 1), a1 + hstep, voffA);
;             PG8_WAIT_V(8); PG8_WAIT_L(0); PG8_BAR; PG8_MMA(0, 0, At, B0); PG8_MMA(0, 1, At, B1); PG8_BAR; PG8_SCHED;
;             PG8_LDA(At, 0, 1); PG8_STAGE(PG8_SB(0, 0), b2, voffB); PG8_STAGE(PG8_SB(0, 1), b2 + hstep, voffB); PG8_STAGE(PG8_SA(0, 0), a2, voffA);
;             PG8_WAIT_V(8); PG8_WAIT_L(0); PG8_BAR; PG8_MMA(1, 0, At, B0); PG8_MMA(1, 1, At, B1); PG8_BAR; PG8_SCHED;
;             PG8_LDB(B0, 1, 0); PG8_LDB(B1, 1, 1); PG8_SCHED; PG8_LDA(At, 1, 0); PG8_STAGE(PG8_SA(0, 1), a2 + hstep, voffA);
;             PG8_WAIT_V(8); PG8_WAIT_L(0); PG8_BAR; PG8_MMA(0, 0, At, B0); PG8_MMA(0, 1, At, B1); PG8_BAR; PG8_SCHED;
;             PG8_LDA(At, 1, 1); PG8_STAGE(PG8_SB(1, 0), b3, voffB); PG8_STAGE(PG8_SB(1, 1), b3 + hstep, voffB); PG8_STAGE(PG8_SA(1, 0), a3, voffA);
;             PG8_WAIT_V(8); PG8_WAIT_L(0); PG8_BAR; PG8_MMA(1, 0, At, B0); PG8_MMA(1, 1, At, B1); PG8_BAR; PG8_SCHED;
	s_add_i32 s58, s94, s66
	v_lshl_add_u64 v[204:205], v[204:205], 0, s[20:21]
	s_mov_b32 m0, s58
	ds_read_b128 v[180:183], v147 offset:49152
	ds_read_b128 v[184:187], v147 offset:50176
	ds_read_b128 v[188:191], v147 offset:51200
	ds_read_b128 v[192:195], v147 offset:52224
	ds_read_b128 v[196:199], v147 offset:53248
	ds_read_b128 v[200:203], v147 offset:54272
	ds_read_b128 v[208:211], v147 offset:55296
	ds_read_b128 v[212:215], v147 offset:56320
	global_load_lds_dwordx4 v[204:205], off
	s_add_i32 m0, s58, 0x2000
	s_add_u32 s56, s56, 0xb0080
	v_lshl_add_u64 v[204:205], v[216:217], 0, s[20:21]
	s_addc_u32 s57, s57, 0
	s_add_i32 s58, s95, s66
	global_load_lds_dwordx4 v[204:205], off
	v_lshl_add_u64 v[204:205], s[56:57], 0, v[130:131]
	s_mov_b32 m0, s58
	s_nop 0
	global_load_lds_dwordx4 v[204:205], off
	v_lshl_add_u64 v[204:205], s[56:57], 0, v[134:135]
	s_add_i32 m0, s58, 0x2000
	s_nop 0
	global_load_lds_dwordx4 v[204:205], off
	v_lshl_add_u64 v[204:205], v[218:219], 0, s[20:21]
	s_mov_b32 m0, s75
	s_nop 0
	global_load_lds_dwordx4 v[204:205], off
	v_lshl_add_u64 v[204:205], v[220:221], 0, s[20:21]
	s_mov_b32 m0, s76
	s_nop 0
	global_load_lds_dwordx4 v[204:205], off
	s_waitcnt vmcnt(8)
	s_waitcnt lgkmcnt(0)
	s_barrier
	s_setprio 1
	s_waitcnt lgkmcnt(0)
	v_mfma_f32_16x16x32_bf16 v[60:63], v[148:151], v[180:183], v[60:63]
	v_mfma_f32_16x16x32_bf16 v[56:59], v[156:159], v[180:183], v[56:59]
	v_mfma_f32_16x16x32_bf16 v[52:55], v[148:151], v[188:191], v[52:55]
	v_mfma_f32_16x16x32_bf16 v[48:51], v[156:159], v[188:191], v[48:51]
	v_mfma_f32_16x16x32_bf16 v[36:39], v[148:151], v[196:199], v[36:39]
	v_mfma_f32_16x16x32_bf16 v[32:35], v[156:159], v[196:199], v[32:35]
	v_mfma_f32_16x16x32_bf16 v[20:23], v[148:151], v[208:211], v[20:23]
	v_mfma_f32_16x16x32_bf16 v[16:19], v[156:159], v[208:211], v[16:19]
	v_mfma_f32_16x16x32_bf16 v[60:63], v[152:155], v[184:187], v[60:63]
	v_mfma_f32_16x16x32_bf16 v[56:59], v[160:163], v[184:187], v[56:59]
	v_mfma_f32_16x16x32_bf16 v[52:55], v[152:155], v[192:195], v[52:55]
	v_mfma_f32_16x16x32_bf16 v[48:51], v[160:163], v[192:195], v[48:51]
	v_mfma_f32_16x16x32_bf16 v[36:39], v[152:155], v[200:203], v[36:39]
	v_mfma_f32_16x16x32_bf16 v[32:35], v[160:163], v[200:203], v[32:35]
	v_mfma_f32_16x16x32_bf16 v[20:23], v[152:155], v[212:215], v[20:23]
	v_mfma_f32_16x16x32_bf16 v[16:19], v[160:163], v[212:215], v[16:19]
	s_setprio 0
	s_setprio 1
	v_mfma_f32_16x16x32_bf16 v[44:47], v[164:167], v[180:183], v[44:47]
	v_mfma_f32_16x16x32_bf16 v[40:43], v[172:175], v[180:183], v[40:43]
	v_mfma_f32_16x16x32_bf16 v[28:31], v[164:167], v[188:191], v[28:31]
	v_mfma_f32_16x16x32_bf16 v[24:27], v[172:175], v[188:191], v[24:27]
	v_mfma_f32_16x16x32_bf16 v[12:15], v[164:167], v[196:199], v[12:15]
	v_mfma_f32_16x16x32_bf16 v[8:11], v[172:175], v[196:199], v[8:11]
	v_mfma_f32_16x16x32_bf16 v[4:7], v[164:167], v[208:211], v[4:7]
	v_mfma_f32_16x16x32_bf16 v[0:3], v[172:175], v[208:211], v[0:3]
	v_mfma_f32_16x16x32_bf16 v[44:47], v[168:171], v[184:187], v[44:47]
	v_mfma_f32_16x16x32_bf16 v[40:43], v[176:179], v[184:187], v[40:43]
	v_mfma_f32_16x16x32_bf16 v[28:31], v[168:171], v[192:195], v[28:31]
	v_mfma_f32_16x16x32_bf16 v[24:27], v[176:179], v[192:195], v[24:27]
	v_mfma_f32_16x16x32_bf16 v[12:15], v[168:171], v[200:203], v[12:15]
	v_mfma_f32_16x16x32_bf16 v[8:11], v[176:179], v[200:203], v[8:11]
	v_mfma_f32_16x16x32_bf16 v[4:7], v[168:171], v[212:215], v[4:7]
	v_mfma_f32_16x16x32_bf16 v[0:3], v[176:179], v[212:215], v[0:3]
	s_setprio 0
	s_barrier
	s_add_i32 s93, s93, 2
	s_add_u32 s46, s46, 0x100
	s_addc_u32 s47, s47, 0
	s_add_u32 s91, s91, 0x100
	s_addc_u32 s92, s92, 0
	s_cmp_gt_u32 s93, 41
	s_cbranch_scc0 .LBB0_1163
	s_branch .Lpeel_exit_8

;     __device__ __forceinline__ bool next(int i, Unit& u) const { if (i != 0) return false; const int c0 = (G >= 8) ? G - 5 : G - 2; int k = -1; if (c == c0) k = 0; else if (c == G - 1) k = 1; if (k < 0 || k >= n) return false; u.pm = k; u.pn = 0; return true; }
; #define PG8_STAGE(bufoff, gbase, voff) do { _Pragma("unroll") for (int _i = 0; _i < 2; ++_i) \
;         __builtin_amdgcn_global_load_lds((const unsigned*)((const char*)(gbase) + (voff)[_i]), (PG8_LAS unsigned*)(lds + (bufoff) + ldsw + _i * 8192), 16, 0, 0); } while (0)
; #define PG8_LDA(dst, b, h) do { _Pragma("unroll") for (int m = 0; m < 4; ++m) _Pragma("unroll") for (int k = 0; k < 2; ++k) dst[m][k] = *(const PG8_LAS bf16x8*)(lds + PG8_SA(b, h) + aoff + m * 2048 + k * 1024); } while (0)
; #define PG8_LDB(dst, b, h) do { _Pragma("unroll") for (int n = 0; n < 2; ++n) _Pragma("unroll") for (int k = 0; k < 2; ++k) dst[n][k] = *(const PG8_LAS bf16x8*)(lds + PG8_SB(b, h) + boff + n * 2048 + k * 1024); } while (0)
; template <class Epi, class Sched, bool ALIGN_EPI = false, bool SP2 = false>
; __device__ __forceinline__ void gemm_phase(PG8_LAS unsigned char* lds, const Gemm g, const Sched& S, const Epi& E) {
;     ...
;         const bool has_next = S.next(ui + 1, nxt);
;         const char* nA = has_next ? (const char*)g.A + (size_t)nxt.pm * tstep : cA; const char* nB = has_next ? (const char*)g.Bt + (size_t)nxt.pn * tstep : cB;
;         for (int t = 0; t < nt; t += 2) {
;             const bool last = (t == nt - 2);
;             const char* a1 = cA + (size_t)(t + 1) * kstep;
;             const char* a2 = last ? nA : cA + (size_t)(t + 2) * kstep; const char* b2 = last ? nB : cB + (size_t)(t + 2) * kstep;
;             const char* a3 = a2 + kstep; const char* b3 = b2 + kstep;
;             if (last && has_next) S.a_ready(nxt);
;             if constexpr (SP2) {
;             PG8_LDB(B0, 0, 0); PG8_LDB(B1, 0, 1); PG8_SCHED; PG8_LDA(At, 0, 0); PG8_STAGE(PG8_SA(1, 1), a1 + hstep, voffA);
;             PG8_WAIT_V(8); PG8_WAIT_L(0); PG8_BAR; PG8_MMA(0, 0, At, B0); PG8_MMA(0, 1, At, B1); PG8_BAR; PG8_SCHED;
;             PG8_LDA(At, 0, 1); PG8_STAGE(PG8_SB(0, 0), b2, voffB); PG8_STAGE(PG8_SB(0, 1), b2 + hstep, voffB); PG8_STAGE(PG8_SA(0, 0), a2, voffA);
;             PG8_WAIT_V(8); PG8_WAIT_L(0); PG8_BAR; PG8_MMA(1, 0, At, B0); PG8_MMA(1, 1, At, B1); PG8_BAR; PG8_SCHED;
.LBB0_1348:
	s_ashr_i32 s25, s24, 31
	s_lshl_b64 s[28:29], s[24:25], 19
	s_add_u32 s28, s97, s28
	s_addc_u32 s29, s3, s29
	s_and_b64 s[30:31], s[26:27], exec
	s_cselect_b32 s25, s29, s39
	s_cselect_b32 s73, s28, s38
	s_ashr_i32 s23, s22, 31
	s_lshl_b64 s[30:31], s[22:23], 19
	s_add_u32 s30, s36, s30
	s_addc_u32 s31, s37, s31
	s_and_b64 s[42:43], s[26:27], exec
	s_cselect_b32 s23, s31, s41
	s_cselect_b32 s74, s30, s40
	s_add_u32 s38, s38, 0x40080
	s_addc_u32 s39, s39, 0
	s_add_u32 s75, s40, 0x100
	v_mov_b32_e32 v0, 0
	s_addc_u32 s76, s41, 0
	s_mov_b32 s77, -2
	ds_read_b128 v[148:151], v145
	ds_read_b128 v[152:155], v145 offset:1024
	ds_read_b128 v[156:159], v145 offset:2048
	ds_read_b128 v[160:163], v145 offset:3072
	ds_read_b128 v[164:167], v146
	ds_read_b128 v[168:171], v146 offset:1024
	ds_read_b128 v[172:175], v146 offset:2048
	ds_read_b128 v[176:179], v146 offset:3072
	s_add_u32 s40, s38, 0xfffc0080
	s_addc_u32 s41, s39, -1
	s_cmp_eq_u32 s77, 12
	s_cselect_b32 s43, s25, s41
	s_cselect_b32 s42, s73, s40
	s_cselect_b32 s41, s23, s76
	s_cselect_b32 s40, s74, s75
	v_lshl_add_u64 v[204:205], s[38:39], 0, v[136:137]
	s_add_i32 m0, s56, 0xc000
	ds_read_b128 v[180:183], v147
	ds_read_b128 v[184:187], v147 offset:1024
	ds_read_b128 v[188:191], v147 offset:2048
	ds_read_b128 v[192:195], v147 offset:3072
	ds_read_b128 v[196:199], v147 offset:4096
	ds_read_b128 v[200:203], v147 offset:5120
	ds_read_b128 v[208:211], v147 offset:6144
	ds_read_b128 v[212:215], v147 offset:7168
	global_load_lds_dwordx4 v[204:205], off
	v_lshl_add_u64 v[204:205], s[38:39], 0, v[138:139]
	s_add_i32 m0, s56, 0xe000
	s_nop 0
	global_load_lds_dwordx4 v[204:205], off
	s_waitcnt vmcnt(8)
	s_waitcnt lgkmcnt(0)
	s_barrier
	s_setprio 1
	s_waitcnt lgkmcnt(0)
	v_mfma_f32_16x16x32_bf16 v[124:127], v[148:151], v[180:183], 0
	v_mfma_f32_16x16x32_bf16 v[120:123], v[156:159], v[180:183], 0
	v_mfma_f32_16x16x32_bf16 v[112:115], v[148:151], v[188:191], 0
	v_mfma_f32_16x16x32_bf16 v[104:107], v[156:159], v[188:191], 0
	v_mfma_f32_16x16x32_bf16 v[96:99], v[148:151], v[196:199], 0
	v_mfma_f32_16x16x32_bf16 v[88:91], v[156:159], v[196:199], 0
	v_mfma_f32_16x16x32_bf16 v[80:83], v[148:151], v[208:211], 0
	v_mfma_f32_16x16x32_bf16 v[72:75], v[156:159], v[208:211], 0
	v_mfma_f32_16x16x32_bf16 v[124:127], v[152:155], v[184:187], v[124:127]
	v_mfma_f32_16x16x32_bf16 v[120:123], v[160:163], v[184:187], v[120:123]
	v_mfma_f32_16x16x32_bf16 v[112:115], v[152:155], v[192:195], v[112:115]
	v_mfma_f32_16x16x32_bf16 v[104:107], v[160:163], v[192:195], v[104:107]
	v_mfma_f32_16x16x32_bf16 v[96:99], v[152:155], v[200:203], v[96:99]
	v_mfma_f32_16x16x32_bf16 v[88:91], v[160:163], v[200:203], v[88:91]
	v_mfma_f32_16x16x32_bf16 v[80:83], v[152:155], v[212:215], v[80:83]
	v_mfma_f32_16x16x32_bf16 v[72:75], v[160:163], v[212:215], v[72:75]
	s_setprio 0
	s_setprio 1
	v_mfma_f32_16x16x32_bf16 v[116:119], v[164:167], v[180:183], 0
	v_mfma_f32_16x16x32_bf16 v[108:111], v[172:175], v[180:183], 0
	v_mfma_f32_16x16x32_bf16 v[100:103], v[164:167], v[188:191], 0
	v_mfma_f32_16x16x32_bf16 v[92:95], v[172:175], v[188:191], 0
	v_mfma_f32_16x16x32_bf16 v[84:87], v[164:167], v[196:199], 0
	v_mfma_f32_16x16x32_bf16 v[76:79], v[172:175], v[196:199], 0
	v_mfma_f32_16x16x32_bf16 v[68:71], v[164:167], v[208:211], 0
	v_mfma_f32_16x16x32_bf16 v[64:67], v[172:175], v[208:211], 0
	v_mfma_f32_16x16x32_bf16 v[116:119], v[168:171], v[184:187], v[116:119]
	v_mfma_f32_16x16x32_bf16 v[108:111], v[176:179], v[184:187], v[108:111]
	v_mfma_f32_16x16x32_bf16 v[100:103], v[168:171], v[192:195], v[100:103]
	v_mfma_f32_16x16x32_bf16 v[92:95], v[176:179], v[192:195], v[92:95]
	v_mfma_f32_16x16x32_bf16 v[84:87], v[168:171], v[200:203], v[84:87]
	v_mfma_f32_16x16x32_bf16 v[76:79], v[176:179], v[200:203], v[76:79]
	v_mfma_f32_16x16x32_bf16 v[68:71], v[168:171], v[212:215], v[68:71]
	v_mfma_f32_16x16x32_bf16 v[64:67], v[176:179], v[212:215], v[64:67]
	s_setprio 0
	s_barrier
	s_add_i32 s78, s67, s47
	v_lshl_add_u64 v[204:205], s[40:41], 0, v[130:131]
	s_mov_b32 m0, s78
	ds_read_b128 v[180:183], v147 offset:16384
	ds_read_b128 v[184:187], v147 offset:17408
	ds_read_b128 v[188:191], v147 offset:18432
	ds_read_b128 v[192:195], v147 offset:19456
	ds_read_b128 v[196:199], v147 offset:20480
	ds_read_b128 v[200:203], v147 offset:21504
	ds_read_b128 v[208:211], v147 offset:22528
	ds_read_b128 v[212:215], v147 offset:23552
	global_load_lds_dwordx4 v[204:205], off
	s_add_i32 m0, s78, 0x2000
	s_add_u32 s78, s40, 0x40000
	v_lshl_add_u64 v[216:217], s[40:41], 0, v[134:135]
	s_addc_u32 s79, s41, 0
	s_add_i32 s80, s68, s47
	global_load_lds_dwordx4 v[216:217], off
	v_lshl_add_u64 v[218:219], s[78:79], 0, v[130:131]
	s_mov_b32 m0, s80
	v_lshl_add_u64 v[220:221], s[42:43], 0, v[132:133]
	global_load_lds_dwordx4 v[218:219], off
	v_lshl_add_u64 v[218:219], s[78:79], 0, v[134:135]
	s_add_i32 m0, s80, 0x2000
	s_nop 0
	global_load_lds_dwordx4 v[218:219], off
	v_lshl_add_u64 v[218:219], s[42:43], 0, v[128:129]
	s_mov_b32 m0, s56
	s_nop 0
	global_load_lds_dwordx4 v[218:219], off
	s_mov_b32 m0, s57
	s_nop 0
	global_load_lds_dwordx4 v[220:221], off
	s_waitcnt vmcnt(8)
	s_waitcnt lgkmcnt(0)
	s_barrier
; #define PG8_STAGE(bufoff, gbase, voff) do { _Pragma("unroll") for (int _i = 0; _i < 2; ++_i) \
;         __builtin_amdgcn_global_load_lds((const unsigned*)((const char*)(gbase) + (voff)[_i]), (PG8_LAS unsigned*)(lds + (bufoff) + ldsw + _i * 8192), 16, 0, 0); } while (0)
; #define PG8_LDA(dst, b, h) do { _Pragma("unroll") for (int m = 0; m < 4; ++m) _Pragma("unroll") for (int k = 0; k < 2; ++k) dst[m][k] = *(const PG8_LAS bf16x8*)(lds + PG8_SA(b, h) + aoff + m * 2048 + k * 1024); } while (0)
; #define PG8_LDB(dst, b, h) do { _Pragma("unroll") for (int n = 0; n < 2; ++n) _Pragma("unroll") for (int k = 0; k < 2; ++k) dst[n][k] = *(const PG8_LAS bf16x8*)(lds + PG8_SB(b, h) + boff + n * 2048 + k * 1024); } while (0)
; #define PG8_MMA(ai, bj, At, Bt) do { __builtin_amdgcn_s_setprio(1); _Pragma("unroll") for (int m = 0; m < 4; ++m) _Pragma("unroll") for (int n = 0; n < 2; ++n) _Pragma("unroll") for (int k = 0; k < 2; ++k) \
;         acc[ai][bj][m][n] = __builtin_amdgcn_mfma_f32_16x16x32_bf16(Bt[n][k], At[m][k], acc[ai][bj][m][n], 0, 0, 0); __builtin_amdgcn_s_setprio(0); } while (0)
; #define PG8_WAIT_V(n) asm volatile("s_waitcnt vmcnt(" #n ")" ::: "memory")
; #define PG8_WAIT_L(n) asm volatile("s_waitcnt lgkmcnt(" #n ")" ::: "memory")
; #define PG8_BAR __builtin_amdgcn_s_barrier()
; #define PG8_SCHED __builtin_amdgcn_sched_barrier(0)
; template <class Epi, class Sched, bool ALIGN_EPI = false, bool SP2 = false>
; __device__ __forceinline__ void gemm_phase(PG8_LAS unsigned char* lds, const Gemm g, const Sched& S, const Epi& E) {
;     ...
;             PG8_WAIT_V(8); PG8_WAIT_L(0); PG8_BAR; PG8_MMA(1, 0, At, B0); PG8_MMA(1, 1, At, B1); PG8_BAR; PG8_SCHED;
;             PG8_LDB(B0, 1, 0); PG8_LDB(B1, 1, 1); PG8_SCHED; PG8_LDA(At, 1, 0); PG8_STAGE(PG8_SA(0, 1), a2 + hstep, voffA);
;             PG8_WAIT_V(8); PG8_WAIT_L(0); PG8_BAR; PG8_MMA(0, 0, At, B0); PG8_MMA(0, 1, At, B1); PG8_BAR; PG8_SCHED;
	s_setprio 1
	s_waitcnt lgkmcnt(0)
	v_mfma_f32_16x16x32_bf16 v[60:63], v[148:151], v[180:183], 0
	v_mfma_f32_16x16x32_bf16 v[56:59], v[156:159], v[180:183], 0
	v_mfma_f32_16x16x32_bf16 v[48:51], v[148:151], v[188:191], 0
	v_mfma_f32_16x16x32_bf16 v[40:43], v[156:159], v[188:191], 0
	v_mfma_f32_16x16x32_bf16 v[32:35], v[148:151], v[196:199], 0
	v_mfma_f32_16x16x32_bf16 v[24:27], v[156:159], v[196:199], 0
	v_mfma_f32_16x16x32_bf16 v[16:19], v[148:151], v[208:211], 0
	v_mfma_f32_16x16x32_bf16 v[8:11], v[156:159], v[208:211], 0
	v_mfma_f32_16x16x32_bf16 v[60:63], v[152:155], v[184:187], v[60:63]
	v_mfma_f32_16x16x32_bf16 v[56:59], v[160:163], v[184:187], v[56:59]
	v_mfma_f32_16x16x32_bf16 v[48:51], v[152:155], v[192:195], v[48:51]
	v_mfma_f32_16x16x32_bf16 v[40:43], v[160:163], v[192:195], v[40:43]
	v_mfma_f32_16x16x32_bf16 v[32:35], v[152:155], v[200:203], v[32:35]
	v_mfma_f32_16x16x32_bf16 v[24:27], v[160:163], v[200:203], v[24:27]
	v_mfma_f32_16x16x32_bf16 v[16:19], v[152:155], v[212:215], v[16:19]
	v_mfma_f32_16x16x32_bf16 v[8:11], v[160:163], v[212:215], v[8:11]
	s_setprio 0
	s_setprio 1
	v_mfma_f32_16x16x32_bf16 v[52:55], v[164:167], v[180:183], 0
	v_mfma_f32_16x16x32_bf16 v[44:47], v[172:175], v[180:183], 0
	v_mfma_f32_16x16x32_bf16 v[36:39], v[164:167], v[188:191], 0
	v_mfma_f32_16x16x32_bf16 v[28:31], v[172:175], v[188:191], 0
	v_mfma_f32_16x16x32_bf16 v[20:23], v[164:167], v[196:199], 0
	v_mfma_f32_16x16x32_bf16 v[12:15], v[172:175], v[196:199], 0
	v_mfma_f32_16x16x32_bf16 v[4:7], v[164:167], v[208:211], 0
	v_mfma_f32_16x16x32_bf16 v[0:3], v[172:175], v[208:211], 0
	v_mfma_f32_16x16x32_bf16 v[52:55], v[168:171], v[184:187], v[52:55]
	v_mfma_f32_16x16x32_bf16 v[44:47], v[176:179], v[184:187], v[44:47]
	v_mfma_f32_16x16x32_bf16 v[36:39], v[168:171], v[192:195], v[36:39]
	v_mfma_f32_16x16x32_bf16 v[28:31], v[176:179], v[192:195], v[28:31]
	v_mfma_f32_16x16x32_bf16 v[20:23], v[168:171], v[200:203], v[20:23]
	v_mfma_f32_16x16x32_bf16 v[12:15], v[176:179], v[200:203], v[12:15]
	v_mfma_f32_16x16x32_bf16 v[4:7], v[168:171], v[212:215], v[4:7]
	v_mfma_f32_16x16x32_bf16 v[0:3], v[176:179], v[212:215], v[0:3]
	s_setprio 0
	s_barrier
	s_add_i32 s78, 0, 0x18000
	s_add_i32 s79, 0, 0x1c000
	v_add_u32_e32 v160, s78, v143
	v_add_u32_e32 v176, s79, v143
	ds_read_b128 v[148:151], v160
	ds_read_b128 v[152:155], v160 offset:1024
	ds_read_b128 v[156:159], v160 offset:2048
	ds_read_b128 v[160:163], v160 offset:3072
	ds_read_b128 v[164:167], v176
	ds_read_b128 v[168:171], v176 offset:1024
	ds_read_b128 v[172:175], v176 offset:2048
	ds_read_b128 v[176:179], v176 offset:3072
	s_add_u32 s42, s42, 0x40000
	s_addc_u32 s43, s43, 0
	s_mov_b32 m0, s58
	v_lshl_add_u64 v[222:223], s[42:43], 0, v[128:129]
	ds_read_b128 v[180:183], v147 offset:32768
	ds_read_b128 v[184:187], v147 offset:33792
	ds_read_b128 v[188:191], v147 offset:34816
	ds_read_b128 v[192:195], v147 offset:35840
	ds_read_b128 v[196:199], v147 offset:36864
	ds_read_b128 v[200:203], v147 offset:37888
	ds_read_b128 v[208:211], v147 offset:38912
	ds_read_b128 v[212:215], v147 offset:39936
	global_load_lds_dwordx4 v[222:223], off
	v_lshl_add_u64 v[222:223], s[42:43], 0, v[132:133]
	s_mov_b32 m0, s59
	s_nop 0
	global_load_lds_dwordx4 v[222:223], off
	s_waitcnt vmcnt(8)
	s_waitcnt lgkmcnt(0)
	s_barrier
	s_setprio 1
	s_waitcnt lgkmcnt(0)
	v_mfma_f32_16x16x32_bf16 v[124:127], v[148:151], v[180:183], v[124:127]
	v_mfma_f32_16x16x32_bf16 v[120:123], v[156:159], v[180:183], v[120:123]
	v_mfma_f32_16x16x32_bf16 v[112:115], v[148:151], v[188:191], v[112:115]
	v_mfma_f32_16x16x32_bf16 v[104:107], v[156:159], v[188:191], v[104:107]
	v_mfma_f32_16x16x32_bf16 v[96:99], v[148:151], v[196:199], v[96:99]
	v_mfma_f32_16x16x32_bf16 v[88:91], v[156:159], v[196:199], v[88:91]
	v_mfma_f32_16x16x32_bf16 v[80:83], v[148:151], v[208:211], v[80:83]
	v_mfma_f32_16x16x32_bf16 v[72:75], v[156:159], v[208:211], v[72:75]
	v_mfma_f32_16x16x32_bf16 v[124:127], v[152:155], v[184:187], v[124:127]
	v_mfma_f32_16x16x32_bf16 v[120:123], v[160:163], v[184:187], v[120:123]
	v_mfma_f32_16x16x32_bf16 v[112:115], v[152:155], v[192:195], v[112:115]
	v_mfma_f32_16x16x32_bf16 v[104:107], v[160:163], v[192:195], v[104:107]
	v_mfma_f32_16x16x32_bf16 v[96:99], v[152:155], v[200:203], v[96:99]
	v_mfma_f32_16x16x32_bf16 v[88:91], v[160:163], v[200:203], v[88:91]
	v_mfma_f32_16x16x32_bf16 v[80:83], v[152:155], v[212:215], v[80:83]
	v_mfma_f32_16x16x32_bf16 v[72:75], v[160:163], v[212:215], v[72:75]
	s_setprio 0
	s_setprio 1
	v_mfma_f32_16x16x32_bf16 v[116:119], v[164:167], v[180:183], v[116:119]
	v_mfma_f32_16x16x32_bf16 v[108:111], v[172:175], v[180:183], v[108:111]
	v_mfma_f32_16x16x32_bf16 v[100:103], v[164:167], v[188:191], v[100:103]
	v_mfma_f32_16x16x32_bf16 v[92:95], v[172:175], v[188:191], v[92:95]
	v_mfma_f32_16x16x32_bf16 v[84:87], v[164:167], v[196:199], v[84:87]
	v_mfma_f32_16x16x32_bf16 v[76:79], v[172:175], v[196:199], v[76:79]
	v_mfma_f32_16x16x32_bf16 v[68:71], v[164:167], v[208:211], v[68:71]
	v_mfma_f32_16x16x32_bf16 v[64:67], v[172:175], v[208:211], v[64:67]
	v_mfma_f32_16x16x32_bf16 v[116:119], v[168:171], v[184:187], v[116:119]
	v_mfma_f32_16x16x32_bf16 v[108:111], v[176:179], v[184:187], v[108:111]
	v_mfma_f32_16x16x32_bf16 v[100:103], v[168:171], v[192:195], v[100:103]
	v_mfma_f32_16x16x32_bf16 v[92:95], v[176:179], v[192:195], v[92:95]
	v_mfma_f32_16x16x32_bf16 v[84:87], v[168:171], v[200:203], v[84:87]
	v_mfma_f32_16x16x32_bf16 v[76:79], v[176:179], v[200:203], v[76:79]
	v_mfma_f32_16x16x32_bf16 v[68:71], v[168:171], v[212:215], v[68:71]
	v_mfma_f32_16x16x32_bf16 v[64:67], v[176:179], v[212:215], v[64:67]
	s_setprio 0
	s_barrier
; #define PG8_STAGE(bufoff, gbase, voff) do { _Pragma("unroll") for (int _i = 0; _i < 2; ++_i) \
;         __builtin_amdgcn_global_load_lds((const unsigned*)((const char*)(gbase) + (voff)[_i]), (PG8_LAS unsigned*)(lds + (bufoff) + ldsw + _i * 8192), 16, 0, 0); } while (0)
; #define PG8_LDA(dst, b, h) do { _Pragma("unroll") for (int m = 0; m < 4; ++m) _Pragma("unroll") for (int k = 0; k < 2; ++k) dst[m][k] = *(const PG8_LAS bf16x8*)(lds + PG8_SA(b, h) + aoff + m * 2048 + k * 1024); } while (0)
; #define PG8_MMA(ai, bj, At, Bt) do { __builtin_amdgcn_s_setprio(1); _Pragma("unroll") for (int m = 0; m < 4; ++m) _Pragma("unroll") for (int n = 0; n < 2; ++n) _Pragma("unroll") for (int k = 0; k < 2; ++k) \
;         acc[ai][bj][m][n] = __builtin_amdgcn_mfma_f32_16x16x32_bf16(Bt[n][k], At[m][k], acc[ai][bj][m][n], 0, 0, 0); __builtin_amdgcn_s_setprio(0); } while (0)
; #define PG8_WAIT_V(n) asm volatile("s_waitcnt vmcnt(" #n ")" ::: "memory")
; #define PG8_WAIT_L(n) asm volatile("s_waitcnt lgkmcnt(" #n ")" ::: "memory")
; #define PG8_BAR __builtin_amdgcn_s_barrier()
; #define PG8_SCHED __builtin_amdgcn_sched_barrier(0)
; template <class Epi, class Sched, bool ALIGN_EPI = false, bool SP2 = false>
; __device__ __forceinline__ void gemm_phase(PG8_LAS unsigned char* lds, const Gemm g, const Sched& S, const Epi& E) {
;     ...
;         for (int t = 0; t < nt; t += 2) {
;             const bool last = (t == nt - 2);
;             const char* a1 = cA + (size_t)(t + 1) * kstep;
;             const char* a2 = last ? nA : cA + (size_t)(t + 2) * kstep; const char* b2 = last ? nB : cB + (size_t)(t + 2) * kstep;
;             const char* a3 = a2 + kstep; const char* b3 = b2 + kstep;
;     ...
;             PG8_LDA(At, 1, 1); PG8_STAGE(PG8_SB(1, 0), b3, voffB); PG8_STAGE(PG8_SB(1, 1), b3 + hstep, voffB); PG8_STAGE(PG8_SA(1, 0), a3, voffA);
;             PG8_WAIT_V(8); PG8_WAIT_L(0); PG8_BAR; PG8_MMA(1, 0, At, B0); PG8_MMA(1, 1, At, B1); PG8_BAR; PG8_SCHED;
	s_add_i32 s42, s78, s47
	v_lshl_add_u64 v[204:205], v[204:205], 0, s[8:9]
	s_mov_b32 m0, s42
	ds_read_b128 v[180:183], v147 offset:49152
	ds_read_b128 v[184:187], v147 offset:50176
	ds_read_b128 v[188:191], v147 offset:51200
	ds_read_b128 v[192:195], v147 offset:52224
	ds_read_b128 v[196:199], v147 offset:53248
	ds_read_b128 v[200:203], v147 offset:54272
	ds_read_b128 v[208:211], v147 offset:55296
	ds_read_b128 v[212:215], v147 offset:56320
	global_load_lds_dwordx4 v[204:205], off
	s_add_i32 m0, s42, 0x2000
	s_add_u32 s40, s40, 0x40080
	v_lshl_add_u64 v[204:205], v[216:217], 0, s[8:9]
	s_addc_u32 s41, s41, 0
	s_add_i32 s42, s79, s47
	global_load_lds_dwordx4 v[204:205], off
	v_lshl_add_u64 v[204:205], s[40:41], 0, v[130:131]
	s_mov_b32 m0, s42
	s_nop 0
	global_load_lds_dwordx4 v[204:205], off
	v_lshl_add_u64 v[204:205], s[40:41], 0, v[134:135]
	s_add_i32 m0, s42, 0x2000
	s_nop 0
	global_load_lds_dwordx4 v[204:205], off
	v_lshl_add_u64 v[204:205], v[218:219], 0, s[8:9]
	s_mov_b32 m0, s64
	s_nop 0
	global_load_lds_dwordx4 v[204:205], off
	v_lshl_add_u64 v[204:205], v[220:221], 0, s[8:9]
	s_mov_b32 m0, s65
	s_nop 0
	global_load_lds_dwordx4 v[204:205], off
	s_waitcnt vmcnt(8)
	s_waitcnt lgkmcnt(0)
	s_barrier
	s_setprio 1
	s_waitcnt lgkmcnt(0)
	v_mfma_f32_16x16x32_bf16 v[60:63], v[148:151], v[180:183], v[60:63]
	v_mfma_f32_16x16x32_bf16 v[56:59], v[156:159], v[180:183], v[56:59]
	v_mfma_f32_16x16x32_bf16 v[48:51], v[148:151], v[188:191], v[48:51]
	v_mfma_f32_16x16x32_bf16 v[40:43], v[156:159], v[188:191], v[40:43]
	v_mfma_f32_16x16x32_bf16 v[32:35], v[148:151], v[196:199], v[32:35]
	v_mfma_f32_16x16x32_bf16 v[24:27], v[156:159], v[196:199], v[24:27]
	v_mfma_f32_16x16x32_bf16 v[16:19], v[148:151], v[208:211], v[16:19]
	v_mfma_f32_16x16x32_bf16 v[8:11], v[156:159], v[208:211], v[8:11]
	v_mfma_f32_16x16x32_bf16 v[60:63], v[152:155], v[184:187], v[60:63]
	v_mfma_f32_16x16x32_bf16 v[56:59], v[160:163], v[184:187], v[56:59]
	v_mfma_f32_16x16x32_bf16 v[48:51], v[152:155], v[192:195], v[48:51]
	v_mfma_f32_16x16x32_bf16 v[40:43], v[160:163], v[192:195], v[40:43]
	v_mfma_f32_16x16x32_bf16 v[32:35], v[152:155], v[200:203], v[32:35]
	v_mfma_f32_16x16x32_bf16 v[24:27], v[160:163], v[200:203], v[24:27]
	v_mfma_f32_16x16x32_bf16 v[16:19], v[152:155], v[212:215], v[16:19]
	v_mfma_f32_16x16x32_bf16 v[8:11], v[160:163], v[212:215], v[8:11]
	s_setprio 0
	s_setprio 1
	v_mfma_f32_16x16x32_bf16 v[52:55], v[164:167], v[180:183], v[52:55]
	v_mfma_f32_16x16x32_bf16 v[44:47], v[172:175], v[180:183], v[44:47]
	v_mfma_f32_16x16x32_bf16 v[36:39], v[164:167], v[188:191], v[36:39]
	v_mfma_f32_16x16x32_bf16 v[28:31], v[172:175], v[188:191], v[28:31]
	v_mfma_f32_16x16x32_bf16 v[20:23], v[164:167], v[196:199], v[20:23]
	v_mfma_f32_16x16x32_bf16 v[12:15], v[172:175], v[196:199], v[12:15]
	v_mfma_f32_16x16x32_bf16 v[4:7], v[164:167], v[208:211], v[4:7]
	v_mfma_f32_16x16x32_bf16 v[0:3], v[172:175], v[208:211], v[0:3]
	v_mfma_f32_16x16x32_bf16 v[52:55], v[168:171], v[184:187], v[52:55]
	v_mfma_f32_16x16x32_bf16 v[44:47], v[176:179], v[184:187], v[44:47]
	v_mfma_f32_16x16x32_bf16 v[36:39], v[168:171], v[192:195], v[36:39]
	v_mfma_f32_16x16x32_bf16 v[28:31], v[176:179], v[192:195], v[28:31]
	v_mfma_f32_16x16x32_bf16 v[20:23], v[168:171], v[200:203], v[20:23]
	v_mfma_f32_16x16x32_bf16 v[12:15], v[176:179], v[200:203], v[12:15]
	v_mfma_f32_16x16x32_bf16 v[4:7], v[168:171], v[212:215], v[4:7]
	v_mfma_f32_16x16x32_bf16 v[0:3], v[176:179], v[212:215], v[0:3]
	s_setprio 0
	s_barrier
	s_add_i32 s77, s77, 2
	s_add_u32 s38, s38, 0x100
	s_addc_u32 s39, s39, 0
	s_add_u32 s75, s75, 0x100
	s_addc_u32 s76, s76, 0
	s_cmp_gt_u32 s77, 13
	s_cbranch_scc0 .LBB0_1349
	s_branch .Lpeel_exit_9

;     __device__ __forceinline__ bool next(int i, Unit& u) const { if (i != 0) return false; const int c0 = (G >= 8) ? G - 5 : G - 2; int k = -1; if (c == c0) k = 0; else if (c == G - 1) k = 1; if (k < 0 || k >= n) return false; u.pm = k; u.pn = 0; return true; }
; #define PG8_STAGE(bufoff, gbase, voff) do { _Pragma("unroll") for (int _i = 0; _i < 2; ++_i) \
;         __builtin_amdgcn_global_load_lds((const unsigned*)((const char*)(gbase) + (voff)[_i]), (PG8_LAS unsigned*)(lds + (bufoff) + ldsw + _i * 8192), 16, 0, 0); } while (0)
; #define PG8_LDA(dst, b, h) do { _Pragma("unroll") for (int m = 0; m < 4; ++m) _Pragma("unroll") for (int k = 0; k < 2; ++k) dst[m][k] = *(const PG8_LAS bf16x8*)(lds + PG8_SA(b, h) + aoff + m * 2048 + k * 1024); } while (0)
; #define PG8_LDB(dst, b, h) do { _Pragma("unroll") for (int n = 0; n < 2; ++n) _Pragma("unroll") for (int k = 0; k < 2; ++k) dst[n][k] = *(const PG8_LAS bf16x8*)(lds + PG8_SB(b, h) + boff + n * 2048 + k * 1024); } while (0)
; template <class Epi, class Sched, bool ALIGN_EPI = false, bool SP2 = false>
; __device__ __forceinline__ void gemm_phase(PG8_LAS unsigned char* lds, const Gemm g, const Sched& S, const Epi& E) {
;     ...
;         const bool has_next = S.next(ui + 1, nxt);
;         const char* nA = has_next ? (const char*)g.A + (size_t)nxt.pm * tstep : cA; const char* nB = has_next ? (const char*)g.Bt + (size_t)nxt.pn * tstep : cB;
;         for (int t = 0; t < nt; t += 2) {
;             const bool last = (t == nt - 2);
;             const char* a1 = cA + (size_t)(t + 1) * kstep;
;             const char* a2 = last ? nA : cA + (size_t)(t + 2) * kstep; const char* b2 = last ? nB : cB + (size_t)(t + 2) * kstep;
;             const char* a3 = a2 + kstep; const char* b3 = b2 + kstep;
;             if (last && has_next) S.a_ready(nxt);
;             if constexpr (SP2) {
;             PG8_LDB(B0, 0, 0); PG8_LDB(B1, 0, 1); PG8_SCHED; PG8_LDA(At, 0, 0); PG8_STAGE(PG8_SA(1, 1), a1 + hstep, voffA);
;             PG8_WAIT_V(8); PG8_WAIT_L(0); PG8_BAR; PG8_MMA(0, 0, At, B0); PG8_MMA(0, 1, At, B1); PG8_BAR; PG8_SCHED;
;             PG8_LDA(At, 0, 1); PG8_STAGE(PG8_SB(0, 0), b2, voffB); PG8_STAGE(PG8_SB(0, 1), b2 + hstep, voffB); PG8_STAGE(PG8_SA(0, 0), a2, voffA);
;             PG8_WAIT_V(8); PG8_WAIT_L(0); PG8_BAR; PG8_MMA(1, 0, At, B0); PG8_MMA(1, 1, At, B1); PG8_BAR; PG8_SCHED;
.LBB0_1471:
	s_ashr_i32 s41, s40, 31
	s_lshl_b64 s[46:47], s[40:41], 19
	s_add_u32 s46, s97, s46
	s_addc_u32 s47, s3, s47
	s_and_b64 s[56:57], s[42:43], exec
	s_cselect_b32 s5, s47, s9
	s_cselect_b32 s7, s46, s8
	s_ashr_i32 s39, s38, 31
	s_lshl_b64 s[56:57], s[38:39], 19
	s_add_u32 s56, s64, s56
	s_addc_u32 s57, s65, s57
	s_and_b64 s[60:61], s[42:43], exec
	s_cselect_b32 s39, s57, s59
	s_cselect_b32 s41, s56, s58
	s_add_u32 s8, s8, 0x40080
	s_addc_u32 s9, s9, 0
	s_add_u32 s81, s58, 0x100
	v_mov_b32_e32 v0, 0
	s_addc_u32 s82, s59, 0
	s_mov_b32 s83, -2
	ds_read_b128 v[108:111], v210
	ds_read_b128 v[112:115], v210 offset:1024
	ds_read_b128 v[116:119], v210 offset:2048
	ds_read_b128 v[124:127], v210 offset:3072
	ds_read_b128 v[128:131], v211
	ds_read_b128 v[136:139], v211 offset:1024
	ds_read_b128 v[152:155], v211 offset:2048
	ds_read_b128 v[156:159], v211 offset:3072
	s_add_u32 s58, s8, 0xfffc0080
	s_addc_u32 s59, s9, -1
	s_cmp_eq_u32 s83, 12
	s_cselect_b32 s61, s5, s59
	s_cselect_b32 s60, s7, s58
	s_cselect_b32 s59, s39, s82
	s_cselect_b32 s58, s41, s81
	v_lshl_add_u64 v[176:177], s[8:9], 0, v[186:187]
	s_add_i32 m0, s67, 0xc000
	ds_read_b128 v[160:163], v212
	ds_read_b128 v[164:167], v212 offset:1024
	ds_read_b128 v[168:171], v212 offset:2048
	ds_read_b128 v[172:175], v212 offset:3072
	ds_read_b128 v[192:195], v212 offset:4096
	ds_read_b128 v[196:199], v212 offset:5120
	ds_read_b128 v[200:203], v212 offset:6144
	ds_read_b128 v[214:217], v212 offset:7168
	global_load_lds_dwordx4 v[176:177], off
	v_lshl_add_u64 v[176:177], s[8:9], 0, v[188:189]
	s_add_i32 m0, s67, 0xe000
	s_nop 0
	global_load_lds_dwordx4 v[176:177], off
	s_waitcnt vmcnt(8)
	s_waitcnt lgkmcnt(0)
	s_barrier
	s_setprio 1
	s_waitcnt lgkmcnt(0)
	v_mfma_f32_16x16x32_bf16 v[148:151], v[108:111], v[160:163], 0
	v_mfma_f32_16x16x32_bf16 v[144:147], v[116:119], v[160:163], 0
	v_mfma_f32_16x16x32_bf16 v[140:143], v[108:111], v[168:171], 0
	v_mfma_f32_16x16x32_bf16 v[132:135], v[116:119], v[168:171], 0
	v_mfma_f32_16x16x32_bf16 v[120:123], v[108:111], v[192:195], 0
	v_mfma_f32_16x16x32_bf16 v[104:107], v[116:119], v[192:195], 0
	v_mfma_f32_16x16x32_bf16 v[100:103], v[108:111], v[200:203], 0
	v_mfma_f32_16x16x32_bf16 v[96:99], v[116:119], v[200:203], 0
	v_mfma_f32_16x16x32_bf16 v[148:151], v[112:115], v[164:167], v[148:151]
	v_mfma_f32_16x16x32_bf16 v[144:147], v[124:127], v[164:167], v[144:147]
	v_mfma_f32_16x16x32_bf16 v[140:143], v[112:115], v[172:175], v[140:143]
	v_mfma_f32_16x16x32_bf16 v[132:135], v[124:127], v[172:175], v[132:135]
	v_mfma_f32_16x16x32_bf16 v[120:123], v[112:115], v[196:199], v[120:123]
	v_mfma_f32_16x16x32_bf16 v[104:107], v[124:127], v[196:199], v[104:107]
	v_mfma_f32_16x16x32_bf16 v[100:103], v[112:115], v[214:217], v[100:103]
	v_mfma_f32_16x16x32_bf16 v[96:99], v[124:127], v[214:217], v[96:99]
	s_setprio 0
	s_setprio 1
	v_mfma_f32_16x16x32_bf16 v[60:63], v[128:131], v[160:163], 0
	v_mfma_f32_16x16x32_bf16 v[56:59], v[152:155], v[160:163], 0
	v_mfma_f32_16x16x32_bf16 v[52:55], v[128:131], v[168:171], 0
	v_mfma_f32_16x16x32_bf16 v[48:51], v[152:155], v[168:171], 0
	v_mfma_f32_16x16x32_bf16 v[44:47], v[128:131], v[192:195], 0
	v_mfma_f32_16x16x32_bf16 v[40:43], v[152:155], v[192:195], 0
	v_mfma_f32_16x16x32_bf16 v[36:39], v[128:131], v[200:203], 0
	v_mfma_f32_16x16x32_bf16 v[32:35], v[152:155], v[200:203], 0
	v_mfma_f32_16x16x32_bf16 v[60:63], v[136:139], v[164:167], v[60:63]
	v_mfma_f32_16x16x32_bf16 v[56:59], v[156:159], v[164:167], v[56:59]
	v_mfma_f32_16x16x32_bf16 v[52:55], v[136:139], v[172:175], v[52:55]
	v_mfma_f32_16x16x32_bf16 v[48:51], v[156:159], v[172:175], v[48:51]
	v_mfma_f32_16x16x32_bf16 v[44:47], v[136:139], v[196:199], v[44:47]
	v_mfma_f32_16x16x32_bf16 v[40:43], v[156:159], v[196:199], v[40:43]
	v_mfma_f32_16x16x32_bf16 v[36:39], v[136:139], v[214:217], v[36:39]
	v_mfma_f32_16x16x32_bf16 v[32:35], v[156:159], v[214:217], v[32:35]
	s_setprio 0
	s_barrier
	s_add_i32 s88, s78, s66
	v_lshl_add_u64 v[176:177], s[58:59], 0, v[180:181]
	s_mov_b32 m0, s88
	ds_read_b128 v[160:163], v212 offset:16384
	ds_read_b128 v[164:167], v212 offset:17408
	ds_read_b128 v[168:171], v212 offset:18432
	ds_read_b128 v[172:175], v212 offset:19456
	ds_read_b128 v[192:195], v212 offset:20480
	ds_read_b128 v[196:199], v212 offset:21504
	ds_read_b128 v[200:203], v212 offset:22528
	ds_read_b128 v[214:217], v212 offset:23552
	global_load_lds_dwordx4 v[176:177], off
	s_add_i32 m0, s88, 0x2000
	s_add_u32 s88, s58, 0x40000
	v_lshl_add_u64 v[204:205], s[58:59], 0, v[184:185]
	s_addc_u32 s89, s59, 0
	s_add_i32 s90, s79, s66
	global_load_lds_dwordx4 v[204:205], off
	v_lshl_add_u64 v[218:219], s[88:89], 0, v[180:181]
	s_mov_b32 m0, s90
	v_lshl_add_u64 v[220:221], s[60:61], 0, v[182:183]
	global_load_lds_dwordx4 v[218:219], off
	v_lshl_add_u64 v[218:219], s[88:89], 0, v[184:185]
	s_add_i32 m0, s90, 0x2000
	s_nop 0
	global_load_lds_dwordx4 v[218:219], off
	v_lshl_add_u64 v[218:219], s[60:61], 0, v[178:179]
	s_mov_b32 m0, s67
	s_nop 0
	global_load_lds_dwordx4 v[218:219], off
	s_mov_b32 m0, s68
	s_nop 0
	global_load_lds_dwordx4 v[220:221], off
	s_waitcnt vmcnt(8)
	s_waitcnt lgkmcnt(0)
	s_barrier
; #define PG8_STAGE(bufoff, gbase, voff) do { _Pragma("unroll") for (int _i = 0; _i < 2; ++_i) \
;         __builtin_amdgcn_global_load_lds((const unsigned*)((const char*)(gbase) + (voff)[_i]), (PG8_LAS unsigned*)(lds + (bufoff) + ldsw + _i * 8192), 16, 0, 0); } while (0)
; #define PG8_LDA(dst, b, h) do { _Pragma("unroll") for (int m = 0; m < 4; ++m) _Pragma("unroll") for (int k = 0; k < 2; ++k) dst[m][k] = *(const PG8_LAS bf16x8*)(lds + PG8_SA(b, h) + aoff + m * 2048 + k * 1024); } while (0)
; #define PG8_LDB(dst, b, h) do { _Pragma("unroll") for (int n = 0; n < 2; ++n) _Pragma("unroll") for (int k = 0; k < 2; ++k) dst[n][k] = *(const PG8_LAS bf16x8*)(lds + PG8_SB(b, h) + boff + n * 2048 + k * 1024); } while (0)
; #define PG8_MMA(ai, bj, At, Bt) do { __builtin_amdgcn_s_setprio(1); _Pragma("unroll") for (int m = 0; m < 4; ++m) _Pragma("unroll") for (int n = 0; n < 2; ++n) _Pragma("unroll") for (int k = 0; k < 2; ++k) \
;         acc[ai][bj][m][n] = __builtin_amdgcn_mfma_f32_16x16x32_bf16(Bt[n][k], At[m][k], acc[ai][bj][m][n], 0, 0, 0); __builtin_amdgcn_s_setprio(0); } while (0)
; #define PG8_WAIT_V(n) asm volatile("s_waitcnt vmcnt(" #n ")" ::: "memory")
; #define PG8_WAIT_L(n) asm volatile("s_waitcnt lgkmcnt(" #n ")" ::: "memory")
; #define PG8_BAR __builtin_amdgcn_s_barrier()
; #define PG8_SCHED __builtin_amdgcn_sched_barrier(0)
; template <class Epi, class Sched, bool ALIGN_EPI = false, bool SP2 = false>
; __device__ __forceinline__ void gemm_phase(PG8_LAS unsigned char* lds, const Gemm g, const Sched& S, const Epi& E) {
;     ...
;             PG8_WAIT_V(8); PG8_WAIT_L(0); PG8_BAR; PG8_MMA(1, 0, At, B0); PG8_MMA(1, 1, At, B1); PG8_BAR; PG8_SCHED;
;             PG8_LDB(B0, 1, 0); PG8_LDB(B1, 1, 1); PG8_SCHED; PG8_LDA(At, 1, 0); PG8_STAGE(PG8_SA(0, 1), a2 + hstep, voffA);
;             PG8_WAIT_V(8); PG8_WAIT_L(0); PG8_BAR; PG8_MMA(0, 0, At, B0); PG8_MMA(0, 1, At, B1); PG8_BAR; PG8_SCHED;
	s_setprio 1
	s_waitcnt lgkmcnt(0)
	v_mfma_f32_16x16x32_bf16 v[92:95], v[108:111], v[160:163], 0
	v_mfma_f32_16x16x32_bf16 v[88:91], v[116:119], v[160:163], 0
	v_mfma_f32_16x16x32_bf16 v[84:87], v[108:111], v[168:171], 0
	v_mfma_f32_16x16x32_bf16 v[80:83], v[116:119], v[168:171], 0
	v_mfma_f32_16x16x32_bf16 v[76:79], v[108:111], v[192:195], 0
	v_mfma_f32_16x16x32_bf16 v[72:75], v[116:119], v[192:195], 0
	v_mfma_f32_16x16x32_bf16 v[68:71], v[108:111], v[200:203], 0
	v_mfma_f32_16x16x32_bf16 v[64:67], v[116:119], v[200:203], 0
	v_mfma_f32_16x16x32_bf16 v[92:95], v[112:115], v[164:167], v[92:95]
	v_mfma_f32_16x16x32_bf16 v[88:91], v[124:127], v[164:167], v[88:91]
	v_mfma_f32_16x16x32_bf16 v[84:87], v[112:115], v[172:175], v[84:87]
	v_mfma_f32_16x16x32_bf16 v[80:83], v[124:127], v[172:175], v[80:83]
	v_mfma_f32_16x16x32_bf16 v[76:79], v[112:115], v[196:199], v[76:79]
	v_mfma_f32_16x16x32_bf16 v[72:75], v[124:127], v[196:199], v[72:75]
	v_mfma_f32_16x16x32_bf16 v[68:71], v[112:115], v[214:217], v[68:71]
	v_mfma_f32_16x16x32_bf16 v[64:67], v[124:127], v[214:217], v[64:67]
	s_setprio 0
	s_setprio 1
	v_mfma_f32_16x16x32_bf16 v[28:31], v[128:131], v[160:163], 0
	v_mfma_f32_16x16x32_bf16 v[24:27], v[152:155], v[160:163], 0
	v_mfma_f32_16x16x32_bf16 v[20:23], v[128:131], v[168:171], 0
	v_mfma_f32_16x16x32_bf16 v[16:19], v[152:155], v[168:171], 0
	v_mfma_f32_16x16x32_bf16 v[12:15], v[128:131], v[192:195], 0
	v_mfma_f32_16x16x32_bf16 v[8:11], v[152:155], v[192:195], 0
	v_mfma_f32_16x16x32_bf16 v[4:7], v[128:131], v[200:203], 0
	v_mfma_f32_16x16x32_bf16 v[0:3], v[152:155], v[200:203], 0
	v_mfma_f32_16x16x32_bf16 v[28:31], v[136:139], v[164:167], v[28:31]
	v_mfma_f32_16x16x32_bf16 v[24:27], v[156:159], v[164:167], v[24:27]
	v_mfma_f32_16x16x32_bf16 v[20:23], v[136:139], v[172:175], v[20:23]
	v_mfma_f32_16x16x32_bf16 v[16:19], v[156:159], v[172:175], v[16:19]
	v_mfma_f32_16x16x32_bf16 v[12:15], v[136:139], v[196:199], v[12:15]
	v_mfma_f32_16x16x32_bf16 v[8:11], v[156:159], v[196:199], v[8:11]
	v_mfma_f32_16x16x32_bf16 v[4:7], v[136:139], v[214:217], v[4:7]
	v_mfma_f32_16x16x32_bf16 v[0:3], v[156:159], v[214:217], v[0:3]
	s_setprio 0
	s_barrier
	s_add_i32 s88, 0, 0x18000
	s_add_i32 s89, 0, 0x1c000
	v_add_u32_e32 v124, s88, v208
	v_add_u32_e32 v156, s89, v208
	ds_read_b128 v[108:111], v124
	ds_read_b128 v[112:115], v124 offset:1024
	ds_read_b128 v[116:119], v124 offset:2048
	ds_read_b128 v[124:127], v124 offset:3072
	ds_read_b128 v[128:131], v156
	ds_read_b128 v[136:139], v156 offset:1024
	ds_read_b128 v[152:155], v156 offset:2048
	ds_read_b128 v[156:159], v156 offset:3072
	s_add_u32 s60, s60, 0x40000
	s_addc_u32 s61, s61, 0
	s_mov_b32 m0, s69
	v_lshl_add_u64 v[222:223], s[60:61], 0, v[178:179]
	ds_read_b128 v[160:163], v212 offset:32768
	ds_read_b128 v[164:167], v212 offset:33792
	ds_read_b128 v[168:171], v212 offset:34816
	ds_read_b128 v[172:175], v212 offset:35840
	ds_read_b128 v[192:195], v212 offset:36864
	ds_read_b128 v[196:199], v212 offset:37888
	ds_read_b128 v[200:203], v212 offset:38912
	ds_read_b128 v[214:217], v212 offset:39936
	global_load_lds_dwordx4 v[222:223], off
	v_lshl_add_u64 v[222:223], s[60:61], 0, v[182:183]
	s_mov_b32 m0, s71
	s_nop 0
	global_load_lds_dwordx4 v[222:223], off
	s_waitcnt vmcnt(8)
	s_waitcnt lgkmcnt(0)
	s_barrier
	s_setprio 1
	s_waitcnt lgkmcnt(0)
	v_mfma_f32_16x16x32_bf16 v[148:151], v[108:111], v[160:163], v[148:151]
	v_mfma_f32_16x16x32_bf16 v[144:147], v[116:119], v[160:163], v[144:147]
	v_mfma_f32_16x16x32_bf16 v[140:143], v[108:111], v[168:171], v[140:143]
	v_mfma_f32_16x16x32_bf16 v[132:135], v[116:119], v[168:171], v[132:135]
	v_mfma_f32_16x16x32_bf16 v[120:123], v[108:111], v[192:195], v[120:123]
	v_mfma_f32_16x16x32_bf16 v[104:107], v[116:119], v[192:195], v[104:107]
	v_mfma_f32_16x16x32_bf16 v[100:103], v[108:111], v[200:203], v[100:103]
	v_mfma_f32_16x16x32_bf16 v[96:99], v[116:119], v[200:203], v[96:99]
	v_mfma_f32_16x16x32_bf16 v[148:151], v[112:115], v[164:167], v[148:151]
	v_mfma_f32_16x16x32_bf16 v[144:147], v[124:127], v[164:167], v[144:147]
	v_mfma_f32_16x16x32_bf16 v[140:143], v[112:115], v[172:175], v[140:143]
	v_mfma_f32_16x16x32_bf16 v[132:135], v[124:127], v[172:175], v[132:135]
	v_mfma_f32_16x16x32_bf16 v[120:123], v[112:115], v[196:199], v[120:123]
	v_mfma_f32_16x16x32_bf16 v[104:107], v[124:127], v[196:199], v[104:107]
	v_mfma_f32_16x16x32_bf16 v[100:103], v[112:115], v[214:217], v[100:103]
	v_mfma_f32_16x16x32_bf16 v[96:99], v[124:127], v[214:217], v[96:99]
	s_setprio 0
	s_setprio 1
	v_mfma_f32_16x16x32_bf16 v[60:63], v[128:131], v[160:163], v[60:63]
	v_mfma_f32_16x16x32_bf16 v[56:59], v[152:155], v[160:163], v[56:59]
	v_mfma_f32_16x16x32_bf16 v[52:55], v[128:131], v[168:171], v[52:55]
	v_mfma_f32_16x16x32_bf16 v[48:51], v[152:155], v[168:171], v[48:51]
	v_mfma_f32_16x16x32_bf16 v[44:47], v[128:131], v[192:195], v[44:47]
	v_mfma_f32_16x16x32_bf16 v[40:43], v[152:155], v[192:195], v[40:43]
	v_mfma_f32_16x16x32_bf16 v[36:39], v[128:131], v[200:203], v[36:39]
	v_mfma_f32_16x16x32_bf16 v[32:35], v[152:155], v[200:203], v[32:35]
	v_mfma_f32_16x16x32_bf16 v[60:63], v[136:139], v[164:167], v[60:63]
	v_mfma_f32_16x16x32_bf16 v[56:59], v[156:159], v[164:167], v[56:59]
	v_mfma_f32_16x16x32_bf16 v[52:55], v[136:139], v[172:175], v[52:55]
	v_mfma_f32_16x16x32_bf16 v[48:51], v[156:159], v[172:175], v[48:51]
	v_mfma_f32_16x16x32_bf16 v[44:47], v[136:139], v[196:199], v[44:47]
	v_mfma_f32_16x16x32_bf16 v[40:43], v[156:159], v[196:199], v[40:43]
	v_mfma_f32_16x16x32_bf16 v[36:39], v[136:139], v[214:217], v[36:39]
	v_mfma_f32_16x16x32_bf16 v[32:35], v[156:159], v[214:217], v[32:35]
	s_setprio 0
	s_barrier
; #define PG8_STAGE(bufoff, gbase, voff) do { _Pragma("unroll") for (int _i = 0; _i < 2; ++_i) \
;         __builtin_amdgcn_global_load_lds((const unsigned*)((const char*)(gbase) + (voff)[_i]), (PG8_LAS unsigned*)(lds + (bufoff) + ldsw + _i * 8192), 16, 0, 0); } while (0)
; #define PG8_LDA(dst, b, h) do { _Pragma("unroll") for (int m = 0; m < 4; ++m) _Pragma("unroll") for (int k = 0; k < 2; ++k) dst[m][k] = *(const PG8_LAS bf16x8*)(lds + PG8_SA(b, h) + aoff + m * 2048 + k * 1024); } while (0)
; #define PG8_MMA(ai, bj, At, Bt) do { __builtin_amdgcn_s_setprio(1); _Pragma("unroll") for (int m = 0; m < 4; ++m) _Pragma("unroll") for (int n = 0; n < 2; ++n) _Pragma("unroll") for (int k = 0; k < 2; ++k) \
;         acc[ai][bj][m][n] = __builtin_amdgcn_mfma_f32_16x16x32_bf16(Bt[n][k], At[m][k], acc[ai][bj][m][n], 0, 0, 0); __builtin_amdgcn_s_setprio(0); } while (0)
; #define PG8_WAIT_V(n) asm volatile("s_waitcnt vmcnt(" #n ")" ::: "memory")
; #define PG8_WAIT_L(n) asm volatile("s_waitcnt lgkmcnt(" #n ")" ::: "memory")
; #define PG8_BAR __builtin_amdgcn_s_barrier()
; #define PG8_SCHED __builtin_amdgcn_sched_barrier(0)
; template <class Epi, class Sched, bool ALIGN_EPI = false, bool SP2 = false>
; __device__ __forceinline__ void gemm_phase(PG8_LAS unsigned char* lds, const Gemm g, const Sched& S, const Epi& E) {
;     ...
;         for (int t = 0; t < nt; t += 2) {
;             const bool last = (t == nt - 2);
;             const char* a1 = cA + (size_t)(t + 1) * kstep;
;             const char* a2 = last ? nA : cA + (size_t)(t + 2) * kstep; const char* b2 = last ? nB : cB + (size_t)(t + 2) * kstep;
;             const char* a3 = a2 + kstep; const char* b3 = b2 + kstep;
;     ...
;             PG8_LDA(At, 1, 1); PG8_STAGE(PG8_SB(1, 0), b3, voffB); PG8_STAGE(PG8_SB(1, 1), b3 + hstep, voffB); PG8_STAGE(PG8_SA(1, 0), a3, voffA);
;             PG8_WAIT_V(8); PG8_WAIT_L(0); PG8_BAR; PG8_MMA(1, 0, At, B0); PG8_MMA(1, 1, At, B1); PG8_BAR; PG8_SCHED;
	s_add_i32 s60, s88, s66
	v_lshl_add_u64 v[176:177], v[176:177], 0, s[22:23]
	s_mov_b32 m0, s60
	ds_read_b128 v[160:163], v212 offset:49152
	ds_read_b128 v[164:167], v212 offset:50176
	ds_read_b128 v[168:171], v212 offset:51200
	ds_read_b128 v[172:175], v212 offset:52224
	ds_read_b128 v[192:195], v212 offset:53248
	ds_read_b128 v[196:199], v212 offset:54272
	ds_read_b128 v[200:203], v212 offset:55296
	ds_read_b128 v[214:217], v212 offset:56320
	global_load_lds_dwordx4 v[176:177], off
	s_add_i32 m0, s60, 0x2000
	s_add_u32 s58, s58, 0x40080
	v_lshl_add_u64 v[176:177], v[204:205], 0, s[22:23]
	s_addc_u32 s59, s59, 0
	s_add_i32 s60, s89, s66
	global_load_lds_dwordx4 v[176:177], off
	v_lshl_add_u64 v[176:177], s[58:59], 0, v[180:181]
	s_mov_b32 m0, s60
	s_nop 0
	global_load_lds_dwordx4 v[176:177], off
	v_lshl_add_u64 v[176:177], s[58:59], 0, v[184:185]
	s_add_i32 m0, s60, 0x2000
	s_nop 0
	global_load_lds_dwordx4 v[176:177], off
	v_lshl_add_u64 v[176:177], v[218:219], 0, s[22:23]
	s_mov_b32 m0, s73
	s_nop 0
	global_load_lds_dwordx4 v[176:177], off
	v_lshl_add_u64 v[176:177], v[220:221], 0, s[22:23]
	s_mov_b32 m0, s74
	s_nop 0
	global_load_lds_dwordx4 v[176:177], off
	s_waitcnt vmcnt(8)
	s_waitcnt lgkmcnt(0)
	s_barrier
	s_setprio 1
	s_waitcnt lgkmcnt(0)
	v_mfma_f32_16x16x32_bf16 v[92:95], v[108:111], v[160:163], v[92:95]
	v_mfma_f32_16x16x32_bf16 v[88:91], v[116:119], v[160:163], v[88:91]
	v_mfma_f32_16x16x32_bf16 v[84:87], v[108:111], v[168:171], v[84:87]
	v_mfma_f32_16x16x32_bf16 v[80:83], v[116:119], v[168:171], v[80:83]
	v_mfma_f32_16x16x32_bf16 v[76:79], v[108:111], v[192:195], v[76:79]
	v_mfma_f32_16x16x32_bf16 v[72:75], v[116:119], v[192:195], v[72:75]
	v_mfma_f32_16x16x32_bf16 v[68:71], v[108:111], v[200:203], v[68:71]
	v_mfma_f32_16x16x32_bf16 v[64:67], v[116:119], v[200:203], v[64:67]
	v_mfma_f32_16x16x32_bf16 v[92:95], v[112:115], v[164:167], v[92:95]
	v_mfma_f32_16x16x32_bf16 v[88:91], v[124:127], v[164:167], v[88:91]
	v_mfma_f32_16x16x32_bf16 v[84:87], v[112:115], v[172:175], v[84:87]
	v_mfma_f32_16x16x32_bf16 v[80:83], v[124:127], v[172:175], v[80:83]
	v_mfma_f32_16x16x32_bf16 v[76:79], v[112:115], v[196:199], v[76:79]
	v_mfma_f32_16x16x32_bf16 v[72:75], v[124:127], v[196:199], v[72:75]
	v_mfma_f32_16x16x32_bf16 v[68:71], v[112:115], v[214:217], v[68:71]
	v_mfma_f32_16x16x32_bf16 v[64:67], v[124:127], v[214:217], v[64:67]
	s_setprio 0
	s_setprio 1
	v_mfma_f32_16x16x32_bf16 v[28:31], v[128:131], v[160:163], v[28:31]
	v_mfma_f32_16x16x32_bf16 v[24:27], v[152:155], v[160:163], v[24:27]
	v_mfma_f32_16x16x32_bf16 v[20:23], v[128:131], v[168:171], v[20:23]
	v_mfma_f32_16x16x32_bf16 v[16:19], v[152:155], v[168:171], v[16:19]
	v_mfma_f32_16x16x32_bf16 v[12:15], v[128:131], v[192:195], v[12:15]
	v_mfma_f32_16x16x32_bf16 v[8:11], v[152:155], v[192:195], v[8:11]
	v_mfma_f32_16x16x32_bf16 v[4:7], v[128:131], v[200:203], v[4:7]
	v_mfma_f32_16x16x32_bf16 v[0:3], v[152:155], v[200:203], v[0:3]
	v_mfma_f32_16x16x32_bf16 v[28:31], v[136:139], v[164:167], v[28:31]
	v_mfma_f32_16x16x32_bf16 v[24:27], v[156:159], v[164:167], v[24:27]
	v_mfma_f32_16x16x32_bf16 v[20:23], v[136:139], v[172:175], v[20:23]
	v_mfma_f32_16x16x32_bf16 v[16:19], v[156:159], v[172:175], v[16:19]
	v_mfma_f32_16x16x32_bf16 v[12:15], v[136:139], v[196:199], v[12:15]
	v_mfma_f32_16x16x32_bf16 v[8:11], v[156:159], v[196:199], v[8:11]
	v_mfma_f32_16x16x32_bf16 v[4:7], v[136:139], v[214:217], v[4:7]
	v_mfma_f32_16x16x32_bf16 v[0:3], v[156:159], v[214:217], v[0:3]
	s_setprio 0
	s_barrier
	s_add_i32 s83, s83, 2
	s_add_u32 s8, s8, 0x100
	s_addc_u32 s9, s9, 0
	s_add_u32 s81, s81, 0x100
	s_addc_u32 s82, s82, 0
	s_cmp_gt_u32 s83, 13
	s_cbranch_scc0 .LBB0_1472
	s_branch .Lpeel_exit_10

; #define PG8_BAR __builtin_amdgcn_s_barrier()
; template <class Epi, class Sched, bool ALIGN_EPI = false, bool SP2 = false>
; __device__ __forceinline__ void gemm_phase(PG8_LAS unsigned char* lds, const Gemm g, const Sched& S, const Epi& E) {
;     ...
;         if constexpr (ALIGN_EPI) { if (wr == 0) PG8_BAR; }
.Lpeel_exit_10:
	s_and_b64 vcc, exec, s[24:25]
	s_cbranch_vccz .LBB0_1475
	s_barrier

;     __device__ __forceinline__ bool next(int i, Unit& u) const { if (i != 0) return false; const int c0 = (G >= 8) ? G - 5 : G - 2; int k = -1; if (c == c0) k = 0; else if (c == G - 1) k = 1; if (k < 0 || k >= n) return false; u.pm = k; u.pn = 0; return true; }
; #define PG8_STAGE(bufoff, gbase, voff) do { _Pragma("unroll") for (int _i = 0; _i < 2; ++_i) \
;         __builtin_amdgcn_global_load_lds((const unsigned*)((const char*)(gbase) + (voff)[_i]), (PG8_LAS unsigned*)(lds + (bufoff) + ldsw + _i * 8192), 16, 0, 0); } while (0)
; #define PG8_LDA(dst, b, h) do { _Pragma("unroll") for (int m = 0; m < 4; ++m) _Pragma("unroll") for (int k = 0; k < 2; ++k) dst[m][k] = *(const PG8_LAS bf16x8*)(lds + PG8_SA(b, h) + aoff + m * 2048 + k * 1024); } while (0)
; #define PG8_LDB(dst, b, h) do { _Pragma("unroll") for (int n = 0; n < 2; ++n) _Pragma("unroll") for (int k = 0; k < 2; ++k) dst[n][k] = *(const PG8_LAS bf16x8*)(lds + PG8_SB(b, h) + boff + n * 2048 + k * 1024); } while (0)
; template <class Epi, class Sched, bool ALIGN_EPI = false, bool SP2 = false>
; __device__ __forceinline__ void gemm_phase(PG8_LAS unsigned char* lds, const Gemm g, const Sched& S, const Epi& E) {
;     ...
;         const bool has_next = S.next(ui + 1, nxt);
;         const char* nA = has_next ? (const char*)g.A + (size_t)nxt.pm * tstep : cA; const char* nB = has_next ? (const char*)g.Bt + (size_t)nxt.pn * tstep : cB;
;         for (int t = 0; t < nt; t += 2) {
;             const bool last = (t == nt - 2);
;             const char* a1 = cA + (size_t)(t + 1) * kstep;
;             const char* a2 = last ? nA : cA + (size_t)(t + 2) * kstep; const char* b2 = last ? nB : cB + (size_t)(t + 2) * kstep;
;             const char* a3 = a2 + kstep; const char* b3 = b2 + kstep;
;             if (last && has_next) S.a_ready(nxt);
;             if constexpr (SP2) {
;             PG8_LDB(B0, 0, 0); PG8_LDB(B1, 0, 1); PG8_SCHED; PG8_LDA(At, 0, 0); PG8_STAGE(PG8_SA(1, 1), a1 + hstep, voffA);
;             PG8_WAIT_V(8); PG8_WAIT_L(0); PG8_BAR; PG8_MMA(0, 0, At, B0); PG8_MMA(0, 1, At, B1); PG8_BAR; PG8_SCHED;
;             PG8_LDA(At, 0, 1); PG8_STAGE(PG8_SB(0, 0), b2, voffB); PG8_STAGE(PG8_SB(0, 1), b2 + hstep, voffB); PG8_STAGE(PG8_SA(0, 0), a2, voffA);
;             PG8_WAIT_V(8); PG8_WAIT_L(0); PG8_BAR; PG8_MMA(1, 0, At, B0); PG8_MMA(1, 1, At, B1); PG8_BAR; PG8_SCHED;
.LBB0_1608:
	s_ashr_i32 s37, s36, 31
	s_lshl_b64 s[40:41], s[36:37], 19
	s_add_u32 s40, s14, s40
	s_addc_u32 s41, s15, s41
	s_and_b64 s[42:43], s[38:39], exec
	s_cselect_b32 s37, s41, s45
	s_cselect_b32 s77, s40, s44
	s_ashr_i32 s31, s30, 31
	s_lshl_b64 s[42:43], s[30:31], 19
	s_add_u32 s42, s34, s42
	s_addc_u32 s43, s35, s43
	s_and_b64 s[56:57], s[38:39], exec
	s_cselect_b32 s31, s43, s47
	s_cselect_b32 s78, s42, s46
	s_add_u32 s44, s44, 0x40080
	s_addc_u32 s45, s45, 0
	s_add_u32 s79, s46, 0x100
	v_mov_b32_e32 v0, 0
	s_addc_u32 s80, s47, 0
	s_mov_b32 s81, -2
	ds_read_b128 v[148:151], v145
	ds_read_b128 v[152:155], v145 offset:1024
	ds_read_b128 v[156:159], v145 offset:2048
	ds_read_b128 v[160:163], v145 offset:3072
	ds_read_b128 v[164:167], v146
	ds_read_b128 v[168:171], v146 offset:1024
	ds_read_b128 v[172:175], v146 offset:2048
	ds_read_b128 v[176:179], v146 offset:3072
	s_add_u32 s46, s44, 0xfffc0080
	s_addc_u32 s47, s45, -1
	s_cmp_eq_u32 s81, 12
	s_cselect_b32 s57, s37, s47
	s_cselect_b32 s56, s77, s46
	s_cselect_b32 s47, s31, s80
	s_cselect_b32 s46, s78, s79
	v_lshl_add_u64 v[204:205], s[44:45], 0, v[136:137]
	s_add_i32 m0, s60, 0xc000
	ds_read_b128 v[180:183], v147
	ds_read_b128 v[184:187], v147 offset:1024
	ds_read_b128 v[188:191], v147 offset:2048
	ds_read_b128 v[192:195], v147 offset:3072
	ds_read_b128 v[196:199], v147 offset:4096
	ds_read_b128 v[200:203], v147 offset:5120
	ds_read_b128 v[208:211], v147 offset:6144
	ds_read_b128 v[212:215], v147 offset:7168
	global_load_lds_dwordx4 v[204:205], off
	v_lshl_add_u64 v[204:205], s[44:45], 0, v[138:139]
	s_add_i32 m0, s60, 0xe000
	s_nop 0
	global_load_lds_dwordx4 v[204:205], off
	s_waitcnt vmcnt(8)
	s_waitcnt lgkmcnt(0)
	s_barrier
	s_setprio 1
	s_waitcnt lgkmcnt(0)
	v_mfma_f32_16x16x32_bf16 v[124:127], v[148:151], v[180:183], 0
	v_mfma_f32_16x16x32_bf16 v[120:123], v[156:159], v[180:183], 0
	v_mfma_f32_16x16x32_bf16 v[116:119], v[148:151], v[188:191], 0
	v_mfma_f32_16x16x32_bf16 v[112:115], v[156:159], v[188:191], 0
	v_mfma_f32_16x16x32_bf16 v[100:103], v[148:151], v[196:199], 0
	v_mfma_f32_16x16x32_bf16 v[96:99], v[156:159], v[196:199], 0
	v_mfma_f32_16x16x32_bf16 v[84:87], v[148:151], v[208:211], 0
	v_mfma_f32_16x16x32_bf16 v[80:83], v[156:159], v[208:211], 0
	v_mfma_f32_16x16x32_bf16 v[124:127], v[152:155], v[184:187], v[124:127]
	v_mfma_f32_16x16x32_bf16 v[120:123], v[160:163], v[184:187], v[120:123]
	v_mfma_f32_16x16x32_bf16 v[116:119], v[152:155], v[192:195], v[116:119]
	v_mfma_f32_16x16x32_bf16 v[112:115], v[160:163], v[192:195], v[112:115]
	v_mfma_f32_16x16x32_bf16 v[100:103], v[152:155], v[200:203], v[100:103]
	v_mfma_f32_16x16x32_bf16 v[96:99], v[160:163], v[200:203], v[96:99]
	v_mfma_f32_16x16x32_bf16 v[84:87], v[152:155], v[212:215], v[84:87]
	v_mfma_f32_16x16x32_bf16 v[80:83], v[160:163], v[212:215], v[80:83]
	s_setprio 0
	s_setprio 1
	v_mfma_f32_16x16x32_bf16 v[108:111], v[164:167], v[180:183], 0
	v_mfma_f32_16x16x32_bf16 v[104:107], v[172:175], v[180:183], 0
	v_mfma_f32_16x16x32_bf16 v[92:95], v[164:167], v[188:191], 0
	v_mfma_f32_16x16x32_bf16 v[88:91], v[172:175], v[188:191], 0
	v_mfma_f32_16x16x32_bf16 v[76:79], v[164:167], v[196:199], 0
	v_mfma_f32_16x16x32_bf16 v[72:75], v[172:175], v[196:199], 0
	v_mfma_f32_16x16x32_bf16 v[68:71], v[164:167], v[208:211], 0
	v_mfma_f32_16x16x32_bf16 v[64:67], v[172:175], v[208:211], 0
	v_mfma_f32_16x16x32_bf16 v[108:111], v[168:171], v[184:187], v[108:111]
	v_mfma_f32_16x16x32_bf16 v[104:107], v[176:179], v[184:187], v[104:107]
	v_mfma_f32_16x16x32_bf16 v[92:95], v[168:171], v[192:195], v[92:95]
	v_mfma_f32_16x16x32_bf16 v[88:91], v[176:179], v[192:195], v[88:91]
	v_mfma_f32_16x16x32_bf16 v[76:79], v[168:171], v[200:203], v[76:79]
	v_mfma_f32_16x16x32_bf16 v[72:75], v[176:179], v[200:203], v[72:75]
	v_mfma_f32_16x16x32_bf16 v[68:71], v[168:171], v[212:215], v[68:71]
	v_mfma_f32_16x16x32_bf16 v[64:67], v[176:179], v[212:215], v[64:67]
	s_setprio 0
	s_barrier
	s_add_i32 s82, s71, s59
	v_lshl_add_u64 v[204:205], s[46:47], 0, v[130:131]
	s_mov_b32 m0, s82
	ds_read_b128 v[180:183], v147 offset:16384
	ds_read_b128 v[184:187], v147 offset:17408
	ds_read_b128 v[188:191], v147 offset:18432
	ds_read_b128 v[192:195], v147 offset:19456
	ds_read_b128 v[196:199], v147 offset:20480
	ds_read_b128 v[200:203], v147 offset:21504
	ds_read_b128 v[208:211], v147 offset:22528
	ds_read_b128 v[212:215], v147 offset:23552
	global_load_lds_dwordx4 v[204:205], off
	s_add_i32 m0, s82, 0x2000
	s_add_u32 s82, s46, 0x40000
	v_lshl_add_u64 v[216:217], s[46:47], 0, v[134:135]
	s_addc_u32 s83, s47, 0
	s_add_i32 s88, s72, s59
	global_load_lds_dwordx4 v[216:217], off
	v_lshl_add_u64 v[218:219], s[82:83], 0, v[130:131]
	s_mov_b32 m0, s88
	v_lshl_add_u64 v[220:221], s[56:57], 0, v[132:133]
	global_load_lds_dwordx4 v[218:219], off
	v_lshl_add_u64 v[218:219], s[82:83], 0, v[134:135]
	s_add_i32 m0, s88, 0x2000
	s_nop 0
	global_load_lds_dwordx4 v[218:219], off
	v_lshl_add_u64 v[218:219], s[56:57], 0, v[128:129]
	s_mov_b32 m0, s60
	s_nop 0
	global_load_lds_dwordx4 v[218:219], off
	s_mov_b32 m0, s61
	s_nop 0
	global_load_lds_dwordx4 v[220:221], off
	s_waitcnt vmcnt(8)
	s_waitcnt lgkmcnt(0)
	s_barrier
; #define PG8_STAGE(bufoff, gbase, voff) do { _Pragma("unroll") for (int _i = 0; _i < 2; ++_i) \
;         __builtin_amdgcn_global_load_lds((const unsigned*)((const char*)(gbase) + (voff)[_i]), (PG8_LAS unsigned*)(lds + (bufoff) + ldsw + _i * 8192), 16, 0, 0); } while (0)
; #define PG8_LDA(dst, b, h) do { _Pragma("unroll") for (int m = 0; m < 4; ++m) _Pragma("unroll") for (int k = 0; k < 2; ++k) dst[m][k] = *(const PG8_LAS bf16x8*)(lds + PG8_SA(b, h) + aoff + m * 2048 + k * 1024); } while (0)
; #define PG8_LDB(dst, b, h) do { _Pragma("unroll") for (int n = 0; n < 2; ++n) _Pragma("unroll") for (int k = 0; k < 2; ++k) dst[n][k] = *(const PG8_LAS bf16x8*)(lds + PG8_SB(b, h) + boff + n * 2048 + k * 1024); } while (0)
; #define PG8_MMA(ai, bj, At, Bt) do { __builtin_amdgcn_s_setprio(1); _Pragma("unroll") for (int m = 0; m < 4; ++m) _Pragma("unroll") for (int n = 0; n < 2; ++n) _Pragma("unroll") for (int k = 0; k < 2; ++k) \
;         acc[ai][bj][m][n] = __builtin_amdgcn_mfma_f32_16x16x32_bf16(Bt[n][k], At[m][k], acc[ai][bj][m][n], 0, 0, 0); __builtin_amdgcn_s_setprio(0); } while (0)
; #define PG8_WAIT_V(n) asm volatile("s_waitcnt vmcnt(" #n ")" ::: "memory")
; #define PG8_WAIT_L(n) asm volatile("s_waitcnt lgkmcnt(" #n ")" ::: "memory")
; #define PG8_BAR __builtin_amdgcn_s_barrier()
; #define PG8_SCHED __builtin_amdgcn_sched_barrier(0)
; template <class Epi, class Sched, bool ALIGN_EPI = false, bool SP2 = false>
; __device__ __forceinline__ void gemm_phase(PG8_LAS unsigned char* lds, const Gemm g, const Sched& S, const Epi& E) {
;     ...
;             PG8_WAIT_V(8); PG8_WAIT_L(0); PG8_BAR; PG8_MMA(1, 0, At, B0); PG8_MMA(1, 1, At, B1); PG8_BAR; PG8_SCHED;
;             PG8_LDB(B0, 1, 0); PG8_LDB(B1, 1, 1); PG8_SCHED; PG8_LDA(At, 1, 0); PG8_STAGE(PG8_SA(0, 1), a2 + hstep, voffA);
;             PG8_WAIT_V(8); PG8_WAIT_L(0); PG8_BAR; PG8_MMA(0, 0, At, B0); PG8_MMA(0, 1, At, B1); PG8_BAR; PG8_SCHED;
	s_setprio 1
	s_waitcnt lgkmcnt(0)
	v_mfma_f32_16x16x32_bf16 v[60:63], v[148:151], v[180:183], 0
	v_mfma_f32_16x16x32_bf16 v[56:59], v[156:159], v[180:183], 0
	v_mfma_f32_16x16x32_bf16 v[52:55], v[148:151], v[188:191], 0
	v_mfma_f32_16x16x32_bf16 v[48:51], v[156:159], v[188:191], 0
	v_mfma_f32_16x16x32_bf16 v[36:39], v[148:151], v[196:199], 0
	v_mfma_f32_16x16x32_bf16 v[32:35], v[156:159], v[196:199], 0
	v_mfma_f32_16x16x32_bf16 v[20:23], v[148:151], v[208:211], 0
	v_mfma_f32_16x16x32_bf16 v[16:19], v[156:159], v[208:211], 0
	v_mfma_f32_16x16x32_bf16 v[60:63], v[152:155], v[184:187], v[60:63]
	v_mfma_f32_16x16x32_bf16 v[56:59], v[160:163], v[184:187], v[56:59]
	v_mfma_f32_16x16x32_bf16 v[52:55], v[152:155], v[192:195], v[52:55]
	v_mfma_f32_16x16x32_bf16 v[48:51], v[160:163], v[192:195], v[48:51]
	v_mfma_f32_16x16x32_bf16 v[36:39], v[152:155], v[200:203], v[36:39]
	v_mfma_f32_16x16x32_bf16 v[32:35], v[160:163], v[200:203], v[32:35]
	v_mfma_f32_16x16x32_bf16 v[20:23], v[152:155], v[212:215], v[20:23]
	v_mfma_f32_16x16x32_bf16 v[16:19], v[160:163], v[212:215], v[16:19]
	s_setprio 0
	s_setprio 1
	v_mfma_f32_16x16x32_bf16 v[44:47], v[164:167], v[180:183], 0
	v_mfma_f32_16x16x32_bf16 v[40:43], v[172:175], v[180:183], 0
	v_mfma_f32_16x16x32_bf16 v[28:31], v[164:167], v[188:191], 0
	v_mfma_f32_16x16x32_bf16 v[24:27], v[172:175], v[188:191], 0
	v_mfma_f32_16x16x32_bf16 v[12:15], v[164:167], v[196:199], 0
	v_mfma_f32_16x16x32_bf16 v[8:11], v[172:175], v[196:199], 0
	v_mfma_f32_16x16x32_bf16 v[4:7], v[164:167], v[208:211], 0
	v_mfma_f32_16x16x32_bf16 v[0:3], v[172:175], v[208:211], 0
	v_mfma_f32_16x16x32_bf16 v[44:47], v[168:171], v[184:187], v[44:47]
	v_mfma_f32_16x16x32_bf16 v[40:43], v[176:179], v[184:187], v[40:43]
	v_mfma_f32_16x16x32_bf16 v[28:31], v[168:171], v[192:195], v[28:31]
	v_mfma_f32_16x16x32_bf16 v[24:27], v[176:179], v[192:195], v[24:27]
	v_mfma_f32_16x16x32_bf16 v[12:15], v[168:171], v[200:203], v[12:15]
	v_mfma_f32_16x16x32_bf16 v[8:11], v[176:179], v[200:203], v[8:11]
	v_mfma_f32_16x16x32_bf16 v[4:7], v[168:171], v[212:215], v[4:7]
	v_mfma_f32_16x16x32_bf16 v[0:3], v[176:179], v[212:215], v[0:3]
	s_setprio 0
	s_barrier
	s_add_i32 s82, 0, 0x18000
	s_add_i32 s83, 0, 0x1c000
	v_add_u32_e32 v160, s82, v143
	v_add_u32_e32 v176, s83, v143
	ds_read_b128 v[148:151], v160
	ds_read_b128 v[152:155], v160 offset:1024
	ds_read_b128 v[156:159], v160 offset:2048
	ds_read_b128 v[160:163], v160 offset:3072
	ds_read_b128 v[164:167], v176
	ds_read_b128 v[168:171], v176 offset:1024
	ds_read_b128 v[172:175], v176 offset:2048
	ds_read_b128 v[176:179], v176 offset:3072
	s_add_u32 s56, s56, 0x40000
	s_addc_u32 s57, s57, 0
	s_mov_b32 m0, s64
	v_lshl_add_u64 v[222:223], s[56:57], 0, v[128:129]
	ds_read_b128 v[180:183], v147 offset:32768
	ds_read_b128 v[184:187], v147 offset:33792
	ds_read_b128 v[188:191], v147 offset:34816
	ds_read_b128 v[192:195], v147 offset:35840
	ds_read_b128 v[196:199], v147 offset:36864
	ds_read_b128 v[200:203], v147 offset:37888
	ds_read_b128 v[208:211], v147 offset:38912
	ds_read_b128 v[212:215], v147 offset:39936
	global_load_lds_dwordx4 v[222:223], off
	v_lshl_add_u64 v[222:223], s[56:57], 0, v[132:133]
	s_mov_b32 m0, s65
	s_nop 0
	global_load_lds_dwordx4 v[222:223], off
	s_waitcnt vmcnt(8)
	s_waitcnt lgkmcnt(0)
	s_barrier
	s_setprio 1
	s_waitcnt lgkmcnt(0)
	v_mfma_f32_16x16x32_bf16 v[124:127], v[148:151], v[180:183], v[124:127]
	v_mfma_f32_16x16x32_bf16 v[120:123], v[156:159], v[180:183], v[120:123]
	v_mfma_f32_16x16x32_bf16 v[116:119], v[148:151], v[188:191], v[116:119]
	v_mfma_f32_16x16x32_bf16 v[112:115], v[156:159], v[188:191], v[112:115]
	v_mfma_f32_16x16x32_bf16 v[100:103], v[148:151], v[196:199], v[100:103]
	v_mfma_f32_16x16x32_bf16 v[96:99], v[156:159], v[196:199], v[96:99]
	v_mfma_f32_16x16x32_bf16 v[84:87], v[148:151], v[208:211], v[84:87]
	v_mfma_f32_16x16x32_bf16 v[80:83], v[156:159], v[208:211], v[80:83]
	v_mfma_f32_16x16x32_bf16 v[124:127], v[152:155], v[184:187], v[124:127]
	v_mfma_f32_16x16x32_bf16 v[120:123], v[160:163], v[184:187], v[120:123]
	v_mfma_f32_16x16x32_bf16 v[116:119], v[152:155], v[192:195], v[116:119]
	v_mfma_f32_16x16x32_bf16 v[112:115], v[160:163], v[192:195], v[112:115]
	v_mfma_f32_16x16x32_bf16 v[100:103], v[152:155], v[200:203], v[100:103]
	v_mfma_f32_16x16x32_bf16 v[96:99], v[160:163], v[200:203], v[96:99]
	v_mfma_f32_16x16x32_bf16 v[84:87], v[152:155], v[212:215], v[84:87]
	v_mfma_f32_16x16x32_bf16 v[80:83], v[160:163], v[212:215], v[80:83]
	s_setprio 0
	s_setprio 1
	v_mfma_f32_16x16x32_bf16 v[108:111], v[164:167], v[180:183], v[108:111]
	v_mfma_f32_16x16x32_bf16 v[104:107], v[172:175], v[180:183], v[104:107]
	v_mfma_f32_16x16x32_bf16 v[92:95], v[164:167], v[188:191], v[92:95]
	v_mfma_f32_16x16x32_bf16 v[88:91], v[172:175], v[188:191], v[88:91]
	v_mfma_f32_16x16x32_bf16 v[76:79], v[164:167], v[196:199], v[76:79]
	v_mfma_f32_16x16x32_bf16 v[72:75], v[172:175], v[196:199], v[72:75]
	v_mfma_f32_16x16x32_bf16 v[68:71], v[164:167], v[208:211], v[68:71]
	v_mfma_f32_16x16x32_bf16 v[64:67], v[172:175], v[208:211], v[64:67]
	v_mfma_f32_16x16x32_bf16 v[108:111], v[168:171], v[184:187], v[108:111]
	v_mfma_f32_16x16x32_bf16 v[104:107], v[176:179], v[184:187], v[104:107]
	v_mfma_f32_16x16x32_bf16 v[92:95], v[168:171], v[192:195], v[92:95]
	v_mfma_f32_16x16x32_bf16 v[88:91], v[176:179], v[192:195], v[88:91]
	v_mfma_f32_16x16x32_bf16 v[76:79], v[168:171], v[200:203], v[76:79]
	v_mfma_f32_16x16x32_bf16 v[72:75], v[176:179], v[200:203], v[72:75]
	v_mfma_f32_16x16x32_bf16 v[68:71], v[168:171], v[212:215], v[68:71]
	v_mfma_f32_16x16x32_bf16 v[64:67], v[176:179], v[212:215], v[64:67]
	s_setprio 0
	s_barrier
; #define PG8_STAGE(bufoff, gbase, voff) do { _Pragma("unroll") for (int _i = 0; _i < 2; ++_i) \
;         __builtin_amdgcn_global_load_lds((const unsigned*)((const char*)(gbase) + (voff)[_i]), (PG8_LAS unsigned*)(lds + (bufoff) + ldsw + _i * 8192), 16, 0, 0); } while (0)
; #define PG8_LDA(dst, b, h) do { _Pragma("unroll") for (int m = 0; m < 4; ++m) _Pragma("unroll") for (int k = 0; k < 2; ++k) dst[m][k] = *(const PG8_LAS bf16x8*)(lds + PG8_SA(b, h) + aoff + m * 2048 + k * 1024); } while (0)
; #define PG8_MMA(ai, bj, At, Bt) do { __builtin_amdgcn_s_setprio(1); _Pragma("unroll") for (int m = 0; m < 4; ++m) _Pragma("unroll") for (int n = 0; n < 2; ++n) _Pragma("unroll") for (int k = 0; k < 2; ++k) \
;         acc[ai][bj][m][n] = __builtin_amdgcn_mfma_f32_16x16x32_bf16(Bt[n][k], At[m][k], acc[ai][bj][m][n], 0, 0, 0); __builtin_amdgcn_s_setprio(0); } while (0)
; #define PG8_WAIT_V(n) asm volatile("s_waitcnt vmcnt(" #n ")" ::: "memory")
; #define PG8_WAIT_L(n) asm volatile("s_waitcnt lgkmcnt(" #n ")" ::: "memory")
; #define PG8_BAR __builtin_amdgcn_s_barrier()
; #define PG8_SCHED __builtin_amdgcn_sched_barrier(0)
; template <class Epi, class Sched, bool ALIGN_EPI = false, bool SP2 = false>
; __device__ __forceinline__ void gemm_phase(PG8_LAS unsigned char* lds, const Gemm g, const Sched& S, const Epi& E) {
;     ...
;         for (int t = 0; t < nt; t += 2) {
;             const bool last = (t == nt - 2);
;             const char* a1 = cA + (size_t)(t + 1) * kstep;
;             const char* a2 = last ? nA : cA + (size_t)(t + 2) * kstep; const char* b2 = last ? nB : cB + (size_t)(t + 2) * kstep;
;             const char* a3 = a2 + kstep; const char* b3 = b2 + kstep;
;     ...
;             PG8_LDA(At, 1, 1); PG8_STAGE(PG8_SB(1, 0), b3, voffB); PG8_STAGE(PG8_SB(1, 1), b3 + hstep, voffB); PG8_STAGE(PG8_SA(1, 0), a3, voffA);
;             PG8_WAIT_V(8); PG8_WAIT_L(0); PG8_BAR; PG8_MMA(1, 0, At, B0); PG8_MMA(1, 1, At, B1); PG8_BAR; PG8_SCHED;
	s_add_i32 s56, s82, s59
	v_lshl_add_u64 v[204:205], v[204:205], 0, s[18:19]
	s_mov_b32 m0, s56
	ds_read_b128 v[180:183], v147 offset:49152
	ds_read_b128 v[184:187], v147 offset:50176
	ds_read_b128 v[188:191], v147 offset:51200
	ds_read_b128 v[192:195], v147 offset:52224
	ds_read_b128 v[196:199], v147 offset:53248
	ds_read_b128 v[200:203], v147 offset:54272
	ds_read_b128 v[208:211], v147 offset:55296
	ds_read_b128 v[212:215], v147 offset:56320
	global_load_lds_dwordx4 v[204:205], off
	s_add_i32 m0, s56, 0x2000
	s_add_u32 s46, s46, 0x40080
	v_lshl_add_u64 v[204:205], v[216:217], 0, s[18:19]
	s_addc_u32 s47, s47, 0
	s_add_i32 s56, s83, s59
	global_load_lds_dwordx4 v[204:205], off
	v_lshl_add_u64 v[204:205], s[46:47], 0, v[130:131]
	s_mov_b32 m0, s56
	s_nop 0
	global_load_lds_dwordx4 v[204:205], off
	v_lshl_add_u64 v[204:205], s[46:47], 0, v[134:135]
	s_add_i32 m0, s56, 0x2000
	s_nop 0
	global_load_lds_dwordx4 v[204:205], off
	v_lshl_add_u64 v[204:205], v[218:219], 0, s[18:19]
	s_mov_b32 m0, s68
	s_nop 0
	global_load_lds_dwordx4 v[204:205], off
	v_lshl_add_u64 v[204:205], v[220:221], 0, s[18:19]
	s_mov_b32 m0, s69
	s_nop 0
	global_load_lds_dwordx4 v[204:205], off
	s_waitcnt vmcnt(8)
	s_waitcnt lgkmcnt(0)
	s_barrier
	s_setprio 1
	s_waitcnt lgkmcnt(0)
	v_mfma_f32_16x16x32_bf16 v[60:63], v[148:151], v[180:183], v[60:63]
	v_mfma_f32_16x16x32_bf16 v[56:59], v[156:159], v[180:183], v[56:59]
	v_mfma_f32_16x16x32_bf16 v[52:55], v[148:151], v[188:191], v[52:55]
	v_mfma_f32_16x16x32_bf16 v[48:51], v[156:159], v[188:191], v[48:51]
	v_mfma_f32_16x16x32_bf16 v[36:39], v[148:151], v[196:199], v[36:39]
	v_mfma_f32_16x16x32_bf16 v[32:35], v[156:159], v[196:199], v[32:35]
	v_mfma_f32_16x16x32_bf16 v[20:23], v[148:151], v[208:211], v[20:23]
	v_mfma_f32_16x16x32_bf16 v[16:19], v[156:159], v[208:211], v[16:19]
	v_mfma_f32_16x16x32_bf16 v[60:63], v[152:155], v[184:187], v[60:63]
	v_mfma_f32_16x16x32_bf16 v[56:59], v[160:163], v[184:187], v[56:59]
	v_mfma_f32_16x16x32_bf16 v[52:55], v[152:155], v[192:195], v[52:55]
	v_mfma_f32_16x16x32_bf16 v[48:51], v[160:163], v[192:195], v[48:51]
	v_mfma_f32_16x16x32_bf16 v[36:39], v[152:155], v[200:203], v[36:39]
	v_mfma_f32_16x16x32_bf16 v[32:35], v[160:163], v[200:203], v[32:35]
	v_mfma_f32_16x16x32_bf16 v[20:23], v[152:155], v[212:215], v[20:23]
	v_mfma_f32_16x16x32_bf16 v[16:19], v[160:163], v[212:215], v[16:19]
	s_setprio 0
	s_setprio 1
	v_mfma_f32_16x16x32_bf16 v[44:47], v[164:167], v[180:183], v[44:47]
	v_mfma_f32_16x16x32_bf16 v[40:43], v[172:175], v[180:183], v[40:43]
	v_mfma_f32_16x16x32_bf16 v[28:31], v[164:167], v[188:191], v[28:31]
	v_mfma_f32_16x16x32_bf16 v[24:27], v[172:175], v[188:191], v[24:27]
	v_mfma_f32_16x16x32_bf16 v[12:15], v[164:167], v[196:199], v[12:15]
	v_mfma_f32_16x16x32_bf16 v[8:11], v[172:175], v[196:199], v[8:11]
	v_mfma_f32_16x16x32_bf16 v[4:7], v[164:167], v[208:211], v[4:7]
	v_mfma_f32_16x16x32_bf16 v[0:3], v[172:175], v[208:211], v[0:3]
	v_mfma_f32_16x16x32_bf16 v[44:47], v[168:171], v[184:187], v[44:47]
	v_mfma_f32_16x16x32_bf16 v[40:43], v[176:179], v[184:187], v[40:43]
	v_mfma_f32_16x16x32_bf16 v[28:31], v[168:171], v[192:195], v[28:31]
	v_mfma_f32_16x16x32_bf16 v[24:27], v[176:179], v[192:195], v[24:27]
	v_mfma_f32_16x16x32_bf16 v[12:15], v[168:171], v[200:203], v[12:15]
	v_mfma_f32_16x16x32_bf16 v[8:11], v[176:179], v[200:203], v[8:11]
	v_mfma_f32_16x16x32_bf16 v[4:7], v[168:171], v[212:215], v[4:7]
	v_mfma_f32_16x16x32_bf16 v[0:3], v[176:179], v[212:215], v[0:3]
	s_setprio 0
	s_barrier
	s_add_i32 s81, s81, 2
	s_add_u32 s44, s44, 0x100
	s_addc_u32 s45, s45, 0
	s_add_u32 s79, s79, 0x100
	s_addc_u32 s80, s80, 0
	s_cmp_gt_u32 s81, 13
	s_cbranch_scc0 .LBB0_1609
	s_branch .Lpeel_exit_11

;     __device__ __forceinline__ bool next(int i, Unit& u) const { if (i != 0) return false; const int c0 = (G >= 8) ? G - 5 : G - 2; int k = -1; if (c == c0) k = 0; else if (c == G - 1) k = 1; if (k < 0 || k >= n) return false; u.pm = k; u.pn = 0; return true; }
; #define PG8_STAGE(bufoff, gbase, voff) do { _Pragma("unroll") for (int _i = 0; _i < 2; ++_i) \
;         __builtin_amdgcn_global_load_lds((const unsigned*)((const char*)(gbase) + (voff)[_i]), (PG8_LAS unsigned*)(lds + (bufoff) + ldsw + _i * 8192), 16, 0, 0); } while (0)
; #define PG8_LDA(dst, b, h) do { _Pragma("unroll") for (int m = 0; m < 4; ++m) _Pragma("unroll") for (int k = 0; k < 2; ++k) dst[m][k] = *(const PG8_LAS bf16x8*)(lds + PG8_SA(b, h) + aoff + m * 2048 + k * 1024); } while (0)
; #define PG8_LDB(dst, b, h) do { _Pragma("unroll") for (int n = 0; n < 2; ++n) _Pragma("unroll") for (int k = 0; k < 2; ++k) dst[n][k] = *(const PG8_LAS bf16x8*)(lds + PG8_SB(b, h) + boff + n * 2048 + k * 1024); } while (0)
; template <class Epi, class Sched, bool ALIGN_EPI = false, bool SP2 = false>
; __device__ __forceinline__ void gemm_phase(PG8_LAS unsigned char* lds, const Gemm g, const Sched& S, const Epi& E) {
;     ...
;         const bool has_next = S.next(ui + 1, nxt);
;         const char* nA = has_next ? (const char*)g.A + (size_t)nxt.pm * tstep : cA; const char* nB = has_next ? (const char*)g.Bt + (size_t)nxt.pn * tstep : cB;
;         for (int t = 0; t < nt; t += 2) {
;             const bool last = (t == nt - 2);
;             const char* a1 = cA + (size_t)(t + 1) * kstep;
;             const char* a2 = last ? nA : cA + (size_t)(t + 2) * kstep; const char* b2 = last ? nB : cB + (size_t)(t + 2) * kstep;
;             const char* a3 = a2 + kstep; const char* b3 = b2 + kstep;
;             if (last && has_next) S.a_ready(nxt);
;             if constexpr (SP2) {
;             PG8_LDB(B0, 0, 0); PG8_LDB(B1, 0, 1); PG8_SCHED; PG8_LDA(At, 0, 0); PG8_STAGE(PG8_SA(1, 1), a1 + hstep, voffA);
;             PG8_WAIT_V(8); PG8_WAIT_L(0); PG8_BAR; PG8_MMA(0, 0, At, B0); PG8_MMA(0, 1, At, B1); PG8_BAR; PG8_SCHED;
;             PG8_LDA(At, 0, 1); PG8_STAGE(PG8_SB(0, 0), b2, voffB); PG8_STAGE(PG8_SB(0, 1), b2 + hstep, voffB); PG8_STAGE(PG8_SA(0, 0), a2, voffA);
;             PG8_WAIT_V(8); PG8_WAIT_L(0); PG8_BAR; PG8_MMA(1, 0, At, B0); PG8_MMA(1, 1, At, B1); PG8_BAR; PG8_SCHED;
.LBB0_1787:
	s_ashr_i32 s21, s20, 31
	s_lshl_b64 s[24:25], s[20:21], 19
	s_add_u32 s24, s97, s24
	s_addc_u32 s25, s3, s25
	s_and_b64 s[26:27], s[22:23], exec
	s_cselect_b32 s21, s25, s31
	s_cselect_b32 s61, s24, s30
	s_ashr_i32 s19, s18, 31
	s_lshl_b64 s[26:27], s[18:19], 19
	s_add_u32 s26, s38, s26
	s_addc_u32 s27, s39, s27
	s_and_b64 s[36:37], s[22:23], exec
	s_cselect_b32 s19, s27, s35
	s_cselect_b32 s64, s26, s34
	s_add_u32 s30, s30, 0x40080
	s_addc_u32 s31, s31, 0
	s_add_u32 s65, s34, 0x100
	v_mov_b32_e32 v0, 0
	s_addc_u32 s66, s35, 0
	s_mov_b32 s67, -2
	ds_read_b128 v[164:167], v160
	ds_read_b128 v[168:171], v160 offset:1024
	ds_read_b128 v[172:175], v160 offset:2048
	ds_read_b128 v[176:179], v160 offset:3072
	ds_read_b128 v[180:183], v161
	ds_read_b128 v[184:187], v161 offset:1024
	ds_read_b128 v[188:191], v161 offset:2048
	ds_read_b128 v[192:195], v161 offset:3072
	s_add_u32 s34, s30, 0xfffc0080
	s_addc_u32 s35, s31, -1
	s_cmp_eq_u32 s67, 12
	s_cselect_b32 s37, s21, s35
	s_cselect_b32 s36, s61, s34
	s_cselect_b32 s35, s19, s66
	s_cselect_b32 s34, s64, s65
	v_lshl_add_u64 v[142:143], s[30:31], 0, v[136:137]
	s_add_i32 m0, s29, 0xc000
	ds_read_b128 v[196:199], v162
	ds_read_b128 v[200:203], v162 offset:1024
	ds_read_b128 v[208:211], v162 offset:2048
	ds_read_b128 v[212:215], v162 offset:3072
	ds_read_b128 v[216:219], v162 offset:4096
	ds_read_b128 v[220:223], v162 offset:5120
	ds_read_b128 v[224:227], v162 offset:6144
	ds_read_b128 v[228:231], v162 offset:7168
	global_load_lds_dwordx4 v[142:143], off
	v_lshl_add_u64 v[142:143], s[30:31], 0, v[138:139]
	s_add_i32 m0, s29, 0xe000
	s_nop 0
	global_load_lds_dwordx4 v[142:143], off
	s_waitcnt vmcnt(8)
	s_waitcnt lgkmcnt(0)
	s_barrier
	s_setprio 1
	s_waitcnt lgkmcnt(0)
	v_mfma_f32_16x16x32_bf16 v[124:127], v[164:167], v[196:199], 0
	v_mfma_f32_16x16x32_bf16 v[120:123], v[172:175], v[196:199], 0
	v_mfma_f32_16x16x32_bf16 v[108:111], v[164:167], v[208:211], 0
	v_mfma_f32_16x16x32_bf16 v[104:107], v[172:175], v[208:211], 0
	v_mfma_f32_16x16x32_bf16 v[92:95], v[164:167], v[216:219], 0
	v_mfma_f32_16x16x32_bf16 v[88:91], v[172:175], v[216:219], 0
	v_mfma_f32_16x16x32_bf16 v[76:79], v[164:167], v[224:227], 0
	v_mfma_f32_16x16x32_bf16 v[72:75], v[172:175], v[224:227], 0
	v_mfma_f32_16x16x32_bf16 v[124:127], v[168:171], v[200:203], v[124:127]
	v_mfma_f32_16x16x32_bf16 v[120:123], v[176:179], v[200:203], v[120:123]
	v_mfma_f32_16x16x32_bf16 v[108:111], v[168:171], v[212:215], v[108:111]
	v_mfma_f32_16x16x32_bf16 v[104:107], v[176:179], v[212:215], v[104:107]
	v_mfma_f32_16x16x32_bf16 v[92:95], v[168:171], v[220:223], v[92:95]
	v_mfma_f32_16x16x32_bf16 v[88:91], v[176:179], v[220:223], v[88:91]
	v_mfma_f32_16x16x32_bf16 v[76:79], v[168:171], v[228:231], v[76:79]
	v_mfma_f32_16x16x32_bf16 v[72:75], v[176:179], v[228:231], v[72:75]
	s_setprio 0
	s_setprio 1
	v_mfma_f32_16x16x32_bf16 v[116:119], v[180:183], v[196:199], 0
	v_mfma_f32_16x16x32_bf16 v[112:115], v[188:191], v[196:199], 0
	v_mfma_f32_16x16x32_bf16 v[100:103], v[180:183], v[208:211], 0
	v_mfma_f32_16x16x32_bf16 v[96:99], v[188:191], v[208:211], 0
	v_mfma_f32_16x16x32_bf16 v[84:87], v[180:183], v[216:219], 0
	v_mfma_f32_16x16x32_bf16 v[80:83], v[188:191], v[216:219], 0
	v_mfma_f32_16x16x32_bf16 v[68:71], v[180:183], v[224:227], 0
	v_mfma_f32_16x16x32_bf16 v[64:67], v[188:191], v[224:227], 0
	v_mfma_f32_16x16x32_bf16 v[116:119], v[184:187], v[200:203], v[116:119]
	v_mfma_f32_16x16x32_bf16 v[112:115], v[192:195], v[200:203], v[112:115]
	v_mfma_f32_16x16x32_bf16 v[100:103], v[184:187], v[212:215], v[100:103]
	v_mfma_f32_16x16x32_bf16 v[96:99], v[192:195], v[212:215], v[96:99]
	v_mfma_f32_16x16x32_bf16 v[84:87], v[184:187], v[220:223], v[84:87]
	v_mfma_f32_16x16x32_bf16 v[80:83], v[192:195], v[220:223], v[80:83]
	v_mfma_f32_16x16x32_bf16 v[68:71], v[184:187], v[228:231], v[68:71]
	v_mfma_f32_16x16x32_bf16 v[64:67], v[192:195], v[228:231], v[64:67]
	s_setprio 0
	s_barrier
	s_add_i32 s68, s57, s40
	v_lshl_add_u64 v[142:143], s[34:35], 0, v[130:131]
	s_mov_b32 m0, s68
	ds_read_b128 v[196:199], v162 offset:16384
	ds_read_b128 v[200:203], v162 offset:17408
	ds_read_b128 v[208:211], v162 offset:18432
	ds_read_b128 v[212:215], v162 offset:19456
	ds_read_b128 v[216:219], v162 offset:20480
	ds_read_b128 v[220:223], v162 offset:21504
	ds_read_b128 v[224:227], v162 offset:22528
	ds_read_b128 v[228:231], v162 offset:23552
	global_load_lds_dwordx4 v[142:143], off
	s_add_i32 m0, s68, 0x2000
	s_add_u32 s68, s34, 0x40000
	v_lshl_add_u64 v[204:205], s[34:35], 0, v[134:135]
	s_addc_u32 s69, s35, 0
	s_add_i32 s70, s58, s40
	global_load_lds_dwordx4 v[204:205], off
	v_lshl_add_u64 v[232:233], s[68:69], 0, v[130:131]
	s_mov_b32 m0, s70
	v_lshl_add_u64 v[234:235], s[36:37], 0, v[132:133]
	global_load_lds_dwordx4 v[232:233], off
	v_lshl_add_u64 v[232:233], s[68:69], 0, v[134:135]
	s_add_i32 m0, s70, 0x2000
	s_nop 0
	global_load_lds_dwordx4 v[232:233], off
	v_lshl_add_u64 v[232:233], s[36:37], 0, v[128:129]
	s_mov_b32 m0, s29
	s_nop 0
	global_load_lds_dwordx4 v[232:233], off
	s_mov_b32 m0, s43
	s_nop 0
	global_load_lds_dwordx4 v[234:235], off
	s_waitcnt vmcnt(8)
	s_waitcnt lgkmcnt(0)
	s_barrier
; #define PG8_STAGE(bufoff, gbase, voff) do { _Pragma("unroll") for (int _i = 0; _i < 2; ++_i) \
;         __builtin_amdgcn_global_load_lds((const unsigned*)((const char*)(gbase) + (voff)[_i]), (PG8_LAS unsigned*)(lds + (bufoff) + ldsw + _i * 8192), 16, 0, 0); } while (0)
; #define PG8_LDA(dst, b, h) do { _Pragma("unroll") for (int m = 0; m < 4; ++m) _Pragma("unroll") for (int k = 0; k < 2; ++k) dst[m][k] = *(const PG8_LAS bf16x8*)(lds + PG8_SA(b, h) + aoff + m * 2048 + k * 1024); } while (0)
; #define PG8_LDB(dst, b, h) do { _Pragma("unroll") for (int n = 0; n < 2; ++n) _Pragma("unroll") for (int k = 0; k < 2; ++k) dst[n][k] = *(const PG8_LAS bf16x8*)(lds + PG8_SB(b, h) + boff + n * 2048 + k * 1024); } while (0)
; #define PG8_MMA(ai, bj, At, Bt) do { __builtin_amdgcn_s_setprio(1); _Pragma("unroll") for (int m = 0; m < 4; ++m) _Pragma("unroll") for (int n = 0; n < 2; ++n) _Pragma("unroll") for (int k = 0; k < 2; ++k) \
;         acc[ai][bj][m][n] = __builtin_amdgcn_mfma_f32_16x16x32_bf16(Bt[n][k], At[m][k], acc[ai][bj][m][n], 0, 0, 0); __builtin_amdgcn_s_setprio(0); } while (0)
; #define PG8_WAIT_V(n) asm volatile("s_waitcnt vmcnt(" #n ")" ::: "memory")
; #define PG8_WAIT_L(n) asm volatile("s_waitcnt lgkmcnt(" #n ")" ::: "memory")
; #define PG8_BAR __builtin_amdgcn_s_barrier()
; #define PG8_SCHED __builtin_amdgcn_sched_barrier(0)
; template <class Epi, class Sched, bool ALIGN_EPI = false, bool SP2 = false>
; __device__ __forceinline__ void gemm_phase(PG8_LAS unsigned char* lds, const Gemm g, const Sched& S, const Epi& E) {
;     ...
;             PG8_WAIT_V(8); PG8_WAIT_L(0); PG8_BAR; PG8_MMA(1, 0, At, B0); PG8_MMA(1, 1, At, B1); PG8_BAR; PG8_SCHED;
;             PG8_LDB(B0, 1, 0); PG8_LDB(B1, 1, 1); PG8_SCHED; PG8_LDA(At, 1, 0); PG8_STAGE(PG8_SA(0, 1), a2 + hstep, voffA);
;             PG8_WAIT_V(8); PG8_WAIT_L(0); PG8_BAR; PG8_MMA(0, 0, At, B0); PG8_MMA(0, 1, At, B1); PG8_BAR; PG8_SCHED;
	s_setprio 1
	s_waitcnt lgkmcnt(0)
	v_mfma_f32_16x16x32_bf16 v[60:63], v[164:167], v[196:199], 0
	v_mfma_f32_16x16x32_bf16 v[56:59], v[172:175], v[196:199], 0
	v_mfma_f32_16x16x32_bf16 v[44:47], v[164:167], v[208:211], 0
	v_mfma_f32_16x16x32_bf16 v[40:43], v[172:175], v[208:211], 0
	v_mfma_f32_16x16x32_bf16 v[28:31], v[164:167], v[216:219], 0
	v_mfma_f32_16x16x32_bf16 v[24:27], v[172:175], v[216:219], 0
	v_mfma_f32_16x16x32_bf16 v[12:15], v[164:167], v[224:227], 0
	v_mfma_f32_16x16x32_bf16 v[8:11], v[172:175], v[224:227], 0
	v_mfma_f32_16x16x32_bf16 v[60:63], v[168:171], v[200:203], v[60:63]
	v_mfma_f32_16x16x32_bf16 v[56:59], v[176:179], v[200:203], v[56:59]
	v_mfma_f32_16x16x32_bf16 v[44:47], v[168:171], v[212:215], v[44:47]
	v_mfma_f32_16x16x32_bf16 v[40:43], v[176:179], v[212:215], v[40:43]
	v_mfma_f32_16x16x32_bf16 v[28:31], v[168:171], v[220:223], v[28:31]
	v_mfma_f32_16x16x32_bf16 v[24:27], v[176:179], v[220:223], v[24:27]
	v_mfma_f32_16x16x32_bf16 v[12:15], v[168:171], v[228:231], v[12:15]
	v_mfma_f32_16x16x32_bf16 v[8:11], v[176:179], v[228:231], v[8:11]
	s_setprio 0
	s_setprio 1
	v_mfma_f32_16x16x32_bf16 v[52:55], v[180:183], v[196:199], 0
	v_mfma_f32_16x16x32_bf16 v[48:51], v[188:191], v[196:199], 0
	v_mfma_f32_16x16x32_bf16 v[36:39], v[180:183], v[208:211], 0
	v_mfma_f32_16x16x32_bf16 v[32:35], v[188:191], v[208:211], 0
	v_mfma_f32_16x16x32_bf16 v[20:23], v[180:183], v[216:219], 0
	v_mfma_f32_16x16x32_bf16 v[16:19], v[188:191], v[216:219], 0
	v_mfma_f32_16x16x32_bf16 v[4:7], v[180:183], v[224:227], 0
	v_mfma_f32_16x16x32_bf16 v[0:3], v[188:191], v[224:227], 0
	v_mfma_f32_16x16x32_bf16 v[52:55], v[184:187], v[200:203], v[52:55]
	v_mfma_f32_16x16x32_bf16 v[48:51], v[192:195], v[200:203], v[48:51]
	v_mfma_f32_16x16x32_bf16 v[36:39], v[184:187], v[212:215], v[36:39]
	v_mfma_f32_16x16x32_bf16 v[32:35], v[192:195], v[212:215], v[32:35]
	v_mfma_f32_16x16x32_bf16 v[20:23], v[184:187], v[220:223], v[20:23]
	v_mfma_f32_16x16x32_bf16 v[16:19], v[192:195], v[220:223], v[16:19]
	v_mfma_f32_16x16x32_bf16 v[4:7], v[184:187], v[228:231], v[4:7]
	v_mfma_f32_16x16x32_bf16 v[0:3], v[192:195], v[228:231], v[0:3]
	s_setprio 0
	s_barrier
	s_add_i32 s68, 0, 0x18000
	v_add_u32_e32 v163, s68, v158
	s_add_i32 s69, 0, 0x1c000
	ds_read_b128 v[164:167], v163
	ds_read_b128 v[168:171], v163 offset:1024
	ds_read_b128 v[172:175], v163 offset:2048
	ds_read_b128 v[176:179], v163 offset:3072
	v_add_u32_e32 v163, s69, v158
	ds_read_b128 v[180:183], v163
	ds_read_b128 v[184:187], v163 offset:1024
	ds_read_b128 v[188:191], v163 offset:2048
	ds_read_b128 v[192:195], v163 offset:3072
	s_add_u32 s36, s36, 0x40000
	s_addc_u32 s37, s37, 0
	s_mov_b32 m0, s44
	v_lshl_add_u64 v[236:237], s[36:37], 0, v[128:129]
	ds_read_b128 v[196:199], v162 offset:32768
	ds_read_b128 v[200:203], v162 offset:33792
	ds_read_b128 v[208:211], v162 offset:34816
	ds_read_b128 v[212:215], v162 offset:35840
	ds_read_b128 v[216:219], v162 offset:36864
	ds_read_b128 v[220:223], v162 offset:37888
	ds_read_b128 v[224:227], v162 offset:38912
	ds_read_b128 v[228:231], v162 offset:39936
	global_load_lds_dwordx4 v[236:237], off
	v_lshl_add_u64 v[236:237], s[36:37], 0, v[132:133]
	s_mov_b32 m0, s45
	s_nop 0
	global_load_lds_dwordx4 v[236:237], off
	s_waitcnt vmcnt(8)
	s_waitcnt lgkmcnt(0)
	s_barrier
	s_setprio 1
	s_waitcnt lgkmcnt(0)
	v_mfma_f32_16x16x32_bf16 v[124:127], v[164:167], v[196:199], v[124:127]
	v_mfma_f32_16x16x32_bf16 v[120:123], v[172:175], v[196:199], v[120:123]
	v_mfma_f32_16x16x32_bf16 v[108:111], v[164:167], v[208:211], v[108:111]
	v_mfma_f32_16x16x32_bf16 v[104:107], v[172:175], v[208:211], v[104:107]
	v_mfma_f32_16x16x32_bf16 v[92:95], v[164:167], v[216:219], v[92:95]
	v_mfma_f32_16x16x32_bf16 v[88:91], v[172:175], v[216:219], v[88:91]
	v_mfma_f32_16x16x32_bf16 v[76:79], v[164:167], v[224:227], v[76:79]
	v_mfma_f32_16x16x32_bf16 v[72:75], v[172:175], v[224:227], v[72:75]
	v_mfma_f32_16x16x32_bf16 v[124:127], v[168:171], v[200:203], v[124:127]
	v_mfma_f32_16x16x32_bf16 v[120:123], v[176:179], v[200:203], v[120:123]
	v_mfma_f32_16x16x32_bf16 v[108:111], v[168:171], v[212:215], v[108:111]
	v_mfma_f32_16x16x32_bf16 v[104:107], v[176:179], v[212:215], v[104:107]
	v_mfma_f32_16x16x32_bf16 v[92:95], v[168:171], v[220:223], v[92:95]
	v_mfma_f32_16x16x32_bf16 v[88:91], v[176:179], v[220:223], v[88:91]
	v_mfma_f32_16x16x32_bf16 v[76:79], v[168:171], v[228:231], v[76:79]
	v_mfma_f32_16x16x32_bf16 v[72:75], v[176:179], v[228:231], v[72:75]
	s_setprio 0
	s_setprio 1
	v_mfma_f32_16x16x32_bf16 v[116:119], v[180:183], v[196:199], v[116:119]
	v_mfma_f32_16x16x32_bf16 v[112:115], v[188:191], v[196:199], v[112:115]
	v_mfma_f32_16x16x32_bf16 v[100:103], v[180:183], v[208:211], v[100:103]
	v_mfma_f32_16x16x32_bf16 v[96:99], v[188:191], v[208:211], v[96:99]
	v_mfma_f32_16x16x32_bf16 v[84:87], v[180:183], v[216:219], v[84:87]
	v_mfma_f32_16x16x32_bf16 v[80:83], v[188:191], v[216:219], v[80:83]
	v_mfma_f32_16x16x32_bf16 v[68:71], v[180:183], v[224:227], v[68:71]
	v_mfma_f32_16x16x32_bf16 v[64:67], v[188:191], v[224:227], v[64:67]
	v_mfma_f32_16x16x32_bf16 v[116:119], v[184:187], v[200:203], v[116:119]
	v_mfma_f32_16x16x32_bf16 v[112:115], v[192:195], v[200:203], v[112:115]
	v_mfma_f32_16x16x32_bf16 v[100:103], v[184:187], v[212:215], v[100:103]
	v_mfma_f32_16x16x32_bf16 v[96:99], v[192:195], v[212:215], v[96:99]
	v_mfma_f32_16x16x32_bf16 v[84:87], v[184:187], v[220:223], v[84:87]
	v_mfma_f32_16x16x32_bf16 v[80:83], v[192:195], v[220:223], v[80:83]
	v_mfma_f32_16x16x32_bf16 v[68:71], v[184:187], v[228:231], v[68:71]
	v_mfma_f32_16x16x32_bf16 v[64:67], v[192:195], v[228:231], v[64:67]
	s_setprio 0
	s_barrier
; #define PG8_STAGE(bufoff, gbase, voff) do { _Pragma("unroll") for (int _i = 0; _i < 2; ++_i) \
;         __builtin_amdgcn_global_load_lds((const unsigned*)((const char*)(gbase) + (voff)[_i]), (PG8_LAS unsigned*)(lds + (bufoff) + ldsw + _i * 8192), 16, 0, 0); } while (0)
; #define PG8_LDA(dst, b, h) do { _Pragma("unroll") for (int m = 0; m < 4; ++m) _Pragma("unroll") for (int k = 0; k < 2; ++k) dst[m][k] = *(const PG8_LAS bf16x8*)(lds + PG8_SA(b, h) + aoff + m * 2048 + k * 1024); } while (0)
; #define PG8_MMA(ai, bj, At, Bt) do { __builtin_amdgcn_s_setprio(1); _Pragma("unroll") for (int m = 0; m < 4; ++m) _Pragma("unroll") for (int n = 0; n < 2; ++n) _Pragma("unroll") for (int k = 0; k < 2; ++k) \
;         acc[ai][bj][m][n] = __builtin_amdgcn_mfma_f32_16x16x32_bf16(Bt[n][k], At[m][k], acc[ai][bj][m][n], 0, 0, 0); __builtin_amdgcn_s_setprio(0); } while (0)
; #define PG8_WAIT_V(n) asm volatile("s_waitcnt vmcnt(" #n ")" ::: "memory")
; #define PG8_WAIT_L(n) asm volatile("s_waitcnt lgkmcnt(" #n ")" ::: "memory")
; #define PG8_BAR __builtin_amdgcn_s_barrier()
; #define PG8_SCHED __builtin_amdgcn_sched_barrier(0)
; template <class Epi, class Sched, bool ALIGN_EPI = false, bool SP2 = false>
; __device__ __forceinline__ void gemm_phase(PG8_LAS unsigned char* lds, const Gemm g, const Sched& S, const Epi& E) {
;     ...
;         for (int t = 0; t < nt; t += 2) {
;             const bool last = (t == nt - 2);
;             const char* a1 = cA + (size_t)(t + 1) * kstep;
;             const char* a2 = last ? nA : cA + (size_t)(t + 2) * kstep; const char* b2 = last ? nB : cB + (size_t)(t + 2) * kstep;
;             const char* a3 = a2 + kstep; const char* b3 = b2 + kstep;
;     ...
;             PG8_LDA(At, 1, 1); PG8_STAGE(PG8_SB(1, 0), b3, voffB); PG8_STAGE(PG8_SB(1, 1), b3 + hstep, voffB); PG8_STAGE(PG8_SA(1, 0), a3, voffA);
;             PG8_WAIT_V(8); PG8_WAIT_L(0); PG8_BAR; PG8_MMA(1, 0, At, B0); PG8_MMA(1, 1, At, B1); PG8_BAR; PG8_SCHED;
	s_add_i32 s36, s68, s40
	v_lshl_add_u64 v[142:143], v[142:143], 0, s[8:9]
	s_mov_b32 m0, s36
	ds_read_b128 v[196:199], v162 offset:49152
	ds_read_b128 v[200:203], v162 offset:50176
	ds_read_b128 v[208:211], v162 offset:51200
	ds_read_b128 v[212:215], v162 offset:52224
	ds_read_b128 v[216:219], v162 offset:53248
	ds_read_b128 v[220:223], v162 offset:54272
	ds_read_b128 v[224:227], v162 offset:55296
	ds_read_b128 v[228:231], v162 offset:56320
	global_load_lds_dwordx4 v[142:143], off
	s_add_i32 m0, s36, 0x2000
	s_add_u32 s34, s34, 0x40080
	v_lshl_add_u64 v[142:143], v[204:205], 0, s[8:9]
	s_addc_u32 s35, s35, 0
	s_add_i32 s36, s69, s40
	global_load_lds_dwordx4 v[142:143], off
	v_lshl_add_u64 v[142:143], s[34:35], 0, v[130:131]
	s_mov_b32 m0, s36
	s_nop 0
	global_load_lds_dwordx4 v[142:143], off
	v_lshl_add_u64 v[142:143], s[34:35], 0, v[134:135]
	s_add_i32 m0, s36, 0x2000
	s_nop 0
	global_load_lds_dwordx4 v[142:143], off
	v_lshl_add_u64 v[142:143], v[232:233], 0, s[8:9]
	s_mov_b32 m0, s52
	s_nop 0
	global_load_lds_dwordx4 v[142:143], off
	v_lshl_add_u64 v[142:143], v[234:235], 0, s[8:9]
	s_mov_b32 m0, s53
	s_nop 0
	global_load_lds_dwordx4 v[142:143], off
	s_waitcnt vmcnt(8)
	s_waitcnt lgkmcnt(0)
	s_barrier
	s_setprio 1
	s_waitcnt lgkmcnt(0)
	v_mfma_f32_16x16x32_bf16 v[60:63], v[164:167], v[196:199], v[60:63]
	v_mfma_f32_16x16x32_bf16 v[56:59], v[172:175], v[196:199], v[56:59]
	v_mfma_f32_16x16x32_bf16 v[44:47], v[164:167], v[208:211], v[44:47]
	v_mfma_f32_16x16x32_bf16 v[40:43], v[172:175], v[208:211], v[40:43]
	v_mfma_f32_16x16x32_bf16 v[28:31], v[164:167], v[216:219], v[28:31]
	v_mfma_f32_16x16x32_bf16 v[24:27], v[172:175], v[216:219], v[24:27]
	v_mfma_f32_16x16x32_bf16 v[12:15], v[164:167], v[224:227], v[12:15]
	v_mfma_f32_16x16x32_bf16 v[8:11], v[172:175], v[224:227], v[8:11]
	v_mfma_f32_16x16x32_bf16 v[60:63], v[168:171], v[200:203], v[60:63]
	v_mfma_f32_16x16x32_bf16 v[56:59], v[176:179], v[200:203], v[56:59]
	v_mfma_f32_16x16x32_bf16 v[44:47], v[168:171], v[212:215], v[44:47]
	v_mfma_f32_16x16x32_bf16 v[40:43], v[176:179], v[212:215], v[40:43]
	v_mfma_f32_16x16x32_bf16 v[28:31], v[168:171], v[220:223], v[28:31]
	v_mfma_f32_16x16x32_bf16 v[24:27], v[176:179], v[220:223], v[24:27]
	v_mfma_f32_16x16x32_bf16 v[12:15], v[168:171], v[228:231], v[12:15]
	v_mfma_f32_16x16x32_bf16 v[8:11], v[176:179], v[228:231], v[8:11]
	s_setprio 0
	s_setprio 1
	v_mfma_f32_16x16x32_bf16 v[52:55], v[180:183], v[196:199], v[52:55]
	v_mfma_f32_16x16x32_bf16 v[48:51], v[188:191], v[196:199], v[48:51]
	v_mfma_f32_16x16x32_bf16 v[36:39], v[180:183], v[208:211], v[36:39]
	v_mfma_f32_16x16x32_bf16 v[32:35], v[188:191], v[208:211], v[32:35]
	v_mfma_f32_16x16x32_bf16 v[20:23], v[180:183], v[216:219], v[20:23]
	v_mfma_f32_16x16x32_bf16 v[16:19], v[188:191], v[216:219], v[16:19]
	v_mfma_f32_16x16x32_bf16 v[4:7], v[180:183], v[224:227], v[4:7]
	v_mfma_f32_16x16x32_bf16 v[0:3], v[188:191], v[224:227], v[0:3]
	v_mfma_f32_16x16x32_bf16 v[52:55], v[184:187], v[200:203], v[52:55]
	v_mfma_f32_16x16x32_bf16 v[48:51], v[192:195], v[200:203], v[48:51]
	v_mfma_f32_16x16x32_bf16 v[36:39], v[184:187], v[212:215], v[36:39]
	v_mfma_f32_16x16x32_bf16 v[32:35], v[192:195], v[212:215], v[32:35]
	v_mfma_f32_16x16x32_bf16 v[20:23], v[184:187], v[220:223], v[20:23]
	v_mfma_f32_16x16x32_bf16 v[16:19], v[192:195], v[220:223], v[16:19]
	v_mfma_f32_16x16x32_bf16 v[4:7], v[184:187], v[228:231], v[4:7]
	v_mfma_f32_16x16x32_bf16 v[0:3], v[192:195], v[228:231], v[0:3]
	s_setprio 0
	s_barrier
	s_add_i32 s67, s67, 2
	s_add_u32 s30, s30, 0x100
	s_addc_u32 s31, s31, 0
	s_add_u32 s65, s65, 0x100
	s_addc_u32 s66, s66, 0
	s_cmp_gt_u32 s67, 13
	s_cbranch_scc0 .LBB0_1788
	s_branch .Lpeel_exit_12

; #define PG8_BAR __builtin_amdgcn_s_barrier()
; template <class Epi, class Sched, bool ALIGN_EPI = false, bool SP2 = false>
; __device__ __forceinline__ void gemm_phase(PG8_LAS unsigned char* lds, const Gemm g, const Sched& S, const Epi& E) {
;     ...
;         if constexpr (ALIGN_EPI) { if (wr == 0) PG8_BAR; }
.Lpeel_exit_12:
	s_and_b64 vcc, exec, s[14:15]
	s_cbranch_vccz .LBB0_1791
	s_barrier

;     __device__ __forceinline__ bool next(int i, Unit& u) const { if (i != 0) return false; const int c0 = (G >= 8) ? G - 5 : G - 2; int k = -1; if (c == c0) k = 0; else if (c == G - 1) k = 1; if (k < 0 || k >= n) return false; u.pm = k; u.pn = 0; return true; }
; #define PG8_STAGE(bufoff, gbase, voff) do { _Pragma("unroll") for (int _i = 0; _i < 2; ++_i) \
;         __builtin_amdgcn_global_load_lds((const unsigned*)((const char*)(gbase) + (voff)[_i]), (PG8_LAS unsigned*)(lds + (bufoff) + ldsw + _i * 8192), 16, 0, 0); } while (0)
; #define PG8_LDA(dst, b, h) do { _Pragma("unroll") for (int m = 0; m < 4; ++m) _Pragma("unroll") for (int k = 0; k < 2; ++k) dst[m][k] = *(const PG8_LAS bf16x8*)(lds + PG8_SA(b, h) + aoff + m * 2048 + k * 1024); } while (0)
; #define PG8_LDB(dst, b, h) do { _Pragma("unroll") for (int n = 0; n < 2; ++n) _Pragma("unroll") for (int k = 0; k < 2; ++k) dst[n][k] = *(const PG8_LAS bf16x8*)(lds + PG8_SB(b, h) + boff + n * 2048 + k * 1024); } while (0)
; template <class Epi, class Sched, bool ALIGN_EPI = false, bool SP2 = false>
; __device__ __forceinline__ void gemm_phase(PG8_LAS unsigned char* lds, const Gemm g, const Sched& S, const Epi& E) {
;     ...
;         const bool has_next = S.next(ui + 1, nxt);
;         const char* nA = has_next ? (const char*)g.A + (size_t)nxt.pm * tstep : cA; const char* nB = has_next ? (const char*)g.Bt + (size_t)nxt.pn * tstep : cB;
;         for (int t = 0; t < nt; t += 2) {
;             const bool last = (t == nt - 2);
;             const char* a1 = cA + (size_t)(t + 1) * kstep;
;             const char* a2 = last ? nA : cA + (size_t)(t + 2) * kstep; const char* b2 = last ? nB : cB + (size_t)(t + 2) * kstep;
;             const char* a3 = a2 + kstep; const char* b3 = b2 + kstep;
;             if (last && has_next) S.a_ready(nxt);
;             if constexpr (SP2) {
;             PG8_LDB(B0, 0, 0); PG8_LDB(B1, 0, 1); PG8_SCHED; PG8_LDA(At, 0, 0); PG8_STAGE(PG8_SA(1, 1), a1 + hstep, voffA);
;             PG8_WAIT_V(8); PG8_WAIT_L(0); PG8_BAR; PG8_MMA(0, 0, At, B0); PG8_MMA(0, 1, At, B1); PG8_BAR; PG8_SCHED;
;             PG8_LDA(At, 0, 1); PG8_STAGE(PG8_SB(0, 0), b2, voffB); PG8_STAGE(PG8_SB(0, 1), b2 + hstep, voffB); PG8_STAGE(PG8_SA(0, 0), a2, voffA);
;             PG8_WAIT_V(8); PG8_WAIT_L(0); PG8_BAR; PG8_MMA(1, 0, At, B0); PG8_MMA(1, 1, At, B1); PG8_BAR; PG8_SCHED;
.LBB0_1808:
	s_ashr_i32 s19, s18, 31
	s_lshl_b64 s[24:25], s[18:19], 19
	s_add_u32 s24, s97, s24
	s_addc_u32 s25, s3, s25
	s_and_b64 s[26:27], s[22:23], exec
	s_cselect_b32 s19, s25, s31
	s_cselect_b32 s59, s24, s30
	s_ashr_i32 s21, s20, 31
	s_lshl_b64 s[26:27], s[20:21], 19
	s_add_u32 s26, s38, s26
	s_addc_u32 s27, s39, s27
	s_and_b64 s[36:37], s[22:23], exec
	s_cselect_b32 s21, s27, s35
	s_cselect_b32 s60, s26, s34
	s_add_u32 s30, s30, 0x40080
	s_addc_u32 s31, s31, 0
	s_add_u32 s61, s34, 0x100
	v_mov_b32_e32 v0, 0
	s_addc_u32 s64, s35, 0
	s_mov_b32 s65, -2
	ds_read_b128 v[164:167], v160
	ds_read_b128 v[168:171], v160 offset:1024
	ds_read_b128 v[172:175], v160 offset:2048
	ds_read_b128 v[176:179], v160 offset:3072
	ds_read_b128 v[180:183], v161
	ds_read_b128 v[184:187], v161 offset:1024
	ds_read_b128 v[188:191], v161 offset:2048
	ds_read_b128 v[192:195], v161 offset:3072
	s_add_u32 s34, s30, 0xfffc0080
	s_addc_u32 s35, s31, -1
	s_cmp_eq_u32 s65, 12
	s_cselect_b32 s37, s19, s35
	s_cselect_b32 s36, s59, s34
	s_cselect_b32 s35, s21, s64
	s_cselect_b32 s34, s60, s61
	v_lshl_add_u64 v[142:143], s[30:31], 0, v[136:137]
	s_add_i32 m0, s29, 0xc000
	ds_read_b128 v[196:199], v162
	ds_read_b128 v[200:203], v162 offset:1024
	ds_read_b128 v[208:211], v162 offset:2048
	ds_read_b128 v[212:215], v162 offset:3072
	ds_read_b128 v[216:219], v162 offset:4096
	ds_read_b128 v[220:223], v162 offset:5120
	ds_read_b128 v[224:227], v162 offset:6144
	ds_read_b128 v[228:231], v162 offset:7168
	global_load_lds_dwordx4 v[142:143], off
	v_lshl_add_u64 v[142:143], s[30:31], 0, v[138:139]
	s_add_i32 m0, s29, 0xe000
	s_nop 0
	global_load_lds_dwordx4 v[142:143], off
	s_waitcnt vmcnt(8)
	s_waitcnt lgkmcnt(0)
	s_barrier
	s_setprio 1
	s_waitcnt lgkmcnt(0)
	v_mfma_f32_16x16x32_bf16 v[124:127], v[164:167], v[196:199], 0
	v_mfma_f32_16x16x32_bf16 v[120:123], v[172:175], v[196:199], 0
	v_mfma_f32_16x16x32_bf16 v[108:111], v[164:167], v[208:211], 0
	v_mfma_f32_16x16x32_bf16 v[104:107], v[172:175], v[208:211], 0
	v_mfma_f32_16x16x32_bf16 v[92:95], v[164:167], v[216:219], 0
	v_mfma_f32_16x16x32_bf16 v[88:91], v[172:175], v[216:219], 0
	v_mfma_f32_16x16x32_bf16 v[76:79], v[164:167], v[224:227], 0
	v_mfma_f32_16x16x32_bf16 v[72:75], v[172:175], v[224:227], 0
	v_mfma_f32_16x16x32_bf16 v[124:127], v[168:171], v[200:203], v[124:127]
	v_mfma_f32_16x16x32_bf16 v[120:123], v[176:179], v[200:203], v[120:123]
	v_mfma_f32_16x16x32_bf16 v[108:111], v[168:171], v[212:215], v[108:111]
	v_mfma_f32_16x16x32_bf16 v[104:107], v[176:179], v[212:215], v[104:107]
	v_mfma_f32_16x16x32_bf16 v[92:95], v[168:171], v[220:223], v[92:95]
	v_mfma_f32_16x16x32_bf16 v[88:91], v[176:179], v[220:223], v[88:91]
	v_mfma_f32_16x16x32_bf16 v[76:79], v[168:171], v[228:231], v[76:79]
	v_mfma_f32_16x16x32_bf16 v[72:75], v[176:179], v[228:231], v[72:75]
	s_setprio 0
	s_setprio 1
	v_mfma_f32_16x16x32_bf16 v[116:119], v[180:183], v[196:199], 0
	v_mfma_f32_16x16x32_bf16 v[112:115], v[188:191], v[196:199], 0
	v_mfma_f32_16x16x32_bf16 v[100:103], v[180:183], v[208:211], 0
	v_mfma_f32_16x16x32_bf16 v[96:99], v[188:191], v[208:211], 0
	v_mfma_f32_16x16x32_bf16 v[84:87], v[180:183], v[216:219], 0
	v_mfma_f32_16x16x32_bf16 v[80:83], v[188:191], v[216:219], 0
	v_mfma_f32_16x16x32_bf16 v[68:71], v[180:183], v[224:227], 0
	v_mfma_f32_16x16x32_bf16 v[64:67], v[188:191], v[224:227], 0
	v_mfma_f32_16x16x32_bf16 v[116:119], v[184:187], v[200:203], v[116:119]
	v_mfma_f32_16x16x32_bf16 v[112:115], v[192:195], v[200:203], v[112:115]
	v_mfma_f32_16x16x32_bf16 v[100:103], v[184:187], v[212:215], v[100:103]
	v_mfma_f32_16x16x32_bf16 v[96:99], v[192:195], v[212:215], v[96:99]
	v_mfma_f32_16x16x32_bf16 v[84:87], v[184:187], v[220:223], v[84:87]
	v_mfma_f32_16x16x32_bf16 v[80:83], v[192:195], v[220:223], v[80:83]
	v_mfma_f32_16x16x32_bf16 v[68:71], v[184:187], v[228:231], v[68:71]
	v_mfma_f32_16x16x32_bf16 v[64:67], v[192:195], v[228:231], v[64:67]
	s_setprio 0
	s_barrier
	s_add_i32 s66, s53, s41
	v_lshl_add_u64 v[142:143], s[34:35], 0, v[130:131]
	s_mov_b32 m0, s66
	ds_read_b128 v[196:199], v162 offset:16384
	ds_read_b128 v[200:203], v162 offset:17408
	ds_read_b128 v[208:211], v162 offset:18432
	ds_read_b128 v[212:215], v162 offset:19456
	ds_read_b128 v[216:219], v162 offset:20480
	ds_read_b128 v[220:223], v162 offset:21504
	ds_read_b128 v[224:227], v162 offset:22528
	ds_read_b128 v[228:231], v162 offset:23552
	global_load_lds_dwordx4 v[142:143], off
	s_add_i32 m0, s66, 0x2000
	s_add_u32 s66, s34, 0x40000
	v_lshl_add_u64 v[204:205], s[34:35], 0, v[134:135]
	s_addc_u32 s67, s35, 0
	s_add_i32 s68, s56, s41
	global_load_lds_dwordx4 v[204:205], off
	v_lshl_add_u64 v[232:233], s[66:67], 0, v[130:131]
	s_mov_b32 m0, s68
	v_lshl_add_u64 v[234:235], s[36:37], 0, v[132:133]
	global_load_lds_dwordx4 v[232:233], off
	v_lshl_add_u64 v[232:233], s[66:67], 0, v[134:135]
	s_add_i32 m0, s68, 0x2000
	s_nop 0
	global_load_lds_dwordx4 v[232:233], off
	v_lshl_add_u64 v[232:233], s[36:37], 0, v[128:129]
	s_mov_b32 m0, s29
	s_nop 0
	global_load_lds_dwordx4 v[232:233], off
	s_mov_b32 m0, s43
	s_nop 0
	global_load_lds_dwordx4 v[234:235], off
	s_waitcnt vmcnt(8)
	s_waitcnt lgkmcnt(0)
	s_barrier
; #define PG8_STAGE(bufoff, gbase, voff) do { _Pragma("unroll") for (int _i = 0; _i < 2; ++_i) \
;         __builtin_amdgcn_global_load_lds((const unsigned*)((const char*)(gbase) + (voff)[_i]), (PG8_LAS unsigned*)(lds + (bufoff) + ldsw + _i * 8192), 16, 0, 0); } while (0)
; #define PG8_LDA(dst, b, h) do { _Pragma("unroll") for (int m = 0; m < 4; ++m) _Pragma("unroll") for (int k = 0; k < 2; ++k) dst[m][k] = *(const PG8_LAS bf16x8*)(lds + PG8_SA(b, h) + aoff + m * 2048 + k * 1024); } while (0)
; #define PG8_LDB(dst, b, h) do { _Pragma("unroll") for (int n = 0; n < 2; ++n) _Pragma("unroll") for (int k = 0; k < 2; ++k) dst[n][k] = *(const PG8_LAS bf16x8*)(lds + PG8_SB(b, h) + boff + n * 2048 + k * 1024); } while (0)
; #define PG8_MMA(ai, bj, At, Bt) do { __builtin_amdgcn_s_setprio(1); _Pragma("unroll") for (int m = 0; m < 4; ++m) _Pragma("unroll") for (int n = 0; n < 2; ++n) _Pragma("unroll") for (int k = 0; k < 2; ++k) \
;         acc[ai][bj][m][n] = __builtin_amdgcn_mfma_f32_16x16x32_bf16(Bt[n][k], At[m][k], acc[ai][bj][m][n], 0, 0, 0); __builtin_amdgcn_s_setprio(0); } while (0)
; #define PG8_WAIT_V(n) asm volatile("s_waitcnt vmcnt(" #n ")" ::: "memory")
; #define PG8_WAIT_L(n) asm volatile("s_waitcnt lgkmcnt(" #n ")" ::: "memory")
; #define PG8_BAR __builtin_amdgcn_s_barrier()
; #define PG8_SCHED __builtin_amdgcn_sched_barrier(0)
; template <class Epi, class Sched, bool ALIGN_EPI = false, bool SP2 = false>
; __device__ __forceinline__ void gemm_phase(PG8_LAS unsigned char* lds, const Gemm g, const Sched& S, const Epi& E) {
;     ...
;             PG8_WAIT_V(8); PG8_WAIT_L(0); PG8_BAR; PG8_MMA(1, 0, At, B0); PG8_MMA(1, 1, At, B1); PG8_BAR; PG8_SCHED;
;             PG8_LDB(B0, 1, 0); PG8_LDB(B1, 1, 1); PG8_SCHED; PG8_LDA(At, 1, 0); PG8_STAGE(PG8_SA(0, 1), a2 + hstep, voffA);
;             PG8_WAIT_V(8); PG8_WAIT_L(0); PG8_BAR; PG8_MMA(0, 0, At, B0); PG8_MMA(0, 1, At, B1); PG8_BAR; PG8_SCHED;
	s_setprio 1
	s_waitcnt lgkmcnt(0)
	v_mfma_f32_16x16x32_bf16 v[60:63], v[164:167], v[196:199], 0
	v_mfma_f32_16x16x32_bf16 v[56:59], v[172:175], v[196:199], 0
	v_mfma_f32_16x16x32_bf16 v[44:47], v[164:167], v[208:211], 0
	v_mfma_f32_16x16x32_bf16 v[40:43], v[172:175], v[208:211], 0
	v_mfma_f32_16x16x32_bf16 v[28:31], v[164:167], v[216:219], 0
	v_mfma_f32_16x16x32_bf16 v[24:27], v[172:175], v[216:219], 0
	v_mfma_f32_16x16x32_bf16 v[12:15], v[164:167], v[224:227], 0
	v_mfma_f32_16x16x32_bf16 v[8:11], v[172:175], v[224:227], 0
	v_mfma_f32_16x16x32_bf16 v[60:63], v[168:171], v[200:203], v[60:63]
	v_mfma_f32_16x16x32_bf16 v[56:59], v[176:179], v[200:203], v[56:59]
	v_mfma_f32_16x16x32_bf16 v[44:47], v[168:171], v[212:215], v[44:47]
	v_mfma_f32_16x16x32_bf16 v[40:43], v[176:179], v[212:215], v[40:43]
	v_mfma_f32_16x16x32_bf16 v[28:31], v[168:171], v[220:223], v[28:31]
	v_mfma_f32_16x16x32_bf16 v[24:27], v[176:179], v[220:223], v[24:27]
	v_mfma_f32_16x16x32_bf16 v[12:15], v[168:171], v[228:231], v[12:15]
	v_mfma_f32_16x16x32_bf16 v[8:11], v[176:179], v[228:231], v[8:11]
	s_setprio 0
	s_setprio 1
	v_mfma_f32_16x16x32_bf16 v[52:55], v[180:183], v[196:199], 0
	v_mfma_f32_16x16x32_bf16 v[48:51], v[188:191], v[196:199], 0
	v_mfma_f32_16x16x32_bf16 v[36:39], v[180:183], v[208:211], 0
	v_mfma_f32_16x16x32_bf16 v[32:35], v[188:191], v[208:211], 0
	v_mfma_f32_16x16x32_bf16 v[20:23], v[180:183], v[216:219], 0
	v_mfma_f32_16x16x32_bf16 v[16:19], v[188:191], v[216:219], 0
	v_mfma_f32_16x16x32_bf16 v[4:7], v[180:183], v[224:227], 0
	v_mfma_f32_16x16x32_bf16 v[0:3], v[188:191], v[224:227], 0
	v_mfma_f32_16x16x32_bf16 v[52:55], v[184:187], v[200:203], v[52:55]
	v_mfma_f32_16x16x32_bf16 v[48:51], v[192:195], v[200:203], v[48:51]
	v_mfma_f32_16x16x32_bf16 v[36:39], v[184:187], v[212:215], v[36:39]
	v_mfma_f32_16x16x32_bf16 v[32:35], v[192:195], v[212:215], v[32:35]
	v_mfma_f32_16x16x32_bf16 v[20:23], v[184:187], v[220:223], v[20:23]
	v_mfma_f32_16x16x32_bf16 v[16:19], v[192:195], v[220:223], v[16:19]
	v_mfma_f32_16x16x32_bf16 v[4:7], v[184:187], v[228:231], v[4:7]
	v_mfma_f32_16x16x32_bf16 v[0:3], v[192:195], v[228:231], v[0:3]
	s_setprio 0
	s_barrier
	s_add_i32 s66, 0, 0x18000
	v_add_u32_e32 v163, s66, v158
	s_add_i32 s67, 0, 0x1c000
	ds_read_b128 v[164:167], v163
	ds_read_b128 v[168:171], v163 offset:1024
	ds_read_b128 v[172:175], v163 offset:2048
	ds_read_b128 v[176:179], v163 offset:3072
	v_add_u32_e32 v163, s67, v158
	ds_read_b128 v[180:183], v163
	ds_read_b128 v[184:187], v163 offset:1024
	ds_read_b128 v[188:191], v163 offset:2048
	ds_read_b128 v[192:195], v163 offset:3072
	s_add_u32 s36, s36, 0x40000
	s_addc_u32 s37, s37, 0
	s_mov_b32 m0, s44
	v_lshl_add_u64 v[236:237], s[36:37], 0, v[128:129]
	ds_read_b128 v[196:199], v162 offset:32768
	ds_read_b128 v[200:203], v162 offset:33792
	ds_read_b128 v[208:211], v162 offset:34816
	ds_read_b128 v[212:215], v162 offset:35840
	ds_read_b128 v[216:219], v162 offset:36864
	ds_read_b128 v[220:223], v162 offset:37888
	ds_read_b128 v[224:227], v162 offset:38912
	ds_read_b128 v[228:231], v162 offset:39936
	global_load_lds_dwordx4 v[236:237], off
	v_lshl_add_u64 v[236:237], s[36:37], 0, v[132:133]
	s_mov_b32 m0, s45
	s_nop 0
	global_load_lds_dwordx4 v[236:237], off
	s_waitcnt vmcnt(8)
	s_waitcnt lgkmcnt(0)
	s_barrier
	s_setprio 1
	s_waitcnt lgkmcnt(0)
	v_mfma_f32_16x16x32_bf16 v[124:127], v[164:167], v[196:199], v[124:127]
	v_mfma_f32_16x16x32_bf16 v[120:123], v[172:175], v[196:199], v[120:123]
	v_mfma_f32_16x16x32_bf16 v[108:111], v[164:167], v[208:211], v[108:111]
	v_mfma_f32_16x16x32_bf16 v[104:107], v[172:175], v[208:211], v[104:107]
	v_mfma_f32_16x16x32_bf16 v[92:95], v[164:167], v[216:219], v[92:95]
	v_mfma_f32_16x16x32_bf16 v[88:91], v[172:175], v[216:219], v[88:91]
	v_mfma_f32_16x16x32_bf16 v[76:79], v[164:167], v[224:227], v[76:79]
	v_mfma_f32_16x16x32_bf16 v[72:75], v[172:175], v[224:227], v[72:75]
	v_mfma_f32_16x16x32_bf16 v[124:127], v[168:171], v[200:203], v[124:127]
	v_mfma_f32_16x16x32_bf16 v[120:123], v[176:179], v[200:203], v[120:123]
	v_mfma_f32_16x16x32_bf16 v[108:111], v[168:171], v[212:215], v[108:111]
	v_mfma_f32_16x16x32_bf16 v[104:107], v[176:179], v[212:215], v[104:107]
	v_mfma_f32_16x16x32_bf16 v[92:95], v[168:171], v[220:223], v[92:95]
	v_mfma_f32_16x16x32_bf16 v[88:91], v[176:179], v[220:223], v[88:91]
	v_mfma_f32_16x16x32_bf16 v[76:79], v[168:171], v[228:231], v[76:79]
	v_mfma_f32_16x16x32_bf16 v[72:75], v[176:179], v[228:231], v[72:75]
	s_setprio 0
	s_setprio 1
	v_mfma_f32_16x16x32_bf16 v[116:119], v[180:183], v[196:199], v[116:119]
	v_mfma_f32_16x16x32_bf16 v[112:115], v[188:191], v[196:199], v[112:115]
	v_mfma_f32_16x16x32_bf16 v[100:103], v[180:183], v[208:211], v[100:103]
	v_mfma_f32_16x16x32_bf16 v[96:99], v[188:191], v[208:211], v[96:99]
	v_mfma_f32_16x16x32_bf16 v[84:87], v[180:183], v[216:219], v[84:87]
	v_mfma_f32_16x16x32_bf16 v[80:83], v[188:191], v[216:219], v[80:83]
	v_mfma_f32_16x16x32_bf16 v[68:71], v[180:183], v[224:227], v[68:71]
	v_mfma_f32_16x16x32_bf16 v[64:67], v[188:191], v[224:227], v[64:67]
	v_mfma_f32_16x16x32_bf16 v[116:119], v[184:187], v[200:203], v[116:119]
	v_mfma_f32_16x16x32_bf16 v[112:115], v[192:195], v[200:203], v[112:115]
	v_mfma_f32_16x16x32_bf16 v[100:103], v[184:187], v[212:215], v[100:103]
	v_mfma_f32_16x16x32_bf16 v[96:99], v[192:195], v[212:215], v[96:99]
	v_mfma_f32_16x16x32_bf16 v[84:87], v[184:187], v[220:223], v[84:87]
	v_mfma_f32_16x16x32_bf16 v[80:83], v[192:195], v[220:223], v[80:83]
	v_mfma_f32_16x16x32_bf16 v[68:71], v[184:187], v[228:231], v[68:71]
	v_mfma_f32_16x16x32_bf16 v[64:67], v[192:195], v[228:231], v[64:67]
	s_setprio 0
	s_barrier
; #define PG8_STAGE(bufoff, gbase, voff) do { _Pragma("unroll") for (int _i = 0; _i < 2; ++_i) \
;         __builtin_amdgcn_global_load_lds((const unsigned*)((const char*)(gbase) + (voff)[_i]), (PG8_LAS unsigned*)(lds + (bufoff) + ldsw + _i * 8192), 16, 0, 0); } while (0)
; #define PG8_LDA(dst, b, h) do { _Pragma("unroll") for (int m = 0; m < 4; ++m) _Pragma("unroll") for (int k = 0; k < 2; ++k) dst[m][k] = *(const PG8_LAS bf16x8*)(lds + PG8_SA(b, h) + aoff + m * 2048 + k * 1024); } while (0)
; #define PG8_MMA(ai, bj, At, Bt) do { __builtin_amdgcn_s_setprio(1); _Pragma("unroll") for (int m = 0; m < 4; ++m) _Pragma("unroll") for (int n = 0; n < 2; ++n) _Pragma("unroll") for (int k = 0; k < 2; ++k) \
;         acc[ai][bj][m][n] = __builtin_amdgcn_mfma_f32_16x16x32_bf16(Bt[n][k], At[m][k], acc[ai][bj][m][n], 0, 0, 0); __builtin_amdgcn_s_setprio(0); } while (0)
; #define PG8_WAIT_V(n) asm volatile("s_waitcnt vmcnt(" #n ")" ::: "memory")
; #define PG8_WAIT_L(n) asm volatile("s_waitcnt lgkmcnt(" #n ")" ::: "memory")
; #define PG8_BAR __builtin_amdgcn_s_barrier()
; #define PG8_SCHED __builtin_amdgcn_sched_barrier(0)
; template <class Epi, class Sched, bool ALIGN_EPI = false, bool SP2 = false>
; __device__ __forceinline__ void gemm_phase(PG8_LAS unsigned char* lds, const Gemm g, const Sched& S, const Epi& E) {
;     ...
;         for (int t = 0; t < nt; t += 2) {
;             const bool last = (t == nt - 2);
;             const char* a1 = cA + (size_t)(t + 1) * kstep;
;             const char* a2 = last ? nA : cA + (size_t)(t + 2) * kstep; const char* b2 = last ? nB : cB + (size_t)(t + 2) * kstep;
;             const char* a3 = a2 + kstep; const char* b3 = b2 + kstep;
;     ...
;             PG8_LDA(At, 1, 1); PG8_STAGE(PG8_SB(1, 0), b3, voffB); PG8_STAGE(PG8_SB(1, 1), b3 + hstep, voffB); PG8_STAGE(PG8_SA(1, 0), a3, voffA);
;             PG8_WAIT_V(8); PG8_WAIT_L(0); PG8_BAR; PG8_MMA(1, 0, At, B0); PG8_MMA(1, 1, At, B1); PG8_BAR; PG8_SCHED;
	s_add_i32 s36, s66, s41
	v_lshl_add_u64 v[142:143], v[142:143], 0, s[8:9]
	s_mov_b32 m0, s36
	ds_read_b128 v[196:199], v162 offset:49152
	ds_read_b128 v[200:203], v162 offset:50176
	ds_read_b128 v[208:211], v162 offset:51200
	ds_read_b128 v[212:215], v162 offset:52224
	ds_read_b128 v[216:219], v162 offset:53248
	ds_read_b128 v[220:223], v162 offset:54272
	ds_read_b128 v[224:227], v162 offset:55296
	ds_read_b128 v[228:231], v162 offset:56320
	global_load_lds_dwordx4 v[142:143], off
	s_add_i32 m0, s36, 0x2000
	s_add_u32 s34, s34, 0x40080
	v_lshl_add_u64 v[142:143], v[204:205], 0, s[8:9]
	s_addc_u32 s35, s35, 0
	s_add_i32 s36, s67, s41
	global_load_lds_dwordx4 v[142:143], off
	v_lshl_add_u64 v[142:143], s[34:35], 0, v[130:131]
	s_mov_b32 m0, s36
	s_nop 0
	global_load_lds_dwordx4 v[142:143], off
	v_lshl_add_u64 v[142:143], s[34:35], 0, v[134:135]
	s_add_i32 m0, s36, 0x2000
	s_nop 0
	global_load_lds_dwordx4 v[142:143], off
	v_lshl_add_u64 v[142:143], v[232:233], 0, s[8:9]
	s_mov_b32 m0, s47
	s_nop 0
	global_load_lds_dwordx4 v[142:143], off
	v_lshl_add_u64 v[142:143], v[234:235], 0, s[8:9]
	s_mov_b32 m0, s52
	s_nop 0
	global_load_lds_dwordx4 v[142:143], off
	s_waitcnt vmcnt(8)
	s_waitcnt lgkmcnt(0)
	s_barrier
	s_setprio 1
	s_waitcnt lgkmcnt(0)
	v_mfma_f32_16x16x32_bf16 v[60:63], v[164:167], v[196:199], v[60:63]
	v_mfma_f32_16x16x32_bf16 v[56:59], v[172:175], v[196:199], v[56:59]
	v_mfma_f32_16x16x32_bf16 v[44:47], v[164:167], v[208:211], v[44:47]
	v_mfma_f32_16x16x32_bf16 v[40:43], v[172:175], v[208:211], v[40:43]
	v_mfma_f32_16x16x32_bf16 v[28:31], v[164:167], v[216:219], v[28:31]
	v_mfma_f32_16x16x32_bf16 v[24:27], v[172:175], v[216:219], v[24:27]
	v_mfma_f32_16x16x32_bf16 v[12:15], v[164:167], v[224:227], v[12:15]
	v_mfma_f32_16x16x32_bf16 v[8:11], v[172:175], v[224:227], v[8:11]
	v_mfma_f32_16x16x32_bf16 v[60:63], v[168:171], v[200:203], v[60:63]
	v_mfma_f32_16x16x32_bf16 v[56:59], v[176:179], v[200:203], v[56:59]
	v_mfma_f32_16x16x32_bf16 v[44:47], v[168:171], v[212:215], v[44:47]
	v_mfma_f32_16x16x32_bf16 v[40:43], v[176:179], v[212:215], v[40:43]
	v_mfma_f32_16x16x32_bf16 v[28:31], v[168:171], v[220:223], v[28:31]
	v_mfma_f32_16x16x32_bf16 v[24:27], v[176:179], v[220:223], v[24:27]
	v_mfma_f32_16x16x32_bf16 v[12:15], v[168:171], v[228:231], v[12:15]
	v_mfma_f32_16x16x32_bf16 v[8:11], v[176:179], v[228:231], v[8:11]
	s_setprio 0
	s_setprio 1
	v_mfma_f32_16x16x32_bf16 v[52:55], v[180:183], v[196:199], v[52:55]
	v_mfma_f32_16x16x32_bf16 v[48:51], v[188:191], v[196:199], v[48:51]
	v_mfma_f32_16x16x32_bf16 v[36:39], v[180:183], v[208:211], v[36:39]
	v_mfma_f32_16x16x32_bf16 v[32:35], v[188:191], v[208:211], v[32:35]
	v_mfma_f32_16x16x32_bf16 v[20:23], v[180:183], v[216:219], v[20:23]
	v_mfma_f32_16x16x32_bf16 v[16:19], v[188:191], v[216:219], v[16:19]
	v_mfma_f32_16x16x32_bf16 v[4:7], v[180:183], v[224:227], v[4:7]
	v_mfma_f32_16x16x32_bf16 v[0:3], v[188:191], v[224:227], v[0:3]
	v_mfma_f32_16x16x32_bf16 v[52:55], v[184:187], v[200:203], v[52:55]
	v_mfma_f32_16x16x32_bf16 v[48:51], v[192:195], v[200:203], v[48:51]
	v_mfma_f32_16x16x32_bf16 v[36:39], v[184:187], v[212:215], v[36:39]
	v_mfma_f32_16x16x32_bf16 v[32:35], v[192:195], v[212:215], v[32:35]
	v_mfma_f32_16x16x32_bf16 v[20:23], v[184:187], v[220:223], v[20:23]
	v_mfma_f32_16x16x32_bf16 v[16:19], v[192:195], v[220:223], v[16:19]
	v_mfma_f32_16x16x32_bf16 v[4:7], v[184:187], v[228:231], v[4:7]
	v_mfma_f32_16x16x32_bf16 v[0:3], v[192:195], v[228:231], v[0:3]
	s_setprio 0
	s_barrier
	s_add_i32 s65, s65, 2
	s_add_u32 s30, s30, 0x100
	s_addc_u32 s31, s31, 0
	s_add_u32 s61, s61, 0x100
	s_addc_u32 s64, s64, 0
	s_cmp_gt_u32 s65, 13
	s_cbranch_scc0 .LBB0_1809
	s_branch .Lpeel_exit_13

; #define PG8_STAGE(bufoff, gbase, voff) do { _Pragma("unroll") for (int _i = 0; _i < 2; ++_i) \
;         __builtin_amdgcn_global_load_lds((const unsigned*)((const char*)(gbase) + (voff)[_i]), (PG8_LAS unsigned*)(lds + (bufoff) + ldsw + _i * 8192), 16, 0, 0); } while (0)
; #define PG8_LDA(dst, b, h) do { _Pragma("unroll") for (int m = 0; m < 4; ++m) _Pragma("unroll") for (int k = 0; k < 2; ++k) dst[m][k] = *(const PG8_LAS bf16x8*)(lds + PG8_SA(b, h) + aoff + m * 2048 + k * 1024); } while (0)
; #define PG8_LDB(dst, b, h) do { _Pragma("unroll") for (int n = 0; n < 2; ++n) _Pragma("unroll") for (int k = 0; k < 2; ++k) dst[n][k] = *(const PG8_LAS bf16x8*)(lds + PG8_SB(b, h) + boff + n * 2048 + k * 1024); } while (0)
; #define PG8_MMA(ai, bj, At, Bt) do { __builtin_amdgcn_s_setprio(1); _Pragma("unroll") for (int m = 0; m < 4; ++m) _Pragma("unroll") for (int n = 0; n < 2; ++n) _Pragma("unroll") for (int k = 0; k < 2; ++k) \
;         acc[ai][bj][m][n] = __builtin_amdgcn_mfma_f32_16x16x32_bf16(Bt[n][k], At[m][k], acc[ai][bj][m][n], 0, 0, 0); __builtin_amdgcn_s_setprio(0); } while (0)
; #define PG8_WAIT_V(n) asm volatile("s_waitcnt vmcnt(" #n ")" ::: "memory")
; #define PG8_WAIT_L(n) asm volatile("s_waitcnt lgkmcnt(" #n ")" ::: "memory")
; #define PG8_BAR __builtin_amdgcn_s_barrier()
; template <class Epi, class Sched, bool ALIGN_EPI = false, bool SP2 = false>
; __device__ __forceinline__ void gemm_phase(PG8_LAS unsigned char* lds, const Gemm g, const Sched& S, const Epi& E) {
;     ...
;         PG8_STAGE(PG8_SB(1, 0), cB + kstep, voffB); PG8_STAGE(PG8_SA(1, 0), cA + kstep, voffA); PG8_STAGE(PG8_SB(1, 1), cB + hstep + kstep, voffB);
;         PG8_WAIT_V(6); PG8_BAR;
;     ...
;         for (int t = 0; t < nt; t += 2) {
;             const bool last = (t == nt - 2);
;             const char* a1 = cA + (size_t)(t + 1) * kstep;
;             const char* a2 = last ? nA : cA + (size_t)(t + 2) * kstep; const char* b2 = last ? nB : cB + (size_t)(t + 2) * kstep;
;             const char* a3 = a2 + kstep; const char* b3 = b2 + kstep;
;             if (last && has_next) S.a_ready(nxt);
;             if constexpr (SP2) {
;             PG8_LDB(B0, 0, 0); PG8_LDB(B1, 0, 1); PG8_SCHED; PG8_LDA(At, 0, 0); PG8_STAGE(PG8_SA(1, 1), a1 + hstep, voffA);
;             PG8_WAIT_V(8); PG8_WAIT_L(0); PG8_BAR; PG8_MMA(0, 0, At, B0); PG8_MMA(0, 1, At, B1); PG8_BAR; PG8_SCHED;
.LBB0_1897:
	v_lshlrev_b32_e32 v11, 2, v153
	v_lshl_or_b32 v129, s15, 6, v153
	v_lshl_or_b32 v10, v153, 6, v154
	s_lshl_b32 s15, s15, 13
	v_and_b32_e32 v11, 32, v11
	s_lshl_b32 s14, s14, 5
	v_bitop3_b32 v10, v10, s15, v11 bitop3:0xde
	s_and_b32 s31, s14, 0x60
	s_mov_b64 s[14:15], 0x80
	s_add_i32 m0, s27, 0x18000
	v_lshl_add_u64 v[6:7], v[6:7], 0, s[14:15]
	s_waitcnt vmcnt(2)
	s_barrier
	global_load_lds_dwordx4 v[6:7], off
	v_lshl_add_u64 v[4:5], v[4:5], 0, s[14:15]
	s_add_i32 m0, s27, 0x1a000
	s_add_i32 s34, s27, 0x8000
	s_add_i32 s35, s27, 0xa000
	global_load_lds_dwordx4 v[4:5], off
	v_lshl_add_u64 v[2:3], v[2:3], 0, s[14:15]
	s_mov_b32 m0, s34
	s_add_u32 s22, s6, 0xb0080
	global_load_lds_dwordx4 v[2:3], off
	v_lshl_add_u64 v[0:1], v[0:1], 0, s[14:15]
	s_mov_b32 m0, s35
	s_addc_u32 s23, s7, 0
	global_load_lds_dwordx4 v[0:1], off
	s_add_i32 m0, s27, 0x1c000
	v_lshl_add_u64 v[0:1], s[22:23], 0, v[138:139]
	global_load_lds_dwordx4 v[0:1], off
	v_lshl_add_u64 v[0:1], s[22:23], 0, v[142:143]
	s_add_i32 m0, s27, 0x1e000
	s_add_u32 s22, s50, s19
	global_load_lds_dwordx4 v[0:1], off
	v_add_u16_e32 v0, v148, v149
	v_lshrrev_b16_e32 v2, 1, v0
	v_lshl_or_b32 v11, s31, 7, v155
	s_waitcnt vmcnt(6)
	v_add_lshl_u32 v0, v9, v2, 1
	v_mov_b32_e32 v1, v139
	s_addc_u32 s23, s51, s18
	s_add_i32 s42, 0, 0x10000
	s_add_i32 s44, 0, 0x14000
	s_add_i32 s46, 0, 0x18000
	s_add_i32 s52, 0, 0x1c000
	v_lshl_add_u64 v[144:145], s[22:23], 0, v[0:1]
	v_add_lshl_u32 v0, v8, v2, 1
	v_add_u32_e32 v131, s42, v11
	v_add_u32_e32 v133, s44, v11
	s_add_i32 s42, s42, s20
	s_add_i32 s44, s44, s20
	v_add_u32_e32 v156, s46, v11
	v_add_u32_e32 v157, s52, v11
	s_add_i32 s46, s46, s20
	s_add_i32 s52, s52, s20
	v_lshl_add_u64 v[146:147], s[22:23], 0, v[0:1]
	s_mov_b32 s36, -2
	s_mov_b64 s[18:19], 0x78b0080
	v_add_u32_e32 v135, 0, v10
	s_add_i32 s37, s27, 0xc000
	s_add_i32 s41, s27, 0xe000
	s_add_i32 s43, s42, 0x2000
	s_add_i32 s45, s44, 0x2000
	s_add_i32 s47, s46, 0x2000
	s_add_i32 s53, s52, 0x2000
	s_barrier
	ds_read_b128 v[158:161], v131
	ds_read_b128 v[162:165], v131 offset:1024
	ds_read_b128 v[166:169], v131 offset:2048
	ds_read_b128 v[170:173], v131 offset:3072
	ds_read_b128 v[174:177], v133
	ds_read_b128 v[178:181], v133 offset:1024
	ds_read_b128 v[182:185], v133 offset:2048
	ds_read_b128 v[186:189], v133 offset:3072
	s_add_u32 s20, s18, 0xf8750080
	s_addc_u32 s21, s19, -1
	s_cmp_lg_u32 s36, 40
	s_cselect_b32 s20, s20, 0
	s_cselect_b32 s21, s21, 0
	s_add_u32 s22, s8, s20
	s_addc_u32 s23, s9, s21
	s_add_u32 s20, s6, s20
	s_addc_u32 s21, s7, s21
	s_mov_b32 m0, s37
	v_lshl_add_u64 v[224:225], v[144:145], 0, s[18:19]
	ds_read_b128 v[190:193], v135
	ds_read_b128 v[194:197], v135 offset:1024
	ds_read_b128 v[198:201], v135 offset:2048
	ds_read_b128 v[202:205], v135 offset:3072
	ds_read_b128 v[208:211], v135 offset:4096
	ds_read_b128 v[212:215], v135 offset:5120
	ds_read_b128 v[216:219], v135 offset:6144
	ds_read_b128 v[220:223], v135 offset:7168
	global_load_lds_dwordx4 v[224:225], off
	v_lshl_add_u64 v[224:225], v[146:147], 0, s[18:19]
	s_mov_b32 m0, s41
	s_nop 0
	global_load_lds_dwordx4 v[224:225], off
	s_waitcnt vmcnt(8)
	s_waitcnt lgkmcnt(0)
	s_barrier
	s_setprio 1
	s_waitcnt lgkmcnt(0)
	v_mfma_f32_16x16x32_bf16 v[124:127], v[158:161], v[190:193], 0
	v_mfma_f32_16x16x32_bf16 v[120:123], v[166:169], v[190:193], 0
	v_mfma_f32_16x16x32_bf16 v[116:119], v[158:161], v[198:201], 0
	v_mfma_f32_16x16x32_bf16 v[112:115], v[166:169], v[198:201], 0
	v_mfma_f32_16x16x32_bf16 v[100:103], v[158:161], v[208:211], 0
	v_mfma_f32_16x16x32_bf16 v[96:99], v[166:169], v[208:211], 0
	v_mfma_f32_16x16x32_bf16 v[84:87], v[158:161], v[216:219], 0
	v_mfma_f32_16x16x32_bf16 v[80:83], v[166:169], v[216:219], 0
	v_mfma_f32_16x16x32_bf16 v[124:127], v[162:165], v[194:197], v[124:127]
	v_mfma_f32_16x16x32_bf16 v[120:123], v[170:173], v[194:197], v[120:123]
	v_mfma_f32_16x16x32_bf16 v[116:119], v[162:165], v[202:205], v[116:119]
	v_mfma_f32_16x16x32_bf16 v[112:115], v[170:173], v[202:205], v[112:115]
	v_mfma_f32_16x16x32_bf16 v[100:103], v[162:165], v[212:215], v[100:103]
	v_mfma_f32_16x16x32_bf16 v[96:99], v[170:173], v[212:215], v[96:99]
	v_mfma_f32_16x16x32_bf16 v[84:87], v[162:165], v[220:223], v[84:87]
	v_mfma_f32_16x16x32_bf16 v[80:83], v[170:173], v[220:223], v[80:83]
	s_setprio 0
	s_setprio 1
	v_mfma_f32_16x16x32_bf16 v[108:111], v[174:177], v[190:193], 0
	v_mfma_f32_16x16x32_bf16 v[104:107], v[182:185], v[190:193], 0
	v_mfma_f32_16x16x32_bf16 v[92:95], v[174:177], v[198:201], 0
	v_mfma_f32_16x16x32_bf16 v[88:91], v[182:185], v[198:201], 0
	v_mfma_f32_16x16x32_bf16 v[76:79], v[174:177], v[208:211], 0
	v_mfma_f32_16x16x32_bf16 v[72:75], v[182:185], v[208:211], 0
	v_mfma_f32_16x16x32_bf16 v[68:71], v[174:177], v[216:219], 0
	v_mfma_f32_16x16x32_bf16 v[64:67], v[182:185], v[216:219], 0
	v_mfma_f32_16x16x32_bf16 v[108:111], v[178:181], v[194:197], v[108:111]
	v_mfma_f32_16x16x32_bf16 v[104:107], v[186:189], v[194:197], v[104:107]
	v_mfma_f32_16x16x32_bf16 v[92:95], v[178:181], v[202:205], v[92:95]
	v_mfma_f32_16x16x32_bf16 v[88:91], v[186:189], v[202:205], v[88:91]
	v_mfma_f32_16x16x32_bf16 v[76:79], v[178:181], v[212:215], v[76:79]
	v_mfma_f32_16x16x32_bf16 v[72:75], v[186:189], v[212:215], v[72:75]
	v_mfma_f32_16x16x32_bf16 v[68:71], v[178:181], v[220:223], v[68:71]
	v_mfma_f32_16x16x32_bf16 v[64:67], v[186:189], v[220:223], v[64:67]
	s_setprio 0
	s_barrier
; #define PG8_STAGE(bufoff, gbase, voff) do { _Pragma("unroll") for (int _i = 0; _i < 2; ++_i) \
;         __builtin_amdgcn_global_load_lds((const unsigned*)((const char*)(gbase) + (voff)[_i]), (PG8_LAS unsigned*)(lds + (bufoff) + ldsw + _i * 8192), 16, 0, 0); } while (0)
; #define PG8_LDA(dst, b, h) do { _Pragma("unroll") for (int m = 0; m < 4; ++m) _Pragma("unroll") for (int k = 0; k < 2; ++k) dst[m][k] = *(const PG8_LAS bf16x8*)(lds + PG8_SA(b, h) + aoff + m * 2048 + k * 1024); } while (0)
; #define PG8_LDB(dst, b, h) do { _Pragma("unroll") for (int n = 0; n < 2; ++n) _Pragma("unroll") for (int k = 0; k < 2; ++k) dst[n][k] = *(const PG8_LAS bf16x8*)(lds + PG8_SB(b, h) + boff + n * 2048 + k * 1024); } while (0)
; #define PG8_MMA(ai, bj, At, Bt) do { __builtin_amdgcn_s_setprio(1); _Pragma("unroll") for (int m = 0; m < 4; ++m) _Pragma("unroll") for (int n = 0; n < 2; ++n) _Pragma("unroll") for (int k = 0; k < 2; ++k) \
;         acc[ai][bj][m][n] = __builtin_amdgcn_mfma_f32_16x16x32_bf16(Bt[n][k], At[m][k], acc[ai][bj][m][n], 0, 0, 0); __builtin_amdgcn_s_setprio(0); } while (0)
; #define PG8_WAIT_V(n) asm volatile("s_waitcnt vmcnt(" #n ")" ::: "memory")
; #define PG8_WAIT_L(n) asm volatile("s_waitcnt lgkmcnt(" #n ")" ::: "memory")
; #define PG8_BAR __builtin_amdgcn_s_barrier()
; #define PG8_SCHED __builtin_amdgcn_sched_barrier(0)
; template <class Epi, class Sched, bool ALIGN_EPI = false, bool SP2 = false>
; __device__ __forceinline__ void gemm_phase(PG8_LAS unsigned char* lds, const Gemm g, const Sched& S, const Epi& E) {
;     ...
;             PG8_LDA(At, 0, 1); PG8_STAGE(PG8_SB(0, 0), b2, voffB); PG8_STAGE(PG8_SB(0, 1), b2 + hstep, voffB); PG8_STAGE(PG8_SA(0, 0), a2, voffA);
;             PG8_WAIT_V(8); PG8_WAIT_L(0); PG8_BAR; PG8_MMA(1, 0, At, B0); PG8_MMA(1, 1, At, B1); PG8_BAR; PG8_SCHED;
;             PG8_LDB(B0, 1, 0); PG8_LDB(B1, 1, 1); PG8_SCHED; PG8_LDA(At, 1, 0); PG8_STAGE(PG8_SA(0, 1), a2 + hstep, voffA);
	s_mov_b32 m0, s42
	v_lshl_add_u64 v[224:225], s[20:21], 0, v[138:139]
	s_add_u32 s56, s20, 0xb0000
	ds_read_b128 v[190:193], v135 offset:16384
	ds_read_b128 v[194:197], v135 offset:17408
	ds_read_b128 v[198:201], v135 offset:18432
	ds_read_b128 v[202:205], v135 offset:19456
	ds_read_b128 v[208:211], v135 offset:20480
	ds_read_b128 v[212:215], v135 offset:21504
	ds_read_b128 v[216:219], v135 offset:22528
	ds_read_b128 v[220:223], v135 offset:23552
	global_load_lds_dwordx4 v[224:225], off
	v_lshl_add_u64 v[226:227], s[20:21], 0, v[142:143]
	s_mov_b32 m0, s43
	s_addc_u32 s57, s21, 0
	global_load_lds_dwordx4 v[226:227], off
	v_lshl_add_u64 v[228:229], s[56:57], 0, v[138:139]
	s_mov_b32 m0, s44
	v_lshl_add_u64 v[230:231], s[22:23], 0, v[140:141]
	global_load_lds_dwordx4 v[228:229], off
	v_lshl_add_u64 v[228:229], s[56:57], 0, v[142:143]
	s_mov_b32 m0, s45
	s_nop 0
	global_load_lds_dwordx4 v[228:229], off
	v_lshl_add_u64 v[228:229], s[22:23], 0, v[136:137]
	s_mov_b32 m0, s27
	s_nop 0
	global_load_lds_dwordx4 v[228:229], off
	s_mov_b32 m0, s28
	s_nop 0
	global_load_lds_dwordx4 v[230:231], off
	s_waitcnt vmcnt(8)
	s_waitcnt lgkmcnt(0)
	s_barrier
	s_setprio 1
	s_waitcnt lgkmcnt(0)
	v_mfma_f32_16x16x32_bf16 v[60:63], v[158:161], v[190:193], 0
	v_mfma_f32_16x16x32_bf16 v[56:59], v[166:169], v[190:193], 0
	v_mfma_f32_16x16x32_bf16 v[52:55], v[158:161], v[198:201], 0
	v_mfma_f32_16x16x32_bf16 v[48:51], v[166:169], v[198:201], 0
	v_mfma_f32_16x16x32_bf16 v[36:39], v[158:161], v[208:211], 0
	v_mfma_f32_16x16x32_bf16 v[32:35], v[166:169], v[208:211], 0
	v_mfma_f32_16x16x32_bf16 v[20:23], v[158:161], v[216:219], 0
	v_mfma_f32_16x16x32_bf16 v[16:19], v[166:169], v[216:219], 0
	v_mfma_f32_16x16x32_bf16 v[60:63], v[162:165], v[194:197], v[60:63]
	v_mfma_f32_16x16x32_bf16 v[56:59], v[170:173], v[194:197], v[56:59]
	v_mfma_f32_16x16x32_bf16 v[52:55], v[162:165], v[202:205], v[52:55]
	v_mfma_f32_16x16x32_bf16 v[48:51], v[170:173], v[202:205], v[48:51]
	v_mfma_f32_16x16x32_bf16 v[36:39], v[162:165], v[212:215], v[36:39]
	v_mfma_f32_16x16x32_bf16 v[32:35], v[170:173], v[212:215], v[32:35]
	v_mfma_f32_16x16x32_bf16 v[20:23], v[162:165], v[220:223], v[20:23]
	v_mfma_f32_16x16x32_bf16 v[16:19], v[170:173], v[220:223], v[16:19]
	s_setprio 0
	s_setprio 1
	v_mfma_f32_16x16x32_bf16 v[44:47], v[174:177], v[190:193], 0
	v_mfma_f32_16x16x32_bf16 v[40:43], v[182:185], v[190:193], 0
	v_mfma_f32_16x16x32_bf16 v[28:31], v[174:177], v[198:201], 0
	v_mfma_f32_16x16x32_bf16 v[24:27], v[182:185], v[198:201], 0
	v_mfma_f32_16x16x32_bf16 v[12:15], v[174:177], v[208:211], 0
	v_mfma_f32_16x16x32_bf16 v[8:11], v[182:185], v[208:211], 0
	v_mfma_f32_16x16x32_bf16 v[4:7], v[174:177], v[216:219], 0
	v_mfma_f32_16x16x32_bf16 v[0:3], v[182:185], v[216:219], 0
	v_mfma_f32_16x16x32_bf16 v[44:47], v[178:181], v[194:197], v[44:47]
	v_mfma_f32_16x16x32_bf16 v[40:43], v[186:189], v[194:197], v[40:43]
	v_mfma_f32_16x16x32_bf16 v[28:31], v[178:181], v[202:205], v[28:31]
	v_mfma_f32_16x16x32_bf16 v[24:27], v[186:189], v[202:205], v[24:27]
	v_mfma_f32_16x16x32_bf16 v[12:15], v[178:181], v[212:215], v[12:15]
	v_mfma_f32_16x16x32_bf16 v[8:11], v[186:189], v[212:215], v[8:11]
	v_mfma_f32_16x16x32_bf16 v[4:7], v[178:181], v[220:223], v[4:7]
	v_mfma_f32_16x16x32_bf16 v[0:3], v[186:189], v[220:223], v[0:3]
	s_setprio 0
	s_barrier
	ds_read_b128 v[158:161], v156
	ds_read_b128 v[162:165], v156 offset:1024
	ds_read_b128 v[166:169], v156 offset:2048
	ds_read_b128 v[170:173], v156 offset:3072
	ds_read_b128 v[174:177], v157
	ds_read_b128 v[178:181], v157 offset:1024
	ds_read_b128 v[182:185], v157 offset:2048
	ds_read_b128 v[186:189], v157 offset:3072
	s_add_u32 s22, s22, 0xb0000
	s_addc_u32 s23, s23, 0
	s_mov_b32 m0, s29
	v_lshl_add_u64 v[232:233], s[22:23], 0, v[136:137]
	ds_read_b128 v[190:193], v135 offset:32768
	ds_read_b128 v[194:197], v135 offset:33792
	ds_read_b128 v[198:201], v135 offset:34816
	ds_read_b128 v[202:205], v135 offset:35840
	ds_read_b128 v[208:211], v135 offset:36864
	ds_read_b128 v[212:215], v135 offset:37888
	ds_read_b128 v[216:219], v135 offset:38912
	ds_read_b128 v[220:223], v135 offset:39936
	global_load_lds_dwordx4 v[232:233], off
	v_lshl_add_u64 v[232:233], s[22:23], 0, v[140:141]
	s_mov_b32 m0, s30
	s_nop 0
	global_load_lds_dwordx4 v[232:233], off
	s_waitcnt vmcnt(8)
	s_waitcnt lgkmcnt(0)
	s_barrier
; #define PG8_STAGE(bufoff, gbase, voff) do { _Pragma("unroll") for (int _i = 0; _i < 2; ++_i) \
;         __builtin_amdgcn_global_load_lds((const unsigned*)((const char*)(gbase) + (voff)[_i]), (PG8_LAS unsigned*)(lds + (bufoff) + ldsw + _i * 8192), 16, 0, 0); } while (0)
; #define PG8_LDA(dst, b, h) do { _Pragma("unroll") for (int m = 0; m < 4; ++m) _Pragma("unroll") for (int k = 0; k < 2; ++k) dst[m][k] = *(const PG8_LAS bf16x8*)(lds + PG8_SA(b, h) + aoff + m * 2048 + k * 1024); } while (0)
; #define PG8_MMA(ai, bj, At, Bt) do { __builtin_amdgcn_s_setprio(1); _Pragma("unroll") for (int m = 0; m < 4; ++m) _Pragma("unroll") for (int n = 0; n < 2; ++n) _Pragma("unroll") for (int k = 0; k < 2; ++k) \
;         acc[ai][bj][m][n] = __builtin_amdgcn_mfma_f32_16x16x32_bf16(Bt[n][k], At[m][k], acc[ai][bj][m][n], 0, 0, 0); __builtin_amdgcn_s_setprio(0); } while (0)
; #define PG8_WAIT_V(n) asm volatile("s_waitcnt vmcnt(" #n ")" ::: "memory")
; #define PG8_WAIT_L(n) asm volatile("s_waitcnt lgkmcnt(" #n ")" ::: "memory")
; #define PG8_BAR __builtin_amdgcn_s_barrier()
; #define PG8_SCHED __builtin_amdgcn_sched_barrier(0)
; template <class Epi, class Sched, bool ALIGN_EPI = false, bool SP2 = false>
; __device__ __forceinline__ void gemm_phase(PG8_LAS unsigned char* lds, const Gemm g, const Sched& S, const Epi& E) {
;     ...
;         for (int t = 0; t < nt; t += 2) {
;             const bool last = (t == nt - 2);
;             const char* a1 = cA + (size_t)(t + 1) * kstep;
;             const char* a2 = last ? nA : cA + (size_t)(t + 2) * kstep; const char* b2 = last ? nB : cB + (size_t)(t + 2) * kstep;
;             const char* a3 = a2 + kstep; const char* b3 = b2 + kstep;
;     ...
;             PG8_WAIT_V(8); PG8_WAIT_L(0); PG8_BAR; PG8_MMA(0, 0, At, B0); PG8_MMA(0, 1, At, B1); PG8_BAR; PG8_SCHED;
;             PG8_LDA(At, 1, 1); PG8_STAGE(PG8_SB(1, 0), b3, voffB); PG8_STAGE(PG8_SB(1, 1), b3 + hstep, voffB); PG8_STAGE(PG8_SA(1, 0), a3, voffA);
;             PG8_WAIT_V(8); PG8_WAIT_L(0); PG8_BAR; PG8_MMA(1, 0, At, B0); PG8_MMA(1, 1, At, B1); PG8_BAR; PG8_SCHED;
	s_setprio 1
	s_waitcnt lgkmcnt(0)
	v_mfma_f32_16x16x32_bf16 v[124:127], v[158:161], v[190:193], v[124:127]
	v_mfma_f32_16x16x32_bf16 v[120:123], v[166:169], v[190:193], v[120:123]
	v_mfma_f32_16x16x32_bf16 v[116:119], v[158:161], v[198:201], v[116:119]
	v_mfma_f32_16x16x32_bf16 v[112:115], v[166:169], v[198:201], v[112:115]
	v_mfma_f32_16x16x32_bf16 v[100:103], v[158:161], v[208:211], v[100:103]
	v_mfma_f32_16x16x32_bf16 v[96:99], v[166:169], v[208:211], v[96:99]
	v_mfma_f32_16x16x32_bf16 v[84:87], v[158:161], v[216:219], v[84:87]
	v_mfma_f32_16x16x32_bf16 v[80:83], v[166:169], v[216:219], v[80:83]
	v_mfma_f32_16x16x32_bf16 v[124:127], v[162:165], v[194:197], v[124:127]
	v_mfma_f32_16x16x32_bf16 v[120:123], v[170:173], v[194:197], v[120:123]
	v_mfma_f32_16x16x32_bf16 v[116:119], v[162:165], v[202:205], v[116:119]
	v_mfma_f32_16x16x32_bf16 v[112:115], v[170:173], v[202:205], v[112:115]
	v_mfma_f32_16x16x32_bf16 v[100:103], v[162:165], v[212:215], v[100:103]
	v_mfma_f32_16x16x32_bf16 v[96:99], v[170:173], v[212:215], v[96:99]
	v_mfma_f32_16x16x32_bf16 v[84:87], v[162:165], v[220:223], v[84:87]
	v_mfma_f32_16x16x32_bf16 v[80:83], v[170:173], v[220:223], v[80:83]
	s_setprio 0
	s_setprio 1
	v_mfma_f32_16x16x32_bf16 v[108:111], v[174:177], v[190:193], v[108:111]
	v_mfma_f32_16x16x32_bf16 v[104:107], v[182:185], v[190:193], v[104:107]
	v_mfma_f32_16x16x32_bf16 v[92:95], v[174:177], v[198:201], v[92:95]
	v_mfma_f32_16x16x32_bf16 v[88:91], v[182:185], v[198:201], v[88:91]
	v_mfma_f32_16x16x32_bf16 v[76:79], v[174:177], v[208:211], v[76:79]
	v_mfma_f32_16x16x32_bf16 v[72:75], v[182:185], v[208:211], v[72:75]
	v_mfma_f32_16x16x32_bf16 v[68:71], v[174:177], v[216:219], v[68:71]
	v_mfma_f32_16x16x32_bf16 v[64:67], v[182:185], v[216:219], v[64:67]
	v_mfma_f32_16x16x32_bf16 v[108:111], v[178:181], v[194:197], v[108:111]
	v_mfma_f32_16x16x32_bf16 v[104:107], v[186:189], v[194:197], v[104:107]
	v_mfma_f32_16x16x32_bf16 v[92:95], v[178:181], v[202:205], v[92:95]
	v_mfma_f32_16x16x32_bf16 v[88:91], v[186:189], v[202:205], v[88:91]
	v_mfma_f32_16x16x32_bf16 v[76:79], v[178:181], v[212:215], v[76:79]
	v_mfma_f32_16x16x32_bf16 v[72:75], v[186:189], v[212:215], v[72:75]
	v_mfma_f32_16x16x32_bf16 v[68:71], v[178:181], v[220:223], v[68:71]
	v_mfma_f32_16x16x32_bf16 v[64:67], v[186:189], v[220:223], v[64:67]
	s_setprio 0
	s_barrier
	s_mov_b32 m0, s46
	v_lshl_add_u64 v[224:225], v[224:225], 0, s[14:15]
	s_add_u32 s20, s20, 0xb0080
	ds_read_b128 v[190:193], v135 offset:49152
	ds_read_b128 v[194:197], v135 offset:50176
	ds_read_b128 v[198:201], v135 offset:51200
	ds_read_b128 v[202:205], v135 offset:52224
	ds_read_b128 v[208:211], v135 offset:53248
	ds_read_b128 v[212:215], v135 offset:54272
	ds_read_b128 v[216:219], v135 offset:55296
	ds_read_b128 v[220:223], v135 offset:56320
	global_load_lds_dwordx4 v[224:225], off
	v_lshl_add_u64 v[224:225], v[226:227], 0, s[14:15]
	s_mov_b32 m0, s47
	s_addc_u32 s21, s21, 0
	global_load_lds_dwordx4 v[224:225], off
	v_lshl_add_u64 v[224:225], s[20:21], 0, v[138:139]
	s_mov_b32 m0, s52
	s_nop 0
	global_load_lds_dwordx4 v[224:225], off
	v_lshl_add_u64 v[224:225], s[20:21], 0, v[142:143]
	s_mov_b32 m0, s53
	s_nop 0
	global_load_lds_dwordx4 v[224:225], off
	v_lshl_add_u64 v[224:225], v[228:229], 0, s[14:15]
	s_mov_b32 m0, s34
	s_nop 0
	global_load_lds_dwordx4 v[224:225], off
	v_lshl_add_u64 v[224:225], v[230:231], 0, s[14:15]
	s_mov_b32 m0, s35
	s_nop 0
	global_load_lds_dwordx4 v[224:225], off
	s_waitcnt vmcnt(8)
	s_waitcnt lgkmcnt(0)
	s_barrier
	s_setprio 1
	s_waitcnt lgkmcnt(0)
	v_mfma_f32_16x16x32_bf16 v[60:63], v[158:161], v[190:193], v[60:63]
	v_mfma_f32_16x16x32_bf16 v[56:59], v[166:169], v[190:193], v[56:59]
	v_mfma_f32_16x16x32_bf16 v[52:55], v[158:161], v[198:201], v[52:55]
	v_mfma_f32_16x16x32_bf16 v[48:51], v[166:169], v[198:201], v[48:51]
	v_mfma_f32_16x16x32_bf16 v[36:39], v[158:161], v[208:211], v[36:39]
	v_mfma_f32_16x16x32_bf16 v[32:35], v[166:169], v[208:211], v[32:35]
	v_mfma_f32_16x16x32_bf16 v[20:23], v[158:161], v[216:219], v[20:23]
	v_mfma_f32_16x16x32_bf16 v[16:19], v[166:169], v[216:219], v[16:19]
	v_mfma_f32_16x16x32_bf16 v[60:63], v[162:165], v[194:197], v[60:63]
	v_mfma_f32_16x16x32_bf16 v[56:59], v[170:173], v[194:197], v[56:59]
	v_mfma_f32_16x16x32_bf16 v[52:55], v[162:165], v[202:205], v[52:55]
	v_mfma_f32_16x16x32_bf16 v[48:51], v[170:173], v[202:205], v[48:51]
	v_mfma_f32_16x16x32_bf16 v[36:39], v[162:165], v[212:215], v[36:39]
	v_mfma_f32_16x16x32_bf16 v[32:35], v[170:173], v[212:215], v[32:35]
	v_mfma_f32_16x16x32_bf16 v[20:23], v[162:165], v[220:223], v[20:23]
	v_mfma_f32_16x16x32_bf16 v[16:19], v[170:173], v[220:223], v[16:19]
	s_setprio 0
	s_setprio 1
	v_mfma_f32_16x16x32_bf16 v[44:47], v[174:177], v[190:193], v[44:47]
	v_mfma_f32_16x16x32_bf16 v[40:43], v[182:185], v[190:193], v[40:43]
	v_mfma_f32_16x16x32_bf16 v[28:31], v[174:177], v[198:201], v[28:31]
	v_mfma_f32_16x16x32_bf16 v[24:27], v[182:185], v[198:201], v[24:27]
	v_mfma_f32_16x16x32_bf16 v[12:15], v[174:177], v[208:211], v[12:15]
	v_mfma_f32_16x16x32_bf16 v[8:11], v[182:185], v[208:211], v[8:11]
	v_mfma_f32_16x16x32_bf16 v[4:7], v[174:177], v[216:219], v[4:7]
	v_mfma_f32_16x16x32_bf16 v[0:3], v[182:185], v[216:219], v[0:3]
	v_mfma_f32_16x16x32_bf16 v[44:47], v[178:181], v[194:197], v[44:47]
	v_mfma_f32_16x16x32_bf16 v[40:43], v[186:189], v[194:197], v[40:43]
	v_mfma_f32_16x16x32_bf16 v[28:31], v[178:181], v[202:205], v[28:31]
	v_mfma_f32_16x16x32_bf16 v[24:27], v[186:189], v[202:205], v[24:27]
	v_mfma_f32_16x16x32_bf16 v[12:15], v[178:181], v[212:215], v[12:15]
	v_mfma_f32_16x16x32_bf16 v[8:11], v[186:189], v[212:215], v[8:11]
	v_mfma_f32_16x16x32_bf16 v[4:7], v[178:181], v[220:223], v[4:7]
	v_mfma_f32_16x16x32_bf16 v[0:3], v[186:189], v[220:223], v[0:3]
	s_setprio 0
	s_barrier
	s_add_i32 s36, s36, 2
	s_add_u32 s18, s18, 0x100
	s_addc_u32 s19, s19, 0
	s_cmp_gt_u32 s36, 41
	s_cbranch_scc0 .LBB0_1898
	s_branch .Lpeel_exit_14

; #define PG8_BAR __builtin_amdgcn_s_barrier()
; template <class Epi, class Sched, bool ALIGN_EPI = false, bool SP2 = false>
; __device__ __forceinline__ void gemm_phase(PG8_LAS unsigned char* lds, const Gemm g, const Sched& S, const Epi& E) {
;     ...
;         if constexpr (ALIGN_EPI) { if (wr == 0) PG8_BAR; }
.Lpeel_exit_14:
	s_cmpk_lt_u32 s24, 0x100
	s_cbranch_scc0 .LBB0_1901
	s_barrier

;     __device__ __forceinline__ bool next(int i, Unit& u) const { if (i != 0) return false; const int c0 = (G >= 8) ? G - 5 : G - 2; int k = -1; if (c == c0) k = 0; else if (c == G - 1) k = 1; if (k < 0 || k >= n) return false; u.pm = k; u.pn = 0; return true; }
; #define PG8_STAGE(bufoff, gbase, voff) do { _Pragma("unroll") for (int _i = 0; _i < 2; ++_i) \
;         __builtin_amdgcn_global_load_lds((const unsigned*)((const char*)(gbase) + (voff)[_i]), (PG8_LAS unsigned*)(lds + (bufoff) + ldsw + _i * 8192), 16, 0, 0); } while (0)
; #define PG8_LDA(dst, b, h) do { _Pragma("unroll") for (int m = 0; m < 4; ++m) _Pragma("unroll") for (int k = 0; k < 2; ++k) dst[m][k] = *(const PG8_LAS bf16x8*)(lds + PG8_SA(b, h) + aoff + m * 2048 + k * 1024); } while (0)
; #define PG8_LDB(dst, b, h) do { _Pragma("unroll") for (int n = 0; n < 2; ++n) _Pragma("unroll") for (int k = 0; k < 2; ++k) dst[n][k] = *(const PG8_LAS bf16x8*)(lds + PG8_SB(b, h) + boff + n * 2048 + k * 1024); } while (0)
; template <class Epi, class Sched, bool ALIGN_EPI = false, bool SP2 = false>
; __device__ __forceinline__ void gemm_phase(PG8_LAS unsigned char* lds, const Gemm g, const Sched& S, const Epi& E) {
;     ...
;         const bool has_next = S.next(ui + 1, nxt);
;         const char* nA = has_next ? (const char*)g.A + (size_t)nxt.pm * tstep : cA; const char* nB = has_next ? (const char*)g.Bt + (size_t)nxt.pn * tstep : cB;
;         for (int t = 0; t < nt; t += 2) {
;             const bool last = (t == nt - 2);
;             const char* a1 = cA + (size_t)(t + 1) * kstep;
;             const char* a2 = last ? nA : cA + (size_t)(t + 2) * kstep; const char* b2 = last ? nB : cB + (size_t)(t + 2) * kstep;
;             const char* a3 = a2 + kstep; const char* b3 = b2 + kstep;
;             if (last && has_next) S.a_ready(nxt);
;             if constexpr (SP2) {
;             PG8_LDB(B0, 0, 0); PG8_LDB(B1, 0, 1); PG8_SCHED; PG8_LDA(At, 0, 0); PG8_STAGE(PG8_SA(1, 1), a1 + hstep, voffA);
;             PG8_WAIT_V(8); PG8_WAIT_L(0); PG8_BAR; PG8_MMA(0, 0, At, B0); PG8_MMA(0, 1, At, B1); PG8_BAR; PG8_SCHED;
;             PG8_LDA(At, 0, 1); PG8_STAGE(PG8_SB(0, 0), b2, voffB); PG8_STAGE(PG8_SB(0, 1), b2 + hstep, voffB); PG8_STAGE(PG8_SA(0, 0), a2, voffA);
;             PG8_WAIT_V(8); PG8_WAIT_L(0); PG8_BAR; PG8_MMA(1, 0, At, B0); PG8_MMA(1, 1, At, B1); PG8_BAR; PG8_SCHED;
.LBB0_1983:
	s_ashr_i32 s19, s18, 31
	s_lshl_b64 s[24:25], s[18:19], 19
	s_add_u32 s24, s97, s24
	s_addc_u32 s25, s3, s25
	s_and_b64 s[26:27], s[22:23], exec
	s_cselect_b32 s19, s25, s31
	s_cselect_b32 s59, s24, s30
	s_ashr_i32 s21, s20, 31
	s_lshl_b64 s[26:27], s[20:21], 19
	s_add_u32 s26, s38, s26
	s_addc_u32 s27, s39, s27
	s_and_b64 s[36:37], s[22:23], exec
	s_cselect_b32 s21, s27, s35
	s_cselect_b32 s60, s26, s34
	s_add_u32 s30, s30, 0x40080
	s_addc_u32 s31, s31, 0
	s_add_u32 s61, s34, 0x100
	v_mov_b32_e32 v0, 0
	s_addc_u32 s64, s35, 0
	s_mov_b32 s65, -2
	ds_read_b128 v[150:153], v147
	ds_read_b128 v[154:157], v147 offset:1024
	ds_read_b128 v[158:161], v147 offset:2048
	ds_read_b128 v[162:165], v147 offset:3072
	ds_read_b128 v[166:169], v148
	ds_read_b128 v[170:173], v148 offset:1024
	ds_read_b128 v[174:177], v148 offset:2048
	ds_read_b128 v[178:181], v148 offset:3072
	s_add_u32 s34, s30, 0xfffc0080
	s_addc_u32 s35, s31, -1
	s_cmp_eq_u32 s65, 12
	s_cselect_b32 s37, s19, s35
	s_cselect_b32 s36, s59, s34
	s_cselect_b32 s35, s21, s64
	s_cselect_b32 s34, s60, s61
	v_lshl_add_u64 v[142:143], s[30:31], 0, v[136:137]
	s_add_i32 m0, s29, 0xc000
	ds_read_b128 v[182:185], v149
	ds_read_b128 v[186:189], v149 offset:1024
	ds_read_b128 v[190:193], v149 offset:2048
	ds_read_b128 v[194:197], v149 offset:3072
	ds_read_b128 v[198:201], v149 offset:4096
	ds_read_b128 v[202:205], v149 offset:5120
	ds_read_b128 v[208:211], v149 offset:6144
	ds_read_b128 v[212:215], v149 offset:7168
	global_load_lds_dwordx4 v[142:143], off
	v_lshl_add_u64 v[142:143], s[30:31], 0, v[138:139]
	s_add_i32 m0, s29, 0xe000
	s_nop 0
	global_load_lds_dwordx4 v[142:143], off
	s_waitcnt vmcnt(8)
	s_waitcnt lgkmcnt(0)
	s_barrier
	s_setprio 1
	s_waitcnt lgkmcnt(0)
	v_mfma_f32_16x16x32_bf16 v[124:127], v[150:153], v[182:185], 0
	v_mfma_f32_16x16x32_bf16 v[120:123], v[158:161], v[182:185], 0
	v_mfma_f32_16x16x32_bf16 v[108:111], v[150:153], v[190:193], 0
	v_mfma_f32_16x16x32_bf16 v[104:107], v[158:161], v[190:193], 0
	v_mfma_f32_16x16x32_bf16 v[92:95], v[150:153], v[198:201], 0
	v_mfma_f32_16x16x32_bf16 v[88:91], v[158:161], v[198:201], 0
	v_mfma_f32_16x16x32_bf16 v[76:79], v[150:153], v[208:211], 0
	v_mfma_f32_16x16x32_bf16 v[72:75], v[158:161], v[208:211], 0
	v_mfma_f32_16x16x32_bf16 v[124:127], v[154:157], v[186:189], v[124:127]
	v_mfma_f32_16x16x32_bf16 v[120:123], v[162:165], v[186:189], v[120:123]
	v_mfma_f32_16x16x32_bf16 v[108:111], v[154:157], v[194:197], v[108:111]
	v_mfma_f32_16x16x32_bf16 v[104:107], v[162:165], v[194:197], v[104:107]
	v_mfma_f32_16x16x32_bf16 v[92:95], v[154:157], v[202:205], v[92:95]
	v_mfma_f32_16x16x32_bf16 v[88:91], v[162:165], v[202:205], v[88:91]
	v_mfma_f32_16x16x32_bf16 v[76:79], v[154:157], v[212:215], v[76:79]
	v_mfma_f32_16x16x32_bf16 v[72:75], v[162:165], v[212:215], v[72:75]
	s_setprio 0
	s_setprio 1
	v_mfma_f32_16x16x32_bf16 v[116:119], v[166:169], v[182:185], 0
	v_mfma_f32_16x16x32_bf16 v[112:115], v[174:177], v[182:185], 0
	v_mfma_f32_16x16x32_bf16 v[100:103], v[166:169], v[190:193], 0
	v_mfma_f32_16x16x32_bf16 v[96:99], v[174:177], v[190:193], 0
	v_mfma_f32_16x16x32_bf16 v[84:87], v[166:169], v[198:201], 0
	v_mfma_f32_16x16x32_bf16 v[80:83], v[174:177], v[198:201], 0
	v_mfma_f32_16x16x32_bf16 v[68:71], v[166:169], v[208:211], 0
	v_mfma_f32_16x16x32_bf16 v[64:67], v[174:177], v[208:211], 0
	v_mfma_f32_16x16x32_bf16 v[116:119], v[170:173], v[186:189], v[116:119]
	v_mfma_f32_16x16x32_bf16 v[112:115], v[178:181], v[186:189], v[112:115]
	v_mfma_f32_16x16x32_bf16 v[100:103], v[170:173], v[194:197], v[100:103]
	v_mfma_f32_16x16x32_bf16 v[96:99], v[178:181], v[194:197], v[96:99]
	v_mfma_f32_16x16x32_bf16 v[84:87], v[170:173], v[202:205], v[84:87]
	v_mfma_f32_16x16x32_bf16 v[80:83], v[178:181], v[202:205], v[80:83]
	v_mfma_f32_16x16x32_bf16 v[68:71], v[170:173], v[212:215], v[68:71]
	v_mfma_f32_16x16x32_bf16 v[64:67], v[178:181], v[212:215], v[64:67]
	s_setprio 0
	s_barrier
	s_add_i32 s66, s53, s41
	v_lshl_add_u64 v[142:143], s[34:35], 0, v[130:131]
	s_mov_b32 m0, s66
	ds_read_b128 v[182:185], v149 offset:16384
	ds_read_b128 v[186:189], v149 offset:17408
	ds_read_b128 v[190:193], v149 offset:18432
	ds_read_b128 v[194:197], v149 offset:19456
	ds_read_b128 v[198:201], v149 offset:20480
	ds_read_b128 v[202:205], v149 offset:21504
	ds_read_b128 v[208:211], v149 offset:22528
	ds_read_b128 v[212:215], v149 offset:23552
	global_load_lds_dwordx4 v[142:143], off
	s_add_i32 m0, s66, 0x2000
	s_add_u32 s66, s34, 0x40000
	v_lshl_add_u64 v[216:217], s[34:35], 0, v[134:135]
	s_addc_u32 s67, s35, 0
	s_add_i32 s68, s56, s41
	global_load_lds_dwordx4 v[216:217], off
	v_lshl_add_u64 v[218:219], s[66:67], 0, v[130:131]
	s_mov_b32 m0, s68
	v_lshl_add_u64 v[220:221], s[36:37], 0, v[132:133]
	global_load_lds_dwordx4 v[218:219], off
	v_lshl_add_u64 v[218:219], s[66:67], 0, v[134:135]
	s_add_i32 m0, s68, 0x2000
	s_nop 0
	global_load_lds_dwordx4 v[218:219], off
	v_lshl_add_u64 v[218:219], s[36:37], 0, v[128:129]
	s_mov_b32 m0, s29
	s_nop 0
	global_load_lds_dwordx4 v[218:219], off
	s_mov_b32 m0, s43
	s_nop 0
	global_load_lds_dwordx4 v[220:221], off
	s_waitcnt vmcnt(8)
	s_waitcnt lgkmcnt(0)
	s_barrier
; #define PG8_STAGE(bufoff, gbase, voff) do { _Pragma("unroll") for (int _i = 0; _i < 2; ++_i) \
;         __builtin_amdgcn_global_load_lds((const unsigned*)((const char*)(gbase) + (voff)[_i]), (PG8_LAS unsigned*)(lds + (bufoff) + ldsw + _i * 8192), 16, 0, 0); } while (0)
; #define PG8_LDA(dst, b, h) do { _Pragma("unroll") for (int m = 0; m < 4; ++m) _Pragma("unroll") for (int k = 0; k < 2; ++k) dst[m][k] = *(const PG8_LAS bf16x8*)(lds + PG8_SA(b, h) + aoff + m * 2048 + k * 1024); } while (0)
; #define PG8_LDB(dst, b, h) do { _Pragma("unroll") for (int n = 0; n < 2; ++n) _Pragma("unroll") for (int k = 0; k < 2; ++k) dst[n][k] = *(const PG8_LAS bf16x8*)(lds + PG8_SB(b, h) + boff + n * 2048 + k * 1024); } while (0)
; #define PG8_MMA(ai, bj, At, Bt) do { __builtin_amdgcn_s_setprio(1); _Pragma("unroll") for (int m = 0; m < 4; ++m) _Pragma("unroll") for (int n = 0; n < 2; ++n) _Pragma("unroll") for (int k = 0; k < 2; ++k) \
;         acc[ai][bj][m][n] = __builtin_amdgcn_mfma_f32_16x16x32_bf16(Bt[n][k], At[m][k], acc[ai][bj][m][n], 0, 0, 0); __builtin_amdgcn_s_setprio(0); } while (0)
; #define PG8_WAIT_V(n) asm volatile("s_waitcnt vmcnt(" #n ")" ::: "memory")
; #define PG8_WAIT_L(n) asm volatile("s_waitcnt lgkmcnt(" #n ")" ::: "memory")
; #define PG8_BAR __builtin_amdgcn_s_barrier()
; #define PG8_SCHED __builtin_amdgcn_sched_barrier(0)
; template <class Epi, class Sched, bool ALIGN_EPI = false, bool SP2 = false>
; __device__ __forceinline__ void gemm_phase(PG8_LAS unsigned char* lds, const Gemm g, const Sched& S, const Epi& E) {
;     ...
;             PG8_WAIT_V(8); PG8_WAIT_L(0); PG8_BAR; PG8_MMA(1, 0, At, B0); PG8_MMA(1, 1, At, B1); PG8_BAR; PG8_SCHED;
;             PG8_LDB(B0, 1, 0); PG8_LDB(B1, 1, 1); PG8_SCHED; PG8_LDA(At, 1, 0); PG8_STAGE(PG8_SA(0, 1), a2 + hstep, voffA);
;             PG8_WAIT_V(8); PG8_WAIT_L(0); PG8_BAR; PG8_MMA(0, 0, At, B0); PG8_MMA(0, 1, At, B1); PG8_BAR; PG8_SCHED;
	s_setprio 1
	s_waitcnt lgkmcnt(0)
	v_mfma_f32_16x16x32_bf16 v[60:63], v[150:153], v[182:185], 0
	v_mfma_f32_16x16x32_bf16 v[56:59], v[158:161], v[182:185], 0
	v_mfma_f32_16x16x32_bf16 v[44:47], v[150:153], v[190:193], 0
	v_mfma_f32_16x16x32_bf16 v[40:43], v[158:161], v[190:193], 0
	v_mfma_f32_16x16x32_bf16 v[28:31], v[150:153], v[198:201], 0
	v_mfma_f32_16x16x32_bf16 v[24:27], v[158:161], v[198:201], 0
	v_mfma_f32_16x16x32_bf16 v[12:15], v[150:153], v[208:211], 0
	v_mfma_f32_16x16x32_bf16 v[8:11], v[158:161], v[208:211], 0
	v_mfma_f32_16x16x32_bf16 v[60:63], v[154:157], v[186:189], v[60:63]
	v_mfma_f32_16x16x32_bf16 v[56:59], v[162:165], v[186:189], v[56:59]
	v_mfma_f32_16x16x32_bf16 v[44:47], v[154:157], v[194:197], v[44:47]
	v_mfma_f32_16x16x32_bf16 v[40:43], v[162:165], v[194:197], v[40:43]
	v_mfma_f32_16x16x32_bf16 v[28:31], v[154:157], v[202:205], v[28:31]
	v_mfma_f32_16x16x32_bf16 v[24:27], v[162:165], v[202:205], v[24:27]
	v_mfma_f32_16x16x32_bf16 v[12:15], v[154:157], v[212:215], v[12:15]
	v_mfma_f32_16x16x32_bf16 v[8:11], v[162:165], v[212:215], v[8:11]
	s_setprio 0
	s_setprio 1
	v_mfma_f32_16x16x32_bf16 v[52:55], v[166:169], v[182:185], 0
	v_mfma_f32_16x16x32_bf16 v[48:51], v[174:177], v[182:185], 0
	v_mfma_f32_16x16x32_bf16 v[36:39], v[166:169], v[190:193], 0
	v_mfma_f32_16x16x32_bf16 v[32:35], v[174:177], v[190:193], 0
	v_mfma_f32_16x16x32_bf16 v[20:23], v[166:169], v[198:201], 0
	v_mfma_f32_16x16x32_bf16 v[16:19], v[174:177], v[198:201], 0
	v_mfma_f32_16x16x32_bf16 v[4:7], v[166:169], v[208:211], 0
	v_mfma_f32_16x16x32_bf16 v[0:3], v[174:177], v[208:211], 0
	v_mfma_f32_16x16x32_bf16 v[52:55], v[170:173], v[186:189], v[52:55]
	v_mfma_f32_16x16x32_bf16 v[48:51], v[178:181], v[186:189], v[48:51]
	v_mfma_f32_16x16x32_bf16 v[36:39], v[170:173], v[194:197], v[36:39]
	v_mfma_f32_16x16x32_bf16 v[32:35], v[178:181], v[194:197], v[32:35]
	v_mfma_f32_16x16x32_bf16 v[20:23], v[170:173], v[202:205], v[20:23]
	v_mfma_f32_16x16x32_bf16 v[16:19], v[178:181], v[202:205], v[16:19]
	v_mfma_f32_16x16x32_bf16 v[4:7], v[170:173], v[212:215], v[4:7]
	v_mfma_f32_16x16x32_bf16 v[0:3], v[178:181], v[212:215], v[0:3]
	s_setprio 0
	s_barrier
	s_add_i32 s66, 0, 0x18000
	s_add_i32 s67, 0, 0x1c000
	v_add_u32_e32 v162, s66, v145
	v_add_u32_e32 v178, s67, v145
	ds_read_b128 v[150:153], v162
	ds_read_b128 v[154:157], v162 offset:1024
	ds_read_b128 v[158:161], v162 offset:2048
	ds_read_b128 v[162:165], v162 offset:3072
	ds_read_b128 v[166:169], v178
	ds_read_b128 v[170:173], v178 offset:1024
	ds_read_b128 v[174:177], v178 offset:2048
	ds_read_b128 v[178:181], v178 offset:3072
	s_add_u32 s36, s36, 0x40000
	s_addc_u32 s37, s37, 0
	s_mov_b32 m0, s44
	v_lshl_add_u64 v[222:223], s[36:37], 0, v[128:129]
	ds_read_b128 v[182:185], v149 offset:32768
	ds_read_b128 v[186:189], v149 offset:33792
	ds_read_b128 v[190:193], v149 offset:34816
	ds_read_b128 v[194:197], v149 offset:35840
	ds_read_b128 v[198:201], v149 offset:36864
	ds_read_b128 v[202:205], v149 offset:37888
	ds_read_b128 v[208:211], v149 offset:38912
	ds_read_b128 v[212:215], v149 offset:39936
	global_load_lds_dwordx4 v[222:223], off
	v_lshl_add_u64 v[222:223], s[36:37], 0, v[132:133]
	s_mov_b32 m0, s45
	s_nop 0
	global_load_lds_dwordx4 v[222:223], off
	s_waitcnt vmcnt(8)
	s_waitcnt lgkmcnt(0)
	s_barrier
	s_setprio 1
	s_waitcnt lgkmcnt(0)
	v_mfma_f32_16x16x32_bf16 v[124:127], v[150:153], v[182:185], v[124:127]
	v_mfma_f32_16x16x32_bf16 v[120:123], v[158:161], v[182:185], v[120:123]
	v_mfma_f32_16x16x32_bf16 v[108:111], v[150:153], v[190:193], v[108:111]
	v_mfma_f32_16x16x32_bf16 v[104:107], v[158:161], v[190:193], v[104:107]
	v_mfma_f32_16x16x32_bf16 v[92:95], v[150:153], v[198:201], v[92:95]
	v_mfma_f32_16x16x32_bf16 v[88:91], v[158:161], v[198:201], v[88:91]
	v_mfma_f32_16x16x32_bf16 v[76:79], v[150:153], v[208:211], v[76:79]
	v_mfma_f32_16x16x32_bf16 v[72:75], v[158:161], v[208:211], v[72:75]
	v_mfma_f32_16x16x32_bf16 v[124:127], v[154:157], v[186:189], v[124:127]
	v_mfma_f32_16x16x32_bf16 v[120:123], v[162:165], v[186:189], v[120:123]
	v_mfma_f32_16x16x32_bf16 v[108:111], v[154:157], v[194:197], v[108:111]
	v_mfma_f32_16x16x32_bf16 v[104:107], v[162:165], v[194:197], v[104:107]
	v_mfma_f32_16x16x32_bf16 v[92:95], v[154:157], v[202:205], v[92:95]
	v_mfma_f32_16x16x32_bf16 v[88:91], v[162:165], v[202:205], v[88:91]
	v_mfma_f32_16x16x32_bf16 v[76:79], v[154:157], v[212:215], v[76:79]
	v_mfma_f32_16x16x32_bf16 v[72:75], v[162:165], v[212:215], v[72:75]
	s_setprio 0
	s_setprio 1
	v_mfma_f32_16x16x32_bf16 v[116:119], v[166:169], v[182:185], v[116:119]
	v_mfma_f32_16x16x32_bf16 v[112:115], v[174:177], v[182:185], v[112:115]
	v_mfma_f32_16x16x32_bf16 v[100:103], v[166:169], v[190:193], v[100:103]
	v_mfma_f32_16x16x32_bf16 v[96:99], v[174:177], v[190:193], v[96:99]
	v_mfma_f32_16x16x32_bf16 v[84:87], v[166:169], v[198:201], v[84:87]
	v_mfma_f32_16x16x32_bf16 v[80:83], v[174:177], v[198:201], v[80:83]
	v_mfma_f32_16x16x32_bf16 v[68:71], v[166:169], v[208:211], v[68:71]
	v_mfma_f32_16x16x32_bf16 v[64:67], v[174:177], v[208:211], v[64:67]
	v_mfma_f32_16x16x32_bf16 v[116:119], v[170:173], v[186:189], v[116:119]
	v_mfma_f32_16x16x32_bf16 v[112:115], v[178:181], v[186:189], v[112:115]
	v_mfma_f32_16x16x32_bf16 v[100:103], v[170:173], v[194:197], v[100:103]
	v_mfma_f32_16x16x32_bf16 v[96:99], v[178:181], v[194:197], v[96:99]
	v_mfma_f32_16x16x32_bf16 v[84:87], v[170:173], v[202:205], v[84:87]
	v_mfma_f32_16x16x32_bf16 v[80:83], v[178:181], v[202:205], v[80:83]
	v_mfma_f32_16x16x32_bf16 v[68:71], v[170:173], v[212:215], v[68:71]
	v_mfma_f32_16x16x32_bf16 v[64:67], v[178:181], v[212:215], v[64:67]
	s_setprio 0
	s_barrier
; #define PG8_STAGE(bufoff, gbase, voff) do { _Pragma("unroll") for (int _i = 0; _i < 2; ++_i) \
;         __builtin_amdgcn_global_load_lds((const unsigned*)((const char*)(gbase) + (voff)[_i]), (PG8_LAS unsigned*)(lds + (bufoff) + ldsw + _i * 8192), 16, 0, 0); } while (0)
; #define PG8_LDA(dst, b, h) do { _Pragma("unroll") for (int m = 0; m < 4; ++m) _Pragma("unroll") for (int k = 0; k < 2; ++k) dst[m][k] = *(const PG8_LAS bf16x8*)(lds + PG8_SA(b, h) + aoff + m * 2048 + k * 1024); } while (0)
; #define PG8_MMA(ai, bj, At, Bt) do { __builtin_amdgcn_s_setprio(1); _Pragma("unroll") for (int m = 0; m < 4; ++m) _Pragma("unroll") for (int n = 0; n < 2; ++n) _Pragma("unroll") for (int k = 0; k < 2; ++k) \
;         acc[ai][bj][m][n] = __builtin_amdgcn_mfma_f32_16x16x32_bf16(Bt[n][k], At[m][k], acc[ai][bj][m][n], 0, 0, 0); __builtin_amdgcn_s_setprio(0); } while (0)
; #define PG8_WAIT_V(n) asm volatile("s_waitcnt vmcnt(" #n ")" ::: "memory")
; #define PG8_WAIT_L(n) asm volatile("s_waitcnt lgkmcnt(" #n ")" ::: "memory")
; #define PG8_BAR __builtin_amdgcn_s_barrier()
; #define PG8_SCHED __builtin_amdgcn_sched_barrier(0)
; template <class Epi, class Sched, bool ALIGN_EPI = false, bool SP2 = false>
; __device__ __forceinline__ void gemm_phase(PG8_LAS unsigned char* lds, const Gemm g, const Sched& S, const Epi& E) {
;     ...
;         for (int t = 0; t < nt; t += 2) {
;             const bool last = (t == nt - 2);
;             const char* a1 = cA + (size_t)(t + 1) * kstep;
;             const char* a2 = last ? nA : cA + (size_t)(t + 2) * kstep; const char* b2 = last ? nB : cB + (size_t)(t + 2) * kstep;
;             const char* a3 = a2 + kstep; const char* b3 = b2 + kstep;
;     ...
;             PG8_LDA(At, 1, 1); PG8_STAGE(PG8_SB(1, 0), b3, voffB); PG8_STAGE(PG8_SB(1, 1), b3 + hstep, voffB); PG8_STAGE(PG8_SA(1, 0), a3, voffA);
;             PG8_WAIT_V(8); PG8_WAIT_L(0); PG8_BAR; PG8_MMA(1, 0, At, B0); PG8_MMA(1, 1, At, B1); PG8_BAR; PG8_SCHED;
	s_add_i32 s36, s66, s41
	v_lshl_add_u64 v[142:143], v[142:143], 0, s[8:9]
	s_mov_b32 m0, s36
	ds_read_b128 v[182:185], v149 offset:49152
	ds_read_b128 v[186:189], v149 offset:50176
	ds_read_b128 v[190:193], v149 offset:51200
	ds_read_b128 v[194:197], v149 offset:52224
	ds_read_b128 v[198:201], v149 offset:53248
	ds_read_b128 v[202:205], v149 offset:54272
	ds_read_b128 v[208:211], v149 offset:55296
	ds_read_b128 v[212:215], v149 offset:56320
	global_load_lds_dwordx4 v[142:143], off
	s_add_i32 m0, s36, 0x2000
	s_add_u32 s34, s34, 0x40080
	v_lshl_add_u64 v[142:143], v[216:217], 0, s[8:9]
	s_addc_u32 s35, s35, 0
	s_add_i32 s36, s67, s41
	global_load_lds_dwordx4 v[142:143], off
	v_lshl_add_u64 v[142:143], s[34:35], 0, v[130:131]
	s_mov_b32 m0, s36
	s_nop 0
	global_load_lds_dwordx4 v[142:143], off
	v_lshl_add_u64 v[142:143], s[34:35], 0, v[134:135]
	s_add_i32 m0, s36, 0x2000
	s_nop 0
	global_load_lds_dwordx4 v[142:143], off
	v_lshl_add_u64 v[142:143], v[218:219], 0, s[8:9]
	s_mov_b32 m0, s47
	s_nop 0
	global_load_lds_dwordx4 v[142:143], off
	v_lshl_add_u64 v[142:143], v[220:221], 0, s[8:9]
	s_mov_b32 m0, s52
	s_nop 0
	global_load_lds_dwordx4 v[142:143], off
	s_waitcnt vmcnt(8)
	s_waitcnt lgkmcnt(0)
	s_barrier
	s_setprio 1
	s_waitcnt lgkmcnt(0)
	v_mfma_f32_16x16x32_bf16 v[60:63], v[150:153], v[182:185], v[60:63]
	v_mfma_f32_16x16x32_bf16 v[56:59], v[158:161], v[182:185], v[56:59]
	v_mfma_f32_16x16x32_bf16 v[44:47], v[150:153], v[190:193], v[44:47]
	v_mfma_f32_16x16x32_bf16 v[40:43], v[158:161], v[190:193], v[40:43]
	v_mfma_f32_16x16x32_bf16 v[28:31], v[150:153], v[198:201], v[28:31]
	v_mfma_f32_16x16x32_bf16 v[24:27], v[158:161], v[198:201], v[24:27]
	v_mfma_f32_16x16x32_bf16 v[12:15], v[150:153], v[208:211], v[12:15]
	v_mfma_f32_16x16x32_bf16 v[8:11], v[158:161], v[208:211], v[8:11]
	v_mfma_f32_16x16x32_bf16 v[60:63], v[154:157], v[186:189], v[60:63]
	v_mfma_f32_16x16x32_bf16 v[56:59], v[162:165], v[186:189], v[56:59]
	v_mfma_f32_16x16x32_bf16 v[44:47], v[154:157], v[194:197], v[44:47]
	v_mfma_f32_16x16x32_bf16 v[40:43], v[162:165], v[194:197], v[40:43]
	v_mfma_f32_16x16x32_bf16 v[28:31], v[154:157], v[202:205], v[28:31]
	v_mfma_f32_16x16x32_bf16 v[24:27], v[162:165], v[202:205], v[24:27]
	v_mfma_f32_16x16x32_bf16 v[12:15], v[154:157], v[212:215], v[12:15]
	v_mfma_f32_16x16x32_bf16 v[8:11], v[162:165], v[212:215], v[8:11]
	s_setprio 0
	s_setprio 1
	v_mfma_f32_16x16x32_bf16 v[52:55], v[166:169], v[182:185], v[52:55]
	v_mfma_f32_16x16x32_bf16 v[48:51], v[174:177], v[182:185], v[48:51]
	v_mfma_f32_16x16x32_bf16 v[36:39], v[166:169], v[190:193], v[36:39]
	v_mfma_f32_16x16x32_bf16 v[32:35], v[174:177], v[190:193], v[32:35]
	v_mfma_f32_16x16x32_bf16 v[20:23], v[166:169], v[198:201], v[20:23]
	v_mfma_f32_16x16x32_bf16 v[16:19], v[174:177], v[198:201], v[16:19]
	v_mfma_f32_16x16x32_bf16 v[4:7], v[166:169], v[208:211], v[4:7]
	v_mfma_f32_16x16x32_bf16 v[0:3], v[174:177], v[208:211], v[0:3]
	v_mfma_f32_16x16x32_bf16 v[52:55], v[170:173], v[186:189], v[52:55]
	v_mfma_f32_16x16x32_bf16 v[48:51], v[178:181], v[186:189], v[48:51]
	v_mfma_f32_16x16x32_bf16 v[36:39], v[170:173], v[194:197], v[36:39]
	v_mfma_f32_16x16x32_bf16 v[32:35], v[178:181], v[194:197], v[32:35]
	v_mfma_f32_16x16x32_bf16 v[20:23], v[170:173], v[202:205], v[20:23]
	v_mfma_f32_16x16x32_bf16 v[16:19], v[178:181], v[202:205], v[16:19]
	v_mfma_f32_16x16x32_bf16 v[4:7], v[170:173], v[212:215], v[4:7]
	v_mfma_f32_16x16x32_bf16 v[0:3], v[178:181], v[212:215], v[0:3]
	s_setprio 0
	s_barrier
	s_add_i32 s65, s65, 2
	s_add_u32 s30, s30, 0x100
	s_addc_u32 s31, s31, 0
	s_add_u32 s61, s61, 0x100
	s_addc_u32 s64, s64, 0
	s_cmp_gt_u32 s65, 13
	s_cbranch_scc0 .LBB0_1984
	s_branch .Lpeel_exit_15

; #define PG8_STAGE(bufoff, gbase, voff) do { _Pragma("unroll") for (int _i = 0; _i < 2; ++_i) \
;         __builtin_amdgcn_global_load_lds((const unsigned*)((const char*)(gbase) + (voff)[_i]), (PG8_LAS unsigned*)(lds + (bufoff) + ldsw + _i * 8192), 16, 0, 0); } while (0)
; #define PG8_LDA(dst, b, h) do { _Pragma("unroll") for (int m = 0; m < 4; ++m) _Pragma("unroll") for (int k = 0; k < 2; ++k) dst[m][k] = *(const PG8_LAS bf16x8*)(lds + PG8_SA(b, h) + aoff + m * 2048 + k * 1024); } while (0)
; #define PG8_LDB(dst, b, h) do { _Pragma("unroll") for (int n = 0; n < 2; ++n) _Pragma("unroll") for (int k = 0; k < 2; ++k) dst[n][k] = *(const PG8_LAS bf16x8*)(lds + PG8_SB(b, h) + boff + n * 2048 + k * 1024); } while (0)
; #define PG8_MMA(ai, bj, At, Bt) do { __builtin_amdgcn_s_setprio(1); _Pragma("unroll") for (int m = 0; m < 4; ++m) _Pragma("unroll") for (int n = 0; n < 2; ++n) _Pragma("unroll") for (int k = 0; k < 2; ++k) \
;         acc[ai][bj][m][n] = __builtin_amdgcn_mfma_f32_16x16x32_bf16(Bt[n][k], At[m][k], acc[ai][bj][m][n], 0, 0, 0); __builtin_amdgcn_s_setprio(0); } while (0)
; #define PG8_WAIT_V(n) asm volatile("s_waitcnt vmcnt(" #n ")" ::: "memory")
; #define PG8_WAIT_L(n) asm volatile("s_waitcnt lgkmcnt(" #n ")" ::: "memory")
; #define PG8_BAR __builtin_amdgcn_s_barrier()
; #define PG8_SCHED __builtin_amdgcn_sched_barrier(0)
; template <class Epi, class Sched, bool ALIGN_EPI = false, bool SP2 = false>
; __device__ __forceinline__ void gemm_phase(PG8_LAS unsigned char* lds, const Gemm g, const Sched& S, const Epi& E) {
;     ...
;         for (int t = 0; t < nt; t += 2) {
;             const bool last = (t == nt - 2);
;             const char* a1 = cA + (size_t)(t + 1) * kstep;
;             const char* a2 = last ? nA : cA + (size_t)(t + 2) * kstep; const char* b2 = last ? nB : cB + (size_t)(t + 2) * kstep;
;             const char* a3 = a2 + kstep; const char* b3 = b2 + kstep;
;             if (last && has_next) S.a_ready(nxt);
;             if constexpr (SP2) {
;             PG8_LDB(B0, 0, 0); PG8_LDB(B1, 0, 1); PG8_SCHED; PG8_LDA(At, 0, 0); PG8_STAGE(PG8_SA(1, 1), a1 + hstep, voffA);
;             PG8_WAIT_V(8); PG8_WAIT_L(0); PG8_BAR; PG8_MMA(0, 0, At, B0); PG8_MMA(0, 1, At, B1); PG8_BAR; PG8_SCHED;
;             PG8_LDA(At, 0, 1); PG8_STAGE(PG8_SB(0, 0), b2, voffB); PG8_STAGE(PG8_SB(0, 1), b2 + hstep, voffB); PG8_STAGE(PG8_SA(0, 0), a2, voffA);
.LBB0_2092:
	s_add_u32 s38, s38, 0xb0080
	s_addc_u32 s39, s39, 0
	s_add_u32 s74, s40, 0x100
	v_mov_b32_e32 v0, 0
	s_addc_u32 s75, s41, 0
	s_mov_b32 s76, -2
	ds_read_b128 v[148:151], v145
	ds_read_b128 v[152:155], v145 offset:1024
	ds_read_b128 v[156:159], v145 offset:2048
	ds_read_b128 v[160:163], v145 offset:3072
	ds_read_b128 v[164:167], v146
	ds_read_b128 v[168:171], v146 offset:1024
	ds_read_b128 v[172:175], v146 offset:2048
	ds_read_b128 v[176:179], v146 offset:3072
	s_add_u32 s40, s38, 0xfff50080
	s_addc_u32 s41, s39, -1
	s_cmp_eq_u32 s76, 40
	s_cselect_b32 s43, s35, s41
	s_cselect_b32 s42, s34, s40
	s_cselect_b32 s41, s37, s75
	s_cselect_b32 s40, s36, s74
	v_lshl_add_u64 v[204:205], s[38:39], 0, v[136:137]
	s_add_i32 m0, s57, 0xc000
	ds_read_b128 v[180:183], v147
	ds_read_b128 v[184:187], v147 offset:1024
	ds_read_b128 v[188:191], v147 offset:2048
	ds_read_b128 v[192:195], v147 offset:3072
	ds_read_b128 v[196:199], v147 offset:4096
	ds_read_b128 v[200:203], v147 offset:5120
	ds_read_b128 v[208:211], v147 offset:6144
	ds_read_b128 v[212:215], v147 offset:7168
	global_load_lds_dwordx4 v[204:205], off
	v_lshl_add_u64 v[204:205], s[38:39], 0, v[138:139]
	s_add_i32 m0, s57, 0xe000
	s_nop 0
	global_load_lds_dwordx4 v[204:205], off
	s_waitcnt vmcnt(8)
	s_waitcnt lgkmcnt(0)
	s_barrier
	s_setprio 1
	s_waitcnt lgkmcnt(0)
	v_mfma_f32_16x16x32_bf16 v[124:127], v[148:151], v[180:183], 0
	v_mfma_f32_16x16x32_bf16 v[120:123], v[156:159], v[180:183], 0
	v_mfma_f32_16x16x32_bf16 v[116:119], v[148:151], v[188:191], 0
	v_mfma_f32_16x16x32_bf16 v[112:115], v[156:159], v[188:191], 0
	v_mfma_f32_16x16x32_bf16 v[100:103], v[148:151], v[196:199], 0
	v_mfma_f32_16x16x32_bf16 v[96:99], v[156:159], v[196:199], 0
	v_mfma_f32_16x16x32_bf16 v[84:87], v[148:151], v[208:211], 0
	v_mfma_f32_16x16x32_bf16 v[80:83], v[156:159], v[208:211], 0
	v_mfma_f32_16x16x32_bf16 v[124:127], v[152:155], v[184:187], v[124:127]
	v_mfma_f32_16x16x32_bf16 v[120:123], v[160:163], v[184:187], v[120:123]
	v_mfma_f32_16x16x32_bf16 v[116:119], v[152:155], v[192:195], v[116:119]
	v_mfma_f32_16x16x32_bf16 v[112:115], v[160:163], v[192:195], v[112:115]
	v_mfma_f32_16x16x32_bf16 v[100:103], v[152:155], v[200:203], v[100:103]
	v_mfma_f32_16x16x32_bf16 v[96:99], v[160:163], v[200:203], v[96:99]
	v_mfma_f32_16x16x32_bf16 v[84:87], v[152:155], v[212:215], v[84:87]
	v_mfma_f32_16x16x32_bf16 v[80:83], v[160:163], v[212:215], v[80:83]
	s_setprio 0
	s_setprio 1
	v_mfma_f32_16x16x32_bf16 v[108:111], v[164:167], v[180:183], 0
	v_mfma_f32_16x16x32_bf16 v[104:107], v[172:175], v[180:183], 0
	v_mfma_f32_16x16x32_bf16 v[92:95], v[164:167], v[188:191], 0
	v_mfma_f32_16x16x32_bf16 v[88:91], v[172:175], v[188:191], 0
	v_mfma_f32_16x16x32_bf16 v[76:79], v[164:167], v[196:199], 0
	v_mfma_f32_16x16x32_bf16 v[72:75], v[172:175], v[196:199], 0
	v_mfma_f32_16x16x32_bf16 v[68:71], v[164:167], v[208:211], 0
	v_mfma_f32_16x16x32_bf16 v[64:67], v[172:175], v[208:211], 0
	v_mfma_f32_16x16x32_bf16 v[108:111], v[168:171], v[184:187], v[108:111]
	v_mfma_f32_16x16x32_bf16 v[104:107], v[176:179], v[184:187], v[104:107]
	v_mfma_f32_16x16x32_bf16 v[92:95], v[168:171], v[192:195], v[92:95]
	v_mfma_f32_16x16x32_bf16 v[88:91], v[176:179], v[192:195], v[88:91]
	v_mfma_f32_16x16x32_bf16 v[76:79], v[168:171], v[200:203], v[76:79]
	v_mfma_f32_16x16x32_bf16 v[72:75], v[176:179], v[200:203], v[72:75]
	v_mfma_f32_16x16x32_bf16 v[68:71], v[168:171], v[212:215], v[68:71]
	v_mfma_f32_16x16x32_bf16 v[64:67], v[176:179], v[212:215], v[64:67]
	s_setprio 0
	s_barrier
	s_add_i32 s77, s64, s52
	v_lshl_add_u64 v[204:205], s[40:41], 0, v[130:131]
	s_mov_b32 m0, s77
	ds_read_b128 v[180:183], v147 offset:16384
	ds_read_b128 v[184:187], v147 offset:17408
	ds_read_b128 v[188:191], v147 offset:18432
	ds_read_b128 v[192:195], v147 offset:19456
	ds_read_b128 v[196:199], v147 offset:20480
	ds_read_b128 v[200:203], v147 offset:21504
	ds_read_b128 v[208:211], v147 offset:22528
	ds_read_b128 v[212:215], v147 offset:23552
	global_load_lds_dwordx4 v[204:205], off
	s_add_i32 m0, s77, 0x2000
	s_add_u32 s78, s40, 0xb0000
	v_lshl_add_u64 v[216:217], s[40:41], 0, v[134:135]
	s_addc_u32 s79, s41, 0
	s_add_i32 s77, s65, s52
	global_load_lds_dwordx4 v[216:217], off
	v_lshl_add_u64 v[218:219], s[78:79], 0, v[130:131]
	s_mov_b32 m0, s77
	v_lshl_add_u64 v[220:221], s[42:43], 0, v[132:133]
	global_load_lds_dwordx4 v[218:219], off
	v_lshl_add_u64 v[218:219], s[78:79], 0, v[134:135]
	s_add_i32 m0, s77, 0x2000
	s_nop 0
	global_load_lds_dwordx4 v[218:219], off
	v_lshl_add_u64 v[218:219], s[42:43], 0, v[128:129]
	s_mov_b32 m0, s57
	s_nop 0
	global_load_lds_dwordx4 v[218:219], off
	s_mov_b32 m0, s58
	s_nop 0
	global_load_lds_dwordx4 v[220:221], off
	s_waitcnt vmcnt(8)
	s_waitcnt lgkmcnt(0)
	s_barrier
; #define PG8_STAGE(bufoff, gbase, voff) do { _Pragma("unroll") for (int _i = 0; _i < 2; ++_i) \
;         __builtin_amdgcn_global_load_lds((const unsigned*)((const char*)(gbase) + (voff)[_i]), (PG8_LAS unsigned*)(lds + (bufoff) + ldsw + _i * 8192), 16, 0, 0); } while (0)
; #define PG8_LDA(dst, b, h) do { _Pragma("unroll") for (int m = 0; m < 4; ++m) _Pragma("unroll") for (int k = 0; k < 2; ++k) dst[m][k] = *(const PG8_LAS bf16x8*)(lds + PG8_SA(b, h) + aoff + m * 2048 + k * 1024); } while (0)
; #define PG8_LDB(dst, b, h) do { _Pragma("unroll") for (int n = 0; n < 2; ++n) _Pragma("unroll") for (int k = 0; k < 2; ++k) dst[n][k] = *(const PG8_LAS bf16x8*)(lds + PG8_SB(b, h) + boff + n * 2048 + k * 1024); } while (0)
; #define PG8_MMA(ai, bj, At, Bt) do { __builtin_amdgcn_s_setprio(1); _Pragma("unroll") for (int m = 0; m < 4; ++m) _Pragma("unroll") for (int n = 0; n < 2; ++n) _Pragma("unroll") for (int k = 0; k < 2; ++k) \
;         acc[ai][bj][m][n] = __builtin_amdgcn_mfma_f32_16x16x32_bf16(Bt[n][k], At[m][k], acc[ai][bj][m][n], 0, 0, 0); __builtin_amdgcn_s_setprio(0); } while (0)
; #define PG8_WAIT_V(n) asm volatile("s_waitcnt vmcnt(" #n ")" ::: "memory")
; #define PG8_WAIT_L(n) asm volatile("s_waitcnt lgkmcnt(" #n ")" ::: "memory")
; #define PG8_BAR __builtin_amdgcn_s_barrier()
; #define PG8_SCHED __builtin_amdgcn_sched_barrier(0)
; template <class Epi, class Sched, bool ALIGN_EPI = false, bool SP2 = false>
; __device__ __forceinline__ void gemm_phase(PG8_LAS unsigned char* lds, const Gemm g, const Sched& S, const Epi& E) {
;     ...
;             PG8_WAIT_V(8); PG8_WAIT_L(0); PG8_BAR; PG8_MMA(1, 0, At, B0); PG8_MMA(1, 1, At, B1); PG8_BAR; PG8_SCHED;
;             PG8_LDB(B0, 1, 0); PG8_LDB(B1, 1, 1); PG8_SCHED; PG8_LDA(At, 1, 0); PG8_STAGE(PG8_SA(0, 1), a2 + hstep, voffA);
;             PG8_WAIT_V(8); PG8_WAIT_L(0); PG8_BAR; PG8_MMA(0, 0, At, B0); PG8_MMA(0, 1, At, B1); PG8_BAR; PG8_SCHED;
	s_setprio 1
	s_waitcnt lgkmcnt(0)
	v_mfma_f32_16x16x32_bf16 v[60:63], v[148:151], v[180:183], 0
	v_mfma_f32_16x16x32_bf16 v[56:59], v[156:159], v[180:183], 0
	v_mfma_f32_16x16x32_bf16 v[52:55], v[148:151], v[188:191], 0
	v_mfma_f32_16x16x32_bf16 v[48:51], v[156:159], v[188:191], 0
	v_mfma_f32_16x16x32_bf16 v[36:39], v[148:151], v[196:199], 0
	v_mfma_f32_16x16x32_bf16 v[32:35], v[156:159], v[196:199], 0
	v_mfma_f32_16x16x32_bf16 v[20:23], v[148:151], v[208:211], 0
	v_mfma_f32_16x16x32_bf16 v[16:19], v[156:159], v[208:211], 0
	v_mfma_f32_16x16x32_bf16 v[60:63], v[152:155], v[184:187], v[60:63]
	v_mfma_f32_16x16x32_bf16 v[56:59], v[160:163], v[184:187], v[56:59]
	v_mfma_f32_16x16x32_bf16 v[52:55], v[152:155], v[192:195], v[52:55]
	v_mfma_f32_16x16x32_bf16 v[48:51], v[160:163], v[192:195], v[48:51]
	v_mfma_f32_16x16x32_bf16 v[36:39], v[152:155], v[200:203], v[36:39]
	v_mfma_f32_16x16x32_bf16 v[32:35], v[160:163], v[200:203], v[32:35]
	v_mfma_f32_16x16x32_bf16 v[20:23], v[152:155], v[212:215], v[20:23]
	v_mfma_f32_16x16x32_bf16 v[16:19], v[160:163], v[212:215], v[16:19]
	s_setprio 0
	s_setprio 1
	v_mfma_f32_16x16x32_bf16 v[44:47], v[164:167], v[180:183], 0
	v_mfma_f32_16x16x32_bf16 v[40:43], v[172:175], v[180:183], 0
	v_mfma_f32_16x16x32_bf16 v[28:31], v[164:167], v[188:191], 0
	v_mfma_f32_16x16x32_bf16 v[24:27], v[172:175], v[188:191], 0
	v_mfma_f32_16x16x32_bf16 v[12:15], v[164:167], v[196:199], 0
	v_mfma_f32_16x16x32_bf16 v[8:11], v[172:175], v[196:199], 0
	v_mfma_f32_16x16x32_bf16 v[4:7], v[164:167], v[208:211], 0
	v_mfma_f32_16x16x32_bf16 v[0:3], v[172:175], v[208:211], 0
	v_mfma_f32_16x16x32_bf16 v[44:47], v[168:171], v[184:187], v[44:47]
	v_mfma_f32_16x16x32_bf16 v[40:43], v[176:179], v[184:187], v[40:43]
	v_mfma_f32_16x16x32_bf16 v[28:31], v[168:171], v[192:195], v[28:31]
	v_mfma_f32_16x16x32_bf16 v[24:27], v[176:179], v[192:195], v[24:27]
	v_mfma_f32_16x16x32_bf16 v[12:15], v[168:171], v[200:203], v[12:15]
	v_mfma_f32_16x16x32_bf16 v[8:11], v[176:179], v[200:203], v[8:11]
	v_mfma_f32_16x16x32_bf16 v[4:7], v[168:171], v[212:215], v[4:7]
	v_mfma_f32_16x16x32_bf16 v[0:3], v[176:179], v[212:215], v[0:3]
	s_setprio 0
	s_barrier
	s_add_i32 s77, 0, 0x18000
	s_add_i32 s78, 0, 0x1c000
	v_add_u32_e32 v160, s77, v143
	v_add_u32_e32 v176, s78, v143
	ds_read_b128 v[148:151], v160
	ds_read_b128 v[152:155], v160 offset:1024
	ds_read_b128 v[156:159], v160 offset:2048
	ds_read_b128 v[160:163], v160 offset:3072
	ds_read_b128 v[164:167], v176
	ds_read_b128 v[168:171], v176 offset:1024
	ds_read_b128 v[172:175], v176 offset:2048
	ds_read_b128 v[176:179], v176 offset:3072
	s_add_u32 s42, s42, 0xb0000
	s_addc_u32 s43, s43, 0
	s_mov_b32 m0, s59
	v_lshl_add_u64 v[222:223], s[42:43], 0, v[128:129]
	ds_read_b128 v[180:183], v147 offset:32768
	ds_read_b128 v[184:187], v147 offset:33792
	ds_read_b128 v[188:191], v147 offset:34816
	ds_read_b128 v[192:195], v147 offset:35840
	ds_read_b128 v[196:199], v147 offset:36864
	ds_read_b128 v[200:203], v147 offset:37888
	ds_read_b128 v[208:211], v147 offset:38912
	ds_read_b128 v[212:215], v147 offset:39936
	global_load_lds_dwordx4 v[222:223], off
	v_lshl_add_u64 v[222:223], s[42:43], 0, v[132:133]
	s_mov_b32 m0, s60
	s_nop 0
	global_load_lds_dwordx4 v[222:223], off
	s_waitcnt vmcnt(8)
	s_waitcnt lgkmcnt(0)
	s_barrier
	s_setprio 1
	s_waitcnt lgkmcnt(0)
	v_mfma_f32_16x16x32_bf16 v[124:127], v[148:151], v[180:183], v[124:127]
	v_mfma_f32_16x16x32_bf16 v[120:123], v[156:159], v[180:183], v[120:123]
	v_mfma_f32_16x16x32_bf16 v[116:119], v[148:151], v[188:191], v[116:119]
	v_mfma_f32_16x16x32_bf16 v[112:115], v[156:159], v[188:191], v[112:115]
	v_mfma_f32_16x16x32_bf16 v[100:103], v[148:151], v[196:199], v[100:103]
	v_mfma_f32_16x16x32_bf16 v[96:99], v[156:159], v[196:199], v[96:99]
	v_mfma_f32_16x16x32_bf16 v[84:87], v[148:151], v[208:211], v[84:87]
	v_mfma_f32_16x16x32_bf16 v[80:83], v[156:159], v[208:211], v[80:83]
	v_mfma_f32_16x16x32_bf16 v[124:127], v[152:155], v[184:187], v[124:127]
	v_mfma_f32_16x16x32_bf16 v[120:123], v[160:163], v[184:187], v[120:123]
	v_mfma_f32_16x16x32_bf16 v[116:119], v[152:155], v[192:195], v[116:119]
	v_mfma_f32_16x16x32_bf16 v[112:115], v[160:163], v[192:195], v[112:115]
	v_mfma_f32_16x16x32_bf16 v[100:103], v[152:155], v[200:203], v[100:103]
	v_mfma_f32_16x16x32_bf16 v[96:99], v[160:163], v[200:203], v[96:99]
	v_mfma_f32_16x16x32_bf16 v[84:87], v[152:155], v[212:215], v[84:87]
	v_mfma_f32_16x16x32_bf16 v[80:83], v[160:163], v[212:215], v[80:83]
	s_setprio 0
	s_setprio 1
	v_mfma_f32_16x16x32_bf16 v[108:111], v[164:167], v[180:183], v[108:111]
	v_mfma_f32_16x16x32_bf16 v[104:107], v[172:175], v[180:183], v[104:107]
	v_mfma_f32_16x16x32_bf16 v[92:95], v[164:167], v[188:191], v[92:95]
	v_mfma_f32_16x16x32_bf16 v[88:91], v[172:175], v[188:191], v[88:91]
	v_mfma_f32_16x16x32_bf16 v[76:79], v[164:167], v[196:199], v[76:79]
	v_mfma_f32_16x16x32_bf16 v[72:75], v[172:175], v[196:199], v[72:75]
	v_mfma_f32_16x16x32_bf16 v[68:71], v[164:167], v[208:211], v[68:71]
	v_mfma_f32_16x16x32_bf16 v[64:67], v[172:175], v[208:211], v[64:67]
	v_mfma_f32_16x16x32_bf16 v[108:111], v[168:171], v[184:187], v[108:111]
	v_mfma_f32_16x16x32_bf16 v[104:107], v[176:179], v[184:187], v[104:107]
	v_mfma_f32_16x16x32_bf16 v[92:95], v[168:171], v[192:195], v[92:95]
	v_mfma_f32_16x16x32_bf16 v[88:91], v[176:179], v[192:195], v[88:91]
	v_mfma_f32_16x16x32_bf16 v[76:79], v[168:171], v[200:203], v[76:79]
	v_mfma_f32_16x16x32_bf16 v[72:75], v[176:179], v[200:203], v[72:75]
	v_mfma_f32_16x16x32_bf16 v[68:71], v[168:171], v[212:215], v[68:71]
	v_mfma_f32_16x16x32_bf16 v[64:67], v[176:179], v[212:215], v[64:67]
	s_setprio 0
	s_barrier
; #define PG8_STAGE(bufoff, gbase, voff) do { _Pragma("unroll") for (int _i = 0; _i < 2; ++_i) \
;         __builtin_amdgcn_global_load_lds((const unsigned*)((const char*)(gbase) + (voff)[_i]), (PG8_LAS unsigned*)(lds + (bufoff) + ldsw + _i * 8192), 16, 0, 0); } while (0)
; #define PG8_LDA(dst, b, h) do { _Pragma("unroll") for (int m = 0; m < 4; ++m) _Pragma("unroll") for (int k = 0; k < 2; ++k) dst[m][k] = *(const PG8_LAS bf16x8*)(lds + PG8_SA(b, h) + aoff + m * 2048 + k * 1024); } while (0)
; #define PG8_MMA(ai, bj, At, Bt) do { __builtin_amdgcn_s_setprio(1); _Pragma("unroll") for (int m = 0; m < 4; ++m) _Pragma("unroll") for (int n = 0; n < 2; ++n) _Pragma("unroll") for (int k = 0; k < 2; ++k) \
;         acc[ai][bj][m][n] = __builtin_amdgcn_mfma_f32_16x16x32_bf16(Bt[n][k], At[m][k], acc[ai][bj][m][n], 0, 0, 0); __builtin_amdgcn_s_setprio(0); } while (0)
; #define PG8_WAIT_V(n) asm volatile("s_waitcnt vmcnt(" #n ")" ::: "memory")
; #define PG8_WAIT_L(n) asm volatile("s_waitcnt lgkmcnt(" #n ")" ::: "memory")
; #define PG8_BAR __builtin_amdgcn_s_barrier()
; #define PG8_SCHED __builtin_amdgcn_sched_barrier(0)
; template <class Epi, class Sched, bool ALIGN_EPI = false, bool SP2 = false>
; __device__ __forceinline__ void gemm_phase(PG8_LAS unsigned char* lds, const Gemm g, const Sched& S, const Epi& E) {
;     ...
;         for (int t = 0; t < nt; t += 2) {
;             const bool last = (t == nt - 2);
;             const char* a1 = cA + (size_t)(t + 1) * kstep;
;             const char* a2 = last ? nA : cA + (size_t)(t + 2) * kstep; const char* b2 = last ? nB : cB + (size_t)(t + 2) * kstep;
;             const char* a3 = a2 + kstep; const char* b3 = b2 + kstep;
;     ...
;             PG8_LDA(At, 1, 1); PG8_STAGE(PG8_SB(1, 0), b3, voffB); PG8_STAGE(PG8_SB(1, 1), b3 + hstep, voffB); PG8_STAGE(PG8_SA(1, 0), a3, voffA);
;             PG8_WAIT_V(8); PG8_WAIT_L(0); PG8_BAR; PG8_MMA(1, 0, At, B0); PG8_MMA(1, 1, At, B1); PG8_BAR; PG8_SCHED;
	s_add_i32 s42, s77, s52
	v_lshl_add_u64 v[204:205], v[204:205], 0, s[18:19]
	s_mov_b32 m0, s42
	ds_read_b128 v[180:183], v147 offset:49152
	ds_read_b128 v[184:187], v147 offset:50176
	ds_read_b128 v[188:191], v147 offset:51200
	ds_read_b128 v[192:195], v147 offset:52224
	ds_read_b128 v[196:199], v147 offset:53248
	ds_read_b128 v[200:203], v147 offset:54272
	ds_read_b128 v[208:211], v147 offset:55296
	ds_read_b128 v[212:215], v147 offset:56320
	global_load_lds_dwordx4 v[204:205], off
	s_add_i32 m0, s42, 0x2000
	s_add_u32 s40, s40, 0xb0080
	v_lshl_add_u64 v[204:205], v[216:217], 0, s[18:19]
	s_addc_u32 s41, s41, 0
	s_add_i32 s42, s78, s52
	global_load_lds_dwordx4 v[204:205], off
	v_lshl_add_u64 v[204:205], s[40:41], 0, v[130:131]
	s_mov_b32 m0, s42
	s_nop 0
	global_load_lds_dwordx4 v[204:205], off
	v_lshl_add_u64 v[204:205], s[40:41], 0, v[134:135]
	s_add_i32 m0, s42, 0x2000
	s_nop 0
	global_load_lds_dwordx4 v[204:205], off
	v_lshl_add_u64 v[204:205], v[218:219], 0, s[18:19]
	s_mov_b32 m0, s62
	s_nop 0
	global_load_lds_dwordx4 v[204:205], off
	v_lshl_add_u64 v[204:205], v[220:221], 0, s[18:19]
	s_mov_b32 m0, s63
	s_nop 0
	global_load_lds_dwordx4 v[204:205], off
	s_waitcnt vmcnt(8)
	s_waitcnt lgkmcnt(0)
	s_barrier
	s_setprio 1
	s_waitcnt lgkmcnt(0)
	v_mfma_f32_16x16x32_bf16 v[60:63], v[148:151], v[180:183], v[60:63]
	v_mfma_f32_16x16x32_bf16 v[56:59], v[156:159], v[180:183], v[56:59]
	v_mfma_f32_16x16x32_bf16 v[52:55], v[148:151], v[188:191], v[52:55]
	v_mfma_f32_16x16x32_bf16 v[48:51], v[156:159], v[188:191], v[48:51]
	v_mfma_f32_16x16x32_bf16 v[36:39], v[148:151], v[196:199], v[36:39]
	v_mfma_f32_16x16x32_bf16 v[32:35], v[156:159], v[196:199], v[32:35]
	v_mfma_f32_16x16x32_bf16 v[20:23], v[148:151], v[208:211], v[20:23]
	v_mfma_f32_16x16x32_bf16 v[16:19], v[156:159], v[208:211], v[16:19]
	v_mfma_f32_16x16x32_bf16 v[60:63], v[152:155], v[184:187], v[60:63]
	v_mfma_f32_16x16x32_bf16 v[56:59], v[160:163], v[184:187], v[56:59]
	v_mfma_f32_16x16x32_bf16 v[52:55], v[152:155], v[192:195], v[52:55]
	v_mfma_f32_16x16x32_bf16 v[48:51], v[160:163], v[192:195], v[48:51]
	v_mfma_f32_16x16x32_bf16 v[36:39], v[152:155], v[200:203], v[36:39]
	v_mfma_f32_16x16x32_bf16 v[32:35], v[160:163], v[200:203], v[32:35]
	v_mfma_f32_16x16x32_bf16 v[20:23], v[152:155], v[212:215], v[20:23]
	v_mfma_f32_16x16x32_bf16 v[16:19], v[160:163], v[212:215], v[16:19]
	s_setprio 0
	s_setprio 1
	v_mfma_f32_16x16x32_bf16 v[44:47], v[164:167], v[180:183], v[44:47]
	v_mfma_f32_16x16x32_bf16 v[40:43], v[172:175], v[180:183], v[40:43]
	v_mfma_f32_16x16x32_bf16 v[28:31], v[164:167], v[188:191], v[28:31]
	v_mfma_f32_16x16x32_bf16 v[24:27], v[172:175], v[188:191], v[24:27]
	v_mfma_f32_16x16x32_bf16 v[12:15], v[164:167], v[196:199], v[12:15]
	v_mfma_f32_16x16x32_bf16 v[8:11], v[172:175], v[196:199], v[8:11]
	v_mfma_f32_16x16x32_bf16 v[4:7], v[164:167], v[208:211], v[4:7]
	v_mfma_f32_16x16x32_bf16 v[0:3], v[172:175], v[208:211], v[0:3]
	v_mfma_f32_16x16x32_bf16 v[44:47], v[168:171], v[184:187], v[44:47]
	v_mfma_f32_16x16x32_bf16 v[40:43], v[176:179], v[184:187], v[40:43]
	v_mfma_f32_16x16x32_bf16 v[28:31], v[168:171], v[192:195], v[28:31]
	v_mfma_f32_16x16x32_bf16 v[24:27], v[176:179], v[192:195], v[24:27]
	v_mfma_f32_16x16x32_bf16 v[12:15], v[168:171], v[200:203], v[12:15]
	v_mfma_f32_16x16x32_bf16 v[8:11], v[176:179], v[200:203], v[8:11]
	v_mfma_f32_16x16x32_bf16 v[4:7], v[168:171], v[212:215], v[4:7]
	v_mfma_f32_16x16x32_bf16 v[0:3], v[176:179], v[212:215], v[0:3]
	s_setprio 0
	s_barrier
	s_add_i32 s76, s76, 2
	s_add_u32 s38, s38, 0x100
	s_addc_u32 s39, s39, 0
	s_add_u32 s74, s74, 0x100
	s_addc_u32 s75, s75, 0
	s_cmp_gt_u32 s76, 41
	s_cbranch_scc0 .LBB0_2093
	s_branch .Lpeel_exit_16
